# K-loops: removed the back-to-back s_setprio 0 / s_setprio 1 pair in the middle of every 32-MFMA block (priority stays 1 for the whole block; two fewer issue slots between MFMAs)
# speedup vs baseline: 1.0031x; 1.0031x over previous
; #define PG8_STAGE(bufoff, gbase, voff) do { _Pragma("unroll") for (int _i = 0; _i < 2; ++_i) \
;         __builtin_amdgcn_global_load_lds((const unsigned*)((const char*)(gbase) + (voff)[_i]), (PG8_LAS unsigned*)(lds + (bufoff) + ldsw + _i * 8192), 16, 0, 0); } while (0)
; #define PG8_LDA(dst, b, h) do { _Pragma("unroll") for (int m = 0; m < 4; ++m) _Pragma("unroll") for (int k = 0; k < 2; ++k) dst[m][k] = *(const PG8_LAS bf16x8*)(lds + PG8_SA(b, h) + aoff + m * 2048 + k * 1024); } while (0)
; #define PG8_LDB(dst, b, h) do { _Pragma("unroll") for (int n = 0; n < 2; ++n) _Pragma("unroll") for (int k = 0; k < 2; ++k) dst[n][k] = *(const PG8_LAS bf16x8*)(lds + PG8_SB(b, h) + boff + n * 2048 + k * 1024); } while (0)
; #define PG8_MMA(ai, bj, At, Bt) do { __builtin_amdgcn_s_setprio(1); _Pragma("unroll") for (int m = 0; m < 4; ++m) _Pragma("unroll") for (int n = 0; n < 2; ++n) _Pragma("unroll") for (int k = 0; k < 2; ++k) \
;         acc[ai][bj][m][n] = mma16<Epi::F16>(Bt[n][k], At[m][k], acc[ai][bj][m][n]); __builtin_amdgcn_s_setprio(0); } while (0)
; #define PG8_WAIT_V(n) asm volatile("s_waitcnt vmcnt(" #n ")" ::: "memory")
; #define PG8_WAIT_L(n) asm volatile("s_waitcnt lgkmcnt(" #n ")" ::: "memory")
; #define PG8_BAR __builtin_amdgcn_s_barrier()
; #define PG8_SCHED __builtin_amdgcn_sched_barrier(0)
; template <class Epi, class Sched, bool ALIGN_EPI = false, bool SP2 = false>
; __device__ __forceinline__ void gemm_phase(PG8_LAS unsigned char* lds, const Gemm g, const Sched& S, const Epi& E) {
;     ...
;             PG8_LDB(B0, 0, 0); PG8_LDB(B1, 0, 1); PG8_SCHED; PG8_LDA(At, 0, 0); PG8_STAGE(PG8_SA(1, 1), a1 + hstep, voffA);
;             PG8_WAIT_V(8); PG8_WAIT_L(0); PG8_BAR; PG8_MMA(0, 0, At, B0); PG8_MMA(0, 1, At, B1); PG8_BAR; PG8_SCHED;
;             PG8_LDA(At, 0, 1); PG8_STAGE(PG8_SB(0, 0), b2, voffB); PG8_STAGE(PG8_SB(0, 1), b2 + hstep, voffB); PG8_STAGE(PG8_SA(0, 0), a2, voffA);
;             PG8_WAIT_V(8); PG8_WAIT_L(0); PG8_BAR; PG8_MMA(1, 0, At, B0); PG8_MMA(1, 1, At, B1); PG8_BAR; PG8_SCHED;
.Lpeel_k1:
	s_add_u32 s30, s30, 0x80
	s_addc_u32 s31, s31, 0
	s_add_u32 s77, s34, 0x100
	s_addc_u32 s82, s35, 0
	s_mov_b32 s34, 0
	s_add_i32 s84, s34, 2
	s_add_u32 s85, s30, 0x80
	s_addc_u32 s35, s31, 0
	s_add_i32 s92, 0, 0x10000
	s_cmp_eq_u32 s68, s34
	s_cselect_b32 s35, s1, s35
	s_cselect_b32 s34, s0, s85
	v_add_u32_e32 v146, s92, v151
	s_cselect_b32 s97, s57, s82
	s_cselect_b32 s96, s56, s77
	s_add_i32 s85, 0, 0x14000
	ds_read_b128 v[142:145], v146
	ds_read_b128 v[162:165], v146 offset:1024
	ds_read_b128 v[166:169], v146 offset:2048
	ds_read_b128 v[170:173], v146 offset:3072
	v_add_u32_e32 v146, s85, v151
	ds_read_b128 v[174:177], v146
	ds_read_b128 v[178:181], v146 offset:1024
	ds_read_b128 v[182:185], v146 offset:2048
	ds_read_b128 v[186:189], v146 offset:3072
	v_lshl_add_u64 v[148:149], s[30:31], 0, v[138:139]
	s_add_i32 m0, s61, 0xc000
	ds_read_b128 v[190:193], v161
	ds_read_b128 v[194:197], v161 offset:1024
	ds_read_b128 v[198:201], v161 offset:2048
	ds_read_b128 v[202:205], v161 offset:3072
	ds_read_b128 v[212:215], v161 offset:4096
	ds_read_b128 v[216:219], v161 offset:5120
	ds_read_b128 v[220:223], v161 offset:6144
	ds_read_b128 v[224:227], v161 offset:7168
	global_load_lds_dwordx4 v[148:149], off
	v_lshl_add_u64 v[148:149], s[30:31], 0, v[140:141]
	s_add_i32 m0, s61, 0xe000
	s_nop 0
	global_load_lds_dwordx4 v[148:149], off
	s_waitcnt vmcnt(8)
	s_waitcnt lgkmcnt(0)
	s_barrier
	s_setprio 1
	s_waitcnt lgkmcnt(0)
	v_mfma_f32_16x16x32_bf16 v[120:123], v[142:145], v[190:193], 0
	v_mfma_f32_16x16x32_bf16 v[116:119], v[166:169], v[190:193], 0
	v_mfma_f32_16x16x32_bf16 v[108:111], v[142:145], v[198:201], 0
	v_mfma_f32_16x16x32_bf16 v[100:103], v[166:169], v[198:201], 0
	v_mfma_f32_16x16x32_bf16 v[92:95], v[142:145], v[212:215], 0
	v_mfma_f32_16x16x32_bf16 v[84:87], v[166:169], v[212:215], 0
	v_mfma_f32_16x16x32_bf16 v[76:79], v[142:145], v[220:223], 0
	v_mfma_f32_16x16x32_bf16 v[68:71], v[166:169], v[220:223], 0
	v_mfma_f32_16x16x32_bf16 v[120:123], v[162:165], v[194:197], v[120:123]
	v_mfma_f32_16x16x32_bf16 v[116:119], v[170:173], v[194:197], v[116:119]
	v_mfma_f32_16x16x32_bf16 v[108:111], v[162:165], v[202:205], v[108:111]
	v_mfma_f32_16x16x32_bf16 v[100:103], v[170:173], v[202:205], v[100:103]
	v_mfma_f32_16x16x32_bf16 v[92:95], v[162:165], v[216:219], v[92:95]
	v_mfma_f32_16x16x32_bf16 v[84:87], v[170:173], v[216:219], v[84:87]
	v_mfma_f32_16x16x32_bf16 v[76:79], v[162:165], v[224:227], v[76:79]
	v_mfma_f32_16x16x32_bf16 v[68:71], v[170:173], v[224:227], v[68:71]
	v_mfma_f32_16x16x32_bf16 v[124:127], v[174:177], v[190:193], 0
	v_mfma_f32_16x16x32_bf16 v[112:115], v[182:185], v[190:193], 0
	v_mfma_f32_16x16x32_bf16 v[104:107], v[174:177], v[198:201], 0
	v_mfma_f32_16x16x32_bf16 v[96:99], v[182:185], v[198:201], 0
	v_mfma_f32_16x16x32_bf16 v[88:91], v[174:177], v[212:215], 0
	v_mfma_f32_16x16x32_bf16 v[80:83], v[182:185], v[212:215], 0
	v_mfma_f32_16x16x32_bf16 v[72:75], v[174:177], v[220:223], 0
	v_mfma_f32_16x16x32_bf16 v[64:67], v[182:185], v[220:223], 0
	v_mfma_f32_16x16x32_bf16 v[124:127], v[178:181], v[194:197], v[124:127]
	v_mfma_f32_16x16x32_bf16 v[112:115], v[186:189], v[194:197], v[112:115]
	v_mfma_f32_16x16x32_bf16 v[104:107], v[178:181], v[202:205], v[104:107]
	v_mfma_f32_16x16x32_bf16 v[96:99], v[186:189], v[202:205], v[96:99]
	v_mfma_f32_16x16x32_bf16 v[88:91], v[178:181], v[216:219], v[88:91]
	v_mfma_f32_16x16x32_bf16 v[80:83], v[186:189], v[216:219], v[80:83]
	v_mfma_f32_16x16x32_bf16 v[72:75], v[178:181], v[224:227], v[72:75]
	v_mfma_f32_16x16x32_bf16 v[64:67], v[186:189], v[224:227], v[64:67]
	s_setprio 0
	s_barrier
	s_add_i32 s92, s92, s11
	v_lshl_add_u64 v[148:149], s[96:97], 0, v[132:133]
	s_mov_b32 m0, s92
	ds_read_b128 v[190:193], v161 offset:16384
	ds_read_b128 v[194:197], v161 offset:17408
	ds_read_b128 v[198:201], v161 offset:18432
	ds_read_b128 v[202:205], v161 offset:19456
	ds_read_b128 v[212:215], v161 offset:20480
	ds_read_b128 v[216:219], v161 offset:21504
	ds_read_b128 v[220:223], v161 offset:22528
	ds_read_b128 v[224:227], v161 offset:23552
	global_load_lds_dwordx4 v[148:149], off
	s_add_i32 m0, s92, 0x2000
	v_lshl_add_u64 v[152:153], s[96:97], 0, v[128:129]
	s_add_u32 s96, s96, s44
	s_addc_u32 s97, s97, s45
	s_add_i32 s85, s85, s11
	global_load_lds_dwordx4 v[152:153], off
	v_lshl_add_u64 v[206:207], s[96:97], 0, v[132:133]
	s_mov_b32 m0, s85
	v_lshl_add_u64 v[228:229], s[96:97], 0, v[128:129]
	global_load_lds_dwordx4 v[206:207], off
	s_add_i32 m0, s85, 0x2000
	v_lshl_add_u64 v[230:231], s[34:35], 0, v[134:135]
	global_load_lds_dwordx4 v[228:229], off
	s_mov_b32 m0, s61
	v_lshl_add_u64 v[232:233], s[34:35], 0, v[130:131]
	global_load_lds_dwordx4 v[230:231], off
	s_mov_b32 m0, s62
	s_nop 0
	global_load_lds_dwordx4 v[232:233], off
	s_waitcnt vmcnt(8)
	s_waitcnt lgkmcnt(0)
	s_barrier
; #define PG8_STAGE(bufoff, gbase, voff) do { _Pragma("unroll") for (int _i = 0; _i < 2; ++_i) \
;         __builtin_amdgcn_global_load_lds((const unsigned*)((const char*)(gbase) + (voff)[_i]), (PG8_LAS unsigned*)(lds + (bufoff) + ldsw + _i * 8192), 16, 0, 0); } while (0)
; #define PG8_LDA(dst, b, h) do { _Pragma("unroll") for (int m = 0; m < 4; ++m) _Pragma("unroll") for (int k = 0; k < 2; ++k) dst[m][k] = *(const PG8_LAS bf16x8*)(lds + PG8_SA(b, h) + aoff + m * 2048 + k * 1024); } while (0)
; #define PG8_LDB(dst, b, h) do { _Pragma("unroll") for (int n = 0; n < 2; ++n) _Pragma("unroll") for (int k = 0; k < 2; ++k) dst[n][k] = *(const PG8_LAS bf16x8*)(lds + PG8_SB(b, h) + boff + n * 2048 + k * 1024); } while (0)
; #define PG8_MMA(ai, bj, At, Bt) do { __builtin_amdgcn_s_setprio(1); _Pragma("unroll") for (int m = 0; m < 4; ++m) _Pragma("unroll") for (int n = 0; n < 2; ++n) _Pragma("unroll") for (int k = 0; k < 2; ++k) \
;         acc[ai][bj][m][n] = mma16<Epi::F16>(Bt[n][k], At[m][k], acc[ai][bj][m][n]); __builtin_amdgcn_s_setprio(0); } while (0)
; #define PG8_WAIT_V(n) asm volatile("s_waitcnt vmcnt(" #n ")" ::: "memory")
; #define PG8_WAIT_L(n) asm volatile("s_waitcnt lgkmcnt(" #n ")" ::: "memory")
; #define PG8_BAR __builtin_amdgcn_s_barrier()
; #define PG8_SCHED __builtin_amdgcn_sched_barrier(0)
; template <class Epi, class Sched, bool ALIGN_EPI = false, bool SP2 = false>
; __device__ __forceinline__ void gemm_phase(PG8_LAS unsigned char* lds, const Gemm g, const Sched& S, const Epi& E) {
;     ...
;             PG8_WAIT_V(8); PG8_WAIT_L(0); PG8_BAR; PG8_MMA(1, 0, At, B0); PG8_MMA(1, 1, At, B1); PG8_BAR; PG8_SCHED;
;             PG8_LDB(B0, 1, 0); PG8_LDB(B1, 1, 1); PG8_SCHED; PG8_LDA(At, 1, 0); PG8_STAGE(PG8_SA(0, 1), a2 + hstep, voffA);
;             PG8_WAIT_V(8); PG8_WAIT_L(0); PG8_BAR; PG8_MMA(0, 0, At, B0); PG8_MMA(0, 1, At, B1); PG8_BAR; PG8_SCHED;
	s_setprio 1
	s_waitcnt lgkmcnt(0)
	v_mfma_f32_16x16x32_bf16 v[60:63], v[142:145], v[190:193], 0
	v_mfma_f32_16x16x32_bf16 v[52:55], v[166:169], v[190:193], 0
	v_mfma_f32_16x16x32_bf16 v[44:47], v[142:145], v[198:201], 0
	v_mfma_f32_16x16x32_bf16 v[36:39], v[166:169], v[198:201], 0
	v_mfma_f32_16x16x32_bf16 v[28:31], v[142:145], v[212:215], 0
	v_mfma_f32_16x16x32_bf16 v[20:23], v[166:169], v[212:215], 0
	v_mfma_f32_16x16x32_bf16 v[12:15], v[142:145], v[220:223], 0
	v_mfma_f32_16x16x32_bf16 v[4:7], v[166:169], v[220:223], 0
	v_mfma_f32_16x16x32_bf16 v[60:63], v[162:165], v[194:197], v[60:63]
	v_mfma_f32_16x16x32_bf16 v[52:55], v[170:173], v[194:197], v[52:55]
	v_mfma_f32_16x16x32_bf16 v[44:47], v[162:165], v[202:205], v[44:47]
	v_mfma_f32_16x16x32_bf16 v[36:39], v[170:173], v[202:205], v[36:39]
	v_mfma_f32_16x16x32_bf16 v[28:31], v[162:165], v[216:219], v[28:31]
	v_mfma_f32_16x16x32_bf16 v[20:23], v[170:173], v[216:219], v[20:23]
	v_mfma_f32_16x16x32_bf16 v[12:15], v[162:165], v[224:227], v[12:15]
	v_mfma_f32_16x16x32_bf16 v[4:7], v[170:173], v[224:227], v[4:7]
	v_mfma_f32_16x16x32_bf16 v[56:59], v[174:177], v[190:193], 0
	v_mfma_f32_16x16x32_bf16 v[48:51], v[182:185], v[190:193], 0
	v_mfma_f32_16x16x32_bf16 v[40:43], v[174:177], v[198:201], 0
	v_mfma_f32_16x16x32_bf16 v[32:35], v[182:185], v[198:201], 0
	v_mfma_f32_16x16x32_bf16 v[24:27], v[174:177], v[212:215], 0
	v_mfma_f32_16x16x32_bf16 v[16:19], v[182:185], v[212:215], 0
	v_mfma_f32_16x16x32_bf16 v[8:11], v[174:177], v[220:223], 0
	v_mfma_f32_16x16x32_bf16 v[0:3], v[182:185], v[220:223], 0
	v_mfma_f32_16x16x32_bf16 v[56:59], v[178:181], v[194:197], v[56:59]
	v_mfma_f32_16x16x32_bf16 v[48:51], v[186:189], v[194:197], v[48:51]
	v_mfma_f32_16x16x32_bf16 v[40:43], v[178:181], v[202:205], v[40:43]
	v_mfma_f32_16x16x32_bf16 v[32:35], v[186:189], v[202:205], v[32:35]
	v_mfma_f32_16x16x32_bf16 v[24:27], v[178:181], v[216:219], v[24:27]
	v_mfma_f32_16x16x32_bf16 v[16:19], v[186:189], v[216:219], v[16:19]
	v_mfma_f32_16x16x32_bf16 v[8:11], v[178:181], v[224:227], v[8:11]
	v_mfma_f32_16x16x32_bf16 v[0:3], v[186:189], v[224:227], v[0:3]
	s_setprio 0
	s_barrier
	s_add_i32 s85, 0, 0x18000
	v_add_u32_e32 v146, s85, v151
	s_add_i32 s92, 0, 0x1c000
	ds_read_b128 v[142:145], v146
	ds_read_b128 v[162:165], v146 offset:1024
	ds_read_b128 v[166:169], v146 offset:2048
	ds_read_b128 v[170:173], v146 offset:3072
	v_add_u32_e32 v146, s92, v151
	ds_read_b128 v[174:177], v146
	ds_read_b128 v[178:181], v146 offset:1024
	ds_read_b128 v[182:185], v146 offset:2048
	ds_read_b128 v[186:189], v146 offset:3072
	s_add_u32 s34, s34, s44
	s_addc_u32 s35, s35, s45
	s_mov_b32 m0, s63
	v_lshl_add_u64 v[234:235], s[34:35], 0, v[134:135]
	ds_read_b128 v[190:193], v161 offset:32768
	ds_read_b128 v[194:197], v161 offset:33792
	ds_read_b128 v[198:201], v161 offset:34816
	ds_read_b128 v[202:205], v161 offset:35840
	ds_read_b128 v[212:215], v161 offset:36864
	ds_read_b128 v[216:219], v161 offset:37888
	ds_read_b128 v[220:223], v161 offset:38912
	ds_read_b128 v[224:227], v161 offset:39936
	global_load_lds_dwordx4 v[234:235], off
	v_lshl_add_u64 v[234:235], s[34:35], 0, v[130:131]
	s_mov_b32 m0, s64
	s_nop 0
	global_load_lds_dwordx4 v[234:235], off
	s_waitcnt vmcnt(8)
	s_waitcnt lgkmcnt(0)
	s_barrier
	s_setprio 1
	s_waitcnt lgkmcnt(0)
	v_mfma_f32_16x16x32_bf16 v[120:123], v[142:145], v[190:193], v[120:123]
	v_mfma_f32_16x16x32_bf16 v[116:119], v[166:169], v[190:193], v[116:119]
	v_mfma_f32_16x16x32_bf16 v[108:111], v[142:145], v[198:201], v[108:111]
	v_mfma_f32_16x16x32_bf16 v[100:103], v[166:169], v[198:201], v[100:103]
	v_mfma_f32_16x16x32_bf16 v[92:95], v[142:145], v[212:215], v[92:95]
	v_mfma_f32_16x16x32_bf16 v[84:87], v[166:169], v[212:215], v[84:87]
	v_mfma_f32_16x16x32_bf16 v[76:79], v[142:145], v[220:223], v[76:79]
	v_mfma_f32_16x16x32_bf16 v[68:71], v[166:169], v[220:223], v[68:71]
	v_mfma_f32_16x16x32_bf16 v[120:123], v[162:165], v[194:197], v[120:123]
	v_mfma_f32_16x16x32_bf16 v[116:119], v[170:173], v[194:197], v[116:119]
	v_mfma_f32_16x16x32_bf16 v[108:111], v[162:165], v[202:205], v[108:111]
	v_mfma_f32_16x16x32_bf16 v[100:103], v[170:173], v[202:205], v[100:103]
	v_mfma_f32_16x16x32_bf16 v[92:95], v[162:165], v[216:219], v[92:95]
	v_mfma_f32_16x16x32_bf16 v[84:87], v[170:173], v[216:219], v[84:87]
	v_mfma_f32_16x16x32_bf16 v[76:79], v[162:165], v[224:227], v[76:79]
	v_mfma_f32_16x16x32_bf16 v[68:71], v[170:173], v[224:227], v[68:71]
	v_mfma_f32_16x16x32_bf16 v[124:127], v[174:177], v[190:193], v[124:127]
	v_mfma_f32_16x16x32_bf16 v[112:115], v[182:185], v[190:193], v[112:115]
	v_mfma_f32_16x16x32_bf16 v[104:107], v[174:177], v[198:201], v[104:107]
	v_mfma_f32_16x16x32_bf16 v[96:99], v[182:185], v[198:201], v[96:99]
	v_mfma_f32_16x16x32_bf16 v[88:91], v[174:177], v[212:215], v[88:91]
	v_mfma_f32_16x16x32_bf16 v[80:83], v[182:185], v[212:215], v[80:83]
	v_mfma_f32_16x16x32_bf16 v[72:75], v[174:177], v[220:223], v[72:75]
	v_mfma_f32_16x16x32_bf16 v[64:67], v[182:185], v[220:223], v[64:67]
	v_mfma_f32_16x16x32_bf16 v[124:127], v[178:181], v[194:197], v[124:127]
	v_mfma_f32_16x16x32_bf16 v[112:115], v[186:189], v[194:197], v[112:115]
	v_mfma_f32_16x16x32_bf16 v[104:107], v[178:181], v[202:205], v[104:107]
	v_mfma_f32_16x16x32_bf16 v[96:99], v[186:189], v[202:205], v[96:99]
	v_mfma_f32_16x16x32_bf16 v[88:91], v[178:181], v[216:219], v[88:91]
	v_mfma_f32_16x16x32_bf16 v[80:83], v[186:189], v[216:219], v[80:83]
	v_mfma_f32_16x16x32_bf16 v[72:75], v[178:181], v[224:227], v[72:75]
	v_mfma_f32_16x16x32_bf16 v[64:67], v[186:189], v[224:227], v[64:67]
	s_setprio 0
	s_barrier
; #define PG8_STAGE(bufoff, gbase, voff) do { _Pragma("unroll") for (int _i = 0; _i < 2; ++_i) \
;         __builtin_amdgcn_global_load_lds((const unsigned*)((const char*)(gbase) + (voff)[_i]), (PG8_LAS unsigned*)(lds + (bufoff) + ldsw + _i * 8192), 16, 0, 0); } while (0)
; #define PG8_LDA(dst, b, h) do { _Pragma("unroll") for (int m = 0; m < 4; ++m) _Pragma("unroll") for (int k = 0; k < 2; ++k) dst[m][k] = *(const PG8_LAS bf16x8*)(lds + PG8_SA(b, h) + aoff + m * 2048 + k * 1024); } while (0)
; #define PG8_LDB(dst, b, h) do { _Pragma("unroll") for (int n = 0; n < 2; ++n) _Pragma("unroll") for (int k = 0; k < 2; ++k) dst[n][k] = *(const PG8_LAS bf16x8*)(lds + PG8_SB(b, h) + boff + n * 2048 + k * 1024); } while (0)
; #define PG8_MMA(ai, bj, At, Bt) do { __builtin_amdgcn_s_setprio(1); _Pragma("unroll") for (int m = 0; m < 4; ++m) _Pragma("unroll") for (int n = 0; n < 2; ++n) _Pragma("unroll") for (int k = 0; k < 2; ++k) \
;         acc[ai][bj][m][n] = mma16<Epi::F16>(Bt[n][k], At[m][k], acc[ai][bj][m][n]); __builtin_amdgcn_s_setprio(0); } while (0)
; #define PG8_WAIT_V(n) asm volatile("s_waitcnt vmcnt(" #n ")" ::: "memory")
; #define PG8_WAIT_L(n) asm volatile("s_waitcnt lgkmcnt(" #n ")" ::: "memory")
; #define PG8_BAR __builtin_amdgcn_s_barrier()
; #define PG8_SCHED __builtin_amdgcn_sched_barrier(0)
; template <class Epi, class Sched, bool ALIGN_EPI = false, bool SP2 = false>
; __device__ __forceinline__ void gemm_phase(PG8_LAS unsigned char* lds, const Gemm g, const Sched& S, const Epi& E) {
;     ...
;         for (int t = 0; t < nt; t += 2) {
;             const bool last = (t == nt - 2);
;             const char* a1 = cA + (size_t)(t + 1) * kstep;
;             const char* a2 = last ? nA : cA + (size_t)(t + 2) * kstep; const char* b2 = last ? nB : cB + (size_t)(t + 2) * kstep;
;             const char* a3 = a2 + kstep; const char* b3 = b2 + kstep;
;             if (last && has_next) S.a_ready(nxt);
;             if constexpr (SP2) {
;             PG8_LDB(B0, 0, 0); PG8_LDB(B1, 0, 1); PG8_SCHED; PG8_LDA(At, 0, 0); PG8_STAGE(PG8_SA(1, 1), a1 + hstep, voffA);
;     ...
;             PG8_LDA(At, 1, 1); PG8_STAGE(PG8_SB(1, 0), b3, voffB); PG8_STAGE(PG8_SB(1, 1), b3 + hstep, voffB); PG8_STAGE(PG8_SA(1, 0), a3, voffA);
;             PG8_WAIT_V(8); PG8_WAIT_L(0); PG8_BAR; PG8_MMA(1, 0, At, B0); PG8_MMA(1, 1, At, B1); PG8_BAR; PG8_SCHED;
	s_add_i32 s34, s85, s11
	v_lshl_add_u64 v[148:149], v[148:149], 0, s[20:21]
	s_mov_b32 m0, s34
	ds_read_b128 v[190:193], v161 offset:49152
	ds_read_b128 v[194:197], v161 offset:50176
	ds_read_b128 v[198:201], v161 offset:51200
	ds_read_b128 v[202:205], v161 offset:52224
	ds_read_b128 v[212:215], v161 offset:53248
	ds_read_b128 v[216:219], v161 offset:54272
	ds_read_b128 v[220:223], v161 offset:55296
	ds_read_b128 v[224:227], v161 offset:56320
	global_load_lds_dwordx4 v[148:149], off
	v_lshl_add_u64 v[148:149], v[152:153], 0, s[20:21]
	s_add_i32 m0, s34, 0x2000
	s_add_i32 s34, s92, s11
	global_load_lds_dwordx4 v[148:149], off
	v_lshl_add_u64 v[148:149], v[206:207], 0, s[20:21]
	s_mov_b32 m0, s34
	s_nop 0
	global_load_lds_dwordx4 v[148:149], off
	v_lshl_add_u64 v[148:149], v[228:229], 0, s[20:21]
	s_add_i32 m0, s34, 0x2000
	s_nop 0
	global_load_lds_dwordx4 v[148:149], off
	v_lshl_add_u64 v[148:149], v[230:231], 0, s[20:21]
	s_mov_b32 m0, s65
	s_nop 0
	global_load_lds_dwordx4 v[148:149], off
	v_lshl_add_u64 v[148:149], v[232:233], 0, s[20:21]
	s_mov_b32 m0, s66
	s_nop 0
	global_load_lds_dwordx4 v[148:149], off
	s_waitcnt vmcnt(8)
	s_waitcnt lgkmcnt(0)
	s_barrier
	s_setprio 1
	s_waitcnt lgkmcnt(0)
	v_mfma_f32_16x16x32_bf16 v[60:63], v[142:145], v[190:193], v[60:63]
	v_mfma_f32_16x16x32_bf16 v[52:55], v[166:169], v[190:193], v[52:55]
	v_mfma_f32_16x16x32_bf16 v[44:47], v[142:145], v[198:201], v[44:47]
	v_mfma_f32_16x16x32_bf16 v[36:39], v[166:169], v[198:201], v[36:39]
	v_mfma_f32_16x16x32_bf16 v[28:31], v[142:145], v[212:215], v[28:31]
	v_mfma_f32_16x16x32_bf16 v[20:23], v[166:169], v[212:215], v[20:23]
	v_mfma_f32_16x16x32_bf16 v[12:15], v[142:145], v[220:223], v[12:15]
	v_mfma_f32_16x16x32_bf16 v[4:7], v[166:169], v[220:223], v[4:7]
	v_mfma_f32_16x16x32_bf16 v[60:63], v[162:165], v[194:197], v[60:63]
	v_mfma_f32_16x16x32_bf16 v[52:55], v[170:173], v[194:197], v[52:55]
	v_mfma_f32_16x16x32_bf16 v[44:47], v[162:165], v[202:205], v[44:47]
	v_mfma_f32_16x16x32_bf16 v[36:39], v[170:173], v[202:205], v[36:39]
	v_mfma_f32_16x16x32_bf16 v[28:31], v[162:165], v[216:219], v[28:31]
	v_mfma_f32_16x16x32_bf16 v[20:23], v[170:173], v[216:219], v[20:23]
	v_mfma_f32_16x16x32_bf16 v[12:15], v[162:165], v[224:227], v[12:15]
	v_mfma_f32_16x16x32_bf16 v[4:7], v[170:173], v[224:227], v[4:7]
	v_mfma_f32_16x16x32_bf16 v[56:59], v[174:177], v[190:193], v[56:59]
	v_mfma_f32_16x16x32_bf16 v[48:51], v[182:185], v[190:193], v[48:51]
	v_mfma_f32_16x16x32_bf16 v[40:43], v[174:177], v[198:201], v[40:43]
	v_mfma_f32_16x16x32_bf16 v[32:35], v[182:185], v[198:201], v[32:35]
	v_mfma_f32_16x16x32_bf16 v[24:27], v[174:177], v[212:215], v[24:27]
	v_mfma_f32_16x16x32_bf16 v[16:19], v[182:185], v[212:215], v[16:19]
	v_mfma_f32_16x16x32_bf16 v[8:11], v[174:177], v[220:223], v[8:11]
	v_mfma_f32_16x16x32_bf16 v[0:3], v[182:185], v[220:223], v[0:3]
	v_mfma_f32_16x16x32_bf16 v[56:59], v[178:181], v[194:197], v[56:59]
	v_mfma_f32_16x16x32_bf16 v[48:51], v[186:189], v[194:197], v[48:51]
	v_mfma_f32_16x16x32_bf16 v[40:43], v[178:181], v[202:205], v[40:43]
	v_mfma_f32_16x16x32_bf16 v[32:35], v[186:189], v[202:205], v[32:35]
	v_mfma_f32_16x16x32_bf16 v[24:27], v[178:181], v[216:219], v[24:27]
	v_mfma_f32_16x16x32_bf16 v[16:19], v[186:189], v[216:219], v[16:19]
	v_mfma_f32_16x16x32_bf16 v[8:11], v[178:181], v[224:227], v[8:11]
	v_mfma_f32_16x16x32_bf16 v[0:3], v[186:189], v[224:227], v[0:3]
	s_setprio 0
	s_barrier
	s_add_u32 s30, s30, 0x100
	s_addc_u32 s31, s31, 0
	s_add_u32 s77, s77, 0x100
	s_addc_u32 s82, s82, 0
	s_cmp_ge_i32 s84, s67
	s_mov_b32 s34, s84
	s_cbranch_scc0 .LBB0_191
	s_branch .LBB0_192
.LBB0_191:
	s_add_i32 s84, s34, 2
	s_add_u32 s85, s30, 0x80
	s_addc_u32 s35, s31, 0
	s_add_i32 s92, 0, 0x10000
	s_cmp_eq_u32 s68, s34
	s_cselect_b32 s35, s1, s35
	s_cselect_b32 s34, s0, s85
	v_add_u32_e32 v146, s92, v151
	s_cselect_b32 s97, s57, s82
	s_cselect_b32 s96, s56, s77
	s_add_i32 s85, 0, 0x14000
	ds_read_b128 v[142:145], v146
	ds_read_b128 v[162:165], v146 offset:1024
	ds_read_b128 v[166:169], v146 offset:2048
	ds_read_b128 v[170:173], v146 offset:3072
	v_add_u32_e32 v146, s85, v151
	ds_read_b128 v[174:177], v146
	ds_read_b128 v[178:181], v146 offset:1024
	ds_read_b128 v[182:185], v146 offset:2048
	ds_read_b128 v[186:189], v146 offset:3072
	v_lshl_add_u64 v[148:149], s[30:31], 0, v[138:139]
	s_add_i32 m0, s61, 0xc000
	ds_read_b128 v[190:193], v161
	ds_read_b128 v[194:197], v161 offset:1024
	ds_read_b128 v[198:201], v161 offset:2048
	ds_read_b128 v[202:205], v161 offset:3072
	ds_read_b128 v[212:215], v161 offset:4096
	ds_read_b128 v[216:219], v161 offset:5120
	ds_read_b128 v[220:223], v161 offset:6144
	ds_read_b128 v[224:227], v161 offset:7168
	global_load_lds_dwordx4 v[148:149], off
	v_lshl_add_u64 v[148:149], s[30:31], 0, v[140:141]
	s_add_i32 m0, s61, 0xe000
	s_nop 0
	global_load_lds_dwordx4 v[148:149], off
	s_waitcnt vmcnt(8)
	s_waitcnt lgkmcnt(0)
	s_barrier
; #define PG8_STAGE(bufoff, gbase, voff) do { _Pragma("unroll") for (int _i = 0; _i < 2; ++_i) \
;         __builtin_amdgcn_global_load_lds((const unsigned*)((const char*)(gbase) + (voff)[_i]), (PG8_LAS unsigned*)(lds + (bufoff) + ldsw + _i * 8192), 16, 0, 0); } while (0)
; #define PG8_LDA(dst, b, h) do { _Pragma("unroll") for (int m = 0; m < 4; ++m) _Pragma("unroll") for (int k = 0; k < 2; ++k) dst[m][k] = *(const PG8_LAS bf16x8*)(lds + PG8_SA(b, h) + aoff + m * 2048 + k * 1024); } while (0)
; #define PG8_MMA(ai, bj, At, Bt) do { __builtin_amdgcn_s_setprio(1); _Pragma("unroll") for (int m = 0; m < 4; ++m) _Pragma("unroll") for (int n = 0; n < 2; ++n) _Pragma("unroll") for (int k = 0; k < 2; ++k) \
;         acc[ai][bj][m][n] = mma16<Epi::F16>(Bt[n][k], At[m][k], acc[ai][bj][m][n]); __builtin_amdgcn_s_setprio(0); } while (0)
; #define PG8_WAIT_V(n) asm volatile("s_waitcnt vmcnt(" #n ")" ::: "memory")
; #define PG8_WAIT_L(n) asm volatile("s_waitcnt lgkmcnt(" #n ")" ::: "memory")
; #define PG8_BAR __builtin_amdgcn_s_barrier()
; #define PG8_SCHED __builtin_amdgcn_sched_barrier(0)
; template <class Epi, class Sched, bool ALIGN_EPI = false, bool SP2 = false>
; __device__ __forceinline__ void gemm_phase(PG8_LAS unsigned char* lds, const Gemm g, const Sched& S, const Epi& E) {
;     ...
;             PG8_WAIT_V(8); PG8_WAIT_L(0); PG8_BAR; PG8_MMA(0, 0, At, B0); PG8_MMA(0, 1, At, B1); PG8_BAR; PG8_SCHED;
;             PG8_LDA(At, 0, 1); PG8_STAGE(PG8_SB(0, 0), b2, voffB); PG8_STAGE(PG8_SB(0, 1), b2 + hstep, voffB); PG8_STAGE(PG8_SA(0, 0), a2, voffA);
;             PG8_WAIT_V(8); PG8_WAIT_L(0); PG8_BAR; PG8_MMA(1, 0, At, B0); PG8_MMA(1, 1, At, B1); PG8_BAR; PG8_SCHED;
	s_setprio 1
	s_waitcnt lgkmcnt(0)
	v_mfma_f32_16x16x32_bf16 v[120:123], v[142:145], v[190:193], v[120:123]
	v_mfma_f32_16x16x32_bf16 v[116:119], v[166:169], v[190:193], v[116:119]
	v_mfma_f32_16x16x32_bf16 v[108:111], v[142:145], v[198:201], v[108:111]
	v_mfma_f32_16x16x32_bf16 v[100:103], v[166:169], v[198:201], v[100:103]
	v_mfma_f32_16x16x32_bf16 v[92:95], v[142:145], v[212:215], v[92:95]
	v_mfma_f32_16x16x32_bf16 v[84:87], v[166:169], v[212:215], v[84:87]
	v_mfma_f32_16x16x32_bf16 v[76:79], v[142:145], v[220:223], v[76:79]
	v_mfma_f32_16x16x32_bf16 v[68:71], v[166:169], v[220:223], v[68:71]
	v_mfma_f32_16x16x32_bf16 v[120:123], v[162:165], v[194:197], v[120:123]
	v_mfma_f32_16x16x32_bf16 v[116:119], v[170:173], v[194:197], v[116:119]
	v_mfma_f32_16x16x32_bf16 v[108:111], v[162:165], v[202:205], v[108:111]
	v_mfma_f32_16x16x32_bf16 v[100:103], v[170:173], v[202:205], v[100:103]
	v_mfma_f32_16x16x32_bf16 v[92:95], v[162:165], v[216:219], v[92:95]
	v_mfma_f32_16x16x32_bf16 v[84:87], v[170:173], v[216:219], v[84:87]
	v_mfma_f32_16x16x32_bf16 v[76:79], v[162:165], v[224:227], v[76:79]
	v_mfma_f32_16x16x32_bf16 v[68:71], v[170:173], v[224:227], v[68:71]
	v_mfma_f32_16x16x32_bf16 v[124:127], v[174:177], v[190:193], v[124:127]
	v_mfma_f32_16x16x32_bf16 v[112:115], v[182:185], v[190:193], v[112:115]
	v_mfma_f32_16x16x32_bf16 v[104:107], v[174:177], v[198:201], v[104:107]
	v_mfma_f32_16x16x32_bf16 v[96:99], v[182:185], v[198:201], v[96:99]
	v_mfma_f32_16x16x32_bf16 v[88:91], v[174:177], v[212:215], v[88:91]
	v_mfma_f32_16x16x32_bf16 v[80:83], v[182:185], v[212:215], v[80:83]
	v_mfma_f32_16x16x32_bf16 v[72:75], v[174:177], v[220:223], v[72:75]
	v_mfma_f32_16x16x32_bf16 v[64:67], v[182:185], v[220:223], v[64:67]
	v_mfma_f32_16x16x32_bf16 v[124:127], v[178:181], v[194:197], v[124:127]
	v_mfma_f32_16x16x32_bf16 v[112:115], v[186:189], v[194:197], v[112:115]
	v_mfma_f32_16x16x32_bf16 v[104:107], v[178:181], v[202:205], v[104:107]
	v_mfma_f32_16x16x32_bf16 v[96:99], v[186:189], v[202:205], v[96:99]
	v_mfma_f32_16x16x32_bf16 v[88:91], v[178:181], v[216:219], v[88:91]
	v_mfma_f32_16x16x32_bf16 v[80:83], v[186:189], v[216:219], v[80:83]
	v_mfma_f32_16x16x32_bf16 v[72:75], v[178:181], v[224:227], v[72:75]
	v_mfma_f32_16x16x32_bf16 v[64:67], v[186:189], v[224:227], v[64:67]
	s_setprio 0
	s_barrier
	s_add_i32 s92, s92, s11
	v_lshl_add_u64 v[148:149], s[96:97], 0, v[132:133]
	s_mov_b32 m0, s92
	ds_read_b128 v[190:193], v161 offset:16384
	ds_read_b128 v[194:197], v161 offset:17408
	ds_read_b128 v[198:201], v161 offset:18432
	ds_read_b128 v[202:205], v161 offset:19456
	ds_read_b128 v[212:215], v161 offset:20480
	ds_read_b128 v[216:219], v161 offset:21504
	ds_read_b128 v[220:223], v161 offset:22528
	ds_read_b128 v[224:227], v161 offset:23552
	global_load_lds_dwordx4 v[148:149], off
	s_add_i32 m0, s92, 0x2000
	v_lshl_add_u64 v[152:153], s[96:97], 0, v[128:129]
	s_add_u32 s96, s96, s44
	s_addc_u32 s97, s97, s45
	s_add_i32 s85, s85, s11
	global_load_lds_dwordx4 v[152:153], off
	v_lshl_add_u64 v[206:207], s[96:97], 0, v[132:133]
	s_mov_b32 m0, s85
	v_lshl_add_u64 v[228:229], s[96:97], 0, v[128:129]
	global_load_lds_dwordx4 v[206:207], off
	s_add_i32 m0, s85, 0x2000
	v_lshl_add_u64 v[230:231], s[34:35], 0, v[134:135]
	global_load_lds_dwordx4 v[228:229], off
	s_mov_b32 m0, s61
	v_lshl_add_u64 v[232:233], s[34:35], 0, v[130:131]
	global_load_lds_dwordx4 v[230:231], off
	s_mov_b32 m0, s62
	s_nop 0
	global_load_lds_dwordx4 v[232:233], off
	s_waitcnt vmcnt(8)
	s_waitcnt lgkmcnt(0)
	s_barrier
	s_setprio 1
	s_waitcnt lgkmcnt(0)
	v_mfma_f32_16x16x32_bf16 v[60:63], v[142:145], v[190:193], v[60:63]
	v_mfma_f32_16x16x32_bf16 v[52:55], v[166:169], v[190:193], v[52:55]
	v_mfma_f32_16x16x32_bf16 v[44:47], v[142:145], v[198:201], v[44:47]
	v_mfma_f32_16x16x32_bf16 v[36:39], v[166:169], v[198:201], v[36:39]
	v_mfma_f32_16x16x32_bf16 v[28:31], v[142:145], v[212:215], v[28:31]
	v_mfma_f32_16x16x32_bf16 v[20:23], v[166:169], v[212:215], v[20:23]
	v_mfma_f32_16x16x32_bf16 v[12:15], v[142:145], v[220:223], v[12:15]
	v_mfma_f32_16x16x32_bf16 v[4:7], v[166:169], v[220:223], v[4:7]
	v_mfma_f32_16x16x32_bf16 v[60:63], v[162:165], v[194:197], v[60:63]
	v_mfma_f32_16x16x32_bf16 v[52:55], v[170:173], v[194:197], v[52:55]
	v_mfma_f32_16x16x32_bf16 v[44:47], v[162:165], v[202:205], v[44:47]
	v_mfma_f32_16x16x32_bf16 v[36:39], v[170:173], v[202:205], v[36:39]
	v_mfma_f32_16x16x32_bf16 v[28:31], v[162:165], v[216:219], v[28:31]
	v_mfma_f32_16x16x32_bf16 v[20:23], v[170:173], v[216:219], v[20:23]
	v_mfma_f32_16x16x32_bf16 v[12:15], v[162:165], v[224:227], v[12:15]
	v_mfma_f32_16x16x32_bf16 v[4:7], v[170:173], v[224:227], v[4:7]
	v_mfma_f32_16x16x32_bf16 v[56:59], v[174:177], v[190:193], v[56:59]
	v_mfma_f32_16x16x32_bf16 v[48:51], v[182:185], v[190:193], v[48:51]
	v_mfma_f32_16x16x32_bf16 v[40:43], v[174:177], v[198:201], v[40:43]
	v_mfma_f32_16x16x32_bf16 v[32:35], v[182:185], v[198:201], v[32:35]
	v_mfma_f32_16x16x32_bf16 v[24:27], v[174:177], v[212:215], v[24:27]
	v_mfma_f32_16x16x32_bf16 v[16:19], v[182:185], v[212:215], v[16:19]
	v_mfma_f32_16x16x32_bf16 v[8:11], v[174:177], v[220:223], v[8:11]
	v_mfma_f32_16x16x32_bf16 v[0:3], v[182:185], v[220:223], v[0:3]
	v_mfma_f32_16x16x32_bf16 v[56:59], v[178:181], v[194:197], v[56:59]
	v_mfma_f32_16x16x32_bf16 v[48:51], v[186:189], v[194:197], v[48:51]
	v_mfma_f32_16x16x32_bf16 v[40:43], v[178:181], v[202:205], v[40:43]
	v_mfma_f32_16x16x32_bf16 v[32:35], v[186:189], v[202:205], v[32:35]
	v_mfma_f32_16x16x32_bf16 v[24:27], v[178:181], v[216:219], v[24:27]
	v_mfma_f32_16x16x32_bf16 v[16:19], v[186:189], v[216:219], v[16:19]
	v_mfma_f32_16x16x32_bf16 v[8:11], v[178:181], v[224:227], v[8:11]
	v_mfma_f32_16x16x32_bf16 v[0:3], v[186:189], v[224:227], v[0:3]
	s_setprio 0
	s_barrier
; #define PG8_STAGE(bufoff, gbase, voff) do { _Pragma("unroll") for (int _i = 0; _i < 2; ++_i) \
;         __builtin_amdgcn_global_load_lds((const unsigned*)((const char*)(gbase) + (voff)[_i]), (PG8_LAS unsigned*)(lds + (bufoff) + ldsw + _i * 8192), 16, 0, 0); } while (0)
; #define PG8_LDA(dst, b, h) do { _Pragma("unroll") for (int m = 0; m < 4; ++m) _Pragma("unroll") for (int k = 0; k < 2; ++k) dst[m][k] = *(const PG8_LAS bf16x8*)(lds + PG8_SA(b, h) + aoff + m * 2048 + k * 1024); } while (0)
; #define PG8_LDB(dst, b, h) do { _Pragma("unroll") for (int n = 0; n < 2; ++n) _Pragma("unroll") for (int k = 0; k < 2; ++k) dst[n][k] = *(const PG8_LAS bf16x8*)(lds + PG8_SB(b, h) + boff + n * 2048 + k * 1024); } while (0)
; #define PG8_MMA(ai, bj, At, Bt) do { __builtin_amdgcn_s_setprio(1); _Pragma("unroll") for (int m = 0; m < 4; ++m) _Pragma("unroll") for (int n = 0; n < 2; ++n) _Pragma("unroll") for (int k = 0; k < 2; ++k) \
;         acc[ai][bj][m][n] = mma16<Epi::F16>(Bt[n][k], At[m][k], acc[ai][bj][m][n]); __builtin_amdgcn_s_setprio(0); } while (0)
; #define PG8_WAIT_V(n) asm volatile("s_waitcnt vmcnt(" #n ")" ::: "memory")
; #define PG8_WAIT_L(n) asm volatile("s_waitcnt lgkmcnt(" #n ")" ::: "memory")
; #define PG8_BAR __builtin_amdgcn_s_barrier()
; #define PG8_SCHED __builtin_amdgcn_sched_barrier(0)
; template <class Epi, class Sched, bool ALIGN_EPI = false, bool SP2 = false>
; __device__ __forceinline__ void gemm_phase(PG8_LAS unsigned char* lds, const Gemm g, const Sched& S, const Epi& E) {
;     ...
;             PG8_LDB(B0, 1, 0); PG8_LDB(B1, 1, 1); PG8_SCHED; PG8_LDA(At, 1, 0); PG8_STAGE(PG8_SA(0, 1), a2 + hstep, voffA);
;             PG8_WAIT_V(8); PG8_WAIT_L(0); PG8_BAR; PG8_MMA(0, 0, At, B0); PG8_MMA(0, 1, At, B1); PG8_BAR; PG8_SCHED;
;             PG8_LDA(At, 1, 1); PG8_STAGE(PG8_SB(1, 0), b3, voffB); PG8_STAGE(PG8_SB(1, 1), b3 + hstep, voffB); PG8_STAGE(PG8_SA(1, 0), a3, voffA);
;             PG8_WAIT_V(8); PG8_WAIT_L(0); PG8_BAR; PG8_MMA(1, 0, At, B0); PG8_MMA(1, 1, At, B1); PG8_BAR; PG8_SCHED;
	s_add_i32 s85, 0, 0x18000
	v_add_u32_e32 v146, s85, v151
	s_add_i32 s92, 0, 0x1c000
	ds_read_b128 v[142:145], v146
	ds_read_b128 v[162:165], v146 offset:1024
	ds_read_b128 v[166:169], v146 offset:2048
	ds_read_b128 v[170:173], v146 offset:3072
	v_add_u32_e32 v146, s92, v151
	ds_read_b128 v[174:177], v146
	ds_read_b128 v[178:181], v146 offset:1024
	ds_read_b128 v[182:185], v146 offset:2048
	ds_read_b128 v[186:189], v146 offset:3072
	s_add_u32 s34, s34, s44
	s_addc_u32 s35, s35, s45
	s_mov_b32 m0, s63
	v_lshl_add_u64 v[234:235], s[34:35], 0, v[134:135]
	ds_read_b128 v[190:193], v161 offset:32768
	ds_read_b128 v[194:197], v161 offset:33792
	ds_read_b128 v[198:201], v161 offset:34816
	ds_read_b128 v[202:205], v161 offset:35840
	ds_read_b128 v[212:215], v161 offset:36864
	ds_read_b128 v[216:219], v161 offset:37888
	ds_read_b128 v[220:223], v161 offset:38912
	ds_read_b128 v[224:227], v161 offset:39936
	global_load_lds_dwordx4 v[234:235], off
	v_lshl_add_u64 v[234:235], s[34:35], 0, v[130:131]
	s_mov_b32 m0, s64
	s_nop 0
	global_load_lds_dwordx4 v[234:235], off
	s_waitcnt vmcnt(8)
	s_waitcnt lgkmcnt(0)
	s_barrier
	s_setprio 1
	s_waitcnt lgkmcnt(0)
	v_mfma_f32_16x16x32_bf16 v[120:123], v[142:145], v[190:193], v[120:123]
	v_mfma_f32_16x16x32_bf16 v[116:119], v[166:169], v[190:193], v[116:119]
	v_mfma_f32_16x16x32_bf16 v[108:111], v[142:145], v[198:201], v[108:111]
	v_mfma_f32_16x16x32_bf16 v[100:103], v[166:169], v[198:201], v[100:103]
	v_mfma_f32_16x16x32_bf16 v[92:95], v[142:145], v[212:215], v[92:95]
	v_mfma_f32_16x16x32_bf16 v[84:87], v[166:169], v[212:215], v[84:87]
	v_mfma_f32_16x16x32_bf16 v[76:79], v[142:145], v[220:223], v[76:79]
	v_mfma_f32_16x16x32_bf16 v[68:71], v[166:169], v[220:223], v[68:71]
	v_mfma_f32_16x16x32_bf16 v[120:123], v[162:165], v[194:197], v[120:123]
	v_mfma_f32_16x16x32_bf16 v[116:119], v[170:173], v[194:197], v[116:119]
	v_mfma_f32_16x16x32_bf16 v[108:111], v[162:165], v[202:205], v[108:111]
	v_mfma_f32_16x16x32_bf16 v[100:103], v[170:173], v[202:205], v[100:103]
	v_mfma_f32_16x16x32_bf16 v[92:95], v[162:165], v[216:219], v[92:95]
	v_mfma_f32_16x16x32_bf16 v[84:87], v[170:173], v[216:219], v[84:87]
	v_mfma_f32_16x16x32_bf16 v[76:79], v[162:165], v[224:227], v[76:79]
	v_mfma_f32_16x16x32_bf16 v[68:71], v[170:173], v[224:227], v[68:71]
	v_mfma_f32_16x16x32_bf16 v[124:127], v[174:177], v[190:193], v[124:127]
	v_mfma_f32_16x16x32_bf16 v[112:115], v[182:185], v[190:193], v[112:115]
	v_mfma_f32_16x16x32_bf16 v[104:107], v[174:177], v[198:201], v[104:107]
	v_mfma_f32_16x16x32_bf16 v[96:99], v[182:185], v[198:201], v[96:99]
	v_mfma_f32_16x16x32_bf16 v[88:91], v[174:177], v[212:215], v[88:91]
	v_mfma_f32_16x16x32_bf16 v[80:83], v[182:185], v[212:215], v[80:83]
	v_mfma_f32_16x16x32_bf16 v[72:75], v[174:177], v[220:223], v[72:75]
	v_mfma_f32_16x16x32_bf16 v[64:67], v[182:185], v[220:223], v[64:67]
	v_mfma_f32_16x16x32_bf16 v[124:127], v[178:181], v[194:197], v[124:127]
	v_mfma_f32_16x16x32_bf16 v[112:115], v[186:189], v[194:197], v[112:115]
	v_mfma_f32_16x16x32_bf16 v[104:107], v[178:181], v[202:205], v[104:107]
	v_mfma_f32_16x16x32_bf16 v[96:99], v[186:189], v[202:205], v[96:99]
	v_mfma_f32_16x16x32_bf16 v[88:91], v[178:181], v[216:219], v[88:91]
	v_mfma_f32_16x16x32_bf16 v[80:83], v[186:189], v[216:219], v[80:83]
	v_mfma_f32_16x16x32_bf16 v[72:75], v[178:181], v[224:227], v[72:75]
	v_mfma_f32_16x16x32_bf16 v[64:67], v[186:189], v[224:227], v[64:67]
	s_setprio 0
	s_barrier
	s_add_i32 s34, s85, s11
	v_lshl_add_u64 v[148:149], v[148:149], 0, s[20:21]
	s_mov_b32 m0, s34
	ds_read_b128 v[190:193], v161 offset:49152
	ds_read_b128 v[194:197], v161 offset:50176
	ds_read_b128 v[198:201], v161 offset:51200
	ds_read_b128 v[202:205], v161 offset:52224
	ds_read_b128 v[212:215], v161 offset:53248
	ds_read_b128 v[216:219], v161 offset:54272
	ds_read_b128 v[220:223], v161 offset:55296
	ds_read_b128 v[224:227], v161 offset:56320
	global_load_lds_dwordx4 v[148:149], off
	v_lshl_add_u64 v[148:149], v[152:153], 0, s[20:21]
	s_add_i32 m0, s34, 0x2000
	s_add_i32 s34, s92, s11
	global_load_lds_dwordx4 v[148:149], off
	v_lshl_add_u64 v[148:149], v[206:207], 0, s[20:21]
	s_mov_b32 m0, s34
	s_nop 0
	global_load_lds_dwordx4 v[148:149], off
	v_lshl_add_u64 v[148:149], v[228:229], 0, s[20:21]
	s_add_i32 m0, s34, 0x2000
	s_nop 0
	global_load_lds_dwordx4 v[148:149], off
	v_lshl_add_u64 v[148:149], v[230:231], 0, s[20:21]
	s_mov_b32 m0, s65
	s_nop 0
	global_load_lds_dwordx4 v[148:149], off
	v_lshl_add_u64 v[148:149], v[232:233], 0, s[20:21]
	s_mov_b32 m0, s66
	s_nop 0
	global_load_lds_dwordx4 v[148:149], off
	s_waitcnt vmcnt(8)
	s_waitcnt lgkmcnt(0)
	s_barrier
	s_setprio 1
	s_waitcnt lgkmcnt(0)
	v_mfma_f32_16x16x32_bf16 v[60:63], v[142:145], v[190:193], v[60:63]
	v_mfma_f32_16x16x32_bf16 v[52:55], v[166:169], v[190:193], v[52:55]
	v_mfma_f32_16x16x32_bf16 v[44:47], v[142:145], v[198:201], v[44:47]
	v_mfma_f32_16x16x32_bf16 v[36:39], v[166:169], v[198:201], v[36:39]
	v_mfma_f32_16x16x32_bf16 v[28:31], v[142:145], v[212:215], v[28:31]
	v_mfma_f32_16x16x32_bf16 v[20:23], v[166:169], v[212:215], v[20:23]
	v_mfma_f32_16x16x32_bf16 v[12:15], v[142:145], v[220:223], v[12:15]
	v_mfma_f32_16x16x32_bf16 v[4:7], v[166:169], v[220:223], v[4:7]
	v_mfma_f32_16x16x32_bf16 v[60:63], v[162:165], v[194:197], v[60:63]
	v_mfma_f32_16x16x32_bf16 v[52:55], v[170:173], v[194:197], v[52:55]
	v_mfma_f32_16x16x32_bf16 v[44:47], v[162:165], v[202:205], v[44:47]
	v_mfma_f32_16x16x32_bf16 v[36:39], v[170:173], v[202:205], v[36:39]
	v_mfma_f32_16x16x32_bf16 v[28:31], v[162:165], v[216:219], v[28:31]
	v_mfma_f32_16x16x32_bf16 v[20:23], v[170:173], v[216:219], v[20:23]
	v_mfma_f32_16x16x32_bf16 v[12:15], v[162:165], v[224:227], v[12:15]
	v_mfma_f32_16x16x32_bf16 v[4:7], v[170:173], v[224:227], v[4:7]
	v_mfma_f32_16x16x32_bf16 v[56:59], v[174:177], v[190:193], v[56:59]
	v_mfma_f32_16x16x32_bf16 v[48:51], v[182:185], v[190:193], v[48:51]
	v_mfma_f32_16x16x32_bf16 v[40:43], v[174:177], v[198:201], v[40:43]
	v_mfma_f32_16x16x32_bf16 v[32:35], v[182:185], v[198:201], v[32:35]
	v_mfma_f32_16x16x32_bf16 v[24:27], v[174:177], v[212:215], v[24:27]
	v_mfma_f32_16x16x32_bf16 v[16:19], v[182:185], v[212:215], v[16:19]
	v_mfma_f32_16x16x32_bf16 v[8:11], v[174:177], v[220:223], v[8:11]
	v_mfma_f32_16x16x32_bf16 v[0:3], v[182:185], v[220:223], v[0:3]
	v_mfma_f32_16x16x32_bf16 v[56:59], v[178:181], v[194:197], v[56:59]
	v_mfma_f32_16x16x32_bf16 v[48:51], v[186:189], v[194:197], v[48:51]
	v_mfma_f32_16x16x32_bf16 v[40:43], v[178:181], v[202:205], v[40:43]
	v_mfma_f32_16x16x32_bf16 v[32:35], v[186:189], v[202:205], v[32:35]
	v_mfma_f32_16x16x32_bf16 v[24:27], v[178:181], v[216:219], v[24:27]
	v_mfma_f32_16x16x32_bf16 v[16:19], v[186:189], v[216:219], v[16:19]
	v_mfma_f32_16x16x32_bf16 v[8:11], v[178:181], v[224:227], v[8:11]
	v_mfma_f32_16x16x32_bf16 v[0:3], v[186:189], v[224:227], v[0:3]
	s_setprio 0
	s_barrier
	s_add_u32 s30, s30, 0x100
	s_addc_u32 s31, s31, 0
	s_add_u32 s77, s77, 0x100
	s_addc_u32 s82, s82, 0
	s_cmp_ge_i32 s84, s67
	s_mov_b32 s34, s84
	s_cbranch_scc0 .LBB0_191

; #define PG8_STAGE(bufoff, gbase, voff) do { _Pragma("unroll") for (int _i = 0; _i < 2; ++_i) \
;         __builtin_amdgcn_global_load_lds((const unsigned*)((const char*)(gbase) + (voff)[_i]), (PG8_LAS unsigned*)(lds + (bufoff) + ldsw + _i * 8192), 16, 0, 0); } while (0)
; #define PG8_LDA(dst, b, h) do { _Pragma("unroll") for (int m = 0; m < 4; ++m) _Pragma("unroll") for (int k = 0; k < 2; ++k) dst[m][k] = *(const PG8_LAS bf16x8*)(lds + PG8_SA(b, h) + aoff + m * 2048 + k * 1024); } while (0)
; #define PG8_LDB(dst, b, h) do { _Pragma("unroll") for (int n = 0; n < 2; ++n) _Pragma("unroll") for (int k = 0; k < 2; ++k) dst[n][k] = *(const PG8_LAS bf16x8*)(lds + PG8_SB(b, h) + boff + n * 2048 + k * 1024); } while (0)
; #define PG8_MMA(ai, bj, At, Bt) do { __builtin_amdgcn_s_setprio(1); _Pragma("unroll") for (int m = 0; m < 4; ++m) _Pragma("unroll") for (int n = 0; n < 2; ++n) _Pragma("unroll") for (int k = 0; k < 2; ++k) \
;         acc[ai][bj][m][n] = mma16<Epi::F16>(Bt[n][k], At[m][k], acc[ai][bj][m][n]); __builtin_amdgcn_s_setprio(0); } while (0)
; #define PG8_WAIT_V(n) asm volatile("s_waitcnt vmcnt(" #n ")" ::: "memory")
; #define PG8_WAIT_L(n) asm volatile("s_waitcnt lgkmcnt(" #n ")" ::: "memory")
; #define PG8_BAR __builtin_amdgcn_s_barrier()
; #define PG8_SCHED __builtin_amdgcn_sched_barrier(0)
; template <class Epi, class Sched, bool ALIGN_EPI = false, bool SP2 = false>
; __device__ __forceinline__ void gemm_phase(PG8_LAS unsigned char* lds, const Gemm g, const Sched& S, const Epi& E) {
;     ...
;             PG8_LDB(B0, 0, 0); PG8_LDB(B1, 0, 1); PG8_SCHED; PG8_LDA(At, 0, 0); PG8_STAGE(PG8_SA(1, 1), a1 + hstep, voffA);
;             PG8_WAIT_V(8); PG8_WAIT_L(0); PG8_BAR; PG8_MMA(0, 0, At, B0); PG8_MMA(0, 1, At, B1); PG8_BAR; PG8_SCHED;
;             PG8_LDA(At, 0, 1); PG8_STAGE(PG8_SB(0, 0), b2, voffB); PG8_STAGE(PG8_SB(0, 1), b2 + hstep, voffB); PG8_STAGE(PG8_SA(0, 0), a2, voffA);
;             PG8_WAIT_V(8); PG8_WAIT_L(0); PG8_BAR; PG8_MMA(1, 0, At, B0); PG8_MMA(1, 1, At, B1); PG8_BAR; PG8_SCHED;
.Lpeel_k2:
	s_add_u32 s30, s30, 0x80
	s_addc_u32 s31, s31, 0
	s_add_u32 s29, s34, 0x100
	s_addc_u32 s85, s35, 0
	s_mov_b32 s34, 0
	s_add_i32 s92, s34, 2
	s_add_u32 s96, s30, 0x80
	s_addc_u32 s35, s31, 0
	s_add_i32 vcc_lo, 0, 0x10000
	s_cmp_eq_u32 s65, s34
	s_cselect_b32 s35, s1, s35
	s_cselect_b32 s34, s0, s96
	s_cselect_b32 s97, s61, s85
	s_cselect_b32 s96, s60, s29
	s_add_i32 vcc_hi, 0, 0x14000
	v_add_u32_e32 v150, vcc_lo, v131
	v_add_u32_e32 v166, vcc_hi, v131
	ds_read_b128 v[138:141], v150
	ds_read_b128 v[142:145], v150 offset:1024
	ds_read_b128 v[146:149], v150 offset:2048
	ds_read_b128 v[150:153], v150 offset:3072
	ds_read_b128 v[154:157], v166
	ds_read_b128 v[158:161], v166 offset:1024
	ds_read_b128 v[162:165], v166 offset:2048
	ds_read_b128 v[166:169], v166 offset:3072
	v_lshl_add_u64 v[190:191], s[30:31], 0, v[134:135]
	s_add_i32 m0, s8, 0xc000
	ds_read_b128 v[170:173], v199
	ds_read_b128 v[174:177], v199 offset:1024
	ds_read_b128 v[178:181], v199 offset:2048
	ds_read_b128 v[182:185], v199 offset:3072
	ds_read_b128 v[186:189], v199 offset:4096
	ds_read_b128 v[200:203], v199 offset:5120
	ds_read_b128 v[204:207], v199 offset:6144
	ds_read_b128 v[212:215], v199 offset:7168
	global_load_lds_dwordx4 v[190:191], off
	v_lshl_add_u64 v[190:191], s[30:31], 0, v[136:137]
	s_add_i32 m0, s8, 0xe000
	s_nop 0
	global_load_lds_dwordx4 v[190:191], off
	s_waitcnt vmcnt(8)
	s_waitcnt lgkmcnt(0)
	s_barrier
	s_setprio 1
	s_waitcnt lgkmcnt(0)
	v_mfma_f32_16x16x32_bf16 v[120:123], v[138:141], v[170:173], 0
	v_mfma_f32_16x16x32_bf16 v[124:127], v[146:149], v[170:173], 0
	v_mfma_f32_16x16x32_bf16 v[108:111], v[138:141], v[178:181], 0
	v_mfma_f32_16x16x32_bf16 v[104:107], v[146:149], v[178:181], 0
	v_mfma_f32_16x16x32_bf16 v[92:95], v[138:141], v[186:189], 0
	v_mfma_f32_16x16x32_bf16 v[88:91], v[146:149], v[186:189], 0
	v_mfma_f32_16x16x32_bf16 v[76:79], v[138:141], v[204:207], 0
	v_mfma_f32_16x16x32_bf16 v[72:75], v[146:149], v[204:207], 0
	v_mfma_f32_16x16x32_bf16 v[120:123], v[142:145], v[174:177], v[120:123]
	v_mfma_f32_16x16x32_bf16 v[124:127], v[150:153], v[174:177], v[124:127]
	v_mfma_f32_16x16x32_bf16 v[108:111], v[142:145], v[182:185], v[108:111]
	v_mfma_f32_16x16x32_bf16 v[104:107], v[150:153], v[182:185], v[104:107]
	v_mfma_f32_16x16x32_bf16 v[92:95], v[142:145], v[200:203], v[92:95]
	v_mfma_f32_16x16x32_bf16 v[88:91], v[150:153], v[200:203], v[88:91]
	v_mfma_f32_16x16x32_bf16 v[76:79], v[142:145], v[212:215], v[76:79]
	v_mfma_f32_16x16x32_bf16 v[72:75], v[150:153], v[212:215], v[72:75]
	v_mfma_f32_16x16x32_bf16 v[116:119], v[154:157], v[170:173], 0
	v_mfma_f32_16x16x32_bf16 v[112:115], v[162:165], v[170:173], 0
	v_mfma_f32_16x16x32_bf16 v[100:103], v[154:157], v[178:181], 0
	v_mfma_f32_16x16x32_bf16 v[96:99], v[162:165], v[178:181], 0
	v_mfma_f32_16x16x32_bf16 v[84:87], v[154:157], v[186:189], 0
	v_mfma_f32_16x16x32_bf16 v[80:83], v[162:165], v[186:189], 0
	v_mfma_f32_16x16x32_bf16 v[68:71], v[154:157], v[204:207], 0
	v_mfma_f32_16x16x32_bf16 v[64:67], v[162:165], v[204:207], 0
	v_mfma_f32_16x16x32_bf16 v[116:119], v[158:161], v[174:177], v[116:119]
	v_mfma_f32_16x16x32_bf16 v[112:115], v[166:169], v[174:177], v[112:115]
	v_mfma_f32_16x16x32_bf16 v[100:103], v[158:161], v[182:185], v[100:103]
	v_mfma_f32_16x16x32_bf16 v[96:99], v[166:169], v[182:185], v[96:99]
	v_mfma_f32_16x16x32_bf16 v[84:87], v[158:161], v[200:203], v[84:87]
	v_mfma_f32_16x16x32_bf16 v[80:83], v[166:169], v[200:203], v[80:83]
	v_mfma_f32_16x16x32_bf16 v[68:71], v[158:161], v[212:215], v[68:71]
	v_mfma_f32_16x16x32_bf16 v[64:67], v[166:169], v[212:215], v[64:67]
	s_setprio 0
	s_barrier
	s_add_i32 vcc_lo, vcc_lo, s3
	v_lshl_add_u64 v[190:191], s[96:97], 0, v[208:209]
	s_mov_b32 m0, vcc_lo
	ds_read_b128 v[170:173], v199 offset:16384
	ds_read_b128 v[174:177], v199 offset:17408
	ds_read_b128 v[178:181], v199 offset:18432
	ds_read_b128 v[182:185], v199 offset:19456
	ds_read_b128 v[186:189], v199 offset:20480
	ds_read_b128 v[200:203], v199 offset:21504
	ds_read_b128 v[204:207], v199 offset:22528
	ds_read_b128 v[212:215], v199 offset:23552
	global_load_lds_dwordx4 v[190:191], off
	s_add_i32 m0, vcc_lo, 0x2000
	v_lshl_add_u64 v[194:195], s[96:97], 0, v[128:129]
	s_add_u32 s96, s96, s50
	s_addc_u32 s97, s97, s51
	s_add_i32 vcc_lo, vcc_hi, s3
	global_load_lds_dwordx4 v[194:195], off
	v_lshl_add_u64 v[216:217], s[96:97], 0, v[208:209]
	s_mov_b32 m0, vcc_lo
	v_lshl_add_u64 v[218:219], s[96:97], 0, v[128:129]
	global_load_lds_dwordx4 v[216:217], off
	s_add_i32 m0, vcc_lo, 0x2000
	v_lshl_add_u64 v[220:221], s[34:35], 0, v[208:209]
	global_load_lds_dwordx4 v[218:219], off
	s_mov_b32 m0, s8
	v_lshl_add_u64 v[222:223], s[34:35], 0, v[128:129]
	global_load_lds_dwordx4 v[220:221], off
	s_mov_b32 m0, s9
	s_nop 0
	global_load_lds_dwordx4 v[222:223], off
	s_waitcnt vmcnt(8)
	s_waitcnt lgkmcnt(0)
	s_barrier
; #define PG8_STAGE(bufoff, gbase, voff) do { _Pragma("unroll") for (int _i = 0; _i < 2; ++_i) \
;         __builtin_amdgcn_global_load_lds((const unsigned*)((const char*)(gbase) + (voff)[_i]), (PG8_LAS unsigned*)(lds + (bufoff) + ldsw + _i * 8192), 16, 0, 0); } while (0)
; #define PG8_LDA(dst, b, h) do { _Pragma("unroll") for (int m = 0; m < 4; ++m) _Pragma("unroll") for (int k = 0; k < 2; ++k) dst[m][k] = *(const PG8_LAS bf16x8*)(lds + PG8_SA(b, h) + aoff + m * 2048 + k * 1024); } while (0)
; #define PG8_LDB(dst, b, h) do { _Pragma("unroll") for (int n = 0; n < 2; ++n) _Pragma("unroll") for (int k = 0; k < 2; ++k) dst[n][k] = *(const PG8_LAS bf16x8*)(lds + PG8_SB(b, h) + boff + n * 2048 + k * 1024); } while (0)
; #define PG8_MMA(ai, bj, At, Bt) do { __builtin_amdgcn_s_setprio(1); _Pragma("unroll") for (int m = 0; m < 4; ++m) _Pragma("unroll") for (int n = 0; n < 2; ++n) _Pragma("unroll") for (int k = 0; k < 2; ++k) \
;         acc[ai][bj][m][n] = mma16<Epi::F16>(Bt[n][k], At[m][k], acc[ai][bj][m][n]); __builtin_amdgcn_s_setprio(0); } while (0)
; #define PG8_WAIT_V(n) asm volatile("s_waitcnt vmcnt(" #n ")" ::: "memory")
; #define PG8_WAIT_L(n) asm volatile("s_waitcnt lgkmcnt(" #n ")" ::: "memory")
; #define PG8_BAR __builtin_amdgcn_s_barrier()
; #define PG8_SCHED __builtin_amdgcn_sched_barrier(0)
; template <class Epi, class Sched, bool ALIGN_EPI = false, bool SP2 = false>
; __device__ __forceinline__ void gemm_phase(PG8_LAS unsigned char* lds, const Gemm g, const Sched& S, const Epi& E) {
;     ...
;             PG8_WAIT_V(8); PG8_WAIT_L(0); PG8_BAR; PG8_MMA(1, 0, At, B0); PG8_MMA(1, 1, At, B1); PG8_BAR; PG8_SCHED;
;             PG8_LDB(B0, 1, 0); PG8_LDB(B1, 1, 1); PG8_SCHED; PG8_LDA(At, 1, 0); PG8_STAGE(PG8_SA(0, 1), a2 + hstep, voffA);
;             PG8_WAIT_V(8); PG8_WAIT_L(0); PG8_BAR; PG8_MMA(0, 0, At, B0); PG8_MMA(0, 1, At, B1); PG8_BAR; PG8_SCHED;
	s_setprio 1
	s_waitcnt lgkmcnt(0)
	v_mfma_f32_16x16x32_bf16 v[60:63], v[138:141], v[170:173], 0
	v_mfma_f32_16x16x32_bf16 v[56:59], v[146:149], v[170:173], 0
	v_mfma_f32_16x16x32_bf16 v[44:47], v[138:141], v[178:181], 0
	v_mfma_f32_16x16x32_bf16 v[40:43], v[146:149], v[178:181], 0
	v_mfma_f32_16x16x32_bf16 v[28:31], v[138:141], v[186:189], 0
	v_mfma_f32_16x16x32_bf16 v[24:27], v[146:149], v[186:189], 0
	v_mfma_f32_16x16x32_bf16 v[12:15], v[138:141], v[204:207], 0
	v_mfma_f32_16x16x32_bf16 v[8:11], v[146:149], v[204:207], 0
	v_mfma_f32_16x16x32_bf16 v[60:63], v[142:145], v[174:177], v[60:63]
	v_mfma_f32_16x16x32_bf16 v[56:59], v[150:153], v[174:177], v[56:59]
	v_mfma_f32_16x16x32_bf16 v[44:47], v[142:145], v[182:185], v[44:47]
	v_mfma_f32_16x16x32_bf16 v[40:43], v[150:153], v[182:185], v[40:43]
	v_mfma_f32_16x16x32_bf16 v[28:31], v[142:145], v[200:203], v[28:31]
	v_mfma_f32_16x16x32_bf16 v[24:27], v[150:153], v[200:203], v[24:27]
	v_mfma_f32_16x16x32_bf16 v[12:15], v[142:145], v[212:215], v[12:15]
	v_mfma_f32_16x16x32_bf16 v[8:11], v[150:153], v[212:215], v[8:11]
	v_mfma_f32_16x16x32_bf16 v[52:55], v[154:157], v[170:173], 0
	v_mfma_f32_16x16x32_bf16 v[48:51], v[162:165], v[170:173], 0
	v_mfma_f32_16x16x32_bf16 v[36:39], v[154:157], v[178:181], 0
	v_mfma_f32_16x16x32_bf16 v[32:35], v[162:165], v[178:181], 0
	v_mfma_f32_16x16x32_bf16 v[20:23], v[154:157], v[186:189], 0
	v_mfma_f32_16x16x32_bf16 v[16:19], v[162:165], v[186:189], 0
	v_mfma_f32_16x16x32_bf16 v[4:7], v[154:157], v[204:207], 0
	v_mfma_f32_16x16x32_bf16 v[0:3], v[162:165], v[204:207], 0
	v_mfma_f32_16x16x32_bf16 v[52:55], v[158:161], v[174:177], v[52:55]
	v_mfma_f32_16x16x32_bf16 v[48:51], v[166:169], v[174:177], v[48:51]
	v_mfma_f32_16x16x32_bf16 v[36:39], v[158:161], v[182:185], v[36:39]
	v_mfma_f32_16x16x32_bf16 v[32:35], v[166:169], v[182:185], v[32:35]
	v_mfma_f32_16x16x32_bf16 v[20:23], v[158:161], v[200:203], v[20:23]
	v_mfma_f32_16x16x32_bf16 v[16:19], v[166:169], v[200:203], v[16:19]
	v_mfma_f32_16x16x32_bf16 v[4:7], v[158:161], v[212:215], v[4:7]
	v_mfma_f32_16x16x32_bf16 v[0:3], v[166:169], v[212:215], v[0:3]
	s_setprio 0
	s_barrier
	s_add_i32 s96, 0, 0x18000
	s_add_i32 s97, 0, 0x1c000
	v_add_u32_e32 v150, s96, v131
	v_add_u32_e32 v166, s97, v131
	ds_read_b128 v[138:141], v150
	ds_read_b128 v[142:145], v150 offset:1024
	ds_read_b128 v[146:149], v150 offset:2048
	ds_read_b128 v[150:153], v150 offset:3072
	ds_read_b128 v[154:157], v166
	ds_read_b128 v[158:161], v166 offset:1024
	ds_read_b128 v[162:165], v166 offset:2048
	ds_read_b128 v[166:169], v166 offset:3072
	s_add_u32 s34, s34, s50
	s_addc_u32 s35, s35, s51
	s_mov_b32 m0, s11
	v_lshl_add_u64 v[224:225], s[34:35], 0, v[208:209]
	ds_read_b128 v[170:173], v199 offset:32768
	ds_read_b128 v[174:177], v199 offset:33792
	ds_read_b128 v[178:181], v199 offset:34816
	ds_read_b128 v[182:185], v199 offset:35840
	ds_read_b128 v[186:189], v199 offset:36864
	ds_read_b128 v[200:203], v199 offset:37888
	ds_read_b128 v[204:207], v199 offset:38912
	ds_read_b128 v[212:215], v199 offset:39936
	global_load_lds_dwordx4 v[224:225], off
	v_lshl_add_u64 v[224:225], s[34:35], 0, v[128:129]
	s_mov_b32 m0, s36
	s_nop 0
	global_load_lds_dwordx4 v[224:225], off
	s_waitcnt vmcnt(8)
	s_waitcnt lgkmcnt(0)
	s_barrier
	s_setprio 1
	s_waitcnt lgkmcnt(0)
	v_mfma_f32_16x16x32_bf16 v[120:123], v[138:141], v[170:173], v[120:123]
	v_mfma_f32_16x16x32_bf16 v[124:127], v[146:149], v[170:173], v[124:127]
	v_mfma_f32_16x16x32_bf16 v[108:111], v[138:141], v[178:181], v[108:111]
	v_mfma_f32_16x16x32_bf16 v[104:107], v[146:149], v[178:181], v[104:107]
	v_mfma_f32_16x16x32_bf16 v[92:95], v[138:141], v[186:189], v[92:95]
	v_mfma_f32_16x16x32_bf16 v[88:91], v[146:149], v[186:189], v[88:91]
	v_mfma_f32_16x16x32_bf16 v[76:79], v[138:141], v[204:207], v[76:79]
	v_mfma_f32_16x16x32_bf16 v[72:75], v[146:149], v[204:207], v[72:75]
	v_mfma_f32_16x16x32_bf16 v[120:123], v[142:145], v[174:177], v[120:123]
	v_mfma_f32_16x16x32_bf16 v[124:127], v[150:153], v[174:177], v[124:127]
	v_mfma_f32_16x16x32_bf16 v[108:111], v[142:145], v[182:185], v[108:111]
	v_mfma_f32_16x16x32_bf16 v[104:107], v[150:153], v[182:185], v[104:107]
	v_mfma_f32_16x16x32_bf16 v[92:95], v[142:145], v[200:203], v[92:95]
	v_mfma_f32_16x16x32_bf16 v[88:91], v[150:153], v[200:203], v[88:91]
	v_mfma_f32_16x16x32_bf16 v[76:79], v[142:145], v[212:215], v[76:79]
	v_mfma_f32_16x16x32_bf16 v[72:75], v[150:153], v[212:215], v[72:75]
	v_mfma_f32_16x16x32_bf16 v[116:119], v[154:157], v[170:173], v[116:119]
	v_mfma_f32_16x16x32_bf16 v[112:115], v[162:165], v[170:173], v[112:115]
	v_mfma_f32_16x16x32_bf16 v[100:103], v[154:157], v[178:181], v[100:103]
	v_mfma_f32_16x16x32_bf16 v[96:99], v[162:165], v[178:181], v[96:99]
	v_mfma_f32_16x16x32_bf16 v[84:87], v[154:157], v[186:189], v[84:87]
	v_mfma_f32_16x16x32_bf16 v[80:83], v[162:165], v[186:189], v[80:83]
	v_mfma_f32_16x16x32_bf16 v[68:71], v[154:157], v[204:207], v[68:71]
	v_mfma_f32_16x16x32_bf16 v[64:67], v[162:165], v[204:207], v[64:67]
	v_mfma_f32_16x16x32_bf16 v[116:119], v[158:161], v[174:177], v[116:119]
	v_mfma_f32_16x16x32_bf16 v[112:115], v[166:169], v[174:177], v[112:115]
	v_mfma_f32_16x16x32_bf16 v[100:103], v[158:161], v[182:185], v[100:103]
	v_mfma_f32_16x16x32_bf16 v[96:99], v[166:169], v[182:185], v[96:99]
	v_mfma_f32_16x16x32_bf16 v[84:87], v[158:161], v[200:203], v[84:87]
	v_mfma_f32_16x16x32_bf16 v[80:83], v[166:169], v[200:203], v[80:83]
	v_mfma_f32_16x16x32_bf16 v[68:71], v[158:161], v[212:215], v[68:71]
	v_mfma_f32_16x16x32_bf16 v[64:67], v[166:169], v[212:215], v[64:67]
	s_setprio 0
	s_barrier
; #define PG8_STAGE(bufoff, gbase, voff) do { _Pragma("unroll") for (int _i = 0; _i < 2; ++_i) \
;         __builtin_amdgcn_global_load_lds((const unsigned*)((const char*)(gbase) + (voff)[_i]), (PG8_LAS unsigned*)(lds + (bufoff) + ldsw + _i * 8192), 16, 0, 0); } while (0)
; #define PG8_LDA(dst, b, h) do { _Pragma("unroll") for (int m = 0; m < 4; ++m) _Pragma("unroll") for (int k = 0; k < 2; ++k) dst[m][k] = *(const PG8_LAS bf16x8*)(lds + PG8_SA(b, h) + aoff + m * 2048 + k * 1024); } while (0)
; template <class Epi, class Sched, bool ALIGN_EPI = false, bool SP2 = false>
; __device__ __forceinline__ void gemm_phase(PG8_LAS unsigned char* lds, const Gemm g, const Sched& S, const Epi& E) {
;     ...
;         const bool has_next = S.next(ui + 1, nxt);
;         const char* nA = has_next ? (const char*)g.A + (size_t)nxt.pm * tstep : cA; const char* nB = has_next ? (const char*)g.Bt + (size_t)nxt.pn * tstep : cB;
;         for (int t = 0; t < nt; t += 2) {
;             const bool last = (t == nt - 2);
;             const char* a1 = cA + (size_t)(t + 1) * kstep;
;             const char* a2 = last ? nA : cA + (size_t)(t + 2) * kstep; const char* b2 = last ? nB : cB + (size_t)(t + 2) * kstep;
;             const char* a3 = a2 + kstep; const char* b3 = b2 + kstep;
;             if (last && has_next) S.a_ready(nxt);
;             if constexpr (SP2) {
;             PG8_LDB(B0, 0, 0); PG8_LDB(B1, 0, 1); PG8_SCHED; PG8_LDA(At, 0, 0); PG8_STAGE(PG8_SA(1, 1), a1 + hstep, voffA);
;             PG8_WAIT_V(8); PG8_WAIT_L(0); PG8_BAR; PG8_MMA(0, 0, At, B0); PG8_MMA(0, 1, At, B1); PG8_BAR; PG8_SCHED;
;             PG8_LDA(At, 0, 1); PG8_STAGE(PG8_SB(0, 0), b2, voffB); PG8_STAGE(PG8_SB(0, 1), b2 + hstep, voffB); PG8_STAGE(PG8_SA(0, 0), a2, voffA);
;             PG8_WAIT_V(8); PG8_WAIT_L(0); PG8_BAR; PG8_MMA(1, 0, At, B0); PG8_MMA(1, 1, At, B1); PG8_BAR; PG8_SCHED;
;             PG8_LDB(B0, 1, 0); PG8_LDB(B1, 1, 1); PG8_SCHED; PG8_LDA(At, 1, 0); PG8_STAGE(PG8_SA(0, 1), a2 + hstep, voffA);
;             PG8_WAIT_V(8); PG8_WAIT_L(0); PG8_BAR; PG8_MMA(0, 0, At, B0); PG8_MMA(0, 1, At, B1); PG8_BAR; PG8_SCHED;
;             PG8_LDA(At, 1, 1); PG8_STAGE(PG8_SB(1, 0), b3, voffB); PG8_STAGE(PG8_SB(1, 1), b3 + hstep, voffB); PG8_STAGE(PG8_SA(1, 0), a3, voffA);
;             PG8_WAIT_V(8); PG8_WAIT_L(0); PG8_BAR; PG8_MMA(1, 0, At, B0); PG8_MMA(1, 1, At, B1); PG8_BAR; PG8_SCHED;
	s_add_i32 s34, s96, s3
	v_lshl_add_u64 v[190:191], v[190:191], 0, s[20:21]
	s_mov_b32 m0, s34
	ds_read_b128 v[170:173], v199 offset:49152
	ds_read_b128 v[174:177], v199 offset:50176
	ds_read_b128 v[178:181], v199 offset:51200
	ds_read_b128 v[182:185], v199 offset:52224
	ds_read_b128 v[186:189], v199 offset:53248
	ds_read_b128 v[200:203], v199 offset:54272
	ds_read_b128 v[204:207], v199 offset:55296
	ds_read_b128 v[212:215], v199 offset:56320
	global_load_lds_dwordx4 v[190:191], off
	v_lshl_add_u64 v[190:191], v[194:195], 0, s[20:21]
	s_add_i32 m0, s34, 0x2000
	s_add_i32 s34, s97, s3
	global_load_lds_dwordx4 v[190:191], off
	v_lshl_add_u64 v[190:191], v[216:217], 0, s[20:21]
	s_mov_b32 m0, s34
	s_nop 0
	global_load_lds_dwordx4 v[190:191], off
	v_lshl_add_u64 v[190:191], v[218:219], 0, s[20:21]
	s_add_i32 m0, s34, 0x2000
	s_nop 0
	global_load_lds_dwordx4 v[190:191], off
	v_lshl_add_u64 v[190:191], v[220:221], 0, s[20:21]
	s_mov_b32 m0, s48
	s_nop 0
	global_load_lds_dwordx4 v[190:191], off
	v_lshl_add_u64 v[190:191], v[222:223], 0, s[20:21]
	s_mov_b32 m0, s64
	s_nop 0
	global_load_lds_dwordx4 v[190:191], off
	s_waitcnt vmcnt(8)
	s_waitcnt lgkmcnt(0)
	s_barrier
	s_setprio 1
	s_waitcnt lgkmcnt(0)
	v_mfma_f32_16x16x32_bf16 v[60:63], v[138:141], v[170:173], v[60:63]
	v_mfma_f32_16x16x32_bf16 v[56:59], v[146:149], v[170:173], v[56:59]
	v_mfma_f32_16x16x32_bf16 v[44:47], v[138:141], v[178:181], v[44:47]
	v_mfma_f32_16x16x32_bf16 v[40:43], v[146:149], v[178:181], v[40:43]
	v_mfma_f32_16x16x32_bf16 v[28:31], v[138:141], v[186:189], v[28:31]
	v_mfma_f32_16x16x32_bf16 v[24:27], v[146:149], v[186:189], v[24:27]
	v_mfma_f32_16x16x32_bf16 v[12:15], v[138:141], v[204:207], v[12:15]
	v_mfma_f32_16x16x32_bf16 v[8:11], v[146:149], v[204:207], v[8:11]
	v_mfma_f32_16x16x32_bf16 v[60:63], v[142:145], v[174:177], v[60:63]
	v_mfma_f32_16x16x32_bf16 v[56:59], v[150:153], v[174:177], v[56:59]
	v_mfma_f32_16x16x32_bf16 v[44:47], v[142:145], v[182:185], v[44:47]
	v_mfma_f32_16x16x32_bf16 v[40:43], v[150:153], v[182:185], v[40:43]
	v_mfma_f32_16x16x32_bf16 v[28:31], v[142:145], v[200:203], v[28:31]
	v_mfma_f32_16x16x32_bf16 v[24:27], v[150:153], v[200:203], v[24:27]
	v_mfma_f32_16x16x32_bf16 v[12:15], v[142:145], v[212:215], v[12:15]
	v_mfma_f32_16x16x32_bf16 v[8:11], v[150:153], v[212:215], v[8:11]
	v_mfma_f32_16x16x32_bf16 v[52:55], v[154:157], v[170:173], v[52:55]
	v_mfma_f32_16x16x32_bf16 v[48:51], v[162:165], v[170:173], v[48:51]
	v_mfma_f32_16x16x32_bf16 v[36:39], v[154:157], v[178:181], v[36:39]
	v_mfma_f32_16x16x32_bf16 v[32:35], v[162:165], v[178:181], v[32:35]
	v_mfma_f32_16x16x32_bf16 v[20:23], v[154:157], v[186:189], v[20:23]
	v_mfma_f32_16x16x32_bf16 v[16:19], v[162:165], v[186:189], v[16:19]
	v_mfma_f32_16x16x32_bf16 v[4:7], v[154:157], v[204:207], v[4:7]
	v_mfma_f32_16x16x32_bf16 v[0:3], v[162:165], v[204:207], v[0:3]
	v_mfma_f32_16x16x32_bf16 v[52:55], v[158:161], v[174:177], v[52:55]
	v_mfma_f32_16x16x32_bf16 v[48:51], v[166:169], v[174:177], v[48:51]
	v_mfma_f32_16x16x32_bf16 v[36:39], v[158:161], v[182:185], v[36:39]
	v_mfma_f32_16x16x32_bf16 v[32:35], v[166:169], v[182:185], v[32:35]
	v_mfma_f32_16x16x32_bf16 v[20:23], v[158:161], v[200:203], v[20:23]
	v_mfma_f32_16x16x32_bf16 v[16:19], v[166:169], v[200:203], v[16:19]
	v_mfma_f32_16x16x32_bf16 v[4:7], v[158:161], v[212:215], v[4:7]
	v_mfma_f32_16x16x32_bf16 v[0:3], v[166:169], v[212:215], v[0:3]
	s_setprio 0
	s_barrier
	s_add_u32 s30, s30, 0x100
	s_addc_u32 s31, s31, 0
	s_add_u32 s29, s29, 0x100
	s_addc_u32 s85, s85, 0
	s_cmp_ge_i32 s92, s37
	s_mov_b32 s34, s92
	s_cbranch_scc0 .LBB0_312
	s_branch .LBB0_313
.LBB0_312:
	s_add_i32 s92, s34, 2
	s_add_u32 s96, s30, 0x80
	s_addc_u32 s35, s31, 0
	s_add_i32 vcc_lo, 0, 0x10000
	s_cmp_eq_u32 s65, s34
	s_cselect_b32 s35, s1, s35
	s_cselect_b32 s34, s0, s96
	s_cselect_b32 s97, s61, s85
	s_cselect_b32 s96, s60, s29
	s_add_i32 vcc_hi, 0, 0x14000
	v_add_u32_e32 v150, vcc_lo, v131
	v_add_u32_e32 v166, vcc_hi, v131
	ds_read_b128 v[138:141], v150
	ds_read_b128 v[142:145], v150 offset:1024
	ds_read_b128 v[146:149], v150 offset:2048
	ds_read_b128 v[150:153], v150 offset:3072
	ds_read_b128 v[154:157], v166
	ds_read_b128 v[158:161], v166 offset:1024
	ds_read_b128 v[162:165], v166 offset:2048
	ds_read_b128 v[166:169], v166 offset:3072
	v_lshl_add_u64 v[190:191], s[30:31], 0, v[134:135]
	s_add_i32 m0, s8, 0xc000
	ds_read_b128 v[170:173], v199
	ds_read_b128 v[174:177], v199 offset:1024
	ds_read_b128 v[178:181], v199 offset:2048
	ds_read_b128 v[182:185], v199 offset:3072
	ds_read_b128 v[186:189], v199 offset:4096
	ds_read_b128 v[200:203], v199 offset:5120
	ds_read_b128 v[204:207], v199 offset:6144
	ds_read_b128 v[212:215], v199 offset:7168
	global_load_lds_dwordx4 v[190:191], off
	v_lshl_add_u64 v[190:191], s[30:31], 0, v[136:137]
	s_add_i32 m0, s8, 0xe000
	s_nop 0
	global_load_lds_dwordx4 v[190:191], off
	s_waitcnt vmcnt(8)
	s_waitcnt lgkmcnt(0)
	s_barrier
; #define PG8_STAGE(bufoff, gbase, voff) do { _Pragma("unroll") for (int _i = 0; _i < 2; ++_i) \
;         __builtin_amdgcn_global_load_lds((const unsigned*)((const char*)(gbase) + (voff)[_i]), (PG8_LAS unsigned*)(lds + (bufoff) + ldsw + _i * 8192), 16, 0, 0); } while (0)
; #define PG8_LDA(dst, b, h) do { _Pragma("unroll") for (int m = 0; m < 4; ++m) _Pragma("unroll") for (int k = 0; k < 2; ++k) dst[m][k] = *(const PG8_LAS bf16x8*)(lds + PG8_SA(b, h) + aoff + m * 2048 + k * 1024); } while (0)
; #define PG8_LDB(dst, b, h) do { _Pragma("unroll") for (int n = 0; n < 2; ++n) _Pragma("unroll") for (int k = 0; k < 2; ++k) dst[n][k] = *(const PG8_LAS bf16x8*)(lds + PG8_SB(b, h) + boff + n * 2048 + k * 1024); } while (0)
; #define PG8_MMA(ai, bj, At, Bt) do { __builtin_amdgcn_s_setprio(1); _Pragma("unroll") for (int m = 0; m < 4; ++m) _Pragma("unroll") for (int n = 0; n < 2; ++n) _Pragma("unroll") for (int k = 0; k < 2; ++k) \
;         acc[ai][bj][m][n] = mma16<Epi::F16>(Bt[n][k], At[m][k], acc[ai][bj][m][n]); __builtin_amdgcn_s_setprio(0); } while (0)
; #define PG8_WAIT_V(n) asm volatile("s_waitcnt vmcnt(" #n ")" ::: "memory")
; #define PG8_WAIT_L(n) asm volatile("s_waitcnt lgkmcnt(" #n ")" ::: "memory")
; #define PG8_BAR __builtin_amdgcn_s_barrier()
; #define PG8_SCHED __builtin_amdgcn_sched_barrier(0)
; template <class Epi, class Sched, bool ALIGN_EPI = false, bool SP2 = false>
; __device__ __forceinline__ void gemm_phase(PG8_LAS unsigned char* lds, const Gemm g, const Sched& S, const Epi& E) {
;     ...
;             if constexpr (SP2) {
;             PG8_LDB(B0, 0, 0); PG8_LDB(B1, 0, 1); PG8_SCHED; PG8_LDA(At, 0, 0); PG8_STAGE(PG8_SA(1, 1), a1 + hstep, voffA);
;             PG8_WAIT_V(8); PG8_WAIT_L(0); PG8_BAR; PG8_MMA(0, 0, At, B0); PG8_MMA(0, 1, At, B1); PG8_BAR; PG8_SCHED;
;             PG8_LDA(At, 0, 1); PG8_STAGE(PG8_SB(0, 0), b2, voffB); PG8_STAGE(PG8_SB(0, 1), b2 + hstep, voffB); PG8_STAGE(PG8_SA(0, 0), a2, voffA);
;             PG8_WAIT_V(8); PG8_WAIT_L(0); PG8_BAR; PG8_MMA(1, 0, At, B0); PG8_MMA(1, 1, At, B1); PG8_BAR; PG8_SCHED;
	s_setprio 1
	s_waitcnt lgkmcnt(0)
	v_mfma_f32_16x16x32_bf16 v[120:123], v[138:141], v[170:173], v[120:123]
	v_mfma_f32_16x16x32_bf16 v[124:127], v[146:149], v[170:173], v[124:127]
	v_mfma_f32_16x16x32_bf16 v[108:111], v[138:141], v[178:181], v[108:111]
	v_mfma_f32_16x16x32_bf16 v[104:107], v[146:149], v[178:181], v[104:107]
	v_mfma_f32_16x16x32_bf16 v[92:95], v[138:141], v[186:189], v[92:95]
	v_mfma_f32_16x16x32_bf16 v[88:91], v[146:149], v[186:189], v[88:91]
	v_mfma_f32_16x16x32_bf16 v[76:79], v[138:141], v[204:207], v[76:79]
	v_mfma_f32_16x16x32_bf16 v[72:75], v[146:149], v[204:207], v[72:75]
	v_mfma_f32_16x16x32_bf16 v[120:123], v[142:145], v[174:177], v[120:123]
	v_mfma_f32_16x16x32_bf16 v[124:127], v[150:153], v[174:177], v[124:127]
	v_mfma_f32_16x16x32_bf16 v[108:111], v[142:145], v[182:185], v[108:111]
	v_mfma_f32_16x16x32_bf16 v[104:107], v[150:153], v[182:185], v[104:107]
	v_mfma_f32_16x16x32_bf16 v[92:95], v[142:145], v[200:203], v[92:95]
	v_mfma_f32_16x16x32_bf16 v[88:91], v[150:153], v[200:203], v[88:91]
	v_mfma_f32_16x16x32_bf16 v[76:79], v[142:145], v[212:215], v[76:79]
	v_mfma_f32_16x16x32_bf16 v[72:75], v[150:153], v[212:215], v[72:75]
	v_mfma_f32_16x16x32_bf16 v[116:119], v[154:157], v[170:173], v[116:119]
	v_mfma_f32_16x16x32_bf16 v[112:115], v[162:165], v[170:173], v[112:115]
	v_mfma_f32_16x16x32_bf16 v[100:103], v[154:157], v[178:181], v[100:103]
	v_mfma_f32_16x16x32_bf16 v[96:99], v[162:165], v[178:181], v[96:99]
	v_mfma_f32_16x16x32_bf16 v[84:87], v[154:157], v[186:189], v[84:87]
	v_mfma_f32_16x16x32_bf16 v[80:83], v[162:165], v[186:189], v[80:83]
	v_mfma_f32_16x16x32_bf16 v[68:71], v[154:157], v[204:207], v[68:71]
	v_mfma_f32_16x16x32_bf16 v[64:67], v[162:165], v[204:207], v[64:67]
	v_mfma_f32_16x16x32_bf16 v[116:119], v[158:161], v[174:177], v[116:119]
	v_mfma_f32_16x16x32_bf16 v[112:115], v[166:169], v[174:177], v[112:115]
	v_mfma_f32_16x16x32_bf16 v[100:103], v[158:161], v[182:185], v[100:103]
	v_mfma_f32_16x16x32_bf16 v[96:99], v[166:169], v[182:185], v[96:99]
	v_mfma_f32_16x16x32_bf16 v[84:87], v[158:161], v[200:203], v[84:87]
	v_mfma_f32_16x16x32_bf16 v[80:83], v[166:169], v[200:203], v[80:83]
	v_mfma_f32_16x16x32_bf16 v[68:71], v[158:161], v[212:215], v[68:71]
	v_mfma_f32_16x16x32_bf16 v[64:67], v[166:169], v[212:215], v[64:67]
	s_setprio 0
	s_barrier
	s_add_i32 vcc_lo, vcc_lo, s3
	v_lshl_add_u64 v[190:191], s[96:97], 0, v[208:209]
	s_mov_b32 m0, vcc_lo
	ds_read_b128 v[170:173], v199 offset:16384
	ds_read_b128 v[174:177], v199 offset:17408
	ds_read_b128 v[178:181], v199 offset:18432
	ds_read_b128 v[182:185], v199 offset:19456
	ds_read_b128 v[186:189], v199 offset:20480
	ds_read_b128 v[200:203], v199 offset:21504
	ds_read_b128 v[204:207], v199 offset:22528
	ds_read_b128 v[212:215], v199 offset:23552
	global_load_lds_dwordx4 v[190:191], off
	s_add_i32 m0, vcc_lo, 0x2000
	v_lshl_add_u64 v[194:195], s[96:97], 0, v[128:129]
	s_add_u32 s96, s96, s50
	s_addc_u32 s97, s97, s51
	s_add_i32 vcc_lo, vcc_hi, s3
	global_load_lds_dwordx4 v[194:195], off
	v_lshl_add_u64 v[216:217], s[96:97], 0, v[208:209]
	s_mov_b32 m0, vcc_lo
	v_lshl_add_u64 v[218:219], s[96:97], 0, v[128:129]
	global_load_lds_dwordx4 v[216:217], off
	s_add_i32 m0, vcc_lo, 0x2000
	v_lshl_add_u64 v[220:221], s[34:35], 0, v[208:209]
	global_load_lds_dwordx4 v[218:219], off
	s_mov_b32 m0, s8
	v_lshl_add_u64 v[222:223], s[34:35], 0, v[128:129]
	global_load_lds_dwordx4 v[220:221], off
	s_mov_b32 m0, s9
	s_nop 0
	global_load_lds_dwordx4 v[222:223], off
	s_waitcnt vmcnt(8)
	s_waitcnt lgkmcnt(0)
	s_barrier
	s_setprio 1
	s_waitcnt lgkmcnt(0)
	v_mfma_f32_16x16x32_bf16 v[60:63], v[138:141], v[170:173], v[60:63]
	v_mfma_f32_16x16x32_bf16 v[56:59], v[146:149], v[170:173], v[56:59]
	v_mfma_f32_16x16x32_bf16 v[44:47], v[138:141], v[178:181], v[44:47]
	v_mfma_f32_16x16x32_bf16 v[40:43], v[146:149], v[178:181], v[40:43]
	v_mfma_f32_16x16x32_bf16 v[28:31], v[138:141], v[186:189], v[28:31]
	v_mfma_f32_16x16x32_bf16 v[24:27], v[146:149], v[186:189], v[24:27]
	v_mfma_f32_16x16x32_bf16 v[12:15], v[138:141], v[204:207], v[12:15]
	v_mfma_f32_16x16x32_bf16 v[8:11], v[146:149], v[204:207], v[8:11]
	v_mfma_f32_16x16x32_bf16 v[60:63], v[142:145], v[174:177], v[60:63]
	v_mfma_f32_16x16x32_bf16 v[56:59], v[150:153], v[174:177], v[56:59]
	v_mfma_f32_16x16x32_bf16 v[44:47], v[142:145], v[182:185], v[44:47]
	v_mfma_f32_16x16x32_bf16 v[40:43], v[150:153], v[182:185], v[40:43]
	v_mfma_f32_16x16x32_bf16 v[28:31], v[142:145], v[200:203], v[28:31]
	v_mfma_f32_16x16x32_bf16 v[24:27], v[150:153], v[200:203], v[24:27]
	v_mfma_f32_16x16x32_bf16 v[12:15], v[142:145], v[212:215], v[12:15]
	v_mfma_f32_16x16x32_bf16 v[8:11], v[150:153], v[212:215], v[8:11]
	v_mfma_f32_16x16x32_bf16 v[52:55], v[154:157], v[170:173], v[52:55]
	v_mfma_f32_16x16x32_bf16 v[48:51], v[162:165], v[170:173], v[48:51]
	v_mfma_f32_16x16x32_bf16 v[36:39], v[154:157], v[178:181], v[36:39]
	v_mfma_f32_16x16x32_bf16 v[32:35], v[162:165], v[178:181], v[32:35]
	v_mfma_f32_16x16x32_bf16 v[20:23], v[154:157], v[186:189], v[20:23]
	v_mfma_f32_16x16x32_bf16 v[16:19], v[162:165], v[186:189], v[16:19]
	v_mfma_f32_16x16x32_bf16 v[4:7], v[154:157], v[204:207], v[4:7]
	v_mfma_f32_16x16x32_bf16 v[0:3], v[162:165], v[204:207], v[0:3]
	v_mfma_f32_16x16x32_bf16 v[52:55], v[158:161], v[174:177], v[52:55]
	v_mfma_f32_16x16x32_bf16 v[48:51], v[166:169], v[174:177], v[48:51]
	v_mfma_f32_16x16x32_bf16 v[36:39], v[158:161], v[182:185], v[36:39]
	v_mfma_f32_16x16x32_bf16 v[32:35], v[166:169], v[182:185], v[32:35]
	v_mfma_f32_16x16x32_bf16 v[20:23], v[158:161], v[200:203], v[20:23]
	v_mfma_f32_16x16x32_bf16 v[16:19], v[166:169], v[200:203], v[16:19]
	v_mfma_f32_16x16x32_bf16 v[4:7], v[158:161], v[212:215], v[4:7]
	v_mfma_f32_16x16x32_bf16 v[0:3], v[166:169], v[212:215], v[0:3]
	s_setprio 0
	s_barrier
; #define PG8_STAGE(bufoff, gbase, voff) do { _Pragma("unroll") for (int _i = 0; _i < 2; ++_i) \
;         __builtin_amdgcn_global_load_lds((const unsigned*)((const char*)(gbase) + (voff)[_i]), (PG8_LAS unsigned*)(lds + (bufoff) + ldsw + _i * 8192), 16, 0, 0); } while (0)
; #define PG8_LDA(dst, b, h) do { _Pragma("unroll") for (int m = 0; m < 4; ++m) _Pragma("unroll") for (int k = 0; k < 2; ++k) dst[m][k] = *(const PG8_LAS bf16x8*)(lds + PG8_SA(b, h) + aoff + m * 2048 + k * 1024); } while (0)
; #define PG8_LDB(dst, b, h) do { _Pragma("unroll") for (int n = 0; n < 2; ++n) _Pragma("unroll") for (int k = 0; k < 2; ++k) dst[n][k] = *(const PG8_LAS bf16x8*)(lds + PG8_SB(b, h) + boff + n * 2048 + k * 1024); } while (0)
; #define PG8_MMA(ai, bj, At, Bt) do { __builtin_amdgcn_s_setprio(1); _Pragma("unroll") for (int m = 0; m < 4; ++m) _Pragma("unroll") for (int n = 0; n < 2; ++n) _Pragma("unroll") for (int k = 0; k < 2; ++k) \
;         acc[ai][bj][m][n] = mma16<Epi::F16>(Bt[n][k], At[m][k], acc[ai][bj][m][n]); __builtin_amdgcn_s_setprio(0); } while (0)
; #define PG8_WAIT_V(n) asm volatile("s_waitcnt vmcnt(" #n ")" ::: "memory")
; #define PG8_WAIT_L(n) asm volatile("s_waitcnt lgkmcnt(" #n ")" ::: "memory")
; #define PG8_BAR __builtin_amdgcn_s_barrier()
; #define PG8_SCHED __builtin_amdgcn_sched_barrier(0)
; template <class Epi, class Sched, bool ALIGN_EPI = false, bool SP2 = false>
; __device__ __forceinline__ void gemm_phase(PG8_LAS unsigned char* lds, const Gemm g, const Sched& S, const Epi& E) {
;     ...
;             PG8_LDB(B0, 1, 0); PG8_LDB(B1, 1, 1); PG8_SCHED; PG8_LDA(At, 1, 0); PG8_STAGE(PG8_SA(0, 1), a2 + hstep, voffA);
;             PG8_WAIT_V(8); PG8_WAIT_L(0); PG8_BAR; PG8_MMA(0, 0, At, B0); PG8_MMA(0, 1, At, B1); PG8_BAR; PG8_SCHED;
;             PG8_LDA(At, 1, 1); PG8_STAGE(PG8_SB(1, 0), b3, voffB); PG8_STAGE(PG8_SB(1, 1), b3 + hstep, voffB); PG8_STAGE(PG8_SA(1, 0), a3, voffA);
;             PG8_WAIT_V(8); PG8_WAIT_L(0); PG8_BAR; PG8_MMA(1, 0, At, B0); PG8_MMA(1, 1, At, B1); PG8_BAR; PG8_SCHED;
	s_add_i32 s96, 0, 0x18000
	s_add_i32 s97, 0, 0x1c000
	v_add_u32_e32 v150, s96, v131
	v_add_u32_e32 v166, s97, v131
	ds_read_b128 v[138:141], v150
	ds_read_b128 v[142:145], v150 offset:1024
	ds_read_b128 v[146:149], v150 offset:2048
	ds_read_b128 v[150:153], v150 offset:3072
	ds_read_b128 v[154:157], v166
	ds_read_b128 v[158:161], v166 offset:1024
	ds_read_b128 v[162:165], v166 offset:2048
	ds_read_b128 v[166:169], v166 offset:3072
	s_add_u32 s34, s34, s50
	s_addc_u32 s35, s35, s51
	s_mov_b32 m0, s11
	v_lshl_add_u64 v[224:225], s[34:35], 0, v[208:209]
	ds_read_b128 v[170:173], v199 offset:32768
	ds_read_b128 v[174:177], v199 offset:33792
	ds_read_b128 v[178:181], v199 offset:34816
	ds_read_b128 v[182:185], v199 offset:35840
	ds_read_b128 v[186:189], v199 offset:36864
	ds_read_b128 v[200:203], v199 offset:37888
	ds_read_b128 v[204:207], v199 offset:38912
	ds_read_b128 v[212:215], v199 offset:39936
	global_load_lds_dwordx4 v[224:225], off
	v_lshl_add_u64 v[224:225], s[34:35], 0, v[128:129]
	s_mov_b32 m0, s36
	s_nop 0
	global_load_lds_dwordx4 v[224:225], off
	s_waitcnt vmcnt(8)
	s_waitcnt lgkmcnt(0)
	s_barrier
	s_setprio 1
	s_waitcnt lgkmcnt(0)
	v_mfma_f32_16x16x32_bf16 v[120:123], v[138:141], v[170:173], v[120:123]
	v_mfma_f32_16x16x32_bf16 v[124:127], v[146:149], v[170:173], v[124:127]
	v_mfma_f32_16x16x32_bf16 v[108:111], v[138:141], v[178:181], v[108:111]
	v_mfma_f32_16x16x32_bf16 v[104:107], v[146:149], v[178:181], v[104:107]
	v_mfma_f32_16x16x32_bf16 v[92:95], v[138:141], v[186:189], v[92:95]
	v_mfma_f32_16x16x32_bf16 v[88:91], v[146:149], v[186:189], v[88:91]
	v_mfma_f32_16x16x32_bf16 v[76:79], v[138:141], v[204:207], v[76:79]
	v_mfma_f32_16x16x32_bf16 v[72:75], v[146:149], v[204:207], v[72:75]
	v_mfma_f32_16x16x32_bf16 v[120:123], v[142:145], v[174:177], v[120:123]
	v_mfma_f32_16x16x32_bf16 v[124:127], v[150:153], v[174:177], v[124:127]
	v_mfma_f32_16x16x32_bf16 v[108:111], v[142:145], v[182:185], v[108:111]
	v_mfma_f32_16x16x32_bf16 v[104:107], v[150:153], v[182:185], v[104:107]
	v_mfma_f32_16x16x32_bf16 v[92:95], v[142:145], v[200:203], v[92:95]
	v_mfma_f32_16x16x32_bf16 v[88:91], v[150:153], v[200:203], v[88:91]
	v_mfma_f32_16x16x32_bf16 v[76:79], v[142:145], v[212:215], v[76:79]
	v_mfma_f32_16x16x32_bf16 v[72:75], v[150:153], v[212:215], v[72:75]
	v_mfma_f32_16x16x32_bf16 v[116:119], v[154:157], v[170:173], v[116:119]
	v_mfma_f32_16x16x32_bf16 v[112:115], v[162:165], v[170:173], v[112:115]
	v_mfma_f32_16x16x32_bf16 v[100:103], v[154:157], v[178:181], v[100:103]
	v_mfma_f32_16x16x32_bf16 v[96:99], v[162:165], v[178:181], v[96:99]
	v_mfma_f32_16x16x32_bf16 v[84:87], v[154:157], v[186:189], v[84:87]
	v_mfma_f32_16x16x32_bf16 v[80:83], v[162:165], v[186:189], v[80:83]
	v_mfma_f32_16x16x32_bf16 v[68:71], v[154:157], v[204:207], v[68:71]
	v_mfma_f32_16x16x32_bf16 v[64:67], v[162:165], v[204:207], v[64:67]
	v_mfma_f32_16x16x32_bf16 v[116:119], v[158:161], v[174:177], v[116:119]
	v_mfma_f32_16x16x32_bf16 v[112:115], v[166:169], v[174:177], v[112:115]
	v_mfma_f32_16x16x32_bf16 v[100:103], v[158:161], v[182:185], v[100:103]
	v_mfma_f32_16x16x32_bf16 v[96:99], v[166:169], v[182:185], v[96:99]
	v_mfma_f32_16x16x32_bf16 v[84:87], v[158:161], v[200:203], v[84:87]
	v_mfma_f32_16x16x32_bf16 v[80:83], v[166:169], v[200:203], v[80:83]
	v_mfma_f32_16x16x32_bf16 v[68:71], v[158:161], v[212:215], v[68:71]
	v_mfma_f32_16x16x32_bf16 v[64:67], v[166:169], v[212:215], v[64:67]
	s_setprio 0
	s_barrier
	s_add_i32 s34, s96, s3
	v_lshl_add_u64 v[190:191], v[190:191], 0, s[20:21]
	s_mov_b32 m0, s34
	ds_read_b128 v[170:173], v199 offset:49152
	ds_read_b128 v[174:177], v199 offset:50176
	ds_read_b128 v[178:181], v199 offset:51200
	ds_read_b128 v[182:185], v199 offset:52224
	ds_read_b128 v[186:189], v199 offset:53248
	ds_read_b128 v[200:203], v199 offset:54272
	ds_read_b128 v[204:207], v199 offset:55296
	ds_read_b128 v[212:215], v199 offset:56320
	global_load_lds_dwordx4 v[190:191], off
	v_lshl_add_u64 v[190:191], v[194:195], 0, s[20:21]
	s_add_i32 m0, s34, 0x2000
	s_add_i32 s34, s97, s3
	global_load_lds_dwordx4 v[190:191], off
	v_lshl_add_u64 v[190:191], v[216:217], 0, s[20:21]
	s_mov_b32 m0, s34
	s_nop 0
	global_load_lds_dwordx4 v[190:191], off
	v_lshl_add_u64 v[190:191], v[218:219], 0, s[20:21]
	s_add_i32 m0, s34, 0x2000
	s_nop 0
	global_load_lds_dwordx4 v[190:191], off
	v_lshl_add_u64 v[190:191], v[220:221], 0, s[20:21]
	s_mov_b32 m0, s48
	s_nop 0
	global_load_lds_dwordx4 v[190:191], off
	v_lshl_add_u64 v[190:191], v[222:223], 0, s[20:21]
	s_mov_b32 m0, s64
	s_nop 0
	global_load_lds_dwordx4 v[190:191], off
	s_waitcnt vmcnt(8)
	s_waitcnt lgkmcnt(0)
	s_barrier
	s_setprio 1
	s_waitcnt lgkmcnt(0)
	v_mfma_f32_16x16x32_bf16 v[60:63], v[138:141], v[170:173], v[60:63]
	v_mfma_f32_16x16x32_bf16 v[56:59], v[146:149], v[170:173], v[56:59]
	v_mfma_f32_16x16x32_bf16 v[44:47], v[138:141], v[178:181], v[44:47]
	v_mfma_f32_16x16x32_bf16 v[40:43], v[146:149], v[178:181], v[40:43]
	v_mfma_f32_16x16x32_bf16 v[28:31], v[138:141], v[186:189], v[28:31]
	v_mfma_f32_16x16x32_bf16 v[24:27], v[146:149], v[186:189], v[24:27]
	v_mfma_f32_16x16x32_bf16 v[12:15], v[138:141], v[204:207], v[12:15]
	v_mfma_f32_16x16x32_bf16 v[8:11], v[146:149], v[204:207], v[8:11]
	v_mfma_f32_16x16x32_bf16 v[60:63], v[142:145], v[174:177], v[60:63]
	v_mfma_f32_16x16x32_bf16 v[56:59], v[150:153], v[174:177], v[56:59]
	v_mfma_f32_16x16x32_bf16 v[44:47], v[142:145], v[182:185], v[44:47]
	v_mfma_f32_16x16x32_bf16 v[40:43], v[150:153], v[182:185], v[40:43]
	v_mfma_f32_16x16x32_bf16 v[28:31], v[142:145], v[200:203], v[28:31]
	v_mfma_f32_16x16x32_bf16 v[24:27], v[150:153], v[200:203], v[24:27]
	v_mfma_f32_16x16x32_bf16 v[12:15], v[142:145], v[212:215], v[12:15]
	v_mfma_f32_16x16x32_bf16 v[8:11], v[150:153], v[212:215], v[8:11]
	v_mfma_f32_16x16x32_bf16 v[52:55], v[154:157], v[170:173], v[52:55]
	v_mfma_f32_16x16x32_bf16 v[48:51], v[162:165], v[170:173], v[48:51]
	v_mfma_f32_16x16x32_bf16 v[36:39], v[154:157], v[178:181], v[36:39]
	v_mfma_f32_16x16x32_bf16 v[32:35], v[162:165], v[178:181], v[32:35]
	v_mfma_f32_16x16x32_bf16 v[20:23], v[154:157], v[186:189], v[20:23]
	v_mfma_f32_16x16x32_bf16 v[16:19], v[162:165], v[186:189], v[16:19]
	v_mfma_f32_16x16x32_bf16 v[4:7], v[154:157], v[204:207], v[4:7]
	v_mfma_f32_16x16x32_bf16 v[0:3], v[162:165], v[204:207], v[0:3]
	v_mfma_f32_16x16x32_bf16 v[52:55], v[158:161], v[174:177], v[52:55]
	v_mfma_f32_16x16x32_bf16 v[48:51], v[166:169], v[174:177], v[48:51]
	v_mfma_f32_16x16x32_bf16 v[36:39], v[158:161], v[182:185], v[36:39]
	v_mfma_f32_16x16x32_bf16 v[32:35], v[166:169], v[182:185], v[32:35]
	v_mfma_f32_16x16x32_bf16 v[20:23], v[158:161], v[200:203], v[20:23]
	v_mfma_f32_16x16x32_bf16 v[16:19], v[166:169], v[200:203], v[16:19]
	v_mfma_f32_16x16x32_bf16 v[4:7], v[158:161], v[212:215], v[4:7]
	v_mfma_f32_16x16x32_bf16 v[0:3], v[166:169], v[212:215], v[0:3]
	s_setprio 0
	s_barrier
	s_add_u32 s30, s30, 0x100
	s_addc_u32 s31, s31, 0
	s_add_u32 s29, s29, 0x100
	s_addc_u32 s85, s85, 0
	s_cmp_ge_i32 s92, s37
	s_mov_b32 s34, s92
	s_cbranch_scc0 .LBB0_312

; #define PG8_STAGE(bufoff, gbase, voff) do { _Pragma("unroll") for (int _i = 0; _i < 2; ++_i) \
;         __builtin_amdgcn_global_load_lds((const unsigned*)((const char*)(gbase) + (voff)[_i]), (PG8_LAS unsigned*)(lds + (bufoff) + ldsw + _i * 8192), 16, 0, 0); } while (0)
; #define PG8_LDA(dst, b, h) do { _Pragma("unroll") for (int m = 0; m < 4; ++m) _Pragma("unroll") for (int k = 0; k < 2; ++k) dst[m][k] = *(const PG8_LAS bf16x8*)(lds + PG8_SA(b, h) + aoff + m * 2048 + k * 1024); } while (0)
; #define PG8_LDB(dst, b, h) do { _Pragma("unroll") for (int n = 0; n < 2; ++n) _Pragma("unroll") for (int k = 0; k < 2; ++k) dst[n][k] = *(const PG8_LAS bf16x8*)(lds + PG8_SB(b, h) + boff + n * 2048 + k * 1024); } while (0)
; #define PG8_MMA(ai, bj, At, Bt) do { __builtin_amdgcn_s_setprio(1); _Pragma("unroll") for (int m = 0; m < 4; ++m) _Pragma("unroll") for (int n = 0; n < 2; ++n) _Pragma("unroll") for (int k = 0; k < 2; ++k) \
;         acc[ai][bj][m][n] = mma16<Epi::F16>(Bt[n][k], At[m][k], acc[ai][bj][m][n]); __builtin_amdgcn_s_setprio(0); } while (0)
; #define PG8_WAIT_V(n) asm volatile("s_waitcnt vmcnt(" #n ")" ::: "memory")
; #define PG8_WAIT_L(n) asm volatile("s_waitcnt lgkmcnt(" #n ")" ::: "memory")
; #define PG8_BAR __builtin_amdgcn_s_barrier()
; #define PG8_SCHED __builtin_amdgcn_sched_barrier(0)
; template <class Epi, class Sched, bool ALIGN_EPI = false, bool SP2 = false>
; __device__ __forceinline__ void gemm_phase(PG8_LAS unsigned char* lds, const Gemm g, const Sched& S, const Epi& E) {
;     ...
;     f32x4 acc[2][2][4][2];
; #pragma unroll
;     for (int a = 0; a < 2; ++a)
; #pragma unroll
;         for (int b = 0; b < 2; ++b)
; #pragma unroll
;             for (int m = 0; m < 4; ++m)
; #pragma unroll
;                 for (int n = 0; n < 2; ++n) acc[a][b][m][n] = (f32x4){0.f, 0.f, 0.f, 0.f};
;     ...
;             if constexpr (SP2) {
;             PG8_LDB(B0, 0, 0); PG8_LDB(B1, 0, 1); PG8_SCHED; PG8_LDA(At, 0, 0); PG8_STAGE(PG8_SA(1, 1), a1 + hstep, voffA);
;             PG8_WAIT_V(8); PG8_WAIT_L(0); PG8_BAR; PG8_MMA(0, 0, At, B0); PG8_MMA(0, 1, At, B1); PG8_BAR; PG8_SCHED;
;             PG8_LDA(At, 0, 1); PG8_STAGE(PG8_SB(0, 0), b2, voffB); PG8_STAGE(PG8_SB(0, 1), b2 + hstep, voffB); PG8_STAGE(PG8_SA(0, 0), a2, voffA);
;             PG8_WAIT_V(8); PG8_WAIT_L(0); PG8_BAR; PG8_MMA(1, 0, At, B0); PG8_MMA(1, 1, At, B1); PG8_BAR; PG8_SCHED;
.Lpeel_k3:
	s_add_u32 s30, s30, 0x80
	s_addc_u32 s31, s31, 0
	s_add_u32 s29, s34, 0x100
	s_addc_u32 s85, s35, 0
	s_mov_b32 s34, 0
	s_add_i32 s92, s34, 2
	s_add_u32 s96, s30, 0x80
	s_addc_u32 s35, s31, 0
	s_add_i32 vcc_lo, 0, 0x10000
	s_cmp_eq_u32 s37, s34
	s_cselect_b32 s35, s1, s35
	s_cselect_b32 s34, s0, s96
	s_cselect_b32 s97, s27, s85
	s_cselect_b32 s96, s26, s29
	s_add_i32 vcc_hi, 0, 0x14000
	v_add_u32_e32 v140, vcc_lo, v197
	v_add_u32_e32 v156, vcc_hi, v197
	ds_read_b128 v[128:131], v140
	ds_read_b128 v[132:135], v140 offset:1024
	ds_read_b128 v[136:139], v140 offset:2048
	ds_read_b128 v[140:143], v140 offset:3072
	ds_read_b128 v[144:147], v156
	ds_read_b128 v[148:151], v156 offset:1024
	ds_read_b128 v[152:155], v156 offset:2048
	ds_read_b128 v[156:159], v156 offset:3072
	v_lshl_add_u64 v[204:205], s[30:31], 0, v[200:201]
	s_add_i32 m0, s8, 0xc000
	ds_read_b128 v[160:163], v230
	ds_read_b128 v[164:167], v230 offset:1024
	ds_read_b128 v[168:171], v230 offset:2048
	ds_read_b128 v[172:175], v230 offset:3072
	ds_read_b128 v[176:179], v230 offset:4096
	ds_read_b128 v[180:183], v230 offset:5120
	ds_read_b128 v[184:187], v230 offset:6144
	ds_read_b128 v[188:191], v230 offset:7168
	global_load_lds_dwordx4 v[204:205], off
	v_lshl_add_u64 v[204:205], s[30:31], 0, v[202:203]
	s_add_i32 m0, s8, 0xe000
	s_nop 0
	global_load_lds_dwordx4 v[204:205], off
	s_waitcnt vmcnt(8)
	s_waitcnt lgkmcnt(0)
	s_barrier
	s_setprio 1
	s_waitcnt lgkmcnt(0)
	v_mfma_f32_16x16x32_bf16 v[124:127], v[128:131], v[160:163], 0
	v_mfma_f32_16x16x32_bf16 v[120:123], v[136:139], v[160:163], 0
	v_mfma_f32_16x16x32_bf16 v[108:111], v[128:131], v[168:171], 0
	v_mfma_f32_16x16x32_bf16 v[104:107], v[136:139], v[168:171], 0
	v_mfma_f32_16x16x32_bf16 v[92:95], v[128:131], v[176:179], 0
	v_mfma_f32_16x16x32_bf16 v[88:91], v[136:139], v[176:179], 0
	v_mfma_f32_16x16x32_bf16 v[76:79], v[128:131], v[184:187], 0
	v_mfma_f32_16x16x32_bf16 v[72:75], v[136:139], v[184:187], 0
	v_mfma_f32_16x16x32_bf16 v[124:127], v[132:135], v[164:167], v[124:127]
	v_mfma_f32_16x16x32_bf16 v[120:123], v[140:143], v[164:167], v[120:123]
	v_mfma_f32_16x16x32_bf16 v[108:111], v[132:135], v[172:175], v[108:111]
	v_mfma_f32_16x16x32_bf16 v[104:107], v[140:143], v[172:175], v[104:107]
	v_mfma_f32_16x16x32_bf16 v[92:95], v[132:135], v[180:183], v[92:95]
	v_mfma_f32_16x16x32_bf16 v[88:91], v[140:143], v[180:183], v[88:91]
	v_mfma_f32_16x16x32_bf16 v[76:79], v[132:135], v[188:191], v[76:79]
	v_mfma_f32_16x16x32_bf16 v[72:75], v[140:143], v[188:191], v[72:75]
	v_mfma_f32_16x16x32_bf16 v[116:119], v[144:147], v[160:163], 0
	v_mfma_f32_16x16x32_bf16 v[112:115], v[152:155], v[160:163], 0
	v_mfma_f32_16x16x32_bf16 v[100:103], v[144:147], v[168:171], 0
	v_mfma_f32_16x16x32_bf16 v[96:99], v[152:155], v[168:171], 0
	v_mfma_f32_16x16x32_bf16 v[84:87], v[144:147], v[176:179], 0
	v_mfma_f32_16x16x32_bf16 v[80:83], v[152:155], v[176:179], 0
	v_mfma_f32_16x16x32_bf16 v[68:71], v[144:147], v[184:187], 0
	v_mfma_f32_16x16x32_bf16 v[64:67], v[152:155], v[184:187], 0
	v_mfma_f32_16x16x32_bf16 v[116:119], v[148:151], v[164:167], v[116:119]
	v_mfma_f32_16x16x32_bf16 v[112:115], v[156:159], v[164:167], v[112:115]
	v_mfma_f32_16x16x32_bf16 v[100:103], v[148:151], v[172:175], v[100:103]
	v_mfma_f32_16x16x32_bf16 v[96:99], v[156:159], v[172:175], v[96:99]
	v_mfma_f32_16x16x32_bf16 v[84:87], v[148:151], v[180:183], v[84:87]
	v_mfma_f32_16x16x32_bf16 v[80:83], v[156:159], v[180:183], v[80:83]
	v_mfma_f32_16x16x32_bf16 v[68:71], v[148:151], v[188:191], v[68:71]
	v_mfma_f32_16x16x32_bf16 v[64:67], v[156:159], v[188:191], v[64:67]
	s_setprio 0
	s_barrier
	s_add_i32 vcc_lo, vcc_lo, s3
	v_lshl_add_u64 v[204:205], s[96:97], 0, v[208:209]
	s_mov_b32 m0, vcc_lo
	ds_read_b128 v[160:163], v230 offset:16384
	ds_read_b128 v[164:167], v230 offset:17408
	ds_read_b128 v[168:171], v230 offset:18432
	ds_read_b128 v[172:175], v230 offset:19456
	ds_read_b128 v[176:179], v230 offset:20480
	ds_read_b128 v[180:183], v230 offset:21504
	ds_read_b128 v[184:187], v230 offset:22528
	ds_read_b128 v[188:191], v230 offset:23552
	global_load_lds_dwordx4 v[204:205], off
	s_add_i32 m0, vcc_lo, 0x2000
	v_lshl_add_u64 v[206:207], s[96:97], 0, v[194:195]
	s_add_u32 s96, s96, s50
	s_addc_u32 s97, s97, s51
	s_add_i32 vcc_lo, vcc_hi, s3
	global_load_lds_dwordx4 v[206:207], off
	v_lshl_add_u64 v[212:213], s[96:97], 0, v[208:209]
	s_mov_b32 m0, vcc_lo
	v_lshl_add_u64 v[214:215], s[96:97], 0, v[194:195]
	global_load_lds_dwordx4 v[212:213], off
	s_add_i32 m0, vcc_lo, 0x2000
	v_lshl_add_u64 v[216:217], s[34:35], 0, v[208:209]
	global_load_lds_dwordx4 v[214:215], off
	s_mov_b32 m0, s8
	v_lshl_add_u64 v[218:219], s[34:35], 0, v[194:195]
	global_load_lds_dwordx4 v[216:217], off
	s_mov_b32 m0, s9
	s_nop 0
	global_load_lds_dwordx4 v[218:219], off
	s_waitcnt vmcnt(8)
	s_waitcnt lgkmcnt(0)
	s_barrier
; #define PG8_STAGE(bufoff, gbase, voff) do { _Pragma("unroll") for (int _i = 0; _i < 2; ++_i) \
;         __builtin_amdgcn_global_load_lds((const unsigned*)((const char*)(gbase) + (voff)[_i]), (PG8_LAS unsigned*)(lds + (bufoff) + ldsw + _i * 8192), 16, 0, 0); } while (0)
; #define PG8_LDA(dst, b, h) do { _Pragma("unroll") for (int m = 0; m < 4; ++m) _Pragma("unroll") for (int k = 0; k < 2; ++k) dst[m][k] = *(const PG8_LAS bf16x8*)(lds + PG8_SA(b, h) + aoff + m * 2048 + k * 1024); } while (0)
; #define PG8_LDB(dst, b, h) do { _Pragma("unroll") for (int n = 0; n < 2; ++n) _Pragma("unroll") for (int k = 0; k < 2; ++k) dst[n][k] = *(const PG8_LAS bf16x8*)(lds + PG8_SB(b, h) + boff + n * 2048 + k * 1024); } while (0)
; #define PG8_MMA(ai, bj, At, Bt) do { __builtin_amdgcn_s_setprio(1); _Pragma("unroll") for (int m = 0; m < 4; ++m) _Pragma("unroll") for (int n = 0; n < 2; ++n) _Pragma("unroll") for (int k = 0; k < 2; ++k) \
;         acc[ai][bj][m][n] = mma16<Epi::F16>(Bt[n][k], At[m][k], acc[ai][bj][m][n]); __builtin_amdgcn_s_setprio(0); } while (0)
; #define PG8_WAIT_V(n) asm volatile("s_waitcnt vmcnt(" #n ")" ::: "memory")
; #define PG8_WAIT_L(n) asm volatile("s_waitcnt lgkmcnt(" #n ")" ::: "memory")
; #define PG8_BAR __builtin_amdgcn_s_barrier()
; #define PG8_SCHED __builtin_amdgcn_sched_barrier(0)
; template <class Epi, class Sched, bool ALIGN_EPI = false, bool SP2 = false>
; __device__ __forceinline__ void gemm_phase(PG8_LAS unsigned char* lds, const Gemm g, const Sched& S, const Epi& E) {
;     ...
;             if constexpr (SP2) {
;             PG8_LDB(B0, 0, 0); PG8_LDB(B1, 0, 1); PG8_SCHED; PG8_LDA(At, 0, 0); PG8_STAGE(PG8_SA(1, 1), a1 + hstep, voffA);
;             PG8_WAIT_V(8); PG8_WAIT_L(0); PG8_BAR; PG8_MMA(0, 0, At, B0); PG8_MMA(0, 1, At, B1); PG8_BAR; PG8_SCHED;
;             PG8_LDA(At, 0, 1); PG8_STAGE(PG8_SB(0, 0), b2, voffB); PG8_STAGE(PG8_SB(0, 1), b2 + hstep, voffB); PG8_STAGE(PG8_SA(0, 0), a2, voffA);
;             PG8_WAIT_V(8); PG8_WAIT_L(0); PG8_BAR; PG8_MMA(1, 0, At, B0); PG8_MMA(1, 1, At, B1); PG8_BAR; PG8_SCHED;
;             PG8_LDB(B0, 1, 0); PG8_LDB(B1, 1, 1); PG8_SCHED; PG8_LDA(At, 1, 0); PG8_STAGE(PG8_SA(0, 1), a2 + hstep, voffA);
;             PG8_WAIT_V(8); PG8_WAIT_L(0); PG8_BAR; PG8_MMA(0, 0, At, B0); PG8_MMA(0, 1, At, B1); PG8_BAR; PG8_SCHED;
	s_setprio 1
	s_waitcnt lgkmcnt(0)
	v_mfma_f32_16x16x32_bf16 v[60:63], v[128:131], v[160:163], 0
	v_mfma_f32_16x16x32_bf16 v[56:59], v[136:139], v[160:163], 0
	v_mfma_f32_16x16x32_bf16 v[44:47], v[128:131], v[168:171], 0
	v_mfma_f32_16x16x32_bf16 v[40:43], v[136:139], v[168:171], 0
	v_mfma_f32_16x16x32_bf16 v[28:31], v[128:131], v[176:179], 0
	v_mfma_f32_16x16x32_bf16 v[24:27], v[136:139], v[176:179], 0
	v_mfma_f32_16x16x32_bf16 v[12:15], v[128:131], v[184:187], 0
	v_mfma_f32_16x16x32_bf16 v[8:11], v[136:139], v[184:187], 0
	v_mfma_f32_16x16x32_bf16 v[60:63], v[132:135], v[164:167], v[60:63]
	v_mfma_f32_16x16x32_bf16 v[56:59], v[140:143], v[164:167], v[56:59]
	v_mfma_f32_16x16x32_bf16 v[44:47], v[132:135], v[172:175], v[44:47]
	v_mfma_f32_16x16x32_bf16 v[40:43], v[140:143], v[172:175], v[40:43]
	v_mfma_f32_16x16x32_bf16 v[28:31], v[132:135], v[180:183], v[28:31]
	v_mfma_f32_16x16x32_bf16 v[24:27], v[140:143], v[180:183], v[24:27]
	v_mfma_f32_16x16x32_bf16 v[12:15], v[132:135], v[188:191], v[12:15]
	v_mfma_f32_16x16x32_bf16 v[8:11], v[140:143], v[188:191], v[8:11]
	v_mfma_f32_16x16x32_bf16 v[52:55], v[144:147], v[160:163], 0
	v_mfma_f32_16x16x32_bf16 v[48:51], v[152:155], v[160:163], 0
	v_mfma_f32_16x16x32_bf16 v[36:39], v[144:147], v[168:171], 0
	v_mfma_f32_16x16x32_bf16 v[32:35], v[152:155], v[168:171], 0
	v_mfma_f32_16x16x32_bf16 v[20:23], v[144:147], v[176:179], 0
	v_mfma_f32_16x16x32_bf16 v[16:19], v[152:155], v[176:179], 0
	v_mfma_f32_16x16x32_bf16 v[4:7], v[144:147], v[184:187], 0
	v_mfma_f32_16x16x32_bf16 v[0:3], v[152:155], v[184:187], 0
	v_mfma_f32_16x16x32_bf16 v[52:55], v[148:151], v[164:167], v[52:55]
	v_mfma_f32_16x16x32_bf16 v[48:51], v[156:159], v[164:167], v[48:51]
	v_mfma_f32_16x16x32_bf16 v[36:39], v[148:151], v[172:175], v[36:39]
	v_mfma_f32_16x16x32_bf16 v[32:35], v[156:159], v[172:175], v[32:35]
	v_mfma_f32_16x16x32_bf16 v[20:23], v[148:151], v[180:183], v[20:23]
	v_mfma_f32_16x16x32_bf16 v[16:19], v[156:159], v[180:183], v[16:19]
	v_mfma_f32_16x16x32_bf16 v[4:7], v[148:151], v[188:191], v[4:7]
	v_mfma_f32_16x16x32_bf16 v[0:3], v[156:159], v[188:191], v[0:3]
	s_setprio 0
	s_barrier
	s_add_i32 s96, 0, 0x18000
	s_add_i32 s97, 0, 0x1c000
	v_add_u32_e32 v140, s96, v197
	v_add_u32_e32 v156, s97, v197
	ds_read_b128 v[128:131], v140
	ds_read_b128 v[132:135], v140 offset:1024
	ds_read_b128 v[136:139], v140 offset:2048
	ds_read_b128 v[140:143], v140 offset:3072
	ds_read_b128 v[144:147], v156
	ds_read_b128 v[148:151], v156 offset:1024
	ds_read_b128 v[152:155], v156 offset:2048
	ds_read_b128 v[156:159], v156 offset:3072
	s_add_u32 s34, s34, s50
	s_addc_u32 s35, s35, s51
	s_mov_b32 m0, s11
	v_lshl_add_u64 v[220:221], s[34:35], 0, v[208:209]
	ds_read_b128 v[160:163], v230 offset:32768
	ds_read_b128 v[164:167], v230 offset:33792
	ds_read_b128 v[168:171], v230 offset:34816
	ds_read_b128 v[172:175], v230 offset:35840
	ds_read_b128 v[176:179], v230 offset:36864
	ds_read_b128 v[180:183], v230 offset:37888
	ds_read_b128 v[184:187], v230 offset:38912
	ds_read_b128 v[188:191], v230 offset:39936
	global_load_lds_dwordx4 v[220:221], off
	v_lshl_add_u64 v[220:221], s[34:35], 0, v[194:195]
	s_mov_b32 m0, s36
	s_nop 0
	global_load_lds_dwordx4 v[220:221], off
	s_waitcnt vmcnt(8)
	s_waitcnt lgkmcnt(0)
	s_barrier
	s_setprio 1
	s_waitcnt lgkmcnt(0)
	v_mfma_f32_16x16x32_bf16 v[124:127], v[128:131], v[160:163], v[124:127]
	v_mfma_f32_16x16x32_bf16 v[120:123], v[136:139], v[160:163], v[120:123]
	v_mfma_f32_16x16x32_bf16 v[108:111], v[128:131], v[168:171], v[108:111]
	v_mfma_f32_16x16x32_bf16 v[104:107], v[136:139], v[168:171], v[104:107]
	v_mfma_f32_16x16x32_bf16 v[92:95], v[128:131], v[176:179], v[92:95]
	v_mfma_f32_16x16x32_bf16 v[88:91], v[136:139], v[176:179], v[88:91]
	v_mfma_f32_16x16x32_bf16 v[76:79], v[128:131], v[184:187], v[76:79]
	v_mfma_f32_16x16x32_bf16 v[72:75], v[136:139], v[184:187], v[72:75]
	v_mfma_f32_16x16x32_bf16 v[124:127], v[132:135], v[164:167], v[124:127]
	v_mfma_f32_16x16x32_bf16 v[120:123], v[140:143], v[164:167], v[120:123]
	v_mfma_f32_16x16x32_bf16 v[108:111], v[132:135], v[172:175], v[108:111]
	v_mfma_f32_16x16x32_bf16 v[104:107], v[140:143], v[172:175], v[104:107]
	v_mfma_f32_16x16x32_bf16 v[92:95], v[132:135], v[180:183], v[92:95]
	v_mfma_f32_16x16x32_bf16 v[88:91], v[140:143], v[180:183], v[88:91]
	v_mfma_f32_16x16x32_bf16 v[76:79], v[132:135], v[188:191], v[76:79]
	v_mfma_f32_16x16x32_bf16 v[72:75], v[140:143], v[188:191], v[72:75]
	v_mfma_f32_16x16x32_bf16 v[116:119], v[144:147], v[160:163], v[116:119]
	v_mfma_f32_16x16x32_bf16 v[112:115], v[152:155], v[160:163], v[112:115]
	v_mfma_f32_16x16x32_bf16 v[100:103], v[144:147], v[168:171], v[100:103]
	v_mfma_f32_16x16x32_bf16 v[96:99], v[152:155], v[168:171], v[96:99]
	v_mfma_f32_16x16x32_bf16 v[84:87], v[144:147], v[176:179], v[84:87]
	v_mfma_f32_16x16x32_bf16 v[80:83], v[152:155], v[176:179], v[80:83]
	v_mfma_f32_16x16x32_bf16 v[68:71], v[144:147], v[184:187], v[68:71]
	v_mfma_f32_16x16x32_bf16 v[64:67], v[152:155], v[184:187], v[64:67]
	v_mfma_f32_16x16x32_bf16 v[116:119], v[148:151], v[164:167], v[116:119]
	v_mfma_f32_16x16x32_bf16 v[112:115], v[156:159], v[164:167], v[112:115]
	v_mfma_f32_16x16x32_bf16 v[100:103], v[148:151], v[172:175], v[100:103]
	v_mfma_f32_16x16x32_bf16 v[96:99], v[156:159], v[172:175], v[96:99]
	v_mfma_f32_16x16x32_bf16 v[84:87], v[148:151], v[180:183], v[84:87]
	v_mfma_f32_16x16x32_bf16 v[80:83], v[156:159], v[180:183], v[80:83]
	v_mfma_f32_16x16x32_bf16 v[68:71], v[148:151], v[188:191], v[68:71]
	v_mfma_f32_16x16x32_bf16 v[64:67], v[156:159], v[188:191], v[64:67]
	s_setprio 0
	s_barrier
; #define PG8_STAGE(bufoff, gbase, voff) do { _Pragma("unroll") for (int _i = 0; _i < 2; ++_i) \
;         __builtin_amdgcn_global_load_lds((const unsigned*)((const char*)(gbase) + (voff)[_i]), (PG8_LAS unsigned*)(lds + (bufoff) + ldsw + _i * 8192), 16, 0, 0); } while (0)
; #define PG8_LDA(dst, b, h) do { _Pragma("unroll") for (int m = 0; m < 4; ++m) _Pragma("unroll") for (int k = 0; k < 2; ++k) dst[m][k] = *(const PG8_LAS bf16x8*)(lds + PG8_SA(b, h) + aoff + m * 2048 + k * 1024); } while (0)
; template <class Epi, class Sched, bool ALIGN_EPI = false, bool SP2 = false>
; __device__ __forceinline__ void gemm_phase(PG8_LAS unsigned char* lds, const Gemm g, const Sched& S, const Epi& E) {
;     ...
;         const bool has_next = S.next(ui + 1, nxt);
;         const char* nA = has_next ? (const char*)g.A + (size_t)nxt.pm * tstep : cA; const char* nB = has_next ? (const char*)g.Bt + (size_t)nxt.pn * tstep : cB;
;         for (int t = 0; t < nt; t += 2) {
;             const bool last = (t == nt - 2);
;             const char* a1 = cA + (size_t)(t + 1) * kstep;
;             const char* a2 = last ? nA : cA + (size_t)(t + 2) * kstep; const char* b2 = last ? nB : cB + (size_t)(t + 2) * kstep;
;             const char* a3 = a2 + kstep; const char* b3 = b2 + kstep;
;             if (last && has_next) S.a_ready(nxt);
;             if constexpr (SP2) {
;             PG8_LDB(B0, 0, 0); PG8_LDB(B1, 0, 1); PG8_SCHED; PG8_LDA(At, 0, 0); PG8_STAGE(PG8_SA(1, 1), a1 + hstep, voffA);
;             PG8_WAIT_V(8); PG8_WAIT_L(0); PG8_BAR; PG8_MMA(0, 0, At, B0); PG8_MMA(0, 1, At, B1); PG8_BAR; PG8_SCHED;
;             PG8_LDA(At, 0, 1); PG8_STAGE(PG8_SB(0, 0), b2, voffB); PG8_STAGE(PG8_SB(0, 1), b2 + hstep, voffB); PG8_STAGE(PG8_SA(0, 0), a2, voffA);
;             PG8_WAIT_V(8); PG8_WAIT_L(0); PG8_BAR; PG8_MMA(1, 0, At, B0); PG8_MMA(1, 1, At, B1); PG8_BAR; PG8_SCHED;
;             PG8_LDB(B0, 1, 0); PG8_LDB(B1, 1, 1); PG8_SCHED; PG8_LDA(At, 1, 0); PG8_STAGE(PG8_SA(0, 1), a2 + hstep, voffA);
;             PG8_WAIT_V(8); PG8_WAIT_L(0); PG8_BAR; PG8_MMA(0, 0, At, B0); PG8_MMA(0, 1, At, B1); PG8_BAR; PG8_SCHED;
;             PG8_LDA(At, 1, 1); PG8_STAGE(PG8_SB(1, 0), b3, voffB); PG8_STAGE(PG8_SB(1, 1), b3 + hstep, voffB); PG8_STAGE(PG8_SA(1, 0), a3, voffA);
;             PG8_WAIT_V(8); PG8_WAIT_L(0); PG8_BAR; PG8_MMA(1, 0, At, B0); PG8_MMA(1, 1, At, B1); PG8_BAR; PG8_SCHED;
	s_add_i32 s34, s96, s3
	v_lshl_add_u64 v[204:205], v[204:205], 0, s[20:21]
	s_mov_b32 m0, s34
	ds_read_b128 v[160:163], v230 offset:49152
	ds_read_b128 v[164:167], v230 offset:50176
	ds_read_b128 v[168:171], v230 offset:51200
	ds_read_b128 v[172:175], v230 offset:52224
	ds_read_b128 v[176:179], v230 offset:53248
	ds_read_b128 v[180:183], v230 offset:54272
	ds_read_b128 v[184:187], v230 offset:55296
	ds_read_b128 v[188:191], v230 offset:56320
	global_load_lds_dwordx4 v[204:205], off
	v_lshl_add_u64 v[204:205], v[206:207], 0, s[20:21]
	s_add_i32 m0, s34, 0x2000
	s_add_i32 s34, s97, s3
	global_load_lds_dwordx4 v[204:205], off
	v_lshl_add_u64 v[204:205], v[212:213], 0, s[20:21]
	s_mov_b32 m0, s34
	s_nop 0
	global_load_lds_dwordx4 v[204:205], off
	v_lshl_add_u64 v[204:205], v[214:215], 0, s[20:21]
	s_add_i32 m0, s34, 0x2000
	s_nop 0
	global_load_lds_dwordx4 v[204:205], off
	v_lshl_add_u64 v[204:205], v[216:217], 0, s[20:21]
	s_mov_b32 m0, s48
	s_nop 0
	global_load_lds_dwordx4 v[204:205], off
	v_lshl_add_u64 v[204:205], v[218:219], 0, s[20:21]
	s_mov_b32 m0, s49
	s_nop 0
	global_load_lds_dwordx4 v[204:205], off
	s_waitcnt vmcnt(8)
	s_waitcnt lgkmcnt(0)
	s_barrier
	s_setprio 1
	s_waitcnt lgkmcnt(0)
	v_mfma_f32_16x16x32_bf16 v[60:63], v[128:131], v[160:163], v[60:63]
	v_mfma_f32_16x16x32_bf16 v[56:59], v[136:139], v[160:163], v[56:59]
	v_mfma_f32_16x16x32_bf16 v[44:47], v[128:131], v[168:171], v[44:47]
	v_mfma_f32_16x16x32_bf16 v[40:43], v[136:139], v[168:171], v[40:43]
	v_mfma_f32_16x16x32_bf16 v[28:31], v[128:131], v[176:179], v[28:31]
	v_mfma_f32_16x16x32_bf16 v[24:27], v[136:139], v[176:179], v[24:27]
	v_mfma_f32_16x16x32_bf16 v[12:15], v[128:131], v[184:187], v[12:15]
	v_mfma_f32_16x16x32_bf16 v[8:11], v[136:139], v[184:187], v[8:11]
	v_mfma_f32_16x16x32_bf16 v[60:63], v[132:135], v[164:167], v[60:63]
	v_mfma_f32_16x16x32_bf16 v[56:59], v[140:143], v[164:167], v[56:59]
	v_mfma_f32_16x16x32_bf16 v[44:47], v[132:135], v[172:175], v[44:47]
	v_mfma_f32_16x16x32_bf16 v[40:43], v[140:143], v[172:175], v[40:43]
	v_mfma_f32_16x16x32_bf16 v[28:31], v[132:135], v[180:183], v[28:31]
	v_mfma_f32_16x16x32_bf16 v[24:27], v[140:143], v[180:183], v[24:27]
	v_mfma_f32_16x16x32_bf16 v[12:15], v[132:135], v[188:191], v[12:15]
	v_mfma_f32_16x16x32_bf16 v[8:11], v[140:143], v[188:191], v[8:11]
	v_mfma_f32_16x16x32_bf16 v[52:55], v[144:147], v[160:163], v[52:55]
	v_mfma_f32_16x16x32_bf16 v[48:51], v[152:155], v[160:163], v[48:51]
	v_mfma_f32_16x16x32_bf16 v[36:39], v[144:147], v[168:171], v[36:39]
	v_mfma_f32_16x16x32_bf16 v[32:35], v[152:155], v[168:171], v[32:35]
	v_mfma_f32_16x16x32_bf16 v[20:23], v[144:147], v[176:179], v[20:23]
	v_mfma_f32_16x16x32_bf16 v[16:19], v[152:155], v[176:179], v[16:19]
	v_mfma_f32_16x16x32_bf16 v[4:7], v[144:147], v[184:187], v[4:7]
	v_mfma_f32_16x16x32_bf16 v[0:3], v[152:155], v[184:187], v[0:3]
	v_mfma_f32_16x16x32_bf16 v[52:55], v[148:151], v[164:167], v[52:55]
	v_mfma_f32_16x16x32_bf16 v[48:51], v[156:159], v[164:167], v[48:51]
	v_mfma_f32_16x16x32_bf16 v[36:39], v[148:151], v[172:175], v[36:39]
	v_mfma_f32_16x16x32_bf16 v[32:35], v[156:159], v[172:175], v[32:35]
	v_mfma_f32_16x16x32_bf16 v[20:23], v[148:151], v[180:183], v[20:23]
	v_mfma_f32_16x16x32_bf16 v[16:19], v[156:159], v[180:183], v[16:19]
	v_mfma_f32_16x16x32_bf16 v[4:7], v[148:151], v[188:191], v[4:7]
	v_mfma_f32_16x16x32_bf16 v[0:3], v[156:159], v[188:191], v[0:3]
	s_setprio 0
	s_barrier
	s_add_u32 s30, s30, 0x100
	s_addc_u32 s31, s31, 0
	s_add_u32 s29, s29, 0x100
	s_addc_u32 s85, s85, 0
	s_cmp_ge_i32 s92, s79
	s_mov_b32 s34, s92
	s_cbranch_scc0 .LBB0_369
	s_branch .LBB0_370
.LBB0_369:
	s_add_i32 s92, s34, 2
	s_add_u32 s96, s30, 0x80
	s_addc_u32 s35, s31, 0
	s_add_i32 vcc_lo, 0, 0x10000
	s_cmp_eq_u32 s37, s34
	s_cselect_b32 s35, s1, s35
	s_cselect_b32 s34, s0, s96
	s_cselect_b32 s97, s27, s85
	s_cselect_b32 s96, s26, s29
	s_add_i32 vcc_hi, 0, 0x14000
	v_add_u32_e32 v140, vcc_lo, v197
	v_add_u32_e32 v156, vcc_hi, v197
	ds_read_b128 v[128:131], v140
	ds_read_b128 v[132:135], v140 offset:1024
	ds_read_b128 v[136:139], v140 offset:2048
	ds_read_b128 v[140:143], v140 offset:3072
	ds_read_b128 v[144:147], v156
	ds_read_b128 v[148:151], v156 offset:1024
	ds_read_b128 v[152:155], v156 offset:2048
	ds_read_b128 v[156:159], v156 offset:3072
	v_lshl_add_u64 v[204:205], s[30:31], 0, v[200:201]
	s_add_i32 m0, s8, 0xc000
	ds_read_b128 v[160:163], v230
	ds_read_b128 v[164:167], v230 offset:1024
	ds_read_b128 v[168:171], v230 offset:2048
	ds_read_b128 v[172:175], v230 offset:3072
	ds_read_b128 v[176:179], v230 offset:4096
	ds_read_b128 v[180:183], v230 offset:5120
	ds_read_b128 v[184:187], v230 offset:6144
	ds_read_b128 v[188:191], v230 offset:7168
	global_load_lds_dwordx4 v[204:205], off
	v_lshl_add_u64 v[204:205], s[30:31], 0, v[202:203]
	s_add_i32 m0, s8, 0xe000
	s_nop 0
	global_load_lds_dwordx4 v[204:205], off
	s_waitcnt vmcnt(8)
	s_waitcnt lgkmcnt(0)
	s_barrier
; #define PG8_STAGE(bufoff, gbase, voff) do { _Pragma("unroll") for (int _i = 0; _i < 2; ++_i) \
;         __builtin_amdgcn_global_load_lds((const unsigned*)((const char*)(gbase) + (voff)[_i]), (PG8_LAS unsigned*)(lds + (bufoff) + ldsw + _i * 8192), 16, 0, 0); } while (0)
; #define PG8_LDA(dst, b, h) do { _Pragma("unroll") for (int m = 0; m < 4; ++m) _Pragma("unroll") for (int k = 0; k < 2; ++k) dst[m][k] = *(const PG8_LAS bf16x8*)(lds + PG8_SA(b, h) + aoff + m * 2048 + k * 1024); } while (0)
; #define PG8_LDB(dst, b, h) do { _Pragma("unroll") for (int n = 0; n < 2; ++n) _Pragma("unroll") for (int k = 0; k < 2; ++k) dst[n][k] = *(const PG8_LAS bf16x8*)(lds + PG8_SB(b, h) + boff + n * 2048 + k * 1024); } while (0)
; #define PG8_MMA(ai, bj, At, Bt) do { __builtin_amdgcn_s_setprio(1); _Pragma("unroll") for (int m = 0; m < 4; ++m) _Pragma("unroll") for (int n = 0; n < 2; ++n) _Pragma("unroll") for (int k = 0; k < 2; ++k) \
;         acc[ai][bj][m][n] = mma16<Epi::F16>(Bt[n][k], At[m][k], acc[ai][bj][m][n]); __builtin_amdgcn_s_setprio(0); } while (0)
; #define PG8_WAIT_V(n) asm volatile("s_waitcnt vmcnt(" #n ")" ::: "memory")
; #define PG8_WAIT_L(n) asm volatile("s_waitcnt lgkmcnt(" #n ")" ::: "memory")
; #define PG8_BAR __builtin_amdgcn_s_barrier()
; #define PG8_SCHED __builtin_amdgcn_sched_barrier(0)
; template <class Epi, class Sched, bool ALIGN_EPI = false, bool SP2 = false>
; __device__ __forceinline__ void gemm_phase(PG8_LAS unsigned char* lds, const Gemm g, const Sched& S, const Epi& E) {
;     ...
;             if constexpr (SP2) {
;             PG8_LDB(B0, 0, 0); PG8_LDB(B1, 0, 1); PG8_SCHED; PG8_LDA(At, 0, 0); PG8_STAGE(PG8_SA(1, 1), a1 + hstep, voffA);
;             PG8_WAIT_V(8); PG8_WAIT_L(0); PG8_BAR; PG8_MMA(0, 0, At, B0); PG8_MMA(0, 1, At, B1); PG8_BAR; PG8_SCHED;
;             PG8_LDA(At, 0, 1); PG8_STAGE(PG8_SB(0, 0), b2, voffB); PG8_STAGE(PG8_SB(0, 1), b2 + hstep, voffB); PG8_STAGE(PG8_SA(0, 0), a2, voffA);
;             PG8_WAIT_V(8); PG8_WAIT_L(0); PG8_BAR; PG8_MMA(1, 0, At, B0); PG8_MMA(1, 1, At, B1); PG8_BAR; PG8_SCHED;
	s_setprio 1
	s_waitcnt lgkmcnt(0)
	v_mfma_f32_16x16x32_bf16 v[124:127], v[128:131], v[160:163], v[124:127]
	v_mfma_f32_16x16x32_bf16 v[120:123], v[136:139], v[160:163], v[120:123]
	v_mfma_f32_16x16x32_bf16 v[108:111], v[128:131], v[168:171], v[108:111]
	v_mfma_f32_16x16x32_bf16 v[104:107], v[136:139], v[168:171], v[104:107]
	v_mfma_f32_16x16x32_bf16 v[92:95], v[128:131], v[176:179], v[92:95]
	v_mfma_f32_16x16x32_bf16 v[88:91], v[136:139], v[176:179], v[88:91]
	v_mfma_f32_16x16x32_bf16 v[76:79], v[128:131], v[184:187], v[76:79]
	v_mfma_f32_16x16x32_bf16 v[72:75], v[136:139], v[184:187], v[72:75]
	v_mfma_f32_16x16x32_bf16 v[124:127], v[132:135], v[164:167], v[124:127]
	v_mfma_f32_16x16x32_bf16 v[120:123], v[140:143], v[164:167], v[120:123]
	v_mfma_f32_16x16x32_bf16 v[108:111], v[132:135], v[172:175], v[108:111]
	v_mfma_f32_16x16x32_bf16 v[104:107], v[140:143], v[172:175], v[104:107]
	v_mfma_f32_16x16x32_bf16 v[92:95], v[132:135], v[180:183], v[92:95]
	v_mfma_f32_16x16x32_bf16 v[88:91], v[140:143], v[180:183], v[88:91]
	v_mfma_f32_16x16x32_bf16 v[76:79], v[132:135], v[188:191], v[76:79]
	v_mfma_f32_16x16x32_bf16 v[72:75], v[140:143], v[188:191], v[72:75]
	v_mfma_f32_16x16x32_bf16 v[116:119], v[144:147], v[160:163], v[116:119]
	v_mfma_f32_16x16x32_bf16 v[112:115], v[152:155], v[160:163], v[112:115]
	v_mfma_f32_16x16x32_bf16 v[100:103], v[144:147], v[168:171], v[100:103]
	v_mfma_f32_16x16x32_bf16 v[96:99], v[152:155], v[168:171], v[96:99]
	v_mfma_f32_16x16x32_bf16 v[84:87], v[144:147], v[176:179], v[84:87]
	v_mfma_f32_16x16x32_bf16 v[80:83], v[152:155], v[176:179], v[80:83]
	v_mfma_f32_16x16x32_bf16 v[68:71], v[144:147], v[184:187], v[68:71]
	v_mfma_f32_16x16x32_bf16 v[64:67], v[152:155], v[184:187], v[64:67]
	v_mfma_f32_16x16x32_bf16 v[116:119], v[148:151], v[164:167], v[116:119]
	v_mfma_f32_16x16x32_bf16 v[112:115], v[156:159], v[164:167], v[112:115]
	v_mfma_f32_16x16x32_bf16 v[100:103], v[148:151], v[172:175], v[100:103]
	v_mfma_f32_16x16x32_bf16 v[96:99], v[156:159], v[172:175], v[96:99]
	v_mfma_f32_16x16x32_bf16 v[84:87], v[148:151], v[180:183], v[84:87]
	v_mfma_f32_16x16x32_bf16 v[80:83], v[156:159], v[180:183], v[80:83]
	v_mfma_f32_16x16x32_bf16 v[68:71], v[148:151], v[188:191], v[68:71]
	v_mfma_f32_16x16x32_bf16 v[64:67], v[156:159], v[188:191], v[64:67]
	s_setprio 0
	s_barrier
	s_add_i32 vcc_lo, vcc_lo, s3
	v_lshl_add_u64 v[204:205], s[96:97], 0, v[208:209]
	s_mov_b32 m0, vcc_lo
	ds_read_b128 v[160:163], v230 offset:16384
	ds_read_b128 v[164:167], v230 offset:17408
	ds_read_b128 v[168:171], v230 offset:18432
	ds_read_b128 v[172:175], v230 offset:19456
	ds_read_b128 v[176:179], v230 offset:20480
	ds_read_b128 v[180:183], v230 offset:21504
	ds_read_b128 v[184:187], v230 offset:22528
	ds_read_b128 v[188:191], v230 offset:23552
	global_load_lds_dwordx4 v[204:205], off
	s_add_i32 m0, vcc_lo, 0x2000
	v_lshl_add_u64 v[206:207], s[96:97], 0, v[194:195]
	s_add_u32 s96, s96, s50
	s_addc_u32 s97, s97, s51
	s_add_i32 vcc_lo, vcc_hi, s3
	global_load_lds_dwordx4 v[206:207], off
	v_lshl_add_u64 v[212:213], s[96:97], 0, v[208:209]
	s_mov_b32 m0, vcc_lo
	v_lshl_add_u64 v[214:215], s[96:97], 0, v[194:195]
	global_load_lds_dwordx4 v[212:213], off
	s_add_i32 m0, vcc_lo, 0x2000
	v_lshl_add_u64 v[216:217], s[34:35], 0, v[208:209]
	global_load_lds_dwordx4 v[214:215], off
	s_mov_b32 m0, s8
	v_lshl_add_u64 v[218:219], s[34:35], 0, v[194:195]
	global_load_lds_dwordx4 v[216:217], off
	s_mov_b32 m0, s9
	s_nop 0
	global_load_lds_dwordx4 v[218:219], off
	s_waitcnt vmcnt(8)
	s_waitcnt lgkmcnt(0)
	s_barrier
	s_setprio 1
	s_waitcnt lgkmcnt(0)
	v_mfma_f32_16x16x32_bf16 v[60:63], v[128:131], v[160:163], v[60:63]
	v_mfma_f32_16x16x32_bf16 v[56:59], v[136:139], v[160:163], v[56:59]
	v_mfma_f32_16x16x32_bf16 v[44:47], v[128:131], v[168:171], v[44:47]
	v_mfma_f32_16x16x32_bf16 v[40:43], v[136:139], v[168:171], v[40:43]
	v_mfma_f32_16x16x32_bf16 v[28:31], v[128:131], v[176:179], v[28:31]
	v_mfma_f32_16x16x32_bf16 v[24:27], v[136:139], v[176:179], v[24:27]
	v_mfma_f32_16x16x32_bf16 v[12:15], v[128:131], v[184:187], v[12:15]
	v_mfma_f32_16x16x32_bf16 v[8:11], v[136:139], v[184:187], v[8:11]
	v_mfma_f32_16x16x32_bf16 v[60:63], v[132:135], v[164:167], v[60:63]
	v_mfma_f32_16x16x32_bf16 v[56:59], v[140:143], v[164:167], v[56:59]
	v_mfma_f32_16x16x32_bf16 v[44:47], v[132:135], v[172:175], v[44:47]
	v_mfma_f32_16x16x32_bf16 v[40:43], v[140:143], v[172:175], v[40:43]
	v_mfma_f32_16x16x32_bf16 v[28:31], v[132:135], v[180:183], v[28:31]
	v_mfma_f32_16x16x32_bf16 v[24:27], v[140:143], v[180:183], v[24:27]
	v_mfma_f32_16x16x32_bf16 v[12:15], v[132:135], v[188:191], v[12:15]
	v_mfma_f32_16x16x32_bf16 v[8:11], v[140:143], v[188:191], v[8:11]
	v_mfma_f32_16x16x32_bf16 v[52:55], v[144:147], v[160:163], v[52:55]
	v_mfma_f32_16x16x32_bf16 v[48:51], v[152:155], v[160:163], v[48:51]
	v_mfma_f32_16x16x32_bf16 v[36:39], v[144:147], v[168:171], v[36:39]
	v_mfma_f32_16x16x32_bf16 v[32:35], v[152:155], v[168:171], v[32:35]
	v_mfma_f32_16x16x32_bf16 v[20:23], v[144:147], v[176:179], v[20:23]
	v_mfma_f32_16x16x32_bf16 v[16:19], v[152:155], v[176:179], v[16:19]
	v_mfma_f32_16x16x32_bf16 v[4:7], v[144:147], v[184:187], v[4:7]
	v_mfma_f32_16x16x32_bf16 v[0:3], v[152:155], v[184:187], v[0:3]
	v_mfma_f32_16x16x32_bf16 v[52:55], v[148:151], v[164:167], v[52:55]
	v_mfma_f32_16x16x32_bf16 v[48:51], v[156:159], v[164:167], v[48:51]
	v_mfma_f32_16x16x32_bf16 v[36:39], v[148:151], v[172:175], v[36:39]
	v_mfma_f32_16x16x32_bf16 v[32:35], v[156:159], v[172:175], v[32:35]
	v_mfma_f32_16x16x32_bf16 v[20:23], v[148:151], v[180:183], v[20:23]
	v_mfma_f32_16x16x32_bf16 v[16:19], v[156:159], v[180:183], v[16:19]
	v_mfma_f32_16x16x32_bf16 v[4:7], v[148:151], v[188:191], v[4:7]
	v_mfma_f32_16x16x32_bf16 v[0:3], v[156:159], v[188:191], v[0:3]
	s_setprio 0
	s_barrier
; #define PG8_STAGE(bufoff, gbase, voff) do { _Pragma("unroll") for (int _i = 0; _i < 2; ++_i) \
;         __builtin_amdgcn_global_load_lds((const unsigned*)((const char*)(gbase) + (voff)[_i]), (PG8_LAS unsigned*)(lds + (bufoff) + ldsw + _i * 8192), 16, 0, 0); } while (0)
; #define PG8_LDA(dst, b, h) do { _Pragma("unroll") for (int m = 0; m < 4; ++m) _Pragma("unroll") for (int k = 0; k < 2; ++k) dst[m][k] = *(const PG8_LAS bf16x8*)(lds + PG8_SA(b, h) + aoff + m * 2048 + k * 1024); } while (0)
; #define PG8_LDB(dst, b, h) do { _Pragma("unroll") for (int n = 0; n < 2; ++n) _Pragma("unroll") for (int k = 0; k < 2; ++k) dst[n][k] = *(const PG8_LAS bf16x8*)(lds + PG8_SB(b, h) + boff + n * 2048 + k * 1024); } while (0)
; #define PG8_MMA(ai, bj, At, Bt) do { __builtin_amdgcn_s_setprio(1); _Pragma("unroll") for (int m = 0; m < 4; ++m) _Pragma("unroll") for (int n = 0; n < 2; ++n) _Pragma("unroll") for (int k = 0; k < 2; ++k) \
;         acc[ai][bj][m][n] = mma16<Epi::F16>(Bt[n][k], At[m][k], acc[ai][bj][m][n]); __builtin_amdgcn_s_setprio(0); } while (0)
; #define PG8_WAIT_V(n) asm volatile("s_waitcnt vmcnt(" #n ")" ::: "memory")
; #define PG8_WAIT_L(n) asm volatile("s_waitcnt lgkmcnt(" #n ")" ::: "memory")
; #define PG8_BAR __builtin_amdgcn_s_barrier()
; #define PG8_SCHED __builtin_amdgcn_sched_barrier(0)
; template <class Epi, class Sched, bool ALIGN_EPI = false, bool SP2 = false>
; __device__ __forceinline__ void gemm_phase(PG8_LAS unsigned char* lds, const Gemm g, const Sched& S, const Epi& E) {
;     ...
;             PG8_LDB(B0, 1, 0); PG8_LDB(B1, 1, 1); PG8_SCHED; PG8_LDA(At, 1, 0); PG8_STAGE(PG8_SA(0, 1), a2 + hstep, voffA);
;             PG8_WAIT_V(8); PG8_WAIT_L(0); PG8_BAR; PG8_MMA(0, 0, At, B0); PG8_MMA(0, 1, At, B1); PG8_BAR; PG8_SCHED;
;             PG8_LDA(At, 1, 1); PG8_STAGE(PG8_SB(1, 0), b3, voffB); PG8_STAGE(PG8_SB(1, 1), b3 + hstep, voffB); PG8_STAGE(PG8_SA(1, 0), a3, voffA);
;             PG8_WAIT_V(8); PG8_WAIT_L(0); PG8_BAR; PG8_MMA(1, 0, At, B0); PG8_MMA(1, 1, At, B1); PG8_BAR; PG8_SCHED;
	s_add_i32 s96, 0, 0x18000
	s_add_i32 s97, 0, 0x1c000
	v_add_u32_e32 v140, s96, v197
	v_add_u32_e32 v156, s97, v197
	ds_read_b128 v[128:131], v140
	ds_read_b128 v[132:135], v140 offset:1024
	ds_read_b128 v[136:139], v140 offset:2048
	ds_read_b128 v[140:143], v140 offset:3072
	ds_read_b128 v[144:147], v156
	ds_read_b128 v[148:151], v156 offset:1024
	ds_read_b128 v[152:155], v156 offset:2048
	ds_read_b128 v[156:159], v156 offset:3072
	s_add_u32 s34, s34, s50
	s_addc_u32 s35, s35, s51
	s_mov_b32 m0, s11
	v_lshl_add_u64 v[220:221], s[34:35], 0, v[208:209]
	ds_read_b128 v[160:163], v230 offset:32768
	ds_read_b128 v[164:167], v230 offset:33792
	ds_read_b128 v[168:171], v230 offset:34816
	ds_read_b128 v[172:175], v230 offset:35840
	ds_read_b128 v[176:179], v230 offset:36864
	ds_read_b128 v[180:183], v230 offset:37888
	ds_read_b128 v[184:187], v230 offset:38912
	ds_read_b128 v[188:191], v230 offset:39936
	global_load_lds_dwordx4 v[220:221], off
	v_lshl_add_u64 v[220:221], s[34:35], 0, v[194:195]
	s_mov_b32 m0, s36
	s_nop 0
	global_load_lds_dwordx4 v[220:221], off
	s_waitcnt vmcnt(8)
	s_waitcnt lgkmcnt(0)
	s_barrier
	s_setprio 1
	s_waitcnt lgkmcnt(0)
	v_mfma_f32_16x16x32_bf16 v[124:127], v[128:131], v[160:163], v[124:127]
	v_mfma_f32_16x16x32_bf16 v[120:123], v[136:139], v[160:163], v[120:123]
	v_mfma_f32_16x16x32_bf16 v[108:111], v[128:131], v[168:171], v[108:111]
	v_mfma_f32_16x16x32_bf16 v[104:107], v[136:139], v[168:171], v[104:107]
	v_mfma_f32_16x16x32_bf16 v[92:95], v[128:131], v[176:179], v[92:95]
	v_mfma_f32_16x16x32_bf16 v[88:91], v[136:139], v[176:179], v[88:91]
	v_mfma_f32_16x16x32_bf16 v[76:79], v[128:131], v[184:187], v[76:79]
	v_mfma_f32_16x16x32_bf16 v[72:75], v[136:139], v[184:187], v[72:75]
	v_mfma_f32_16x16x32_bf16 v[124:127], v[132:135], v[164:167], v[124:127]
	v_mfma_f32_16x16x32_bf16 v[120:123], v[140:143], v[164:167], v[120:123]
	v_mfma_f32_16x16x32_bf16 v[108:111], v[132:135], v[172:175], v[108:111]
	v_mfma_f32_16x16x32_bf16 v[104:107], v[140:143], v[172:175], v[104:107]
	v_mfma_f32_16x16x32_bf16 v[92:95], v[132:135], v[180:183], v[92:95]
	v_mfma_f32_16x16x32_bf16 v[88:91], v[140:143], v[180:183], v[88:91]
	v_mfma_f32_16x16x32_bf16 v[76:79], v[132:135], v[188:191], v[76:79]
	v_mfma_f32_16x16x32_bf16 v[72:75], v[140:143], v[188:191], v[72:75]
	v_mfma_f32_16x16x32_bf16 v[116:119], v[144:147], v[160:163], v[116:119]
	v_mfma_f32_16x16x32_bf16 v[112:115], v[152:155], v[160:163], v[112:115]
	v_mfma_f32_16x16x32_bf16 v[100:103], v[144:147], v[168:171], v[100:103]
	v_mfma_f32_16x16x32_bf16 v[96:99], v[152:155], v[168:171], v[96:99]
	v_mfma_f32_16x16x32_bf16 v[84:87], v[144:147], v[176:179], v[84:87]
	v_mfma_f32_16x16x32_bf16 v[80:83], v[152:155], v[176:179], v[80:83]
	v_mfma_f32_16x16x32_bf16 v[68:71], v[144:147], v[184:187], v[68:71]
	v_mfma_f32_16x16x32_bf16 v[64:67], v[152:155], v[184:187], v[64:67]
	v_mfma_f32_16x16x32_bf16 v[116:119], v[148:151], v[164:167], v[116:119]
	v_mfma_f32_16x16x32_bf16 v[112:115], v[156:159], v[164:167], v[112:115]
	v_mfma_f32_16x16x32_bf16 v[100:103], v[148:151], v[172:175], v[100:103]
	v_mfma_f32_16x16x32_bf16 v[96:99], v[156:159], v[172:175], v[96:99]
	v_mfma_f32_16x16x32_bf16 v[84:87], v[148:151], v[180:183], v[84:87]
	v_mfma_f32_16x16x32_bf16 v[80:83], v[156:159], v[180:183], v[80:83]
	v_mfma_f32_16x16x32_bf16 v[68:71], v[148:151], v[188:191], v[68:71]
	v_mfma_f32_16x16x32_bf16 v[64:67], v[156:159], v[188:191], v[64:67]
	s_setprio 0
	s_barrier
	s_add_i32 s34, s96, s3
	v_lshl_add_u64 v[204:205], v[204:205], 0, s[20:21]
	s_mov_b32 m0, s34
	ds_read_b128 v[160:163], v230 offset:49152
	ds_read_b128 v[164:167], v230 offset:50176
	ds_read_b128 v[168:171], v230 offset:51200
	ds_read_b128 v[172:175], v230 offset:52224
	ds_read_b128 v[176:179], v230 offset:53248
	ds_read_b128 v[180:183], v230 offset:54272
	ds_read_b128 v[184:187], v230 offset:55296
	ds_read_b128 v[188:191], v230 offset:56320
	global_load_lds_dwordx4 v[204:205], off
	v_lshl_add_u64 v[204:205], v[206:207], 0, s[20:21]
	s_add_i32 m0, s34, 0x2000
	s_add_i32 s34, s97, s3
	global_load_lds_dwordx4 v[204:205], off
	v_lshl_add_u64 v[204:205], v[212:213], 0, s[20:21]
	s_mov_b32 m0, s34
	s_nop 0
	global_load_lds_dwordx4 v[204:205], off
	v_lshl_add_u64 v[204:205], v[214:215], 0, s[20:21]
	s_add_i32 m0, s34, 0x2000
	s_nop 0
	global_load_lds_dwordx4 v[204:205], off
	v_lshl_add_u64 v[204:205], v[216:217], 0, s[20:21]
	s_mov_b32 m0, s48
	s_nop 0
	global_load_lds_dwordx4 v[204:205], off
	v_lshl_add_u64 v[204:205], v[218:219], 0, s[20:21]
	s_mov_b32 m0, s49
	s_nop 0
	global_load_lds_dwordx4 v[204:205], off
	s_waitcnt vmcnt(8)
	s_waitcnt lgkmcnt(0)
	s_barrier
	s_setprio 1
	s_waitcnt lgkmcnt(0)
	v_mfma_f32_16x16x32_bf16 v[60:63], v[128:131], v[160:163], v[60:63]
	v_mfma_f32_16x16x32_bf16 v[56:59], v[136:139], v[160:163], v[56:59]
	v_mfma_f32_16x16x32_bf16 v[44:47], v[128:131], v[168:171], v[44:47]
	v_mfma_f32_16x16x32_bf16 v[40:43], v[136:139], v[168:171], v[40:43]
	v_mfma_f32_16x16x32_bf16 v[28:31], v[128:131], v[176:179], v[28:31]
	v_mfma_f32_16x16x32_bf16 v[24:27], v[136:139], v[176:179], v[24:27]
	v_mfma_f32_16x16x32_bf16 v[12:15], v[128:131], v[184:187], v[12:15]
	v_mfma_f32_16x16x32_bf16 v[8:11], v[136:139], v[184:187], v[8:11]
	v_mfma_f32_16x16x32_bf16 v[60:63], v[132:135], v[164:167], v[60:63]
	v_mfma_f32_16x16x32_bf16 v[56:59], v[140:143], v[164:167], v[56:59]
	v_mfma_f32_16x16x32_bf16 v[44:47], v[132:135], v[172:175], v[44:47]
	v_mfma_f32_16x16x32_bf16 v[40:43], v[140:143], v[172:175], v[40:43]
	v_mfma_f32_16x16x32_bf16 v[28:31], v[132:135], v[180:183], v[28:31]
	v_mfma_f32_16x16x32_bf16 v[24:27], v[140:143], v[180:183], v[24:27]
	v_mfma_f32_16x16x32_bf16 v[12:15], v[132:135], v[188:191], v[12:15]
	v_mfma_f32_16x16x32_bf16 v[8:11], v[140:143], v[188:191], v[8:11]
	v_mfma_f32_16x16x32_bf16 v[52:55], v[144:147], v[160:163], v[52:55]
	v_mfma_f32_16x16x32_bf16 v[48:51], v[152:155], v[160:163], v[48:51]
	v_mfma_f32_16x16x32_bf16 v[36:39], v[144:147], v[168:171], v[36:39]
	v_mfma_f32_16x16x32_bf16 v[32:35], v[152:155], v[168:171], v[32:35]
	v_mfma_f32_16x16x32_bf16 v[20:23], v[144:147], v[176:179], v[20:23]
	v_mfma_f32_16x16x32_bf16 v[16:19], v[152:155], v[176:179], v[16:19]
	v_mfma_f32_16x16x32_bf16 v[4:7], v[144:147], v[184:187], v[4:7]
	v_mfma_f32_16x16x32_bf16 v[0:3], v[152:155], v[184:187], v[0:3]
	v_mfma_f32_16x16x32_bf16 v[52:55], v[148:151], v[164:167], v[52:55]
	v_mfma_f32_16x16x32_bf16 v[48:51], v[156:159], v[164:167], v[48:51]
	v_mfma_f32_16x16x32_bf16 v[36:39], v[148:151], v[172:175], v[36:39]
	v_mfma_f32_16x16x32_bf16 v[32:35], v[156:159], v[172:175], v[32:35]
	v_mfma_f32_16x16x32_bf16 v[20:23], v[148:151], v[180:183], v[20:23]
	v_mfma_f32_16x16x32_bf16 v[16:19], v[156:159], v[180:183], v[16:19]
	v_mfma_f32_16x16x32_bf16 v[4:7], v[148:151], v[188:191], v[4:7]
	v_mfma_f32_16x16x32_bf16 v[0:3], v[156:159], v[188:191], v[0:3]
	s_setprio 0
	s_barrier
	s_add_u32 s30, s30, 0x100
	s_addc_u32 s31, s31, 0
	s_add_u32 s29, s29, 0x100
	s_addc_u32 s85, s85, 0
	s_cmp_ge_i32 s92, s79
	s_mov_b32 s34, s92
	s_cbranch_scc0 .LBB0_369

; #define PG8_STAGE(bufoff, gbase, voff) do { _Pragma("unroll") for (int _i = 0; _i < 2; ++_i) \
;         __builtin_amdgcn_global_load_lds((const unsigned*)((const char*)(gbase) + (voff)[_i]), (PG8_LAS unsigned*)(lds + (bufoff) + ldsw + _i * 8192), 16, 0, 0); } while (0)
; #define PG8_LDA(dst, b, h) do { _Pragma("unroll") for (int m = 0; m < 4; ++m) _Pragma("unroll") for (int k = 0; k < 2; ++k) dst[m][k] = *(const PG8_LAS bf16x8*)(lds + PG8_SA(b, h) + aoff + m * 2048 + k * 1024); } while (0)
; #define PG8_LDB(dst, b, h) do { _Pragma("unroll") for (int n = 0; n < 2; ++n) _Pragma("unroll") for (int k = 0; k < 2; ++k) dst[n][k] = *(const PG8_LAS bf16x8*)(lds + PG8_SB(b, h) + boff + n * 2048 + k * 1024); } while (0)
; #define PG8_MMA(ai, bj, At, Bt) do { __builtin_amdgcn_s_setprio(1); _Pragma("unroll") for (int m = 0; m < 4; ++m) _Pragma("unroll") for (int n = 0; n < 2; ++n) _Pragma("unroll") for (int k = 0; k < 2; ++k) \
;         acc[ai][bj][m][n] = mma16<Epi::F16>(Bt[n][k], At[m][k], acc[ai][bj][m][n]); __builtin_amdgcn_s_setprio(0); } while (0)
; #define PG8_WAIT_V(n) asm volatile("s_waitcnt vmcnt(" #n ")" ::: "memory")
; #define PG8_WAIT_L(n) asm volatile("s_waitcnt lgkmcnt(" #n ")" ::: "memory")
; #define PG8_BAR __builtin_amdgcn_s_barrier()
; #define PG8_SCHED __builtin_amdgcn_sched_barrier(0)
; template <class Epi, class Sched, bool ALIGN_EPI = false, bool SP2 = false>
; __device__ __forceinline__ void gemm_phase(PG8_LAS unsigned char* lds, const Gemm g, const Sched& S, const Epi& E) {
;     ...
;     f32x4 acc[2][2][4][2];
; #pragma unroll
;     for (int a = 0; a < 2; ++a)
; #pragma unroll
;         for (int b = 0; b < 2; ++b)
; #pragma unroll
;             for (int m = 0; m < 4; ++m)
; #pragma unroll
;                 for (int n = 0; n < 2; ++n) acc[a][b][m][n] = (f32x4){0.f, 0.f, 0.f, 0.f};
;     ...
;             if constexpr (SP2) {
;             PG8_LDB(B0, 0, 0); PG8_LDB(B1, 0, 1); PG8_SCHED; PG8_LDA(At, 0, 0); PG8_STAGE(PG8_SA(1, 1), a1 + hstep, voffA);
;             PG8_WAIT_V(8); PG8_WAIT_L(0); PG8_BAR; PG8_MMA(0, 0, At, B0); PG8_MMA(0, 1, At, B1); PG8_BAR; PG8_SCHED;
;             PG8_LDA(At, 0, 1); PG8_STAGE(PG8_SB(0, 0), b2, voffB); PG8_STAGE(PG8_SB(0, 1), b2 + hstep, voffB); PG8_STAGE(PG8_SA(0, 0), a2, voffA);
;             PG8_WAIT_V(8); PG8_WAIT_L(0); PG8_BAR; PG8_MMA(1, 0, At, B0); PG8_MMA(1, 1, At, B1); PG8_BAR; PG8_SCHED;
.Lpeel_k4:
	s_add_u32 s30, s30, 0x80
	s_addc_u32 s31, s31, 0
	s_add_u32 s67, s34, 0x100
	s_addc_u32 s68, s35, 0
	s_mov_b32 s34, 0
	s_add_i32 s69, s34, 2
	s_add_u32 s70, s30, 0x80
	s_addc_u32 s35, s31, 0
	s_add_i32 s72, 0, 0x10000
	s_cmp_eq_u32 s61, s34
	s_cselect_b32 s35, s1, s35
	s_cselect_b32 s34, s0, s70
	v_add_u32_e32 v146, s72, v153
	s_cselect_b32 s71, s55, s68
	s_cselect_b32 s70, s54, s67
	s_add_i32 s73, 0, 0x14000
	ds_read_b128 v[142:145], v146
	ds_read_b128 v[158:161], v146 offset:1024
	ds_read_b128 v[162:165], v146 offset:2048
	ds_read_b128 v[166:169], v146 offset:3072
	v_add_u32_e32 v146, s73, v153
	ds_read_b128 v[170:173], v146
	ds_read_b128 v[174:177], v146 offset:1024
	ds_read_b128 v[178:181], v146 offset:2048
	ds_read_b128 v[182:185], v146 offset:3072
	v_lshl_add_u64 v[146:147], s[30:31], 0, v[138:139]
	s_add_i32 m0, s39, 0xc000
	ds_read_b128 v[186:189], v157
	ds_read_b128 v[190:193], v157 offset:1024
	ds_read_b128 v[194:197], v157 offset:2048
	ds_read_b128 v[198:201], v157 offset:3072
	ds_read_b128 v[202:205], v157 offset:4096
	ds_read_b128 v[212:215], v157 offset:5120
	ds_read_b128 v[216:219], v157 offset:6144
	ds_read_b128 v[220:223], v157 offset:7168
	global_load_lds_dwordx4 v[146:147], off
	v_lshl_add_u64 v[146:147], s[30:31], 0, v[140:141]
	s_add_i32 m0, s39, 0xe000
	s_nop 0
	global_load_lds_dwordx4 v[146:147], off
	s_waitcnt vmcnt(8)
	s_waitcnt lgkmcnt(0)
	s_barrier
	s_setprio 1
	s_waitcnt lgkmcnt(0)
	v_mfma_f32_16x16x32_bf16 v[124:127], v[142:145], v[186:189], 0
	v_mfma_f32_16x16x32_bf16 v[120:123], v[162:165], v[186:189], 0
	v_mfma_f32_16x16x32_bf16 v[108:111], v[142:145], v[194:197], 0
	v_mfma_f32_16x16x32_bf16 v[104:107], v[162:165], v[194:197], 0
	v_mfma_f32_16x16x32_bf16 v[92:95], v[142:145], v[202:205], 0
	v_mfma_f32_16x16x32_bf16 v[88:91], v[162:165], v[202:205], 0
	v_mfma_f32_16x16x32_bf16 v[76:79], v[142:145], v[216:219], 0
	v_mfma_f32_16x16x32_bf16 v[72:75], v[162:165], v[216:219], 0
	v_mfma_f32_16x16x32_bf16 v[124:127], v[158:161], v[190:193], v[124:127]
	v_mfma_f32_16x16x32_bf16 v[120:123], v[166:169], v[190:193], v[120:123]
	v_mfma_f32_16x16x32_bf16 v[108:111], v[158:161], v[198:201], v[108:111]
	v_mfma_f32_16x16x32_bf16 v[104:107], v[166:169], v[198:201], v[104:107]
	v_mfma_f32_16x16x32_bf16 v[92:95], v[158:161], v[212:215], v[92:95]
	v_mfma_f32_16x16x32_bf16 v[88:91], v[166:169], v[212:215], v[88:91]
	v_mfma_f32_16x16x32_bf16 v[76:79], v[158:161], v[220:223], v[76:79]
	v_mfma_f32_16x16x32_bf16 v[72:75], v[166:169], v[220:223], v[72:75]
	v_mfma_f32_16x16x32_bf16 v[116:119], v[170:173], v[186:189], 0
	v_mfma_f32_16x16x32_bf16 v[112:115], v[178:181], v[186:189], 0
	v_mfma_f32_16x16x32_bf16 v[100:103], v[170:173], v[194:197], 0
	v_mfma_f32_16x16x32_bf16 v[96:99], v[178:181], v[194:197], 0
	v_mfma_f32_16x16x32_bf16 v[84:87], v[170:173], v[202:205], 0
	v_mfma_f32_16x16x32_bf16 v[80:83], v[178:181], v[202:205], 0
	v_mfma_f32_16x16x32_bf16 v[68:71], v[170:173], v[216:219], 0
	v_mfma_f32_16x16x32_bf16 v[64:67], v[178:181], v[216:219], 0
	v_mfma_f32_16x16x32_bf16 v[116:119], v[174:177], v[190:193], v[116:119]
	v_mfma_f32_16x16x32_bf16 v[112:115], v[182:185], v[190:193], v[112:115]
	v_mfma_f32_16x16x32_bf16 v[100:103], v[174:177], v[198:201], v[100:103]
	v_mfma_f32_16x16x32_bf16 v[96:99], v[182:185], v[198:201], v[96:99]
	v_mfma_f32_16x16x32_bf16 v[84:87], v[174:177], v[212:215], v[84:87]
	v_mfma_f32_16x16x32_bf16 v[80:83], v[182:185], v[212:215], v[80:83]
	v_mfma_f32_16x16x32_bf16 v[68:71], v[174:177], v[220:223], v[68:71]
	v_mfma_f32_16x16x32_bf16 v[64:67], v[182:185], v[220:223], v[64:67]
	s_setprio 0
	s_barrier
	s_add_i32 s72, s72, s7
	v_lshl_add_u64 v[146:147], s[70:71], 0, v[132:133]
	s_mov_b32 m0, s72
	ds_read_b128 v[186:189], v157 offset:16384
	ds_read_b128 v[190:193], v157 offset:17408
	ds_read_b128 v[194:197], v157 offset:18432
	ds_read_b128 v[198:201], v157 offset:19456
	ds_read_b128 v[202:205], v157 offset:20480
	ds_read_b128 v[212:215], v157 offset:21504
	ds_read_b128 v[216:219], v157 offset:22528
	ds_read_b128 v[220:223], v157 offset:23552
	global_load_lds_dwordx4 v[146:147], off
	s_add_i32 m0, s72, 0x2000
	v_lshl_add_u64 v[150:151], s[70:71], 0, v[128:129]
	s_add_u32 s70, s70, s28
	s_addc_u32 s71, s71, s29
	s_add_i32 s72, s73, s7
	global_load_lds_dwordx4 v[150:151], off
	v_lshl_add_u64 v[154:155], s[70:71], 0, v[132:133]
	s_mov_b32 m0, s72
	v_lshl_add_u64 v[206:207], s[70:71], 0, v[128:129]
	global_load_lds_dwordx4 v[154:155], off
	s_add_i32 m0, s72, 0x2000
	v_lshl_add_u64 v[224:225], s[34:35], 0, v[134:135]
	global_load_lds_dwordx4 v[206:207], off
	s_mov_b32 m0, s39
	v_lshl_add_u64 v[226:227], s[34:35], 0, v[130:131]
	global_load_lds_dwordx4 v[224:225], off
	s_mov_b32 m0, s48
	s_nop 0
	global_load_lds_dwordx4 v[226:227], off
	s_waitcnt vmcnt(8)
	s_waitcnt lgkmcnt(0)
	s_barrier
; #define PG8_STAGE(bufoff, gbase, voff) do { _Pragma("unroll") for (int _i = 0; _i < 2; ++_i) \
;         __builtin_amdgcn_global_load_lds((const unsigned*)((const char*)(gbase) + (voff)[_i]), (PG8_LAS unsigned*)(lds + (bufoff) + ldsw + _i * 8192), 16, 0, 0); } while (0)
; #define PG8_LDA(dst, b, h) do { _Pragma("unroll") for (int m = 0; m < 4; ++m) _Pragma("unroll") for (int k = 0; k < 2; ++k) dst[m][k] = *(const PG8_LAS bf16x8*)(lds + PG8_SA(b, h) + aoff + m * 2048 + k * 1024); } while (0)
; #define PG8_LDB(dst, b, h) do { _Pragma("unroll") for (int n = 0; n < 2; ++n) _Pragma("unroll") for (int k = 0; k < 2; ++k) dst[n][k] = *(const PG8_LAS bf16x8*)(lds + PG8_SB(b, h) + boff + n * 2048 + k * 1024); } while (0)
; #define PG8_MMA(ai, bj, At, Bt) do { __builtin_amdgcn_s_setprio(1); _Pragma("unroll") for (int m = 0; m < 4; ++m) _Pragma("unroll") for (int n = 0; n < 2; ++n) _Pragma("unroll") for (int k = 0; k < 2; ++k) \
;         acc[ai][bj][m][n] = mma16<Epi::F16>(Bt[n][k], At[m][k], acc[ai][bj][m][n]); __builtin_amdgcn_s_setprio(0); } while (0)
; #define PG8_WAIT_V(n) asm volatile("s_waitcnt vmcnt(" #n ")" ::: "memory")
; #define PG8_WAIT_L(n) asm volatile("s_waitcnt lgkmcnt(" #n ")" ::: "memory")
; #define PG8_BAR __builtin_amdgcn_s_barrier()
; #define PG8_SCHED __builtin_amdgcn_sched_barrier(0)
; template <class Epi, class Sched, bool ALIGN_EPI = false, bool SP2 = false>
; __device__ __forceinline__ void gemm_phase(PG8_LAS unsigned char* lds, const Gemm g, const Sched& S, const Epi& E) {
;     ...
;             if constexpr (SP2) {
;             PG8_LDB(B0, 0, 0); PG8_LDB(B1, 0, 1); PG8_SCHED; PG8_LDA(At, 0, 0); PG8_STAGE(PG8_SA(1, 1), a1 + hstep, voffA);
;             PG8_WAIT_V(8); PG8_WAIT_L(0); PG8_BAR; PG8_MMA(0, 0, At, B0); PG8_MMA(0, 1, At, B1); PG8_BAR; PG8_SCHED;
;             PG8_LDA(At, 0, 1); PG8_STAGE(PG8_SB(0, 0), b2, voffB); PG8_STAGE(PG8_SB(0, 1), b2 + hstep, voffB); PG8_STAGE(PG8_SA(0, 0), a2, voffA);
;             PG8_WAIT_V(8); PG8_WAIT_L(0); PG8_BAR; PG8_MMA(1, 0, At, B0); PG8_MMA(1, 1, At, B1); PG8_BAR; PG8_SCHED;
;             PG8_LDB(B0, 1, 0); PG8_LDB(B1, 1, 1); PG8_SCHED; PG8_LDA(At, 1, 0); PG8_STAGE(PG8_SA(0, 1), a2 + hstep, voffA);
;             PG8_WAIT_V(8); PG8_WAIT_L(0); PG8_BAR; PG8_MMA(0, 0, At, B0); PG8_MMA(0, 1, At, B1); PG8_BAR; PG8_SCHED;
	s_setprio 1
	s_waitcnt lgkmcnt(0)
	v_mfma_f32_16x16x32_bf16 v[60:63], v[142:145], v[186:189], 0
	v_mfma_f32_16x16x32_bf16 v[56:59], v[162:165], v[186:189], 0
	v_mfma_f32_16x16x32_bf16 v[44:47], v[142:145], v[194:197], 0
	v_mfma_f32_16x16x32_bf16 v[40:43], v[162:165], v[194:197], 0
	v_mfma_f32_16x16x32_bf16 v[28:31], v[142:145], v[202:205], 0
	v_mfma_f32_16x16x32_bf16 v[24:27], v[162:165], v[202:205], 0
	v_mfma_f32_16x16x32_bf16 v[12:15], v[142:145], v[216:219], 0
	v_mfma_f32_16x16x32_bf16 v[8:11], v[162:165], v[216:219], 0
	v_mfma_f32_16x16x32_bf16 v[60:63], v[158:161], v[190:193], v[60:63]
	v_mfma_f32_16x16x32_bf16 v[56:59], v[166:169], v[190:193], v[56:59]
	v_mfma_f32_16x16x32_bf16 v[44:47], v[158:161], v[198:201], v[44:47]
	v_mfma_f32_16x16x32_bf16 v[40:43], v[166:169], v[198:201], v[40:43]
	v_mfma_f32_16x16x32_bf16 v[28:31], v[158:161], v[212:215], v[28:31]
	v_mfma_f32_16x16x32_bf16 v[24:27], v[166:169], v[212:215], v[24:27]
	v_mfma_f32_16x16x32_bf16 v[12:15], v[158:161], v[220:223], v[12:15]
	v_mfma_f32_16x16x32_bf16 v[8:11], v[166:169], v[220:223], v[8:11]
	v_mfma_f32_16x16x32_bf16 v[52:55], v[170:173], v[186:189], 0
	v_mfma_f32_16x16x32_bf16 v[48:51], v[178:181], v[186:189], 0
	v_mfma_f32_16x16x32_bf16 v[36:39], v[170:173], v[194:197], 0
	v_mfma_f32_16x16x32_bf16 v[32:35], v[178:181], v[194:197], 0
	v_mfma_f32_16x16x32_bf16 v[20:23], v[170:173], v[202:205], 0
	v_mfma_f32_16x16x32_bf16 v[16:19], v[178:181], v[202:205], 0
	v_mfma_f32_16x16x32_bf16 v[4:7], v[170:173], v[216:219], 0
	v_mfma_f32_16x16x32_bf16 v[0:3], v[178:181], v[216:219], 0
	v_mfma_f32_16x16x32_bf16 v[52:55], v[174:177], v[190:193], v[52:55]
	v_mfma_f32_16x16x32_bf16 v[48:51], v[182:185], v[190:193], v[48:51]
	v_mfma_f32_16x16x32_bf16 v[36:39], v[174:177], v[198:201], v[36:39]
	v_mfma_f32_16x16x32_bf16 v[32:35], v[182:185], v[198:201], v[32:35]
	v_mfma_f32_16x16x32_bf16 v[20:23], v[174:177], v[212:215], v[20:23]
	v_mfma_f32_16x16x32_bf16 v[16:19], v[182:185], v[212:215], v[16:19]
	v_mfma_f32_16x16x32_bf16 v[4:7], v[174:177], v[220:223], v[4:7]
	v_mfma_f32_16x16x32_bf16 v[0:3], v[182:185], v[220:223], v[0:3]
	s_setprio 0
	s_barrier
	s_add_i32 s70, 0, 0x18000
	v_add_u32_e32 v148, s70, v153
	s_add_i32 s71, 0, 0x1c000
	ds_read_b128 v[142:145], v148
	ds_read_b128 v[158:161], v148 offset:1024
	ds_read_b128 v[162:165], v148 offset:2048
	ds_read_b128 v[166:169], v148 offset:3072
	v_add_u32_e32 v148, s71, v153
	ds_read_b128 v[170:173], v148
	ds_read_b128 v[174:177], v148 offset:1024
	ds_read_b128 v[178:181], v148 offset:2048
	ds_read_b128 v[182:185], v148 offset:3072
	s_add_u32 s34, s34, s28
	s_addc_u32 s35, s35, s29
	s_mov_b32 m0, s56
	v_lshl_add_u64 v[228:229], s[34:35], 0, v[134:135]
	ds_read_b128 v[186:189], v157 offset:32768
	ds_read_b128 v[190:193], v157 offset:33792
	ds_read_b128 v[194:197], v157 offset:34816
	ds_read_b128 v[198:201], v157 offset:35840
	ds_read_b128 v[202:205], v157 offset:36864
	ds_read_b128 v[212:215], v157 offset:37888
	ds_read_b128 v[216:219], v157 offset:38912
	ds_read_b128 v[220:223], v157 offset:39936
	global_load_lds_dwordx4 v[228:229], off
	v_lshl_add_u64 v[228:229], s[34:35], 0, v[130:131]
	s_mov_b32 m0, s57
	s_nop 0
	global_load_lds_dwordx4 v[228:229], off
	s_waitcnt vmcnt(8)
	s_waitcnt lgkmcnt(0)
	s_barrier
	s_setprio 1
	s_waitcnt lgkmcnt(0)
	v_mfma_f32_16x16x32_bf16 v[124:127], v[142:145], v[186:189], v[124:127]
	v_mfma_f32_16x16x32_bf16 v[120:123], v[162:165], v[186:189], v[120:123]
	v_mfma_f32_16x16x32_bf16 v[108:111], v[142:145], v[194:197], v[108:111]
	v_mfma_f32_16x16x32_bf16 v[104:107], v[162:165], v[194:197], v[104:107]
	v_mfma_f32_16x16x32_bf16 v[92:95], v[142:145], v[202:205], v[92:95]
	v_mfma_f32_16x16x32_bf16 v[88:91], v[162:165], v[202:205], v[88:91]
	v_mfma_f32_16x16x32_bf16 v[76:79], v[142:145], v[216:219], v[76:79]
	v_mfma_f32_16x16x32_bf16 v[72:75], v[162:165], v[216:219], v[72:75]
	v_mfma_f32_16x16x32_bf16 v[124:127], v[158:161], v[190:193], v[124:127]
	v_mfma_f32_16x16x32_bf16 v[120:123], v[166:169], v[190:193], v[120:123]
	v_mfma_f32_16x16x32_bf16 v[108:111], v[158:161], v[198:201], v[108:111]
	v_mfma_f32_16x16x32_bf16 v[104:107], v[166:169], v[198:201], v[104:107]
	v_mfma_f32_16x16x32_bf16 v[92:95], v[158:161], v[212:215], v[92:95]
	v_mfma_f32_16x16x32_bf16 v[88:91], v[166:169], v[212:215], v[88:91]
	v_mfma_f32_16x16x32_bf16 v[76:79], v[158:161], v[220:223], v[76:79]
	v_mfma_f32_16x16x32_bf16 v[72:75], v[166:169], v[220:223], v[72:75]
	v_mfma_f32_16x16x32_bf16 v[116:119], v[170:173], v[186:189], v[116:119]
	v_mfma_f32_16x16x32_bf16 v[112:115], v[178:181], v[186:189], v[112:115]
	v_mfma_f32_16x16x32_bf16 v[100:103], v[170:173], v[194:197], v[100:103]
	v_mfma_f32_16x16x32_bf16 v[96:99], v[178:181], v[194:197], v[96:99]
	v_mfma_f32_16x16x32_bf16 v[84:87], v[170:173], v[202:205], v[84:87]
	v_mfma_f32_16x16x32_bf16 v[80:83], v[178:181], v[202:205], v[80:83]
	v_mfma_f32_16x16x32_bf16 v[68:71], v[170:173], v[216:219], v[68:71]
	v_mfma_f32_16x16x32_bf16 v[64:67], v[178:181], v[216:219], v[64:67]
	v_mfma_f32_16x16x32_bf16 v[116:119], v[174:177], v[190:193], v[116:119]
	v_mfma_f32_16x16x32_bf16 v[112:115], v[182:185], v[190:193], v[112:115]
	v_mfma_f32_16x16x32_bf16 v[100:103], v[174:177], v[198:201], v[100:103]
	v_mfma_f32_16x16x32_bf16 v[96:99], v[182:185], v[198:201], v[96:99]
	v_mfma_f32_16x16x32_bf16 v[84:87], v[174:177], v[212:215], v[84:87]
	v_mfma_f32_16x16x32_bf16 v[80:83], v[182:185], v[212:215], v[80:83]
	v_mfma_f32_16x16x32_bf16 v[68:71], v[174:177], v[220:223], v[68:71]
	v_mfma_f32_16x16x32_bf16 v[64:67], v[182:185], v[220:223], v[64:67]
	s_setprio 0
	s_barrier
; #define PG8_STAGE(bufoff, gbase, voff) do { _Pragma("unroll") for (int _i = 0; _i < 2; ++_i) \
;         __builtin_amdgcn_global_load_lds((const unsigned*)((const char*)(gbase) + (voff)[_i]), (PG8_LAS unsigned*)(lds + (bufoff) + ldsw + _i * 8192), 16, 0, 0); } while (0)
; #define PG8_LDA(dst, b, h) do { _Pragma("unroll") for (int m = 0; m < 4; ++m) _Pragma("unroll") for (int k = 0; k < 2; ++k) dst[m][k] = *(const PG8_LAS bf16x8*)(lds + PG8_SA(b, h) + aoff + m * 2048 + k * 1024); } while (0)
; template <class Epi, class Sched, bool ALIGN_EPI = false, bool SP2 = false>
; __device__ __forceinline__ void gemm_phase(PG8_LAS unsigned char* lds, const Gemm g, const Sched& S, const Epi& E) {
;     ...
;         const bool has_next = S.next(ui + 1, nxt);
;         const char* nA = has_next ? (const char*)g.A + (size_t)nxt.pm * tstep : cA; const char* nB = has_next ? (const char*)g.Bt + (size_t)nxt.pn * tstep : cB;
;         for (int t = 0; t < nt; t += 2) {
;             const bool last = (t == nt - 2);
;             const char* a1 = cA + (size_t)(t + 1) * kstep;
;             const char* a2 = last ? nA : cA + (size_t)(t + 2) * kstep; const char* b2 = last ? nB : cB + (size_t)(t + 2) * kstep;
;             const char* a3 = a2 + kstep; const char* b3 = b2 + kstep;
;             if (last && has_next) S.a_ready(nxt);
;             if constexpr (SP2) {
;             PG8_LDB(B0, 0, 0); PG8_LDB(B1, 0, 1); PG8_SCHED; PG8_LDA(At, 0, 0); PG8_STAGE(PG8_SA(1, 1), a1 + hstep, voffA);
;             PG8_WAIT_V(8); PG8_WAIT_L(0); PG8_BAR; PG8_MMA(0, 0, At, B0); PG8_MMA(0, 1, At, B1); PG8_BAR; PG8_SCHED;
;             PG8_LDA(At, 0, 1); PG8_STAGE(PG8_SB(0, 0), b2, voffB); PG8_STAGE(PG8_SB(0, 1), b2 + hstep, voffB); PG8_STAGE(PG8_SA(0, 0), a2, voffA);
;             PG8_WAIT_V(8); PG8_WAIT_L(0); PG8_BAR; PG8_MMA(1, 0, At, B0); PG8_MMA(1, 1, At, B1); PG8_BAR; PG8_SCHED;
;             PG8_LDB(B0, 1, 0); PG8_LDB(B1, 1, 1); PG8_SCHED; PG8_LDA(At, 1, 0); PG8_STAGE(PG8_SA(0, 1), a2 + hstep, voffA);
;             PG8_WAIT_V(8); PG8_WAIT_L(0); PG8_BAR; PG8_MMA(0, 0, At, B0); PG8_MMA(0, 1, At, B1); PG8_BAR; PG8_SCHED;
;             PG8_LDA(At, 1, 1); PG8_STAGE(PG8_SB(1, 0), b3, voffB); PG8_STAGE(PG8_SB(1, 1), b3 + hstep, voffB); PG8_STAGE(PG8_SA(1, 0), a3, voffA);
;             PG8_WAIT_V(8); PG8_WAIT_L(0); PG8_BAR; PG8_MMA(1, 0, At, B0); PG8_MMA(1, 1, At, B1); PG8_BAR; PG8_SCHED;
	s_add_i32 s34, s70, s7
	v_lshl_add_u64 v[146:147], v[146:147], 0, s[20:21]
	s_mov_b32 m0, s34
	ds_read_b128 v[186:189], v157 offset:49152
	ds_read_b128 v[190:193], v157 offset:50176
	ds_read_b128 v[194:197], v157 offset:51200
	ds_read_b128 v[198:201], v157 offset:52224
	ds_read_b128 v[202:205], v157 offset:53248
	ds_read_b128 v[212:215], v157 offset:54272
	ds_read_b128 v[216:219], v157 offset:55296
	ds_read_b128 v[220:223], v157 offset:56320
	global_load_lds_dwordx4 v[146:147], off
	v_lshl_add_u64 v[146:147], v[150:151], 0, s[20:21]
	s_add_i32 m0, s34, 0x2000
	s_add_i32 s34, s71, s7
	global_load_lds_dwordx4 v[146:147], off
	v_lshl_add_u64 v[146:147], v[154:155], 0, s[20:21]
	s_mov_b32 m0, s34
	s_nop 0
	global_load_lds_dwordx4 v[146:147], off
	v_lshl_add_u64 v[146:147], v[206:207], 0, s[20:21]
	s_add_i32 m0, s34, 0x2000
	s_nop 0
	global_load_lds_dwordx4 v[146:147], off
	v_lshl_add_u64 v[146:147], v[224:225], 0, s[20:21]
	s_mov_b32 m0, s58
	s_nop 0
	global_load_lds_dwordx4 v[146:147], off
	v_lshl_add_u64 v[146:147], v[226:227], 0, s[20:21]
	s_mov_b32 m0, s59
	s_nop 0
	global_load_lds_dwordx4 v[146:147], off
	s_waitcnt vmcnt(8)
	s_waitcnt lgkmcnt(0)
	s_barrier
	s_setprio 1
	s_waitcnt lgkmcnt(0)
	v_mfma_f32_16x16x32_bf16 v[60:63], v[142:145], v[186:189], v[60:63]
	v_mfma_f32_16x16x32_bf16 v[56:59], v[162:165], v[186:189], v[56:59]
	v_mfma_f32_16x16x32_bf16 v[44:47], v[142:145], v[194:197], v[44:47]
	v_mfma_f32_16x16x32_bf16 v[40:43], v[162:165], v[194:197], v[40:43]
	v_mfma_f32_16x16x32_bf16 v[28:31], v[142:145], v[202:205], v[28:31]
	v_mfma_f32_16x16x32_bf16 v[24:27], v[162:165], v[202:205], v[24:27]
	v_mfma_f32_16x16x32_bf16 v[12:15], v[142:145], v[216:219], v[12:15]
	v_mfma_f32_16x16x32_bf16 v[8:11], v[162:165], v[216:219], v[8:11]
	v_mfma_f32_16x16x32_bf16 v[60:63], v[158:161], v[190:193], v[60:63]
	v_mfma_f32_16x16x32_bf16 v[56:59], v[166:169], v[190:193], v[56:59]
	v_mfma_f32_16x16x32_bf16 v[44:47], v[158:161], v[198:201], v[44:47]
	v_mfma_f32_16x16x32_bf16 v[40:43], v[166:169], v[198:201], v[40:43]
	v_mfma_f32_16x16x32_bf16 v[28:31], v[158:161], v[212:215], v[28:31]
	v_mfma_f32_16x16x32_bf16 v[24:27], v[166:169], v[212:215], v[24:27]
	v_mfma_f32_16x16x32_bf16 v[12:15], v[158:161], v[220:223], v[12:15]
	v_mfma_f32_16x16x32_bf16 v[8:11], v[166:169], v[220:223], v[8:11]
	v_mfma_f32_16x16x32_bf16 v[52:55], v[170:173], v[186:189], v[52:55]
	v_mfma_f32_16x16x32_bf16 v[48:51], v[178:181], v[186:189], v[48:51]
	v_mfma_f32_16x16x32_bf16 v[36:39], v[170:173], v[194:197], v[36:39]
	v_mfma_f32_16x16x32_bf16 v[32:35], v[178:181], v[194:197], v[32:35]
	v_mfma_f32_16x16x32_bf16 v[20:23], v[170:173], v[202:205], v[20:23]
	v_mfma_f32_16x16x32_bf16 v[16:19], v[178:181], v[202:205], v[16:19]
	v_mfma_f32_16x16x32_bf16 v[4:7], v[170:173], v[216:219], v[4:7]
	v_mfma_f32_16x16x32_bf16 v[0:3], v[178:181], v[216:219], v[0:3]
	v_mfma_f32_16x16x32_bf16 v[52:55], v[174:177], v[190:193], v[52:55]
	v_mfma_f32_16x16x32_bf16 v[48:51], v[182:185], v[190:193], v[48:51]
	v_mfma_f32_16x16x32_bf16 v[36:39], v[174:177], v[198:201], v[36:39]
	v_mfma_f32_16x16x32_bf16 v[32:35], v[182:185], v[198:201], v[32:35]
	v_mfma_f32_16x16x32_bf16 v[20:23], v[174:177], v[212:215], v[20:23]
	v_mfma_f32_16x16x32_bf16 v[16:19], v[182:185], v[212:215], v[16:19]
	v_mfma_f32_16x16x32_bf16 v[4:7], v[174:177], v[220:223], v[4:7]
	v_mfma_f32_16x16x32_bf16 v[0:3], v[182:185], v[220:223], v[0:3]
	s_setprio 0
	s_barrier
	s_add_u32 s30, s30, 0x100
	s_addc_u32 s31, s31, 0
	s_add_u32 s67, s67, 0x100
	s_addc_u32 s68, s68, 0
	s_cmp_ge_i32 s69, s60
	s_mov_b32 s34, s69
	s_cbranch_scc0 .LBB0_511
	s_branch .LBB0_512
.LBB0_511:
	s_add_i32 s69, s34, 2
	s_add_u32 s70, s30, 0x80
	s_addc_u32 s35, s31, 0
	s_add_i32 s72, 0, 0x10000
	s_cmp_eq_u32 s61, s34
	s_cselect_b32 s35, s1, s35
	s_cselect_b32 s34, s0, s70
	v_add_u32_e32 v146, s72, v153
	s_cselect_b32 s71, s55, s68
	s_cselect_b32 s70, s54, s67
	s_add_i32 s73, 0, 0x14000
	ds_read_b128 v[142:145], v146
	ds_read_b128 v[158:161], v146 offset:1024
	ds_read_b128 v[162:165], v146 offset:2048
	ds_read_b128 v[166:169], v146 offset:3072
	v_add_u32_e32 v146, s73, v153
	ds_read_b128 v[170:173], v146
	ds_read_b128 v[174:177], v146 offset:1024
	ds_read_b128 v[178:181], v146 offset:2048
	ds_read_b128 v[182:185], v146 offset:3072
	v_lshl_add_u64 v[146:147], s[30:31], 0, v[138:139]
	s_add_i32 m0, s39, 0xc000
	ds_read_b128 v[186:189], v157
	ds_read_b128 v[190:193], v157 offset:1024
	ds_read_b128 v[194:197], v157 offset:2048
	ds_read_b128 v[198:201], v157 offset:3072
	ds_read_b128 v[202:205], v157 offset:4096
	ds_read_b128 v[212:215], v157 offset:5120
	ds_read_b128 v[216:219], v157 offset:6144
	ds_read_b128 v[220:223], v157 offset:7168
	global_load_lds_dwordx4 v[146:147], off
	v_lshl_add_u64 v[146:147], s[30:31], 0, v[140:141]
	s_add_i32 m0, s39, 0xe000
	s_nop 0
	global_load_lds_dwordx4 v[146:147], off
	s_waitcnt vmcnt(8)
	s_waitcnt lgkmcnt(0)
	s_barrier
; #define PG8_STAGE(bufoff, gbase, voff) do { _Pragma("unroll") for (int _i = 0; _i < 2; ++_i) \
;         __builtin_amdgcn_global_load_lds((const unsigned*)((const char*)(gbase) + (voff)[_i]), (PG8_LAS unsigned*)(lds + (bufoff) + ldsw + _i * 8192), 16, 0, 0); } while (0)
; #define PG8_LDA(dst, b, h) do { _Pragma("unroll") for (int m = 0; m < 4; ++m) _Pragma("unroll") for (int k = 0; k < 2; ++k) dst[m][k] = *(const PG8_LAS bf16x8*)(lds + PG8_SA(b, h) + aoff + m * 2048 + k * 1024); } while (0)
; #define PG8_LDB(dst, b, h) do { _Pragma("unroll") for (int n = 0; n < 2; ++n) _Pragma("unroll") for (int k = 0; k < 2; ++k) dst[n][k] = *(const PG8_LAS bf16x8*)(lds + PG8_SB(b, h) + boff + n * 2048 + k * 1024); } while (0)
; #define PG8_MMA(ai, bj, At, Bt) do { __builtin_amdgcn_s_setprio(1); _Pragma("unroll") for (int m = 0; m < 4; ++m) _Pragma("unroll") for (int n = 0; n < 2; ++n) _Pragma("unroll") for (int k = 0; k < 2; ++k) \
;         acc[ai][bj][m][n] = mma16<Epi::F16>(Bt[n][k], At[m][k], acc[ai][bj][m][n]); __builtin_amdgcn_s_setprio(0); } while (0)
; #define PG8_WAIT_V(n) asm volatile("s_waitcnt vmcnt(" #n ")" ::: "memory")
; #define PG8_WAIT_L(n) asm volatile("s_waitcnt lgkmcnt(" #n ")" ::: "memory")
; #define PG8_BAR __builtin_amdgcn_s_barrier()
; #define PG8_SCHED __builtin_amdgcn_sched_barrier(0)
; template <class Epi, class Sched, bool ALIGN_EPI = false, bool SP2 = false>
; __device__ __forceinline__ void gemm_phase(PG8_LAS unsigned char* lds, const Gemm g, const Sched& S, const Epi& E) {
;     ...
;             if constexpr (SP2) {
;             PG8_LDB(B0, 0, 0); PG8_LDB(B1, 0, 1); PG8_SCHED; PG8_LDA(At, 0, 0); PG8_STAGE(PG8_SA(1, 1), a1 + hstep, voffA);
;             PG8_WAIT_V(8); PG8_WAIT_L(0); PG8_BAR; PG8_MMA(0, 0, At, B0); PG8_MMA(0, 1, At, B1); PG8_BAR; PG8_SCHED;
;             PG8_LDA(At, 0, 1); PG8_STAGE(PG8_SB(0, 0), b2, voffB); PG8_STAGE(PG8_SB(0, 1), b2 + hstep, voffB); PG8_STAGE(PG8_SA(0, 0), a2, voffA);
;             PG8_WAIT_V(8); PG8_WAIT_L(0); PG8_BAR; PG8_MMA(1, 0, At, B0); PG8_MMA(1, 1, At, B1); PG8_BAR; PG8_SCHED;
	s_setprio 1
	s_waitcnt lgkmcnt(0)
	v_mfma_f32_16x16x32_bf16 v[124:127], v[142:145], v[186:189], v[124:127]
	v_mfma_f32_16x16x32_bf16 v[120:123], v[162:165], v[186:189], v[120:123]
	v_mfma_f32_16x16x32_bf16 v[108:111], v[142:145], v[194:197], v[108:111]
	v_mfma_f32_16x16x32_bf16 v[104:107], v[162:165], v[194:197], v[104:107]
	v_mfma_f32_16x16x32_bf16 v[92:95], v[142:145], v[202:205], v[92:95]
	v_mfma_f32_16x16x32_bf16 v[88:91], v[162:165], v[202:205], v[88:91]
	v_mfma_f32_16x16x32_bf16 v[76:79], v[142:145], v[216:219], v[76:79]
	v_mfma_f32_16x16x32_bf16 v[72:75], v[162:165], v[216:219], v[72:75]
	v_mfma_f32_16x16x32_bf16 v[124:127], v[158:161], v[190:193], v[124:127]
	v_mfma_f32_16x16x32_bf16 v[120:123], v[166:169], v[190:193], v[120:123]
	v_mfma_f32_16x16x32_bf16 v[108:111], v[158:161], v[198:201], v[108:111]
	v_mfma_f32_16x16x32_bf16 v[104:107], v[166:169], v[198:201], v[104:107]
	v_mfma_f32_16x16x32_bf16 v[92:95], v[158:161], v[212:215], v[92:95]
	v_mfma_f32_16x16x32_bf16 v[88:91], v[166:169], v[212:215], v[88:91]
	v_mfma_f32_16x16x32_bf16 v[76:79], v[158:161], v[220:223], v[76:79]
	v_mfma_f32_16x16x32_bf16 v[72:75], v[166:169], v[220:223], v[72:75]
	v_mfma_f32_16x16x32_bf16 v[116:119], v[170:173], v[186:189], v[116:119]
	v_mfma_f32_16x16x32_bf16 v[112:115], v[178:181], v[186:189], v[112:115]
	v_mfma_f32_16x16x32_bf16 v[100:103], v[170:173], v[194:197], v[100:103]
	v_mfma_f32_16x16x32_bf16 v[96:99], v[178:181], v[194:197], v[96:99]
	v_mfma_f32_16x16x32_bf16 v[84:87], v[170:173], v[202:205], v[84:87]
	v_mfma_f32_16x16x32_bf16 v[80:83], v[178:181], v[202:205], v[80:83]
	v_mfma_f32_16x16x32_bf16 v[68:71], v[170:173], v[216:219], v[68:71]
	v_mfma_f32_16x16x32_bf16 v[64:67], v[178:181], v[216:219], v[64:67]
	v_mfma_f32_16x16x32_bf16 v[116:119], v[174:177], v[190:193], v[116:119]
	v_mfma_f32_16x16x32_bf16 v[112:115], v[182:185], v[190:193], v[112:115]
	v_mfma_f32_16x16x32_bf16 v[100:103], v[174:177], v[198:201], v[100:103]
	v_mfma_f32_16x16x32_bf16 v[96:99], v[182:185], v[198:201], v[96:99]
	v_mfma_f32_16x16x32_bf16 v[84:87], v[174:177], v[212:215], v[84:87]
	v_mfma_f32_16x16x32_bf16 v[80:83], v[182:185], v[212:215], v[80:83]
	v_mfma_f32_16x16x32_bf16 v[68:71], v[174:177], v[220:223], v[68:71]
	v_mfma_f32_16x16x32_bf16 v[64:67], v[182:185], v[220:223], v[64:67]
	s_setprio 0
	s_barrier
	s_add_i32 s72, s72, s7
	v_lshl_add_u64 v[146:147], s[70:71], 0, v[132:133]
	s_mov_b32 m0, s72
	ds_read_b128 v[186:189], v157 offset:16384
	ds_read_b128 v[190:193], v157 offset:17408
	ds_read_b128 v[194:197], v157 offset:18432
	ds_read_b128 v[198:201], v157 offset:19456
	ds_read_b128 v[202:205], v157 offset:20480
	ds_read_b128 v[212:215], v157 offset:21504
	ds_read_b128 v[216:219], v157 offset:22528
	ds_read_b128 v[220:223], v157 offset:23552
	global_load_lds_dwordx4 v[146:147], off
	s_add_i32 m0, s72, 0x2000
	v_lshl_add_u64 v[150:151], s[70:71], 0, v[128:129]
	s_add_u32 s70, s70, s28
	s_addc_u32 s71, s71, s29
	s_add_i32 s72, s73, s7
	global_load_lds_dwordx4 v[150:151], off
	v_lshl_add_u64 v[154:155], s[70:71], 0, v[132:133]
	s_mov_b32 m0, s72
	v_lshl_add_u64 v[206:207], s[70:71], 0, v[128:129]
	global_load_lds_dwordx4 v[154:155], off
	s_add_i32 m0, s72, 0x2000
	v_lshl_add_u64 v[224:225], s[34:35], 0, v[134:135]
	global_load_lds_dwordx4 v[206:207], off
	s_mov_b32 m0, s39
	v_lshl_add_u64 v[226:227], s[34:35], 0, v[130:131]
	global_load_lds_dwordx4 v[224:225], off
	s_mov_b32 m0, s48
	s_nop 0
	global_load_lds_dwordx4 v[226:227], off
	s_waitcnt vmcnt(8)
	s_waitcnt lgkmcnt(0)
	s_barrier
	s_setprio 1
	s_waitcnt lgkmcnt(0)
	v_mfma_f32_16x16x32_bf16 v[60:63], v[142:145], v[186:189], v[60:63]
	v_mfma_f32_16x16x32_bf16 v[56:59], v[162:165], v[186:189], v[56:59]
	v_mfma_f32_16x16x32_bf16 v[44:47], v[142:145], v[194:197], v[44:47]
	v_mfma_f32_16x16x32_bf16 v[40:43], v[162:165], v[194:197], v[40:43]
	v_mfma_f32_16x16x32_bf16 v[28:31], v[142:145], v[202:205], v[28:31]
	v_mfma_f32_16x16x32_bf16 v[24:27], v[162:165], v[202:205], v[24:27]
	v_mfma_f32_16x16x32_bf16 v[12:15], v[142:145], v[216:219], v[12:15]
	v_mfma_f32_16x16x32_bf16 v[8:11], v[162:165], v[216:219], v[8:11]
	v_mfma_f32_16x16x32_bf16 v[60:63], v[158:161], v[190:193], v[60:63]
	v_mfma_f32_16x16x32_bf16 v[56:59], v[166:169], v[190:193], v[56:59]
	v_mfma_f32_16x16x32_bf16 v[44:47], v[158:161], v[198:201], v[44:47]
	v_mfma_f32_16x16x32_bf16 v[40:43], v[166:169], v[198:201], v[40:43]
	v_mfma_f32_16x16x32_bf16 v[28:31], v[158:161], v[212:215], v[28:31]
	v_mfma_f32_16x16x32_bf16 v[24:27], v[166:169], v[212:215], v[24:27]
	v_mfma_f32_16x16x32_bf16 v[12:15], v[158:161], v[220:223], v[12:15]
	v_mfma_f32_16x16x32_bf16 v[8:11], v[166:169], v[220:223], v[8:11]
	v_mfma_f32_16x16x32_bf16 v[52:55], v[170:173], v[186:189], v[52:55]
	v_mfma_f32_16x16x32_bf16 v[48:51], v[178:181], v[186:189], v[48:51]
	v_mfma_f32_16x16x32_bf16 v[36:39], v[170:173], v[194:197], v[36:39]
	v_mfma_f32_16x16x32_bf16 v[32:35], v[178:181], v[194:197], v[32:35]
	v_mfma_f32_16x16x32_bf16 v[20:23], v[170:173], v[202:205], v[20:23]
	v_mfma_f32_16x16x32_bf16 v[16:19], v[178:181], v[202:205], v[16:19]
	v_mfma_f32_16x16x32_bf16 v[4:7], v[170:173], v[216:219], v[4:7]
	v_mfma_f32_16x16x32_bf16 v[0:3], v[178:181], v[216:219], v[0:3]
	v_mfma_f32_16x16x32_bf16 v[52:55], v[174:177], v[190:193], v[52:55]
	v_mfma_f32_16x16x32_bf16 v[48:51], v[182:185], v[190:193], v[48:51]
	v_mfma_f32_16x16x32_bf16 v[36:39], v[174:177], v[198:201], v[36:39]
	v_mfma_f32_16x16x32_bf16 v[32:35], v[182:185], v[198:201], v[32:35]
	v_mfma_f32_16x16x32_bf16 v[20:23], v[174:177], v[212:215], v[20:23]
	v_mfma_f32_16x16x32_bf16 v[16:19], v[182:185], v[212:215], v[16:19]
	v_mfma_f32_16x16x32_bf16 v[4:7], v[174:177], v[220:223], v[4:7]
	v_mfma_f32_16x16x32_bf16 v[0:3], v[182:185], v[220:223], v[0:3]
	s_setprio 0
	s_barrier
; #define PG8_STAGE(bufoff, gbase, voff) do { _Pragma("unroll") for (int _i = 0; _i < 2; ++_i) \
;         __builtin_amdgcn_global_load_lds((const unsigned*)((const char*)(gbase) + (voff)[_i]), (PG8_LAS unsigned*)(lds + (bufoff) + ldsw + _i * 8192), 16, 0, 0); } while (0)
; #define PG8_LDA(dst, b, h) do { _Pragma("unroll") for (int m = 0; m < 4; ++m) _Pragma("unroll") for (int k = 0; k < 2; ++k) dst[m][k] = *(const PG8_LAS bf16x8*)(lds + PG8_SA(b, h) + aoff + m * 2048 + k * 1024); } while (0)
; #define PG8_LDB(dst, b, h) do { _Pragma("unroll") for (int n = 0; n < 2; ++n) _Pragma("unroll") for (int k = 0; k < 2; ++k) dst[n][k] = *(const PG8_LAS bf16x8*)(lds + PG8_SB(b, h) + boff + n * 2048 + k * 1024); } while (0)
; #define PG8_MMA(ai, bj, At, Bt) do { __builtin_amdgcn_s_setprio(1); _Pragma("unroll") for (int m = 0; m < 4; ++m) _Pragma("unroll") for (int n = 0; n < 2; ++n) _Pragma("unroll") for (int k = 0; k < 2; ++k) \
;         acc[ai][bj][m][n] = mma16<Epi::F16>(Bt[n][k], At[m][k], acc[ai][bj][m][n]); __builtin_amdgcn_s_setprio(0); } while (0)
; #define PG8_WAIT_V(n) asm volatile("s_waitcnt vmcnt(" #n ")" ::: "memory")
; #define PG8_WAIT_L(n) asm volatile("s_waitcnt lgkmcnt(" #n ")" ::: "memory")
; #define PG8_BAR __builtin_amdgcn_s_barrier()
; #define PG8_SCHED __builtin_amdgcn_sched_barrier(0)
; template <class Epi, class Sched, bool ALIGN_EPI = false, bool SP2 = false>
; __device__ __forceinline__ void gemm_phase(PG8_LAS unsigned char* lds, const Gemm g, const Sched& S, const Epi& E) {
;     ...
;             PG8_LDB(B0, 1, 0); PG8_LDB(B1, 1, 1); PG8_SCHED; PG8_LDA(At, 1, 0); PG8_STAGE(PG8_SA(0, 1), a2 + hstep, voffA);
;             PG8_WAIT_V(8); PG8_WAIT_L(0); PG8_BAR; PG8_MMA(0, 0, At, B0); PG8_MMA(0, 1, At, B1); PG8_BAR; PG8_SCHED;
;             PG8_LDA(At, 1, 1); PG8_STAGE(PG8_SB(1, 0), b3, voffB); PG8_STAGE(PG8_SB(1, 1), b3 + hstep, voffB); PG8_STAGE(PG8_SA(1, 0), a3, voffA);
;             PG8_WAIT_V(8); PG8_WAIT_L(0); PG8_BAR; PG8_MMA(1, 0, At, B0); PG8_MMA(1, 1, At, B1); PG8_BAR; PG8_SCHED;
	s_add_i32 s70, 0, 0x18000
	v_add_u32_e32 v148, s70, v153
	s_add_i32 s71, 0, 0x1c000
	ds_read_b128 v[142:145], v148
	ds_read_b128 v[158:161], v148 offset:1024
	ds_read_b128 v[162:165], v148 offset:2048
	ds_read_b128 v[166:169], v148 offset:3072
	v_add_u32_e32 v148, s71, v153
	ds_read_b128 v[170:173], v148
	ds_read_b128 v[174:177], v148 offset:1024
	ds_read_b128 v[178:181], v148 offset:2048
	ds_read_b128 v[182:185], v148 offset:3072
	s_add_u32 s34, s34, s28
	s_addc_u32 s35, s35, s29
	s_mov_b32 m0, s56
	v_lshl_add_u64 v[228:229], s[34:35], 0, v[134:135]
	ds_read_b128 v[186:189], v157 offset:32768
	ds_read_b128 v[190:193], v157 offset:33792
	ds_read_b128 v[194:197], v157 offset:34816
	ds_read_b128 v[198:201], v157 offset:35840
	ds_read_b128 v[202:205], v157 offset:36864
	ds_read_b128 v[212:215], v157 offset:37888
	ds_read_b128 v[216:219], v157 offset:38912
	ds_read_b128 v[220:223], v157 offset:39936
	global_load_lds_dwordx4 v[228:229], off
	v_lshl_add_u64 v[228:229], s[34:35], 0, v[130:131]
	s_mov_b32 m0, s57
	s_nop 0
	global_load_lds_dwordx4 v[228:229], off
	s_waitcnt vmcnt(8)
	s_waitcnt lgkmcnt(0)
	s_barrier
	s_setprio 1
	s_waitcnt lgkmcnt(0)
	v_mfma_f32_16x16x32_bf16 v[124:127], v[142:145], v[186:189], v[124:127]
	v_mfma_f32_16x16x32_bf16 v[120:123], v[162:165], v[186:189], v[120:123]
	v_mfma_f32_16x16x32_bf16 v[108:111], v[142:145], v[194:197], v[108:111]
	v_mfma_f32_16x16x32_bf16 v[104:107], v[162:165], v[194:197], v[104:107]
	v_mfma_f32_16x16x32_bf16 v[92:95], v[142:145], v[202:205], v[92:95]
	v_mfma_f32_16x16x32_bf16 v[88:91], v[162:165], v[202:205], v[88:91]
	v_mfma_f32_16x16x32_bf16 v[76:79], v[142:145], v[216:219], v[76:79]
	v_mfma_f32_16x16x32_bf16 v[72:75], v[162:165], v[216:219], v[72:75]
	v_mfma_f32_16x16x32_bf16 v[124:127], v[158:161], v[190:193], v[124:127]
	v_mfma_f32_16x16x32_bf16 v[120:123], v[166:169], v[190:193], v[120:123]
	v_mfma_f32_16x16x32_bf16 v[108:111], v[158:161], v[198:201], v[108:111]
	v_mfma_f32_16x16x32_bf16 v[104:107], v[166:169], v[198:201], v[104:107]
	v_mfma_f32_16x16x32_bf16 v[92:95], v[158:161], v[212:215], v[92:95]
	v_mfma_f32_16x16x32_bf16 v[88:91], v[166:169], v[212:215], v[88:91]
	v_mfma_f32_16x16x32_bf16 v[76:79], v[158:161], v[220:223], v[76:79]
	v_mfma_f32_16x16x32_bf16 v[72:75], v[166:169], v[220:223], v[72:75]
	v_mfma_f32_16x16x32_bf16 v[116:119], v[170:173], v[186:189], v[116:119]
	v_mfma_f32_16x16x32_bf16 v[112:115], v[178:181], v[186:189], v[112:115]
	v_mfma_f32_16x16x32_bf16 v[100:103], v[170:173], v[194:197], v[100:103]
	v_mfma_f32_16x16x32_bf16 v[96:99], v[178:181], v[194:197], v[96:99]
	v_mfma_f32_16x16x32_bf16 v[84:87], v[170:173], v[202:205], v[84:87]
	v_mfma_f32_16x16x32_bf16 v[80:83], v[178:181], v[202:205], v[80:83]
	v_mfma_f32_16x16x32_bf16 v[68:71], v[170:173], v[216:219], v[68:71]
	v_mfma_f32_16x16x32_bf16 v[64:67], v[178:181], v[216:219], v[64:67]
	v_mfma_f32_16x16x32_bf16 v[116:119], v[174:177], v[190:193], v[116:119]
	v_mfma_f32_16x16x32_bf16 v[112:115], v[182:185], v[190:193], v[112:115]
	v_mfma_f32_16x16x32_bf16 v[100:103], v[174:177], v[198:201], v[100:103]
	v_mfma_f32_16x16x32_bf16 v[96:99], v[182:185], v[198:201], v[96:99]
	v_mfma_f32_16x16x32_bf16 v[84:87], v[174:177], v[212:215], v[84:87]
	v_mfma_f32_16x16x32_bf16 v[80:83], v[182:185], v[212:215], v[80:83]
	v_mfma_f32_16x16x32_bf16 v[68:71], v[174:177], v[220:223], v[68:71]
	v_mfma_f32_16x16x32_bf16 v[64:67], v[182:185], v[220:223], v[64:67]
	s_setprio 0
	s_barrier
	s_add_i32 s34, s70, s7
	v_lshl_add_u64 v[146:147], v[146:147], 0, s[20:21]
	s_mov_b32 m0, s34
	ds_read_b128 v[186:189], v157 offset:49152
	ds_read_b128 v[190:193], v157 offset:50176
	ds_read_b128 v[194:197], v157 offset:51200
	ds_read_b128 v[198:201], v157 offset:52224
	ds_read_b128 v[202:205], v157 offset:53248
	ds_read_b128 v[212:215], v157 offset:54272
	ds_read_b128 v[216:219], v157 offset:55296
	ds_read_b128 v[220:223], v157 offset:56320
	global_load_lds_dwordx4 v[146:147], off
	v_lshl_add_u64 v[146:147], v[150:151], 0, s[20:21]
	s_add_i32 m0, s34, 0x2000
	s_add_i32 s34, s71, s7
	global_load_lds_dwordx4 v[146:147], off
	v_lshl_add_u64 v[146:147], v[154:155], 0, s[20:21]
	s_mov_b32 m0, s34
	s_nop 0
	global_load_lds_dwordx4 v[146:147], off
	v_lshl_add_u64 v[146:147], v[206:207], 0, s[20:21]
	s_add_i32 m0, s34, 0x2000
	s_nop 0
	global_load_lds_dwordx4 v[146:147], off
	v_lshl_add_u64 v[146:147], v[224:225], 0, s[20:21]
	s_mov_b32 m0, s58
	s_nop 0
	global_load_lds_dwordx4 v[146:147], off
	v_lshl_add_u64 v[146:147], v[226:227], 0, s[20:21]
	s_mov_b32 m0, s59
	s_nop 0
	global_load_lds_dwordx4 v[146:147], off
	s_waitcnt vmcnt(8)
	s_waitcnt lgkmcnt(0)
	s_barrier
	s_setprio 1
	s_waitcnt lgkmcnt(0)
	v_mfma_f32_16x16x32_bf16 v[60:63], v[142:145], v[186:189], v[60:63]
	v_mfma_f32_16x16x32_bf16 v[56:59], v[162:165], v[186:189], v[56:59]
	v_mfma_f32_16x16x32_bf16 v[44:47], v[142:145], v[194:197], v[44:47]
	v_mfma_f32_16x16x32_bf16 v[40:43], v[162:165], v[194:197], v[40:43]
	v_mfma_f32_16x16x32_bf16 v[28:31], v[142:145], v[202:205], v[28:31]
	v_mfma_f32_16x16x32_bf16 v[24:27], v[162:165], v[202:205], v[24:27]
	v_mfma_f32_16x16x32_bf16 v[12:15], v[142:145], v[216:219], v[12:15]
	v_mfma_f32_16x16x32_bf16 v[8:11], v[162:165], v[216:219], v[8:11]
	v_mfma_f32_16x16x32_bf16 v[60:63], v[158:161], v[190:193], v[60:63]
	v_mfma_f32_16x16x32_bf16 v[56:59], v[166:169], v[190:193], v[56:59]
	v_mfma_f32_16x16x32_bf16 v[44:47], v[158:161], v[198:201], v[44:47]
	v_mfma_f32_16x16x32_bf16 v[40:43], v[166:169], v[198:201], v[40:43]
	v_mfma_f32_16x16x32_bf16 v[28:31], v[158:161], v[212:215], v[28:31]
	v_mfma_f32_16x16x32_bf16 v[24:27], v[166:169], v[212:215], v[24:27]
	v_mfma_f32_16x16x32_bf16 v[12:15], v[158:161], v[220:223], v[12:15]
	v_mfma_f32_16x16x32_bf16 v[8:11], v[166:169], v[220:223], v[8:11]
	v_mfma_f32_16x16x32_bf16 v[52:55], v[170:173], v[186:189], v[52:55]
	v_mfma_f32_16x16x32_bf16 v[48:51], v[178:181], v[186:189], v[48:51]
	v_mfma_f32_16x16x32_bf16 v[36:39], v[170:173], v[194:197], v[36:39]
	v_mfma_f32_16x16x32_bf16 v[32:35], v[178:181], v[194:197], v[32:35]
	v_mfma_f32_16x16x32_bf16 v[20:23], v[170:173], v[202:205], v[20:23]
	v_mfma_f32_16x16x32_bf16 v[16:19], v[178:181], v[202:205], v[16:19]
	v_mfma_f32_16x16x32_bf16 v[4:7], v[170:173], v[216:219], v[4:7]
	v_mfma_f32_16x16x32_bf16 v[0:3], v[178:181], v[216:219], v[0:3]
	v_mfma_f32_16x16x32_bf16 v[52:55], v[174:177], v[190:193], v[52:55]
	v_mfma_f32_16x16x32_bf16 v[48:51], v[182:185], v[190:193], v[48:51]
	v_mfma_f32_16x16x32_bf16 v[36:39], v[174:177], v[198:201], v[36:39]
	v_mfma_f32_16x16x32_bf16 v[32:35], v[182:185], v[198:201], v[32:35]
	v_mfma_f32_16x16x32_bf16 v[20:23], v[174:177], v[212:215], v[20:23]
	v_mfma_f32_16x16x32_bf16 v[16:19], v[182:185], v[212:215], v[16:19]
	v_mfma_f32_16x16x32_bf16 v[4:7], v[174:177], v[220:223], v[4:7]
	v_mfma_f32_16x16x32_bf16 v[0:3], v[182:185], v[220:223], v[0:3]
	s_setprio 0
	s_barrier
	s_add_u32 s30, s30, 0x100
	s_addc_u32 s31, s31, 0
	s_add_u32 s67, s67, 0x100
	s_addc_u32 s68, s68, 0
	s_cmp_ge_i32 s69, s60
	s_mov_b32 s34, s69
	s_cbranch_scc0 .LBB0_511

; #define PG8_STAGE(bufoff, gbase, voff) do { _Pragma("unroll") for (int _i = 0; _i < 2; ++_i) \
;         __builtin_amdgcn_global_load_lds((const unsigned*)((const char*)(gbase) + (voff)[_i]), (PG8_LAS unsigned*)(lds + (bufoff) + ldsw + _i * 8192), 16, 0, 0); } while (0)
; #define PG8_LDA(dst, b, h) do { _Pragma("unroll") for (int m = 0; m < 4; ++m) _Pragma("unroll") for (int k = 0; k < 2; ++k) dst[m][k] = *(const PG8_LAS bf16x8*)(lds + PG8_SA(b, h) + aoff + m * 2048 + k * 1024); } while (0)
; #define PG8_LDB(dst, b, h) do { _Pragma("unroll") for (int n = 0; n < 2; ++n) _Pragma("unroll") for (int k = 0; k < 2; ++k) dst[n][k] = *(const PG8_LAS bf16x8*)(lds + PG8_SB(b, h) + boff + n * 2048 + k * 1024); } while (0)
; #define PG8_MMA(ai, bj, At, Bt) do { __builtin_amdgcn_s_setprio(1); _Pragma("unroll") for (int m = 0; m < 4; ++m) _Pragma("unroll") for (int n = 0; n < 2; ++n) _Pragma("unroll") for (int k = 0; k < 2; ++k) \
;         acc[ai][bj][m][n] = mma16<Epi::F16>(Bt[n][k], At[m][k], acc[ai][bj][m][n]); __builtin_amdgcn_s_setprio(0); } while (0)
; #define PG8_WAIT_V(n) asm volatile("s_waitcnt vmcnt(" #n ")" ::: "memory")
; #define PG8_WAIT_L(n) asm volatile("s_waitcnt lgkmcnt(" #n ")" ::: "memory")
; #define PG8_BAR __builtin_amdgcn_s_barrier()
; #define PG8_SCHED __builtin_amdgcn_sched_barrier(0)
; template <class Epi, class Sched, bool ALIGN_EPI = false, bool SP2 = false>
; __device__ __forceinline__ void gemm_phase(PG8_LAS unsigned char* lds, const Gemm g, const Sched& S, const Epi& E) {
;     ...
;     f32x4 acc[2][2][4][2];
; #pragma unroll
;     for (int a = 0; a < 2; ++a)
; #pragma unroll
;         for (int b = 0; b < 2; ++b)
; #pragma unroll
;             for (int m = 0; m < 4; ++m)
; #pragma unroll
;                 for (int n = 0; n < 2; ++n) acc[a][b][m][n] = (f32x4){0.f, 0.f, 0.f, 0.f};
;     ...
;             if constexpr (SP2) {
;             PG8_LDB(B0, 0, 0); PG8_LDB(B1, 0, 1); PG8_SCHED; PG8_LDA(At, 0, 0); PG8_STAGE(PG8_SA(1, 1), a1 + hstep, voffA);
;             PG8_WAIT_V(8); PG8_WAIT_L(0); PG8_BAR; PG8_MMA(0, 0, At, B0); PG8_MMA(0, 1, At, B1); PG8_BAR; PG8_SCHED;
;             PG8_LDA(At, 0, 1); PG8_STAGE(PG8_SB(0, 0), b2, voffB); PG8_STAGE(PG8_SB(0, 1), b2 + hstep, voffB); PG8_STAGE(PG8_SA(0, 0), a2, voffA);
;             PG8_WAIT_V(8); PG8_WAIT_L(0); PG8_BAR; PG8_MMA(1, 0, At, B0); PG8_MMA(1, 1, At, B1); PG8_BAR; PG8_SCHED;
.Lpeel_k5:
	s_add_u32 s30, s30, 0x80
	s_addc_u32 s31, s31, 0
	s_add_u32 s29, s34, 0x100
	s_addc_u32 s73, s35, 0
	s_mov_b32 s34, 0
	s_add_i32 s77, s34, 2
	s_add_u32 s82, s30, 0x80
	s_addc_u32 s35, s31, 0
	s_add_i32 s92, 0, 0x10000
	s_cmp_eq_u32 s48, s34
	s_cselect_b32 s35, s1, s35
	s_cselect_b32 s34, s0, s82
	v_add_u32_e32 v131, s92, v133
	s_cselect_b32 s85, s61, s73
	s_cselect_b32 s84, s60, s29
	s_add_i32 s82, 0, 0x14000
	ds_read_b128 v[140:143], v131
	ds_read_b128 v[144:147], v131 offset:1024
	ds_read_b128 v[148:151], v131 offset:2048
	ds_read_b128 v[152:155], v131 offset:3072
	v_add_u32_e32 v131, s82, v133
	ds_read_b128 v[156:159], v131
	ds_read_b128 v[160:163], v131 offset:1024
	ds_read_b128 v[164:167], v131 offset:2048
	ds_read_b128 v[168:171], v131 offset:3072
	v_lshl_add_u64 v[212:213], s[30:31], 0, v[136:137]
	s_add_i32 m0, s8, 0xc000
	ds_read_b128 v[172:175], v199
	ds_read_b128 v[176:179], v199 offset:1024
	ds_read_b128 v[180:183], v199 offset:2048
	ds_read_b128 v[184:187], v199 offset:3072
	ds_read_b128 v[188:191], v199 offset:4096
	ds_read_b128 v[192:195], v199 offset:5120
	ds_read_b128 v[200:203], v199 offset:6144
	ds_read_b128 v[204:207], v199 offset:7168
	global_load_lds_dwordx4 v[212:213], off
	v_lshl_add_u64 v[212:213], s[30:31], 0, v[138:139]
	s_add_i32 m0, s8, 0xe000
	s_nop 0
	global_load_lds_dwordx4 v[212:213], off
	s_waitcnt vmcnt(8)
	s_waitcnt lgkmcnt(0)
	s_barrier
	s_setprio 1
	s_waitcnt lgkmcnt(0)
	v_mfma_f32_16x16x32_bf16 v[120:123], v[140:143], v[172:175], 0
	v_mfma_f32_16x16x32_bf16 v[124:127], v[148:151], v[172:175], 0
	v_mfma_f32_16x16x32_bf16 v[108:111], v[140:143], v[180:183], 0
	v_mfma_f32_16x16x32_bf16 v[104:107], v[148:151], v[180:183], 0
	v_mfma_f32_16x16x32_bf16 v[92:95], v[140:143], v[188:191], 0
	v_mfma_f32_16x16x32_bf16 v[88:91], v[148:151], v[188:191], 0
	v_mfma_f32_16x16x32_bf16 v[76:79], v[140:143], v[200:203], 0
	v_mfma_f32_16x16x32_bf16 v[72:75], v[148:151], v[200:203], 0
	v_mfma_f32_16x16x32_bf16 v[120:123], v[144:147], v[176:179], v[120:123]
	v_mfma_f32_16x16x32_bf16 v[124:127], v[152:155], v[176:179], v[124:127]
	v_mfma_f32_16x16x32_bf16 v[108:111], v[144:147], v[184:187], v[108:111]
	v_mfma_f32_16x16x32_bf16 v[104:107], v[152:155], v[184:187], v[104:107]
	v_mfma_f32_16x16x32_bf16 v[92:95], v[144:147], v[192:195], v[92:95]
	v_mfma_f32_16x16x32_bf16 v[88:91], v[152:155], v[192:195], v[88:91]
	v_mfma_f32_16x16x32_bf16 v[76:79], v[144:147], v[204:207], v[76:79]
	v_mfma_f32_16x16x32_bf16 v[72:75], v[152:155], v[204:207], v[72:75]
	v_mfma_f32_16x16x32_bf16 v[116:119], v[156:159], v[172:175], 0
	v_mfma_f32_16x16x32_bf16 v[112:115], v[164:167], v[172:175], 0
	v_mfma_f32_16x16x32_bf16 v[100:103], v[156:159], v[180:183], 0
	v_mfma_f32_16x16x32_bf16 v[96:99], v[164:167], v[180:183], 0
	v_mfma_f32_16x16x32_bf16 v[84:87], v[156:159], v[188:191], 0
	v_mfma_f32_16x16x32_bf16 v[80:83], v[164:167], v[188:191], 0
	v_mfma_f32_16x16x32_bf16 v[68:71], v[156:159], v[200:203], 0
	v_mfma_f32_16x16x32_bf16 v[64:67], v[164:167], v[200:203], 0
	v_mfma_f32_16x16x32_bf16 v[116:119], v[160:163], v[176:179], v[116:119]
	v_mfma_f32_16x16x32_bf16 v[112:115], v[168:171], v[176:179], v[112:115]
	v_mfma_f32_16x16x32_bf16 v[100:103], v[160:163], v[184:187], v[100:103]
	v_mfma_f32_16x16x32_bf16 v[96:99], v[168:171], v[184:187], v[96:99]
	v_mfma_f32_16x16x32_bf16 v[84:87], v[160:163], v[192:195], v[84:87]
	v_mfma_f32_16x16x32_bf16 v[80:83], v[168:171], v[192:195], v[80:83]
	v_mfma_f32_16x16x32_bf16 v[68:71], v[160:163], v[204:207], v[68:71]
	v_mfma_f32_16x16x32_bf16 v[64:67], v[168:171], v[204:207], v[64:67]
	s_setprio 0
	s_barrier
	s_add_i32 s92, s92, s7
	v_lshl_add_u64 v[212:213], s[84:85], 0, v[208:209]
	s_mov_b32 m0, s92
	ds_read_b128 v[172:175], v199 offset:16384
	ds_read_b128 v[176:179], v199 offset:17408
	ds_read_b128 v[180:183], v199 offset:18432
	ds_read_b128 v[184:187], v199 offset:19456
	ds_read_b128 v[188:191], v199 offset:20480
	ds_read_b128 v[192:195], v199 offset:21504
	ds_read_b128 v[200:203], v199 offset:22528
	ds_read_b128 v[204:207], v199 offset:23552
	global_load_lds_dwordx4 v[212:213], off
	s_add_i32 m0, s92, 0x2000
	v_lshl_add_u64 v[214:215], s[84:85], 0, v[128:129]
	s_add_u32 s84, s84, s50
	s_addc_u32 s85, s85, s51
	s_add_i32 s82, s82, s7
	global_load_lds_dwordx4 v[214:215], off
	v_lshl_add_u64 v[216:217], s[84:85], 0, v[208:209]
	s_mov_b32 m0, s82
	v_lshl_add_u64 v[218:219], s[84:85], 0, v[128:129]
	global_load_lds_dwordx4 v[216:217], off
	s_add_i32 m0, s82, 0x2000
	v_lshl_add_u64 v[220:221], s[34:35], 0, v[208:209]
	global_load_lds_dwordx4 v[218:219], off
	s_mov_b32 m0, s8
	v_lshl_add_u64 v[222:223], s[34:35], 0, v[128:129]
	global_load_lds_dwordx4 v[220:221], off
	s_mov_b32 m0, s9
	s_nop 0
	global_load_lds_dwordx4 v[222:223], off
	s_waitcnt vmcnt(8)
	s_waitcnt lgkmcnt(0)
	s_barrier
; #define PG8_STAGE(bufoff, gbase, voff) do { _Pragma("unroll") for (int _i = 0; _i < 2; ++_i) \
;         __builtin_amdgcn_global_load_lds((const unsigned*)((const char*)(gbase) + (voff)[_i]), (PG8_LAS unsigned*)(lds + (bufoff) + ldsw + _i * 8192), 16, 0, 0); } while (0)
; #define PG8_LDA(dst, b, h) do { _Pragma("unroll") for (int m = 0; m < 4; ++m) _Pragma("unroll") for (int k = 0; k < 2; ++k) dst[m][k] = *(const PG8_LAS bf16x8*)(lds + PG8_SA(b, h) + aoff + m * 2048 + k * 1024); } while (0)
; #define PG8_LDB(dst, b, h) do { _Pragma("unroll") for (int n = 0; n < 2; ++n) _Pragma("unroll") for (int k = 0; k < 2; ++k) dst[n][k] = *(const PG8_LAS bf16x8*)(lds + PG8_SB(b, h) + boff + n * 2048 + k * 1024); } while (0)
; #define PG8_MMA(ai, bj, At, Bt) do { __builtin_amdgcn_s_setprio(1); _Pragma("unroll") for (int m = 0; m < 4; ++m) _Pragma("unroll") for (int n = 0; n < 2; ++n) _Pragma("unroll") for (int k = 0; k < 2; ++k) \
;         acc[ai][bj][m][n] = mma16<Epi::F16>(Bt[n][k], At[m][k], acc[ai][bj][m][n]); __builtin_amdgcn_s_setprio(0); } while (0)
; #define PG8_WAIT_V(n) asm volatile("s_waitcnt vmcnt(" #n ")" ::: "memory")
; #define PG8_WAIT_L(n) asm volatile("s_waitcnt lgkmcnt(" #n ")" ::: "memory")
; #define PG8_BAR __builtin_amdgcn_s_barrier()
; #define PG8_SCHED __builtin_amdgcn_sched_barrier(0)
; template <class Epi, class Sched, bool ALIGN_EPI = false, bool SP2 = false>
; __device__ __forceinline__ void gemm_phase(PG8_LAS unsigned char* lds, const Gemm g, const Sched& S, const Epi& E) {
;     ...
;             if constexpr (SP2) {
;             PG8_LDB(B0, 0, 0); PG8_LDB(B1, 0, 1); PG8_SCHED; PG8_LDA(At, 0, 0); PG8_STAGE(PG8_SA(1, 1), a1 + hstep, voffA);
;             PG8_WAIT_V(8); PG8_WAIT_L(0); PG8_BAR; PG8_MMA(0, 0, At, B0); PG8_MMA(0, 1, At, B1); PG8_BAR; PG8_SCHED;
;             PG8_LDA(At, 0, 1); PG8_STAGE(PG8_SB(0, 0), b2, voffB); PG8_STAGE(PG8_SB(0, 1), b2 + hstep, voffB); PG8_STAGE(PG8_SA(0, 0), a2, voffA);
;             PG8_WAIT_V(8); PG8_WAIT_L(0); PG8_BAR; PG8_MMA(1, 0, At, B0); PG8_MMA(1, 1, At, B1); PG8_BAR; PG8_SCHED;
;             PG8_LDB(B0, 1, 0); PG8_LDB(B1, 1, 1); PG8_SCHED; PG8_LDA(At, 1, 0); PG8_STAGE(PG8_SA(0, 1), a2 + hstep, voffA);
;             PG8_WAIT_V(8); PG8_WAIT_L(0); PG8_BAR; PG8_MMA(0, 0, At, B0); PG8_MMA(0, 1, At, B1); PG8_BAR; PG8_SCHED;
	s_setprio 1
	s_waitcnt lgkmcnt(0)
	v_mfma_f32_16x16x32_bf16 v[60:63], v[140:143], v[172:175], 0
	v_mfma_f32_16x16x32_bf16 v[56:59], v[148:151], v[172:175], 0
	v_mfma_f32_16x16x32_bf16 v[44:47], v[140:143], v[180:183], 0
	v_mfma_f32_16x16x32_bf16 v[40:43], v[148:151], v[180:183], 0
	v_mfma_f32_16x16x32_bf16 v[28:31], v[140:143], v[188:191], 0
	v_mfma_f32_16x16x32_bf16 v[24:27], v[148:151], v[188:191], 0
	v_mfma_f32_16x16x32_bf16 v[12:15], v[140:143], v[200:203], 0
	v_mfma_f32_16x16x32_bf16 v[8:11], v[148:151], v[200:203], 0
	v_mfma_f32_16x16x32_bf16 v[60:63], v[144:147], v[176:179], v[60:63]
	v_mfma_f32_16x16x32_bf16 v[56:59], v[152:155], v[176:179], v[56:59]
	v_mfma_f32_16x16x32_bf16 v[44:47], v[144:147], v[184:187], v[44:47]
	v_mfma_f32_16x16x32_bf16 v[40:43], v[152:155], v[184:187], v[40:43]
	v_mfma_f32_16x16x32_bf16 v[28:31], v[144:147], v[192:195], v[28:31]
	v_mfma_f32_16x16x32_bf16 v[24:27], v[152:155], v[192:195], v[24:27]
	v_mfma_f32_16x16x32_bf16 v[12:15], v[144:147], v[204:207], v[12:15]
	v_mfma_f32_16x16x32_bf16 v[8:11], v[152:155], v[204:207], v[8:11]
	v_mfma_f32_16x16x32_bf16 v[52:55], v[156:159], v[172:175], 0
	v_mfma_f32_16x16x32_bf16 v[48:51], v[164:167], v[172:175], 0
	v_mfma_f32_16x16x32_bf16 v[36:39], v[156:159], v[180:183], 0
	v_mfma_f32_16x16x32_bf16 v[32:35], v[164:167], v[180:183], 0
	v_mfma_f32_16x16x32_bf16 v[20:23], v[156:159], v[188:191], 0
	v_mfma_f32_16x16x32_bf16 v[16:19], v[164:167], v[188:191], 0
	v_mfma_f32_16x16x32_bf16 v[4:7], v[156:159], v[200:203], 0
	v_mfma_f32_16x16x32_bf16 v[0:3], v[164:167], v[200:203], 0
	v_mfma_f32_16x16x32_bf16 v[52:55], v[160:163], v[176:179], v[52:55]
	v_mfma_f32_16x16x32_bf16 v[48:51], v[168:171], v[176:179], v[48:51]
	v_mfma_f32_16x16x32_bf16 v[36:39], v[160:163], v[184:187], v[36:39]
	v_mfma_f32_16x16x32_bf16 v[32:35], v[168:171], v[184:187], v[32:35]
	v_mfma_f32_16x16x32_bf16 v[20:23], v[160:163], v[192:195], v[20:23]
	v_mfma_f32_16x16x32_bf16 v[16:19], v[168:171], v[192:195], v[16:19]
	v_mfma_f32_16x16x32_bf16 v[4:7], v[160:163], v[204:207], v[4:7]
	v_mfma_f32_16x16x32_bf16 v[0:3], v[168:171], v[204:207], v[0:3]
	s_setprio 0
	s_barrier
	s_add_i32 s82, 0, 0x18000
	v_add_u32_e32 v131, s82, v133
	s_add_i32 s84, 0, 0x1c000
	ds_read_b128 v[140:143], v131
	ds_read_b128 v[144:147], v131 offset:1024
	ds_read_b128 v[148:151], v131 offset:2048
	ds_read_b128 v[152:155], v131 offset:3072
	v_add_u32_e32 v131, s84, v133
	ds_read_b128 v[156:159], v131
	ds_read_b128 v[160:163], v131 offset:1024
	ds_read_b128 v[164:167], v131 offset:2048
	ds_read_b128 v[168:171], v131 offset:3072
	s_add_u32 s34, s34, s50
	s_addc_u32 s35, s35, s51
	s_mov_b32 m0, s11
	v_lshl_add_u64 v[224:225], s[34:35], 0, v[208:209]
	ds_read_b128 v[172:175], v199 offset:32768
	ds_read_b128 v[176:179], v199 offset:33792
	ds_read_b128 v[180:183], v199 offset:34816
	ds_read_b128 v[184:187], v199 offset:35840
	ds_read_b128 v[188:191], v199 offset:36864
	ds_read_b128 v[192:195], v199 offset:37888
	ds_read_b128 v[200:203], v199 offset:38912
	ds_read_b128 v[204:207], v199 offset:39936
	global_load_lds_dwordx4 v[224:225], off
	v_lshl_add_u64 v[224:225], s[34:35], 0, v[128:129]
	s_mov_b32 m0, s36
	s_nop 0
	global_load_lds_dwordx4 v[224:225], off
	s_waitcnt vmcnt(8)
	s_waitcnt lgkmcnt(0)
	s_barrier
	s_setprio 1
	s_waitcnt lgkmcnt(0)
	v_mfma_f32_16x16x32_bf16 v[120:123], v[140:143], v[172:175], v[120:123]
	v_mfma_f32_16x16x32_bf16 v[124:127], v[148:151], v[172:175], v[124:127]
	v_mfma_f32_16x16x32_bf16 v[108:111], v[140:143], v[180:183], v[108:111]
	v_mfma_f32_16x16x32_bf16 v[104:107], v[148:151], v[180:183], v[104:107]
	v_mfma_f32_16x16x32_bf16 v[92:95], v[140:143], v[188:191], v[92:95]
	v_mfma_f32_16x16x32_bf16 v[88:91], v[148:151], v[188:191], v[88:91]
	v_mfma_f32_16x16x32_bf16 v[76:79], v[140:143], v[200:203], v[76:79]
	v_mfma_f32_16x16x32_bf16 v[72:75], v[148:151], v[200:203], v[72:75]
	v_mfma_f32_16x16x32_bf16 v[120:123], v[144:147], v[176:179], v[120:123]
	v_mfma_f32_16x16x32_bf16 v[124:127], v[152:155], v[176:179], v[124:127]
	v_mfma_f32_16x16x32_bf16 v[108:111], v[144:147], v[184:187], v[108:111]
	v_mfma_f32_16x16x32_bf16 v[104:107], v[152:155], v[184:187], v[104:107]
	v_mfma_f32_16x16x32_bf16 v[92:95], v[144:147], v[192:195], v[92:95]
	v_mfma_f32_16x16x32_bf16 v[88:91], v[152:155], v[192:195], v[88:91]
	v_mfma_f32_16x16x32_bf16 v[76:79], v[144:147], v[204:207], v[76:79]
	v_mfma_f32_16x16x32_bf16 v[72:75], v[152:155], v[204:207], v[72:75]
	v_mfma_f32_16x16x32_bf16 v[116:119], v[156:159], v[172:175], v[116:119]
	v_mfma_f32_16x16x32_bf16 v[112:115], v[164:167], v[172:175], v[112:115]
	v_mfma_f32_16x16x32_bf16 v[100:103], v[156:159], v[180:183], v[100:103]
	v_mfma_f32_16x16x32_bf16 v[96:99], v[164:167], v[180:183], v[96:99]
	v_mfma_f32_16x16x32_bf16 v[84:87], v[156:159], v[188:191], v[84:87]
	v_mfma_f32_16x16x32_bf16 v[80:83], v[164:167], v[188:191], v[80:83]
	v_mfma_f32_16x16x32_bf16 v[68:71], v[156:159], v[200:203], v[68:71]
	v_mfma_f32_16x16x32_bf16 v[64:67], v[164:167], v[200:203], v[64:67]
	v_mfma_f32_16x16x32_bf16 v[116:119], v[160:163], v[176:179], v[116:119]
	v_mfma_f32_16x16x32_bf16 v[112:115], v[168:171], v[176:179], v[112:115]
	v_mfma_f32_16x16x32_bf16 v[100:103], v[160:163], v[184:187], v[100:103]
	v_mfma_f32_16x16x32_bf16 v[96:99], v[168:171], v[184:187], v[96:99]
	v_mfma_f32_16x16x32_bf16 v[84:87], v[160:163], v[192:195], v[84:87]
	v_mfma_f32_16x16x32_bf16 v[80:83], v[168:171], v[192:195], v[80:83]
	v_mfma_f32_16x16x32_bf16 v[68:71], v[160:163], v[204:207], v[68:71]
	v_mfma_f32_16x16x32_bf16 v[64:67], v[168:171], v[204:207], v[64:67]
	s_setprio 0
	s_barrier
; #define PG8_STAGE(bufoff, gbase, voff) do { _Pragma("unroll") for (int _i = 0; _i < 2; ++_i) \
;         __builtin_amdgcn_global_load_lds((const unsigned*)((const char*)(gbase) + (voff)[_i]), (PG8_LAS unsigned*)(lds + (bufoff) + ldsw + _i * 8192), 16, 0, 0); } while (0)
; #define PG8_LDA(dst, b, h) do { _Pragma("unroll") for (int m = 0; m < 4; ++m) _Pragma("unroll") for (int k = 0; k < 2; ++k) dst[m][k] = *(const PG8_LAS bf16x8*)(lds + PG8_SA(b, h) + aoff + m * 2048 + k * 1024); } while (0)
; template <class Epi, class Sched, bool ALIGN_EPI = false, bool SP2 = false>
; __device__ __forceinline__ void gemm_phase(PG8_LAS unsigned char* lds, const Gemm g, const Sched& S, const Epi& E) {
;     ...
;         const bool has_next = S.next(ui + 1, nxt);
;         const char* nA = has_next ? (const char*)g.A + (size_t)nxt.pm * tstep : cA; const char* nB = has_next ? (const char*)g.Bt + (size_t)nxt.pn * tstep : cB;
;         for (int t = 0; t < nt; t += 2) {
;             const bool last = (t == nt - 2);
;             const char* a1 = cA + (size_t)(t + 1) * kstep;
;             const char* a2 = last ? nA : cA + (size_t)(t + 2) * kstep; const char* b2 = last ? nB : cB + (size_t)(t + 2) * kstep;
;             const char* a3 = a2 + kstep; const char* b3 = b2 + kstep;
;             if (last && has_next) S.a_ready(nxt);
;             if constexpr (SP2) {
;             PG8_LDB(B0, 0, 0); PG8_LDB(B1, 0, 1); PG8_SCHED; PG8_LDA(At, 0, 0); PG8_STAGE(PG8_SA(1, 1), a1 + hstep, voffA);
;             PG8_WAIT_V(8); PG8_WAIT_L(0); PG8_BAR; PG8_MMA(0, 0, At, B0); PG8_MMA(0, 1, At, B1); PG8_BAR; PG8_SCHED;
;             PG8_LDA(At, 0, 1); PG8_STAGE(PG8_SB(0, 0), b2, voffB); PG8_STAGE(PG8_SB(0, 1), b2 + hstep, voffB); PG8_STAGE(PG8_SA(0, 0), a2, voffA);
;             PG8_WAIT_V(8); PG8_WAIT_L(0); PG8_BAR; PG8_MMA(1, 0, At, B0); PG8_MMA(1, 1, At, B1); PG8_BAR; PG8_SCHED;
;             PG8_LDB(B0, 1, 0); PG8_LDB(B1, 1, 1); PG8_SCHED; PG8_LDA(At, 1, 0); PG8_STAGE(PG8_SA(0, 1), a2 + hstep, voffA);
;             PG8_WAIT_V(8); PG8_WAIT_L(0); PG8_BAR; PG8_MMA(0, 0, At, B0); PG8_MMA(0, 1, At, B1); PG8_BAR; PG8_SCHED;
;             PG8_LDA(At, 1, 1); PG8_STAGE(PG8_SB(1, 0), b3, voffB); PG8_STAGE(PG8_SB(1, 1), b3 + hstep, voffB); PG8_STAGE(PG8_SA(1, 0), a3, voffA);
;             PG8_WAIT_V(8); PG8_WAIT_L(0); PG8_BAR; PG8_MMA(1, 0, At, B0); PG8_MMA(1, 1, At, B1); PG8_BAR; PG8_SCHED;
	s_add_i32 s34, s82, s7
	v_lshl_add_u64 v[212:213], v[212:213], 0, s[20:21]
	s_mov_b32 m0, s34
	ds_read_b128 v[172:175], v199 offset:49152
	ds_read_b128 v[176:179], v199 offset:50176
	ds_read_b128 v[180:183], v199 offset:51200
	ds_read_b128 v[184:187], v199 offset:52224
	ds_read_b128 v[188:191], v199 offset:53248
	ds_read_b128 v[192:195], v199 offset:54272
	ds_read_b128 v[200:203], v199 offset:55296
	ds_read_b128 v[204:207], v199 offset:56320
	global_load_lds_dwordx4 v[212:213], off
	v_lshl_add_u64 v[212:213], v[214:215], 0, s[20:21]
	s_add_i32 m0, s34, 0x2000
	s_add_i32 s34, s84, s7
	global_load_lds_dwordx4 v[212:213], off
	v_lshl_add_u64 v[212:213], v[216:217], 0, s[20:21]
	s_mov_b32 m0, s34
	s_nop 0
	global_load_lds_dwordx4 v[212:213], off
	v_lshl_add_u64 v[212:213], v[218:219], 0, s[20:21]
	s_add_i32 m0, s34, 0x2000
	s_nop 0
	global_load_lds_dwordx4 v[212:213], off
	v_lshl_add_u64 v[212:213], v[220:221], 0, s[20:21]
	s_mov_b32 m0, s37
	s_nop 0
	global_load_lds_dwordx4 v[212:213], off
	v_lshl_add_u64 v[212:213], v[222:223], 0, s[20:21]
	s_mov_b32 m0, s38
	s_nop 0
	global_load_lds_dwordx4 v[212:213], off
	s_waitcnt vmcnt(8)
	s_waitcnt lgkmcnt(0)
	s_barrier
	s_setprio 1
	s_waitcnt lgkmcnt(0)
	v_mfma_f32_16x16x32_bf16 v[60:63], v[140:143], v[172:175], v[60:63]
	v_mfma_f32_16x16x32_bf16 v[56:59], v[148:151], v[172:175], v[56:59]
	v_mfma_f32_16x16x32_bf16 v[44:47], v[140:143], v[180:183], v[44:47]
	v_mfma_f32_16x16x32_bf16 v[40:43], v[148:151], v[180:183], v[40:43]
	v_mfma_f32_16x16x32_bf16 v[28:31], v[140:143], v[188:191], v[28:31]
	v_mfma_f32_16x16x32_bf16 v[24:27], v[148:151], v[188:191], v[24:27]
	v_mfma_f32_16x16x32_bf16 v[12:15], v[140:143], v[200:203], v[12:15]
	v_mfma_f32_16x16x32_bf16 v[8:11], v[148:151], v[200:203], v[8:11]
	v_mfma_f32_16x16x32_bf16 v[60:63], v[144:147], v[176:179], v[60:63]
	v_mfma_f32_16x16x32_bf16 v[56:59], v[152:155], v[176:179], v[56:59]
	v_mfma_f32_16x16x32_bf16 v[44:47], v[144:147], v[184:187], v[44:47]
	v_mfma_f32_16x16x32_bf16 v[40:43], v[152:155], v[184:187], v[40:43]
	v_mfma_f32_16x16x32_bf16 v[28:31], v[144:147], v[192:195], v[28:31]
	v_mfma_f32_16x16x32_bf16 v[24:27], v[152:155], v[192:195], v[24:27]
	v_mfma_f32_16x16x32_bf16 v[12:15], v[144:147], v[204:207], v[12:15]
	v_mfma_f32_16x16x32_bf16 v[8:11], v[152:155], v[204:207], v[8:11]
	v_mfma_f32_16x16x32_bf16 v[52:55], v[156:159], v[172:175], v[52:55]
	v_mfma_f32_16x16x32_bf16 v[48:51], v[164:167], v[172:175], v[48:51]
	v_mfma_f32_16x16x32_bf16 v[36:39], v[156:159], v[180:183], v[36:39]
	v_mfma_f32_16x16x32_bf16 v[32:35], v[164:167], v[180:183], v[32:35]
	v_mfma_f32_16x16x32_bf16 v[20:23], v[156:159], v[188:191], v[20:23]
	v_mfma_f32_16x16x32_bf16 v[16:19], v[164:167], v[188:191], v[16:19]
	v_mfma_f32_16x16x32_bf16 v[4:7], v[156:159], v[200:203], v[4:7]
	v_mfma_f32_16x16x32_bf16 v[0:3], v[164:167], v[200:203], v[0:3]
	v_mfma_f32_16x16x32_bf16 v[52:55], v[160:163], v[176:179], v[52:55]
	v_mfma_f32_16x16x32_bf16 v[48:51], v[168:171], v[176:179], v[48:51]
	v_mfma_f32_16x16x32_bf16 v[36:39], v[160:163], v[184:187], v[36:39]
	v_mfma_f32_16x16x32_bf16 v[32:35], v[168:171], v[184:187], v[32:35]
	v_mfma_f32_16x16x32_bf16 v[20:23], v[160:163], v[192:195], v[20:23]
	v_mfma_f32_16x16x32_bf16 v[16:19], v[168:171], v[192:195], v[16:19]
	v_mfma_f32_16x16x32_bf16 v[4:7], v[160:163], v[204:207], v[4:7]
	v_mfma_f32_16x16x32_bf16 v[0:3], v[168:171], v[204:207], v[0:3]
	s_setprio 0
	s_barrier
	s_add_u32 s30, s30, 0x100
	s_addc_u32 s31, s31, 0
	s_add_u32 s29, s29, 0x100
	s_addc_u32 s73, s73, 0
	s_cmp_ge_i32 s77, s39
	s_mov_b32 s34, s77
	s_cbranch_scc0 .LBB0_757
	s_branch .LBB0_758
.LBB0_757:
	s_add_i32 s77, s34, 2
	s_add_u32 s82, s30, 0x80
	s_addc_u32 s35, s31, 0
	s_add_i32 s92, 0, 0x10000
	s_cmp_eq_u32 s48, s34
	s_cselect_b32 s35, s1, s35
	s_cselect_b32 s34, s0, s82
	v_add_u32_e32 v131, s92, v133
	s_cselect_b32 s85, s61, s73
	s_cselect_b32 s84, s60, s29
	s_add_i32 s82, 0, 0x14000
	ds_read_b128 v[140:143], v131
	ds_read_b128 v[144:147], v131 offset:1024
	ds_read_b128 v[148:151], v131 offset:2048
	ds_read_b128 v[152:155], v131 offset:3072
	v_add_u32_e32 v131, s82, v133
	ds_read_b128 v[156:159], v131
	ds_read_b128 v[160:163], v131 offset:1024
	ds_read_b128 v[164:167], v131 offset:2048
	ds_read_b128 v[168:171], v131 offset:3072
	v_lshl_add_u64 v[212:213], s[30:31], 0, v[136:137]
	s_add_i32 m0, s8, 0xc000
	ds_read_b128 v[172:175], v199
	ds_read_b128 v[176:179], v199 offset:1024
	ds_read_b128 v[180:183], v199 offset:2048
	ds_read_b128 v[184:187], v199 offset:3072
	ds_read_b128 v[188:191], v199 offset:4096
	ds_read_b128 v[192:195], v199 offset:5120
	ds_read_b128 v[200:203], v199 offset:6144
	ds_read_b128 v[204:207], v199 offset:7168
	global_load_lds_dwordx4 v[212:213], off
	v_lshl_add_u64 v[212:213], s[30:31], 0, v[138:139]
	s_add_i32 m0, s8, 0xe000
	s_nop 0
	global_load_lds_dwordx4 v[212:213], off
	s_waitcnt vmcnt(8)
	s_waitcnt lgkmcnt(0)
	s_barrier
; #define PG8_STAGE(bufoff, gbase, voff) do { _Pragma("unroll") for (int _i = 0; _i < 2; ++_i) \
;         __builtin_amdgcn_global_load_lds((const unsigned*)((const char*)(gbase) + (voff)[_i]), (PG8_LAS unsigned*)(lds + (bufoff) + ldsw + _i * 8192), 16, 0, 0); } while (0)
; #define PG8_LDA(dst, b, h) do { _Pragma("unroll") for (int m = 0; m < 4; ++m) _Pragma("unroll") for (int k = 0; k < 2; ++k) dst[m][k] = *(const PG8_LAS bf16x8*)(lds + PG8_SA(b, h) + aoff + m * 2048 + k * 1024); } while (0)
; #define PG8_LDB(dst, b, h) do { _Pragma("unroll") for (int n = 0; n < 2; ++n) _Pragma("unroll") for (int k = 0; k < 2; ++k) dst[n][k] = *(const PG8_LAS bf16x8*)(lds + PG8_SB(b, h) + boff + n * 2048 + k * 1024); } while (0)
; #define PG8_MMA(ai, bj, At, Bt) do { __builtin_amdgcn_s_setprio(1); _Pragma("unroll") for (int m = 0; m < 4; ++m) _Pragma("unroll") for (int n = 0; n < 2; ++n) _Pragma("unroll") for (int k = 0; k < 2; ++k) \
;         acc[ai][bj][m][n] = mma16<Epi::F16>(Bt[n][k], At[m][k], acc[ai][bj][m][n]); __builtin_amdgcn_s_setprio(0); } while (0)
; #define PG8_WAIT_V(n) asm volatile("s_waitcnt vmcnt(" #n ")" ::: "memory")
; #define PG8_WAIT_L(n) asm volatile("s_waitcnt lgkmcnt(" #n ")" ::: "memory")
; #define PG8_BAR __builtin_amdgcn_s_barrier()
; #define PG8_SCHED __builtin_amdgcn_sched_barrier(0)
; template <class Epi, class Sched, bool ALIGN_EPI = false, bool SP2 = false>
; __device__ __forceinline__ void gemm_phase(PG8_LAS unsigned char* lds, const Gemm g, const Sched& S, const Epi& E) {
;     ...
;             if constexpr (SP2) {
;             PG8_LDB(B0, 0, 0); PG8_LDB(B1, 0, 1); PG8_SCHED; PG8_LDA(At, 0, 0); PG8_STAGE(PG8_SA(1, 1), a1 + hstep, voffA);
;             PG8_WAIT_V(8); PG8_WAIT_L(0); PG8_BAR; PG8_MMA(0, 0, At, B0); PG8_MMA(0, 1, At, B1); PG8_BAR; PG8_SCHED;
;             PG8_LDA(At, 0, 1); PG8_STAGE(PG8_SB(0, 0), b2, voffB); PG8_STAGE(PG8_SB(0, 1), b2 + hstep, voffB); PG8_STAGE(PG8_SA(0, 0), a2, voffA);
;             PG8_WAIT_V(8); PG8_WAIT_L(0); PG8_BAR; PG8_MMA(1, 0, At, B0); PG8_MMA(1, 1, At, B1); PG8_BAR; PG8_SCHED;
	s_setprio 1
	s_waitcnt lgkmcnt(0)
	v_mfma_f32_16x16x32_bf16 v[120:123], v[140:143], v[172:175], v[120:123]
	v_mfma_f32_16x16x32_bf16 v[124:127], v[148:151], v[172:175], v[124:127]
	v_mfma_f32_16x16x32_bf16 v[108:111], v[140:143], v[180:183], v[108:111]
	v_mfma_f32_16x16x32_bf16 v[104:107], v[148:151], v[180:183], v[104:107]
	v_mfma_f32_16x16x32_bf16 v[92:95], v[140:143], v[188:191], v[92:95]
	v_mfma_f32_16x16x32_bf16 v[88:91], v[148:151], v[188:191], v[88:91]
	v_mfma_f32_16x16x32_bf16 v[76:79], v[140:143], v[200:203], v[76:79]
	v_mfma_f32_16x16x32_bf16 v[72:75], v[148:151], v[200:203], v[72:75]
	v_mfma_f32_16x16x32_bf16 v[120:123], v[144:147], v[176:179], v[120:123]
	v_mfma_f32_16x16x32_bf16 v[124:127], v[152:155], v[176:179], v[124:127]
	v_mfma_f32_16x16x32_bf16 v[108:111], v[144:147], v[184:187], v[108:111]
	v_mfma_f32_16x16x32_bf16 v[104:107], v[152:155], v[184:187], v[104:107]
	v_mfma_f32_16x16x32_bf16 v[92:95], v[144:147], v[192:195], v[92:95]
	v_mfma_f32_16x16x32_bf16 v[88:91], v[152:155], v[192:195], v[88:91]
	v_mfma_f32_16x16x32_bf16 v[76:79], v[144:147], v[204:207], v[76:79]
	v_mfma_f32_16x16x32_bf16 v[72:75], v[152:155], v[204:207], v[72:75]
	v_mfma_f32_16x16x32_bf16 v[116:119], v[156:159], v[172:175], v[116:119]
	v_mfma_f32_16x16x32_bf16 v[112:115], v[164:167], v[172:175], v[112:115]
	v_mfma_f32_16x16x32_bf16 v[100:103], v[156:159], v[180:183], v[100:103]
	v_mfma_f32_16x16x32_bf16 v[96:99], v[164:167], v[180:183], v[96:99]
	v_mfma_f32_16x16x32_bf16 v[84:87], v[156:159], v[188:191], v[84:87]
	v_mfma_f32_16x16x32_bf16 v[80:83], v[164:167], v[188:191], v[80:83]
	v_mfma_f32_16x16x32_bf16 v[68:71], v[156:159], v[200:203], v[68:71]
	v_mfma_f32_16x16x32_bf16 v[64:67], v[164:167], v[200:203], v[64:67]
	v_mfma_f32_16x16x32_bf16 v[116:119], v[160:163], v[176:179], v[116:119]
	v_mfma_f32_16x16x32_bf16 v[112:115], v[168:171], v[176:179], v[112:115]
	v_mfma_f32_16x16x32_bf16 v[100:103], v[160:163], v[184:187], v[100:103]
	v_mfma_f32_16x16x32_bf16 v[96:99], v[168:171], v[184:187], v[96:99]
	v_mfma_f32_16x16x32_bf16 v[84:87], v[160:163], v[192:195], v[84:87]
	v_mfma_f32_16x16x32_bf16 v[80:83], v[168:171], v[192:195], v[80:83]
	v_mfma_f32_16x16x32_bf16 v[68:71], v[160:163], v[204:207], v[68:71]
	v_mfma_f32_16x16x32_bf16 v[64:67], v[168:171], v[204:207], v[64:67]
	s_setprio 0
	s_barrier
	s_add_i32 s92, s92, s7
	v_lshl_add_u64 v[212:213], s[84:85], 0, v[208:209]
	s_mov_b32 m0, s92
	ds_read_b128 v[172:175], v199 offset:16384
	ds_read_b128 v[176:179], v199 offset:17408
	ds_read_b128 v[180:183], v199 offset:18432
	ds_read_b128 v[184:187], v199 offset:19456
	ds_read_b128 v[188:191], v199 offset:20480
	ds_read_b128 v[192:195], v199 offset:21504
	ds_read_b128 v[200:203], v199 offset:22528
	ds_read_b128 v[204:207], v199 offset:23552
	global_load_lds_dwordx4 v[212:213], off
	s_add_i32 m0, s92, 0x2000
	v_lshl_add_u64 v[214:215], s[84:85], 0, v[128:129]
	s_add_u32 s84, s84, s50
	s_addc_u32 s85, s85, s51
	s_add_i32 s82, s82, s7
	global_load_lds_dwordx4 v[214:215], off
	v_lshl_add_u64 v[216:217], s[84:85], 0, v[208:209]
	s_mov_b32 m0, s82
	v_lshl_add_u64 v[218:219], s[84:85], 0, v[128:129]
	global_load_lds_dwordx4 v[216:217], off
	s_add_i32 m0, s82, 0x2000
	v_lshl_add_u64 v[220:221], s[34:35], 0, v[208:209]
	global_load_lds_dwordx4 v[218:219], off
	s_mov_b32 m0, s8
	v_lshl_add_u64 v[222:223], s[34:35], 0, v[128:129]
	global_load_lds_dwordx4 v[220:221], off
	s_mov_b32 m0, s9
	s_nop 0
	global_load_lds_dwordx4 v[222:223], off
	s_waitcnt vmcnt(8)
	s_waitcnt lgkmcnt(0)
	s_barrier
	s_setprio 1
	s_waitcnt lgkmcnt(0)
	v_mfma_f32_16x16x32_bf16 v[60:63], v[140:143], v[172:175], v[60:63]
	v_mfma_f32_16x16x32_bf16 v[56:59], v[148:151], v[172:175], v[56:59]
	v_mfma_f32_16x16x32_bf16 v[44:47], v[140:143], v[180:183], v[44:47]
	v_mfma_f32_16x16x32_bf16 v[40:43], v[148:151], v[180:183], v[40:43]
	v_mfma_f32_16x16x32_bf16 v[28:31], v[140:143], v[188:191], v[28:31]
	v_mfma_f32_16x16x32_bf16 v[24:27], v[148:151], v[188:191], v[24:27]
	v_mfma_f32_16x16x32_bf16 v[12:15], v[140:143], v[200:203], v[12:15]
	v_mfma_f32_16x16x32_bf16 v[8:11], v[148:151], v[200:203], v[8:11]
	v_mfma_f32_16x16x32_bf16 v[60:63], v[144:147], v[176:179], v[60:63]
	v_mfma_f32_16x16x32_bf16 v[56:59], v[152:155], v[176:179], v[56:59]
	v_mfma_f32_16x16x32_bf16 v[44:47], v[144:147], v[184:187], v[44:47]
	v_mfma_f32_16x16x32_bf16 v[40:43], v[152:155], v[184:187], v[40:43]
	v_mfma_f32_16x16x32_bf16 v[28:31], v[144:147], v[192:195], v[28:31]
	v_mfma_f32_16x16x32_bf16 v[24:27], v[152:155], v[192:195], v[24:27]
	v_mfma_f32_16x16x32_bf16 v[12:15], v[144:147], v[204:207], v[12:15]
	v_mfma_f32_16x16x32_bf16 v[8:11], v[152:155], v[204:207], v[8:11]
	v_mfma_f32_16x16x32_bf16 v[52:55], v[156:159], v[172:175], v[52:55]
	v_mfma_f32_16x16x32_bf16 v[48:51], v[164:167], v[172:175], v[48:51]
	v_mfma_f32_16x16x32_bf16 v[36:39], v[156:159], v[180:183], v[36:39]
	v_mfma_f32_16x16x32_bf16 v[32:35], v[164:167], v[180:183], v[32:35]
	v_mfma_f32_16x16x32_bf16 v[20:23], v[156:159], v[188:191], v[20:23]
	v_mfma_f32_16x16x32_bf16 v[16:19], v[164:167], v[188:191], v[16:19]
	v_mfma_f32_16x16x32_bf16 v[4:7], v[156:159], v[200:203], v[4:7]
	v_mfma_f32_16x16x32_bf16 v[0:3], v[164:167], v[200:203], v[0:3]
	v_mfma_f32_16x16x32_bf16 v[52:55], v[160:163], v[176:179], v[52:55]
	v_mfma_f32_16x16x32_bf16 v[48:51], v[168:171], v[176:179], v[48:51]
	v_mfma_f32_16x16x32_bf16 v[36:39], v[160:163], v[184:187], v[36:39]
	v_mfma_f32_16x16x32_bf16 v[32:35], v[168:171], v[184:187], v[32:35]
	v_mfma_f32_16x16x32_bf16 v[20:23], v[160:163], v[192:195], v[20:23]
	v_mfma_f32_16x16x32_bf16 v[16:19], v[168:171], v[192:195], v[16:19]
	v_mfma_f32_16x16x32_bf16 v[4:7], v[160:163], v[204:207], v[4:7]
	v_mfma_f32_16x16x32_bf16 v[0:3], v[168:171], v[204:207], v[0:3]
	s_setprio 0
	s_barrier
; #define PG8_STAGE(bufoff, gbase, voff) do { _Pragma("unroll") for (int _i = 0; _i < 2; ++_i) \
;         __builtin_amdgcn_global_load_lds((const unsigned*)((const char*)(gbase) + (voff)[_i]), (PG8_LAS unsigned*)(lds + (bufoff) + ldsw + _i * 8192), 16, 0, 0); } while (0)
; #define PG8_LDA(dst, b, h) do { _Pragma("unroll") for (int m = 0; m < 4; ++m) _Pragma("unroll") for (int k = 0; k < 2; ++k) dst[m][k] = *(const PG8_LAS bf16x8*)(lds + PG8_SA(b, h) + aoff + m * 2048 + k * 1024); } while (0)
; #define PG8_LDB(dst, b, h) do { _Pragma("unroll") for (int n = 0; n < 2; ++n) _Pragma("unroll") for (int k = 0; k < 2; ++k) dst[n][k] = *(const PG8_LAS bf16x8*)(lds + PG8_SB(b, h) + boff + n * 2048 + k * 1024); } while (0)
; #define PG8_MMA(ai, bj, At, Bt) do { __builtin_amdgcn_s_setprio(1); _Pragma("unroll") for (int m = 0; m < 4; ++m) _Pragma("unroll") for (int n = 0; n < 2; ++n) _Pragma("unroll") for (int k = 0; k < 2; ++k) \
;         acc[ai][bj][m][n] = mma16<Epi::F16>(Bt[n][k], At[m][k], acc[ai][bj][m][n]); __builtin_amdgcn_s_setprio(0); } while (0)
; #define PG8_WAIT_V(n) asm volatile("s_waitcnt vmcnt(" #n ")" ::: "memory")
; #define PG8_WAIT_L(n) asm volatile("s_waitcnt lgkmcnt(" #n ")" ::: "memory")
; #define PG8_BAR __builtin_amdgcn_s_barrier()
; #define PG8_SCHED __builtin_amdgcn_sched_barrier(0)
; template <class Epi, class Sched, bool ALIGN_EPI = false, bool SP2 = false>
; __device__ __forceinline__ void gemm_phase(PG8_LAS unsigned char* lds, const Gemm g, const Sched& S, const Epi& E) {
;     ...
;             PG8_LDB(B0, 1, 0); PG8_LDB(B1, 1, 1); PG8_SCHED; PG8_LDA(At, 1, 0); PG8_STAGE(PG8_SA(0, 1), a2 + hstep, voffA);
;             PG8_WAIT_V(8); PG8_WAIT_L(0); PG8_BAR; PG8_MMA(0, 0, At, B0); PG8_MMA(0, 1, At, B1); PG8_BAR; PG8_SCHED;
;             PG8_LDA(At, 1, 1); PG8_STAGE(PG8_SB(1, 0), b3, voffB); PG8_STAGE(PG8_SB(1, 1), b3 + hstep, voffB); PG8_STAGE(PG8_SA(1, 0), a3, voffA);
;             PG8_WAIT_V(8); PG8_WAIT_L(0); PG8_BAR; PG8_MMA(1, 0, At, B0); PG8_MMA(1, 1, At, B1); PG8_BAR; PG8_SCHED;
	s_add_i32 s82, 0, 0x18000
	v_add_u32_e32 v131, s82, v133
	s_add_i32 s84, 0, 0x1c000
	ds_read_b128 v[140:143], v131
	ds_read_b128 v[144:147], v131 offset:1024
	ds_read_b128 v[148:151], v131 offset:2048
	ds_read_b128 v[152:155], v131 offset:3072
	v_add_u32_e32 v131, s84, v133
	ds_read_b128 v[156:159], v131
	ds_read_b128 v[160:163], v131 offset:1024
	ds_read_b128 v[164:167], v131 offset:2048
	ds_read_b128 v[168:171], v131 offset:3072
	s_add_u32 s34, s34, s50
	s_addc_u32 s35, s35, s51
	s_mov_b32 m0, s11
	v_lshl_add_u64 v[224:225], s[34:35], 0, v[208:209]
	ds_read_b128 v[172:175], v199 offset:32768
	ds_read_b128 v[176:179], v199 offset:33792
	ds_read_b128 v[180:183], v199 offset:34816
	ds_read_b128 v[184:187], v199 offset:35840
	ds_read_b128 v[188:191], v199 offset:36864
	ds_read_b128 v[192:195], v199 offset:37888
	ds_read_b128 v[200:203], v199 offset:38912
	ds_read_b128 v[204:207], v199 offset:39936
	global_load_lds_dwordx4 v[224:225], off
	v_lshl_add_u64 v[224:225], s[34:35], 0, v[128:129]
	s_mov_b32 m0, s36
	s_nop 0
	global_load_lds_dwordx4 v[224:225], off
	s_waitcnt vmcnt(8)
	s_waitcnt lgkmcnt(0)
	s_barrier
	s_setprio 1
	s_waitcnt lgkmcnt(0)
	v_mfma_f32_16x16x32_bf16 v[120:123], v[140:143], v[172:175], v[120:123]
	v_mfma_f32_16x16x32_bf16 v[124:127], v[148:151], v[172:175], v[124:127]
	v_mfma_f32_16x16x32_bf16 v[108:111], v[140:143], v[180:183], v[108:111]
	v_mfma_f32_16x16x32_bf16 v[104:107], v[148:151], v[180:183], v[104:107]
	v_mfma_f32_16x16x32_bf16 v[92:95], v[140:143], v[188:191], v[92:95]
	v_mfma_f32_16x16x32_bf16 v[88:91], v[148:151], v[188:191], v[88:91]
	v_mfma_f32_16x16x32_bf16 v[76:79], v[140:143], v[200:203], v[76:79]
	v_mfma_f32_16x16x32_bf16 v[72:75], v[148:151], v[200:203], v[72:75]
	v_mfma_f32_16x16x32_bf16 v[120:123], v[144:147], v[176:179], v[120:123]
	v_mfma_f32_16x16x32_bf16 v[124:127], v[152:155], v[176:179], v[124:127]
	v_mfma_f32_16x16x32_bf16 v[108:111], v[144:147], v[184:187], v[108:111]
	v_mfma_f32_16x16x32_bf16 v[104:107], v[152:155], v[184:187], v[104:107]
	v_mfma_f32_16x16x32_bf16 v[92:95], v[144:147], v[192:195], v[92:95]
	v_mfma_f32_16x16x32_bf16 v[88:91], v[152:155], v[192:195], v[88:91]
	v_mfma_f32_16x16x32_bf16 v[76:79], v[144:147], v[204:207], v[76:79]
	v_mfma_f32_16x16x32_bf16 v[72:75], v[152:155], v[204:207], v[72:75]
	v_mfma_f32_16x16x32_bf16 v[116:119], v[156:159], v[172:175], v[116:119]
	v_mfma_f32_16x16x32_bf16 v[112:115], v[164:167], v[172:175], v[112:115]
	v_mfma_f32_16x16x32_bf16 v[100:103], v[156:159], v[180:183], v[100:103]
	v_mfma_f32_16x16x32_bf16 v[96:99], v[164:167], v[180:183], v[96:99]
	v_mfma_f32_16x16x32_bf16 v[84:87], v[156:159], v[188:191], v[84:87]
	v_mfma_f32_16x16x32_bf16 v[80:83], v[164:167], v[188:191], v[80:83]
	v_mfma_f32_16x16x32_bf16 v[68:71], v[156:159], v[200:203], v[68:71]
	v_mfma_f32_16x16x32_bf16 v[64:67], v[164:167], v[200:203], v[64:67]
	v_mfma_f32_16x16x32_bf16 v[116:119], v[160:163], v[176:179], v[116:119]
	v_mfma_f32_16x16x32_bf16 v[112:115], v[168:171], v[176:179], v[112:115]
	v_mfma_f32_16x16x32_bf16 v[100:103], v[160:163], v[184:187], v[100:103]
	v_mfma_f32_16x16x32_bf16 v[96:99], v[168:171], v[184:187], v[96:99]
	v_mfma_f32_16x16x32_bf16 v[84:87], v[160:163], v[192:195], v[84:87]
	v_mfma_f32_16x16x32_bf16 v[80:83], v[168:171], v[192:195], v[80:83]
	v_mfma_f32_16x16x32_bf16 v[68:71], v[160:163], v[204:207], v[68:71]
	v_mfma_f32_16x16x32_bf16 v[64:67], v[168:171], v[204:207], v[64:67]
	s_setprio 0
	s_barrier
	s_add_i32 s34, s82, s7
	v_lshl_add_u64 v[212:213], v[212:213], 0, s[20:21]
	s_mov_b32 m0, s34
	ds_read_b128 v[172:175], v199 offset:49152
	ds_read_b128 v[176:179], v199 offset:50176
	ds_read_b128 v[180:183], v199 offset:51200
	ds_read_b128 v[184:187], v199 offset:52224
	ds_read_b128 v[188:191], v199 offset:53248
	ds_read_b128 v[192:195], v199 offset:54272
	ds_read_b128 v[200:203], v199 offset:55296
	ds_read_b128 v[204:207], v199 offset:56320
	global_load_lds_dwordx4 v[212:213], off
	v_lshl_add_u64 v[212:213], v[214:215], 0, s[20:21]
	s_add_i32 m0, s34, 0x2000
	s_add_i32 s34, s84, s7
	global_load_lds_dwordx4 v[212:213], off
	v_lshl_add_u64 v[212:213], v[216:217], 0, s[20:21]
	s_mov_b32 m0, s34
	s_nop 0
	global_load_lds_dwordx4 v[212:213], off
	v_lshl_add_u64 v[212:213], v[218:219], 0, s[20:21]
	s_add_i32 m0, s34, 0x2000
	s_nop 0
	global_load_lds_dwordx4 v[212:213], off
	v_lshl_add_u64 v[212:213], v[220:221], 0, s[20:21]
	s_mov_b32 m0, s37
	s_nop 0
	global_load_lds_dwordx4 v[212:213], off
	v_lshl_add_u64 v[212:213], v[222:223], 0, s[20:21]
	s_mov_b32 m0, s38
	s_nop 0
	global_load_lds_dwordx4 v[212:213], off
	s_waitcnt vmcnt(8)
	s_waitcnt lgkmcnt(0)
	s_barrier
	s_setprio 1
	s_waitcnt lgkmcnt(0)
	v_mfma_f32_16x16x32_bf16 v[60:63], v[140:143], v[172:175], v[60:63]
	v_mfma_f32_16x16x32_bf16 v[56:59], v[148:151], v[172:175], v[56:59]
	v_mfma_f32_16x16x32_bf16 v[44:47], v[140:143], v[180:183], v[44:47]
	v_mfma_f32_16x16x32_bf16 v[40:43], v[148:151], v[180:183], v[40:43]
	v_mfma_f32_16x16x32_bf16 v[28:31], v[140:143], v[188:191], v[28:31]
	v_mfma_f32_16x16x32_bf16 v[24:27], v[148:151], v[188:191], v[24:27]
	v_mfma_f32_16x16x32_bf16 v[12:15], v[140:143], v[200:203], v[12:15]
	v_mfma_f32_16x16x32_bf16 v[8:11], v[148:151], v[200:203], v[8:11]
	v_mfma_f32_16x16x32_bf16 v[60:63], v[144:147], v[176:179], v[60:63]
	v_mfma_f32_16x16x32_bf16 v[56:59], v[152:155], v[176:179], v[56:59]
	v_mfma_f32_16x16x32_bf16 v[44:47], v[144:147], v[184:187], v[44:47]
	v_mfma_f32_16x16x32_bf16 v[40:43], v[152:155], v[184:187], v[40:43]
	v_mfma_f32_16x16x32_bf16 v[28:31], v[144:147], v[192:195], v[28:31]
	v_mfma_f32_16x16x32_bf16 v[24:27], v[152:155], v[192:195], v[24:27]
	v_mfma_f32_16x16x32_bf16 v[12:15], v[144:147], v[204:207], v[12:15]
	v_mfma_f32_16x16x32_bf16 v[8:11], v[152:155], v[204:207], v[8:11]
	v_mfma_f32_16x16x32_bf16 v[52:55], v[156:159], v[172:175], v[52:55]
	v_mfma_f32_16x16x32_bf16 v[48:51], v[164:167], v[172:175], v[48:51]
	v_mfma_f32_16x16x32_bf16 v[36:39], v[156:159], v[180:183], v[36:39]
	v_mfma_f32_16x16x32_bf16 v[32:35], v[164:167], v[180:183], v[32:35]
	v_mfma_f32_16x16x32_bf16 v[20:23], v[156:159], v[188:191], v[20:23]
	v_mfma_f32_16x16x32_bf16 v[16:19], v[164:167], v[188:191], v[16:19]
	v_mfma_f32_16x16x32_bf16 v[4:7], v[156:159], v[200:203], v[4:7]
	v_mfma_f32_16x16x32_bf16 v[0:3], v[164:167], v[200:203], v[0:3]
	v_mfma_f32_16x16x32_bf16 v[52:55], v[160:163], v[176:179], v[52:55]
	v_mfma_f32_16x16x32_bf16 v[48:51], v[168:171], v[176:179], v[48:51]
	v_mfma_f32_16x16x32_bf16 v[36:39], v[160:163], v[184:187], v[36:39]
	v_mfma_f32_16x16x32_bf16 v[32:35], v[168:171], v[184:187], v[32:35]
	v_mfma_f32_16x16x32_bf16 v[20:23], v[160:163], v[192:195], v[20:23]
	v_mfma_f32_16x16x32_bf16 v[16:19], v[168:171], v[192:195], v[16:19]
	v_mfma_f32_16x16x32_bf16 v[4:7], v[160:163], v[204:207], v[4:7]
	v_mfma_f32_16x16x32_bf16 v[0:3], v[168:171], v[204:207], v[0:3]
	s_setprio 0
	s_barrier
	s_add_u32 s30, s30, 0x100
	s_addc_u32 s31, s31, 0
	s_add_u32 s29, s29, 0x100
	s_addc_u32 s73, s73, 0
	s_cmp_ge_i32 s77, s39
	s_mov_b32 s34, s77
	s_cbranch_scc0 .LBB0_757

; #define PG8_STAGE(bufoff, gbase, voff) do { _Pragma("unroll") for (int _i = 0; _i < 2; ++_i) \
;         __builtin_amdgcn_global_load_lds((const unsigned*)((const char*)(gbase) + (voff)[_i]), (PG8_LAS unsigned*)(lds + (bufoff) + ldsw + _i * 8192), 16, 0, 0); } while (0)
; #define PG8_LDA(dst, b, h) do { _Pragma("unroll") for (int m = 0; m < 4; ++m) _Pragma("unroll") for (int k = 0; k < 2; ++k) dst[m][k] = *(const PG8_LAS bf16x8*)(lds + PG8_SA(b, h) + aoff + m * 2048 + k * 1024); } while (0)
; #define PG8_LDB(dst, b, h) do { _Pragma("unroll") for (int n = 0; n < 2; ++n) _Pragma("unroll") for (int k = 0; k < 2; ++k) dst[n][k] = *(const PG8_LAS bf16x8*)(lds + PG8_SB(b, h) + boff + n * 2048 + k * 1024); } while (0)
; #define PG8_MMA(ai, bj, At, Bt) do { __builtin_amdgcn_s_setprio(1); _Pragma("unroll") for (int m = 0; m < 4; ++m) _Pragma("unroll") for (int n = 0; n < 2; ++n) _Pragma("unroll") for (int k = 0; k < 2; ++k) \
;         acc[ai][bj][m][n] = mma16<Epi::F16>(Bt[n][k], At[m][k], acc[ai][bj][m][n]); __builtin_amdgcn_s_setprio(0); } while (0)
; #define PG8_WAIT_V(n) asm volatile("s_waitcnt vmcnt(" #n ")" ::: "memory")
; #define PG8_WAIT_L(n) asm volatile("s_waitcnt lgkmcnt(" #n ")" ::: "memory")
; #define PG8_BAR __builtin_amdgcn_s_barrier()
; #define PG8_SCHED __builtin_amdgcn_sched_barrier(0)
; template <class Epi, class Sched, bool ALIGN_EPI = false, bool SP2 = false>
; __device__ __forceinline__ void gemm_phase(PG8_LAS unsigned char* lds, const Gemm g, const Sched& S, const Epi& E) {
;     ...
;     f32x4 acc[2][2][4][2];
; #pragma unroll
;     for (int a = 0; a < 2; ++a)
; #pragma unroll
;         for (int b = 0; b < 2; ++b)
; #pragma unroll
;             for (int m = 0; m < 4; ++m)
; #pragma unroll
;                 for (int n = 0; n < 2; ++n) acc[a][b][m][n] = (f32x4){0.f, 0.f, 0.f, 0.f};
;     ...
;             if constexpr (SP2) {
;             PG8_LDB(B0, 0, 0); PG8_LDB(B1, 0, 1); PG8_SCHED; PG8_LDA(At, 0, 0); PG8_STAGE(PG8_SA(1, 1), a1 + hstep, voffA);
;             PG8_WAIT_V(8); PG8_WAIT_L(0); PG8_BAR; PG8_MMA(0, 0, At, B0); PG8_MMA(0, 1, At, B1); PG8_BAR; PG8_SCHED;
;             PG8_LDA(At, 0, 1); PG8_STAGE(PG8_SB(0, 0), b2, voffB); PG8_STAGE(PG8_SB(0, 1), b2 + hstep, voffB); PG8_STAGE(PG8_SA(0, 0), a2, voffA);
;             PG8_WAIT_V(8); PG8_WAIT_L(0); PG8_BAR; PG8_MMA(1, 0, At, B0); PG8_MMA(1, 1, At, B1); PG8_BAR; PG8_SCHED;
.Lpeel_k6:
	s_add_u32 s28, s28, 0x80
	s_addc_u32 s29, s29, 0
	s_add_u32 s34, s30, 0x100
	s_addc_u32 s35, s31, 0
	s_mov_b32 s30, 0
	s_add_i32 s43, s30, 2
	s_add_u32 s44, s28, 0x80
	s_addc_u32 s31, s29, 0
	s_add_i32 s68, 0, 0x10000
	s_cmp_eq_u32 s85, s30
	s_cselect_b32 s31, s1, s31
	s_cselect_b32 s30, s0, s44
	s_cselect_b32 s45, s67, s35
	s_cselect_b32 s44, s66, s34
	s_add_i32 s69, 0, 0x14000
	v_add_u32_e32 v160, s68, v170
	v_add_u32_e32 v168, s69, v170
	ds_read_b128 v[148:151], v160
	ds_read_b128 v[152:155], v160 offset:1024
	ds_read_b128 v[156:159], v160 offset:2048
	ds_read_b128 v[160:163], v160 offset:3072
	ds_read_b128 v[164:167], v168
	ds_read_b128 v[172:175], v168 offset:1024
	ds_read_b128 v[176:179], v168 offset:2048
	ds_read_b128 v[180:183], v168 offset:3072
	v_lshl_add_u64 v[168:169], s[28:29], 0, v[144:145]
	s_add_i32 m0, s72, 0xc000
	ds_read_b128 v[184:187], v171
	ds_read_b128 v[188:191], v171 offset:1024
	ds_read_b128 v[192:195], v171 offset:2048
	ds_read_b128 v[196:199], v171 offset:3072
	ds_read_b128 v[200:203], v171 offset:4096
	ds_read_b128 v[204:207], v171 offset:5120
	ds_read_b128 v[212:215], v171 offset:6144
	ds_read_b128 v[216:219], v171 offset:7168
	global_load_lds_dwordx4 v[168:169], off
	v_lshl_add_u64 v[168:169], s[28:29], 0, v[146:147]
	s_add_i32 m0, s72, 0xe000
	s_nop 0
	global_load_lds_dwordx4 v[168:169], off
	s_waitcnt vmcnt(8)
	s_waitcnt lgkmcnt(0)
	s_barrier
	s_setprio 1
	s_waitcnt lgkmcnt(0)
	v_mfma_f32_16x16x32_bf16 v[124:127], v[148:151], v[184:187], 0
	v_mfma_f32_16x16x32_bf16 v[120:123], v[156:159], v[184:187], 0
	v_mfma_f32_16x16x32_bf16 v[108:111], v[148:151], v[192:195], 0
	v_mfma_f32_16x16x32_bf16 v[104:107], v[156:159], v[192:195], 0
	v_mfma_f32_16x16x32_bf16 v[92:95], v[148:151], v[200:203], 0
	v_mfma_f32_16x16x32_bf16 v[88:91], v[156:159], v[200:203], 0
	v_mfma_f32_16x16x32_bf16 v[76:79], v[148:151], v[212:215], 0
	v_mfma_f32_16x16x32_bf16 v[72:75], v[156:159], v[212:215], 0
	v_mfma_f32_16x16x32_bf16 v[124:127], v[152:155], v[188:191], v[124:127]
	v_mfma_f32_16x16x32_bf16 v[120:123], v[160:163], v[188:191], v[120:123]
	v_mfma_f32_16x16x32_bf16 v[108:111], v[152:155], v[196:199], v[108:111]
	v_mfma_f32_16x16x32_bf16 v[104:107], v[160:163], v[196:199], v[104:107]
	v_mfma_f32_16x16x32_bf16 v[92:95], v[152:155], v[204:207], v[92:95]
	v_mfma_f32_16x16x32_bf16 v[88:91], v[160:163], v[204:207], v[88:91]
	v_mfma_f32_16x16x32_bf16 v[76:79], v[152:155], v[216:219], v[76:79]
	v_mfma_f32_16x16x32_bf16 v[72:75], v[160:163], v[216:219], v[72:75]
	v_mfma_f32_16x16x32_bf16 v[116:119], v[164:167], v[184:187], 0
	v_mfma_f32_16x16x32_bf16 v[112:115], v[176:179], v[184:187], 0
	v_mfma_f32_16x16x32_bf16 v[100:103], v[164:167], v[192:195], 0
	v_mfma_f32_16x16x32_bf16 v[96:99], v[176:179], v[192:195], 0
	v_mfma_f32_16x16x32_bf16 v[84:87], v[164:167], v[200:203], 0
	v_mfma_f32_16x16x32_bf16 v[80:83], v[176:179], v[200:203], 0
	v_mfma_f32_16x16x32_bf16 v[68:71], v[164:167], v[212:215], 0
	v_mfma_f32_16x16x32_bf16 v[64:67], v[176:179], v[212:215], 0
	v_mfma_f32_16x16x32_bf16 v[116:119], v[172:175], v[188:191], v[116:119]
	v_mfma_f32_16x16x32_bf16 v[112:115], v[180:183], v[188:191], v[112:115]
	v_mfma_f32_16x16x32_bf16 v[100:103], v[172:175], v[196:199], v[100:103]
	v_mfma_f32_16x16x32_bf16 v[96:99], v[180:183], v[196:199], v[96:99]
	v_mfma_f32_16x16x32_bf16 v[84:87], v[172:175], v[204:207], v[84:87]
	v_mfma_f32_16x16x32_bf16 v[80:83], v[180:183], v[204:207], v[80:83]
	v_mfma_f32_16x16x32_bf16 v[68:71], v[172:175], v[216:219], v[68:71]
	v_mfma_f32_16x16x32_bf16 v[64:67], v[180:183], v[216:219], v[64:67]
	s_setprio 0
	s_barrier
	s_add_i32 s68, s68, s71
	v_lshl_add_u64 v[168:169], s[44:45], 0, v[128:129]
	s_mov_b32 m0, s68
	ds_read_b128 v[184:187], v171 offset:16384
	ds_read_b128 v[188:191], v171 offset:17408
	ds_read_b128 v[192:195], v171 offset:18432
	ds_read_b128 v[196:199], v171 offset:19456
	ds_read_b128 v[200:203], v171 offset:20480
	ds_read_b128 v[204:207], v171 offset:21504
	ds_read_b128 v[212:215], v171 offset:22528
	ds_read_b128 v[216:219], v171 offset:23552
	global_load_lds_dwordx4 v[168:169], off
	s_add_i32 m0, s68, 0x2000
	v_lshl_add_u64 v[220:221], s[44:45], 0, v[130:131]
	s_add_u32 s44, s44, s50
	s_addc_u32 s45, s45, s51
	s_add_i32 s68, s69, s71
	global_load_lds_dwordx4 v[220:221], off
	v_lshl_add_u64 v[222:223], s[44:45], 0, v[128:129]
	s_mov_b32 m0, s68
	v_lshl_add_u64 v[224:225], s[44:45], 0, v[130:131]
	global_load_lds_dwordx4 v[222:223], off
	s_add_i32 m0, s68, 0x2000
	v_lshl_add_u64 v[226:227], s[30:31], 0, v[128:129]
	global_load_lds_dwordx4 v[224:225], off
	s_mov_b32 m0, s72
	v_lshl_add_u64 v[228:229], s[30:31], 0, v[130:131]
	global_load_lds_dwordx4 v[226:227], off
	s_mov_b32 m0, s73
	s_nop 0
	global_load_lds_dwordx4 v[228:229], off
	s_waitcnt vmcnt(8)
	s_waitcnt lgkmcnt(0)
	s_barrier
; #define PG8_STAGE(bufoff, gbase, voff) do { _Pragma("unroll") for (int _i = 0; _i < 2; ++_i) \
;         __builtin_amdgcn_global_load_lds((const unsigned*)((const char*)(gbase) + (voff)[_i]), (PG8_LAS unsigned*)(lds + (bufoff) + ldsw + _i * 8192), 16, 0, 0); } while (0)
; #define PG8_LDA(dst, b, h) do { _Pragma("unroll") for (int m = 0; m < 4; ++m) _Pragma("unroll") for (int k = 0; k < 2; ++k) dst[m][k] = *(const PG8_LAS bf16x8*)(lds + PG8_SA(b, h) + aoff + m * 2048 + k * 1024); } while (0)
; #define PG8_LDB(dst, b, h) do { _Pragma("unroll") for (int n = 0; n < 2; ++n) _Pragma("unroll") for (int k = 0; k < 2; ++k) dst[n][k] = *(const PG8_LAS bf16x8*)(lds + PG8_SB(b, h) + boff + n * 2048 + k * 1024); } while (0)
; #define PG8_MMA(ai, bj, At, Bt) do { __builtin_amdgcn_s_setprio(1); _Pragma("unroll") for (int m = 0; m < 4; ++m) _Pragma("unroll") for (int n = 0; n < 2; ++n) _Pragma("unroll") for (int k = 0; k < 2; ++k) \
;         acc[ai][bj][m][n] = mma16<Epi::F16>(Bt[n][k], At[m][k], acc[ai][bj][m][n]); __builtin_amdgcn_s_setprio(0); } while (0)
; #define PG8_WAIT_V(n) asm volatile("s_waitcnt vmcnt(" #n ")" ::: "memory")
; #define PG8_WAIT_L(n) asm volatile("s_waitcnt lgkmcnt(" #n ")" ::: "memory")
; #define PG8_BAR __builtin_amdgcn_s_barrier()
; #define PG8_SCHED __builtin_amdgcn_sched_barrier(0)
; template <class Epi, class Sched, bool ALIGN_EPI = false, bool SP2 = false>
; __device__ __forceinline__ void gemm_phase(PG8_LAS unsigned char* lds, const Gemm g, const Sched& S, const Epi& E) {
;     ...
;             if constexpr (SP2) {
;             PG8_LDB(B0, 0, 0); PG8_LDB(B1, 0, 1); PG8_SCHED; PG8_LDA(At, 0, 0); PG8_STAGE(PG8_SA(1, 1), a1 + hstep, voffA);
;             PG8_WAIT_V(8); PG8_WAIT_L(0); PG8_BAR; PG8_MMA(0, 0, At, B0); PG8_MMA(0, 1, At, B1); PG8_BAR; PG8_SCHED;
;             PG8_LDA(At, 0, 1); PG8_STAGE(PG8_SB(0, 0), b2, voffB); PG8_STAGE(PG8_SB(0, 1), b2 + hstep, voffB); PG8_STAGE(PG8_SA(0, 0), a2, voffA);
;             PG8_WAIT_V(8); PG8_WAIT_L(0); PG8_BAR; PG8_MMA(1, 0, At, B0); PG8_MMA(1, 1, At, B1); PG8_BAR; PG8_SCHED;
;             PG8_LDB(B0, 1, 0); PG8_LDB(B1, 1, 1); PG8_SCHED; PG8_LDA(At, 1, 0); PG8_STAGE(PG8_SA(0, 1), a2 + hstep, voffA);
;             PG8_WAIT_V(8); PG8_WAIT_L(0); PG8_BAR; PG8_MMA(0, 0, At, B0); PG8_MMA(0, 1, At, B1); PG8_BAR; PG8_SCHED;
	s_setprio 1
	s_waitcnt lgkmcnt(0)
	v_mfma_f32_16x16x32_bf16 v[60:63], v[148:151], v[184:187], 0
	v_mfma_f32_16x16x32_bf16 v[56:59], v[156:159], v[184:187], 0
	v_mfma_f32_16x16x32_bf16 v[44:47], v[148:151], v[192:195], 0
	v_mfma_f32_16x16x32_bf16 v[40:43], v[156:159], v[192:195], 0
	v_mfma_f32_16x16x32_bf16 v[28:31], v[148:151], v[200:203], 0
	v_mfma_f32_16x16x32_bf16 v[24:27], v[156:159], v[200:203], 0
	v_mfma_f32_16x16x32_bf16 v[12:15], v[148:151], v[212:215], 0
	v_mfma_f32_16x16x32_bf16 v[8:11], v[156:159], v[212:215], 0
	v_mfma_f32_16x16x32_bf16 v[60:63], v[152:155], v[188:191], v[60:63]
	v_mfma_f32_16x16x32_bf16 v[56:59], v[160:163], v[188:191], v[56:59]
	v_mfma_f32_16x16x32_bf16 v[44:47], v[152:155], v[196:199], v[44:47]
	v_mfma_f32_16x16x32_bf16 v[40:43], v[160:163], v[196:199], v[40:43]
	v_mfma_f32_16x16x32_bf16 v[28:31], v[152:155], v[204:207], v[28:31]
	v_mfma_f32_16x16x32_bf16 v[24:27], v[160:163], v[204:207], v[24:27]
	v_mfma_f32_16x16x32_bf16 v[12:15], v[152:155], v[216:219], v[12:15]
	v_mfma_f32_16x16x32_bf16 v[8:11], v[160:163], v[216:219], v[8:11]
	v_mfma_f32_16x16x32_bf16 v[52:55], v[164:167], v[184:187], 0
	v_mfma_f32_16x16x32_bf16 v[48:51], v[176:179], v[184:187], 0
	v_mfma_f32_16x16x32_bf16 v[36:39], v[164:167], v[192:195], 0
	v_mfma_f32_16x16x32_bf16 v[32:35], v[176:179], v[192:195], 0
	v_mfma_f32_16x16x32_bf16 v[20:23], v[164:167], v[200:203], 0
	v_mfma_f32_16x16x32_bf16 v[16:19], v[176:179], v[200:203], 0
	v_mfma_f32_16x16x32_bf16 v[4:7], v[164:167], v[212:215], 0
	v_mfma_f32_16x16x32_bf16 v[0:3], v[176:179], v[212:215], 0
	v_mfma_f32_16x16x32_bf16 v[52:55], v[172:175], v[188:191], v[52:55]
	v_mfma_f32_16x16x32_bf16 v[48:51], v[180:183], v[188:191], v[48:51]
	v_mfma_f32_16x16x32_bf16 v[36:39], v[172:175], v[196:199], v[36:39]
	v_mfma_f32_16x16x32_bf16 v[32:35], v[180:183], v[196:199], v[32:35]
	v_mfma_f32_16x16x32_bf16 v[20:23], v[172:175], v[204:207], v[20:23]
	v_mfma_f32_16x16x32_bf16 v[16:19], v[180:183], v[204:207], v[16:19]
	v_mfma_f32_16x16x32_bf16 v[4:7], v[172:175], v[216:219], v[4:7]
	v_mfma_f32_16x16x32_bf16 v[0:3], v[180:183], v[216:219], v[0:3]
	s_setprio 0
	s_barrier
	s_add_i32 s44, 0, 0x18000
	s_add_i32 s45, 0, 0x1c000
	v_add_u32_e32 v160, s44, v170
	v_add_u32_e32 v180, s45, v170
	ds_read_b128 v[148:151], v160
	ds_read_b128 v[152:155], v160 offset:1024
	ds_read_b128 v[156:159], v160 offset:2048
	ds_read_b128 v[160:163], v160 offset:3072
	ds_read_b128 v[164:167], v180
	ds_read_b128 v[172:175], v180 offset:1024
	ds_read_b128 v[176:179], v180 offset:2048
	ds_read_b128 v[180:183], v180 offset:3072
	s_add_u32 s30, s30, s50
	s_addc_u32 s31, s31, s51
	s_mov_b32 m0, s7
	v_lshl_add_u64 v[230:231], s[30:31], 0, v[128:129]
	ds_read_b128 v[184:187], v171 offset:32768
	ds_read_b128 v[188:191], v171 offset:33792
	ds_read_b128 v[192:195], v171 offset:34816
	ds_read_b128 v[196:199], v171 offset:35840
	ds_read_b128 v[200:203], v171 offset:36864
	ds_read_b128 v[204:207], v171 offset:37888
	ds_read_b128 v[212:215], v171 offset:38912
	ds_read_b128 v[216:219], v171 offset:39936
	global_load_lds_dwordx4 v[230:231], off
	v_lshl_add_u64 v[230:231], s[30:31], 0, v[130:131]
	s_mov_b32 m0, s8
	s_nop 0
	global_load_lds_dwordx4 v[230:231], off
	s_waitcnt vmcnt(8)
	s_waitcnt lgkmcnt(0)
	s_barrier
	s_setprio 1
	s_waitcnt lgkmcnt(0)
	v_mfma_f32_16x16x32_bf16 v[124:127], v[148:151], v[184:187], v[124:127]
	v_mfma_f32_16x16x32_bf16 v[120:123], v[156:159], v[184:187], v[120:123]
	v_mfma_f32_16x16x32_bf16 v[108:111], v[148:151], v[192:195], v[108:111]
	v_mfma_f32_16x16x32_bf16 v[104:107], v[156:159], v[192:195], v[104:107]
	v_mfma_f32_16x16x32_bf16 v[92:95], v[148:151], v[200:203], v[92:95]
	v_mfma_f32_16x16x32_bf16 v[88:91], v[156:159], v[200:203], v[88:91]
	v_mfma_f32_16x16x32_bf16 v[76:79], v[148:151], v[212:215], v[76:79]
	v_mfma_f32_16x16x32_bf16 v[72:75], v[156:159], v[212:215], v[72:75]
	v_mfma_f32_16x16x32_bf16 v[124:127], v[152:155], v[188:191], v[124:127]
	v_mfma_f32_16x16x32_bf16 v[120:123], v[160:163], v[188:191], v[120:123]
	v_mfma_f32_16x16x32_bf16 v[108:111], v[152:155], v[196:199], v[108:111]
	v_mfma_f32_16x16x32_bf16 v[104:107], v[160:163], v[196:199], v[104:107]
	v_mfma_f32_16x16x32_bf16 v[92:95], v[152:155], v[204:207], v[92:95]
	v_mfma_f32_16x16x32_bf16 v[88:91], v[160:163], v[204:207], v[88:91]
	v_mfma_f32_16x16x32_bf16 v[76:79], v[152:155], v[216:219], v[76:79]
	v_mfma_f32_16x16x32_bf16 v[72:75], v[160:163], v[216:219], v[72:75]
	v_mfma_f32_16x16x32_bf16 v[116:119], v[164:167], v[184:187], v[116:119]
	v_mfma_f32_16x16x32_bf16 v[112:115], v[176:179], v[184:187], v[112:115]
	v_mfma_f32_16x16x32_bf16 v[100:103], v[164:167], v[192:195], v[100:103]
	v_mfma_f32_16x16x32_bf16 v[96:99], v[176:179], v[192:195], v[96:99]
	v_mfma_f32_16x16x32_bf16 v[84:87], v[164:167], v[200:203], v[84:87]
	v_mfma_f32_16x16x32_bf16 v[80:83], v[176:179], v[200:203], v[80:83]
	v_mfma_f32_16x16x32_bf16 v[68:71], v[164:167], v[212:215], v[68:71]
	v_mfma_f32_16x16x32_bf16 v[64:67], v[176:179], v[212:215], v[64:67]
	v_mfma_f32_16x16x32_bf16 v[116:119], v[172:175], v[188:191], v[116:119]
	v_mfma_f32_16x16x32_bf16 v[112:115], v[180:183], v[188:191], v[112:115]
	v_mfma_f32_16x16x32_bf16 v[100:103], v[172:175], v[196:199], v[100:103]
	v_mfma_f32_16x16x32_bf16 v[96:99], v[180:183], v[196:199], v[96:99]
	v_mfma_f32_16x16x32_bf16 v[84:87], v[172:175], v[204:207], v[84:87]
	v_mfma_f32_16x16x32_bf16 v[80:83], v[180:183], v[204:207], v[80:83]
	v_mfma_f32_16x16x32_bf16 v[68:71], v[172:175], v[216:219], v[68:71]
	v_mfma_f32_16x16x32_bf16 v[64:67], v[180:183], v[216:219], v[64:67]
	s_setprio 0
	s_barrier
; #define PG8_STAGE(bufoff, gbase, voff) do { _Pragma("unroll") for (int _i = 0; _i < 2; ++_i) \
;         __builtin_amdgcn_global_load_lds((const unsigned*)((const char*)(gbase) + (voff)[_i]), (PG8_LAS unsigned*)(lds + (bufoff) + ldsw + _i * 8192), 16, 0, 0); } while (0)
; #define PG8_LDA(dst, b, h) do { _Pragma("unroll") for (int m = 0; m < 4; ++m) _Pragma("unroll") for (int k = 0; k < 2; ++k) dst[m][k] = *(const PG8_LAS bf16x8*)(lds + PG8_SA(b, h) + aoff + m * 2048 + k * 1024); } while (0)
; template <class Epi, class Sched, bool ALIGN_EPI = false, bool SP2 = false>
; __device__ __forceinline__ void gemm_phase(PG8_LAS unsigned char* lds, const Gemm g, const Sched& S, const Epi& E) {
;     ...
;         const bool has_next = S.next(ui + 1, nxt);
;         const char* nA = has_next ? (const char*)g.A + (size_t)nxt.pm * tstep : cA; const char* nB = has_next ? (const char*)g.Bt + (size_t)nxt.pn * tstep : cB;
;         for (int t = 0; t < nt; t += 2) {
;             const bool last = (t == nt - 2);
;             const char* a1 = cA + (size_t)(t + 1) * kstep;
;             const char* a2 = last ? nA : cA + (size_t)(t + 2) * kstep; const char* b2 = last ? nB : cB + (size_t)(t + 2) * kstep;
;             const char* a3 = a2 + kstep; const char* b3 = b2 + kstep;
;             if (last && has_next) S.a_ready(nxt);
;             if constexpr (SP2) {
;             PG8_LDB(B0, 0, 0); PG8_LDB(B1, 0, 1); PG8_SCHED; PG8_LDA(At, 0, 0); PG8_STAGE(PG8_SA(1, 1), a1 + hstep, voffA);
;             PG8_WAIT_V(8); PG8_WAIT_L(0); PG8_BAR; PG8_MMA(0, 0, At, B0); PG8_MMA(0, 1, At, B1); PG8_BAR; PG8_SCHED;
;             PG8_LDA(At, 0, 1); PG8_STAGE(PG8_SB(0, 0), b2, voffB); PG8_STAGE(PG8_SB(0, 1), b2 + hstep, voffB); PG8_STAGE(PG8_SA(0, 0), a2, voffA);
;             PG8_WAIT_V(8); PG8_WAIT_L(0); PG8_BAR; PG8_MMA(1, 0, At, B0); PG8_MMA(1, 1, At, B1); PG8_BAR; PG8_SCHED;
;             PG8_LDB(B0, 1, 0); PG8_LDB(B1, 1, 1); PG8_SCHED; PG8_LDA(At, 1, 0); PG8_STAGE(PG8_SA(0, 1), a2 + hstep, voffA);
;             PG8_WAIT_V(8); PG8_WAIT_L(0); PG8_BAR; PG8_MMA(0, 0, At, B0); PG8_MMA(0, 1, At, B1); PG8_BAR; PG8_SCHED;
;             PG8_LDA(At, 1, 1); PG8_STAGE(PG8_SB(1, 0), b3, voffB); PG8_STAGE(PG8_SB(1, 1), b3 + hstep, voffB); PG8_STAGE(PG8_SA(1, 0), a3, voffA);
;             PG8_WAIT_V(8); PG8_WAIT_L(0); PG8_BAR; PG8_MMA(1, 0, At, B0); PG8_MMA(1, 1, At, B1); PG8_BAR; PG8_SCHED;
	s_add_i32 s30, s44, s71
	v_lshl_add_u64 v[168:169], v[168:169], 0, s[20:21]
	s_mov_b32 m0, s30
	ds_read_b128 v[184:187], v171 offset:49152
	ds_read_b128 v[188:191], v171 offset:50176
	ds_read_b128 v[192:195], v171 offset:51200
	ds_read_b128 v[196:199], v171 offset:52224
	ds_read_b128 v[200:203], v171 offset:53248
	ds_read_b128 v[204:207], v171 offset:54272
	ds_read_b128 v[212:215], v171 offset:55296
	ds_read_b128 v[216:219], v171 offset:56320
	global_load_lds_dwordx4 v[168:169], off
	v_lshl_add_u64 v[168:169], v[220:221], 0, s[20:21]
	s_add_i32 m0, s30, 0x2000
	s_add_i32 s30, s45, s71
	global_load_lds_dwordx4 v[168:169], off
	v_lshl_add_u64 v[168:169], v[222:223], 0, s[20:21]
	s_mov_b32 m0, s30
	s_nop 0
	global_load_lds_dwordx4 v[168:169], off
	v_lshl_add_u64 v[168:169], v[224:225], 0, s[20:21]
	s_add_i32 m0, s30, 0x2000
	s_nop 0
	global_load_lds_dwordx4 v[168:169], off
	v_lshl_add_u64 v[168:169], v[226:227], 0, s[20:21]
	s_mov_b32 m0, s9
	s_nop 0
	global_load_lds_dwordx4 v[168:169], off
	v_lshl_add_u64 v[168:169], v[228:229], 0, s[20:21]
	s_mov_b32 m0, s84
	s_nop 0
	global_load_lds_dwordx4 v[168:169], off
	s_waitcnt vmcnt(8)
	s_waitcnt lgkmcnt(0)
	s_barrier
	s_setprio 1
	s_waitcnt lgkmcnt(0)
	v_mfma_f32_16x16x32_bf16 v[60:63], v[148:151], v[184:187], v[60:63]
	v_mfma_f32_16x16x32_bf16 v[56:59], v[156:159], v[184:187], v[56:59]
	v_mfma_f32_16x16x32_bf16 v[44:47], v[148:151], v[192:195], v[44:47]
	v_mfma_f32_16x16x32_bf16 v[40:43], v[156:159], v[192:195], v[40:43]
	v_mfma_f32_16x16x32_bf16 v[28:31], v[148:151], v[200:203], v[28:31]
	v_mfma_f32_16x16x32_bf16 v[24:27], v[156:159], v[200:203], v[24:27]
	v_mfma_f32_16x16x32_bf16 v[12:15], v[148:151], v[212:215], v[12:15]
	v_mfma_f32_16x16x32_bf16 v[8:11], v[156:159], v[212:215], v[8:11]
	v_mfma_f32_16x16x32_bf16 v[60:63], v[152:155], v[188:191], v[60:63]
	v_mfma_f32_16x16x32_bf16 v[56:59], v[160:163], v[188:191], v[56:59]
	v_mfma_f32_16x16x32_bf16 v[44:47], v[152:155], v[196:199], v[44:47]
	v_mfma_f32_16x16x32_bf16 v[40:43], v[160:163], v[196:199], v[40:43]
	v_mfma_f32_16x16x32_bf16 v[28:31], v[152:155], v[204:207], v[28:31]
	v_mfma_f32_16x16x32_bf16 v[24:27], v[160:163], v[204:207], v[24:27]
	v_mfma_f32_16x16x32_bf16 v[12:15], v[152:155], v[216:219], v[12:15]
	v_mfma_f32_16x16x32_bf16 v[8:11], v[160:163], v[216:219], v[8:11]
	v_mfma_f32_16x16x32_bf16 v[52:55], v[164:167], v[184:187], v[52:55]
	v_mfma_f32_16x16x32_bf16 v[48:51], v[176:179], v[184:187], v[48:51]
	v_mfma_f32_16x16x32_bf16 v[36:39], v[164:167], v[192:195], v[36:39]
	v_mfma_f32_16x16x32_bf16 v[32:35], v[176:179], v[192:195], v[32:35]
	v_mfma_f32_16x16x32_bf16 v[20:23], v[164:167], v[200:203], v[20:23]
	v_mfma_f32_16x16x32_bf16 v[16:19], v[176:179], v[200:203], v[16:19]
	v_mfma_f32_16x16x32_bf16 v[4:7], v[164:167], v[212:215], v[4:7]
	v_mfma_f32_16x16x32_bf16 v[0:3], v[176:179], v[212:215], v[0:3]
	v_mfma_f32_16x16x32_bf16 v[52:55], v[172:175], v[188:191], v[52:55]
	v_mfma_f32_16x16x32_bf16 v[48:51], v[180:183], v[188:191], v[48:51]
	v_mfma_f32_16x16x32_bf16 v[36:39], v[172:175], v[196:199], v[36:39]
	v_mfma_f32_16x16x32_bf16 v[32:35], v[180:183], v[196:199], v[32:35]
	v_mfma_f32_16x16x32_bf16 v[20:23], v[172:175], v[204:207], v[20:23]
	v_mfma_f32_16x16x32_bf16 v[16:19], v[180:183], v[204:207], v[16:19]
	v_mfma_f32_16x16x32_bf16 v[4:7], v[172:175], v[216:219], v[4:7]
	v_mfma_f32_16x16x32_bf16 v[0:3], v[180:183], v[216:219], v[0:3]
	s_setprio 0
	s_barrier
	s_add_u32 s28, s28, 0x100
	s_addc_u32 s29, s29, 0
	s_add_u32 s34, s34, 0x100
	s_addc_u32 s35, s35, 0
	s_cmp_ge_i32 s43, s96
	s_mov_b32 s30, s43
	s_cbranch_scc0 .LBB0_901
	s_branch .LBB0_902
.LBB0_901:
	s_add_i32 s43, s30, 2
	s_add_u32 s44, s28, 0x80
	s_addc_u32 s31, s29, 0
	s_add_i32 s68, 0, 0x10000
	s_cmp_eq_u32 s85, s30
	s_cselect_b32 s31, s1, s31
	s_cselect_b32 s30, s0, s44
	s_cselect_b32 s45, s67, s35
	s_cselect_b32 s44, s66, s34
	s_add_i32 s69, 0, 0x14000
	v_add_u32_e32 v160, s68, v170
	v_add_u32_e32 v168, s69, v170
	ds_read_b128 v[148:151], v160
	ds_read_b128 v[152:155], v160 offset:1024
	ds_read_b128 v[156:159], v160 offset:2048
	ds_read_b128 v[160:163], v160 offset:3072
	ds_read_b128 v[164:167], v168
	ds_read_b128 v[172:175], v168 offset:1024
	ds_read_b128 v[176:179], v168 offset:2048
	ds_read_b128 v[180:183], v168 offset:3072
	v_lshl_add_u64 v[168:169], s[28:29], 0, v[144:145]
	s_add_i32 m0, s72, 0xc000
	ds_read_b128 v[184:187], v171
	ds_read_b128 v[188:191], v171 offset:1024
	ds_read_b128 v[192:195], v171 offset:2048
	ds_read_b128 v[196:199], v171 offset:3072
	ds_read_b128 v[200:203], v171 offset:4096
	ds_read_b128 v[204:207], v171 offset:5120
	ds_read_b128 v[212:215], v171 offset:6144
	ds_read_b128 v[216:219], v171 offset:7168
	global_load_lds_dwordx4 v[168:169], off
	v_lshl_add_u64 v[168:169], s[28:29], 0, v[146:147]
	s_add_i32 m0, s72, 0xe000
	s_nop 0
	global_load_lds_dwordx4 v[168:169], off
	s_waitcnt vmcnt(8)
	s_waitcnt lgkmcnt(0)
	s_barrier
; #define PG8_STAGE(bufoff, gbase, voff) do { _Pragma("unroll") for (int _i = 0; _i < 2; ++_i) \
;         __builtin_amdgcn_global_load_lds((const unsigned*)((const char*)(gbase) + (voff)[_i]), (PG8_LAS unsigned*)(lds + (bufoff) + ldsw + _i * 8192), 16, 0, 0); } while (0)
; #define PG8_LDA(dst, b, h) do { _Pragma("unroll") for (int m = 0; m < 4; ++m) _Pragma("unroll") for (int k = 0; k < 2; ++k) dst[m][k] = *(const PG8_LAS bf16x8*)(lds + PG8_SA(b, h) + aoff + m * 2048 + k * 1024); } while (0)
; #define PG8_LDB(dst, b, h) do { _Pragma("unroll") for (int n = 0; n < 2; ++n) _Pragma("unroll") for (int k = 0; k < 2; ++k) dst[n][k] = *(const PG8_LAS bf16x8*)(lds + PG8_SB(b, h) + boff + n * 2048 + k * 1024); } while (0)
; #define PG8_MMA(ai, bj, At, Bt) do { __builtin_amdgcn_s_setprio(1); _Pragma("unroll") for (int m = 0; m < 4; ++m) _Pragma("unroll") for (int n = 0; n < 2; ++n) _Pragma("unroll") for (int k = 0; k < 2; ++k) \
;         acc[ai][bj][m][n] = mma16<Epi::F16>(Bt[n][k], At[m][k], acc[ai][bj][m][n]); __builtin_amdgcn_s_setprio(0); } while (0)
; #define PG8_WAIT_V(n) asm volatile("s_waitcnt vmcnt(" #n ")" ::: "memory")
; #define PG8_WAIT_L(n) asm volatile("s_waitcnt lgkmcnt(" #n ")" ::: "memory")
; #define PG8_BAR __builtin_amdgcn_s_barrier()
; #define PG8_SCHED __builtin_amdgcn_sched_barrier(0)
; template <class Epi, class Sched, bool ALIGN_EPI = false, bool SP2 = false>
; __device__ __forceinline__ void gemm_phase(PG8_LAS unsigned char* lds, const Gemm g, const Sched& S, const Epi& E) {
;     ...
;             if constexpr (SP2) {
;             PG8_LDB(B0, 0, 0); PG8_LDB(B1, 0, 1); PG8_SCHED; PG8_LDA(At, 0, 0); PG8_STAGE(PG8_SA(1, 1), a1 + hstep, voffA);
;             PG8_WAIT_V(8); PG8_WAIT_L(0); PG8_BAR; PG8_MMA(0, 0, At, B0); PG8_MMA(0, 1, At, B1); PG8_BAR; PG8_SCHED;
;             PG8_LDA(At, 0, 1); PG8_STAGE(PG8_SB(0, 0), b2, voffB); PG8_STAGE(PG8_SB(0, 1), b2 + hstep, voffB); PG8_STAGE(PG8_SA(0, 0), a2, voffA);
;             PG8_WAIT_V(8); PG8_WAIT_L(0); PG8_BAR; PG8_MMA(1, 0, At, B0); PG8_MMA(1, 1, At, B1); PG8_BAR; PG8_SCHED;
	s_setprio 1
	s_waitcnt lgkmcnt(0)
	v_mfma_f32_16x16x32_bf16 v[124:127], v[148:151], v[184:187], v[124:127]
	v_mfma_f32_16x16x32_bf16 v[120:123], v[156:159], v[184:187], v[120:123]
	v_mfma_f32_16x16x32_bf16 v[108:111], v[148:151], v[192:195], v[108:111]
	v_mfma_f32_16x16x32_bf16 v[104:107], v[156:159], v[192:195], v[104:107]
	v_mfma_f32_16x16x32_bf16 v[92:95], v[148:151], v[200:203], v[92:95]
	v_mfma_f32_16x16x32_bf16 v[88:91], v[156:159], v[200:203], v[88:91]
	v_mfma_f32_16x16x32_bf16 v[76:79], v[148:151], v[212:215], v[76:79]
	v_mfma_f32_16x16x32_bf16 v[72:75], v[156:159], v[212:215], v[72:75]
	v_mfma_f32_16x16x32_bf16 v[124:127], v[152:155], v[188:191], v[124:127]
	v_mfma_f32_16x16x32_bf16 v[120:123], v[160:163], v[188:191], v[120:123]
	v_mfma_f32_16x16x32_bf16 v[108:111], v[152:155], v[196:199], v[108:111]
	v_mfma_f32_16x16x32_bf16 v[104:107], v[160:163], v[196:199], v[104:107]
	v_mfma_f32_16x16x32_bf16 v[92:95], v[152:155], v[204:207], v[92:95]
	v_mfma_f32_16x16x32_bf16 v[88:91], v[160:163], v[204:207], v[88:91]
	v_mfma_f32_16x16x32_bf16 v[76:79], v[152:155], v[216:219], v[76:79]
	v_mfma_f32_16x16x32_bf16 v[72:75], v[160:163], v[216:219], v[72:75]
	v_mfma_f32_16x16x32_bf16 v[116:119], v[164:167], v[184:187], v[116:119]
	v_mfma_f32_16x16x32_bf16 v[112:115], v[176:179], v[184:187], v[112:115]
	v_mfma_f32_16x16x32_bf16 v[100:103], v[164:167], v[192:195], v[100:103]
	v_mfma_f32_16x16x32_bf16 v[96:99], v[176:179], v[192:195], v[96:99]
	v_mfma_f32_16x16x32_bf16 v[84:87], v[164:167], v[200:203], v[84:87]
	v_mfma_f32_16x16x32_bf16 v[80:83], v[176:179], v[200:203], v[80:83]
	v_mfma_f32_16x16x32_bf16 v[68:71], v[164:167], v[212:215], v[68:71]
	v_mfma_f32_16x16x32_bf16 v[64:67], v[176:179], v[212:215], v[64:67]
	v_mfma_f32_16x16x32_bf16 v[116:119], v[172:175], v[188:191], v[116:119]
	v_mfma_f32_16x16x32_bf16 v[112:115], v[180:183], v[188:191], v[112:115]
	v_mfma_f32_16x16x32_bf16 v[100:103], v[172:175], v[196:199], v[100:103]
	v_mfma_f32_16x16x32_bf16 v[96:99], v[180:183], v[196:199], v[96:99]
	v_mfma_f32_16x16x32_bf16 v[84:87], v[172:175], v[204:207], v[84:87]
	v_mfma_f32_16x16x32_bf16 v[80:83], v[180:183], v[204:207], v[80:83]
	v_mfma_f32_16x16x32_bf16 v[68:71], v[172:175], v[216:219], v[68:71]
	v_mfma_f32_16x16x32_bf16 v[64:67], v[180:183], v[216:219], v[64:67]
	s_setprio 0
	s_barrier
	s_add_i32 s68, s68, s71
	v_lshl_add_u64 v[168:169], s[44:45], 0, v[128:129]
	s_mov_b32 m0, s68
	ds_read_b128 v[184:187], v171 offset:16384
	ds_read_b128 v[188:191], v171 offset:17408
	ds_read_b128 v[192:195], v171 offset:18432
	ds_read_b128 v[196:199], v171 offset:19456
	ds_read_b128 v[200:203], v171 offset:20480
	ds_read_b128 v[204:207], v171 offset:21504
	ds_read_b128 v[212:215], v171 offset:22528
	ds_read_b128 v[216:219], v171 offset:23552
	global_load_lds_dwordx4 v[168:169], off
	s_add_i32 m0, s68, 0x2000
	v_lshl_add_u64 v[220:221], s[44:45], 0, v[130:131]
	s_add_u32 s44, s44, s50
	s_addc_u32 s45, s45, s51
	s_add_i32 s68, s69, s71
	global_load_lds_dwordx4 v[220:221], off
	v_lshl_add_u64 v[222:223], s[44:45], 0, v[128:129]
	s_mov_b32 m0, s68
	v_lshl_add_u64 v[224:225], s[44:45], 0, v[130:131]
	global_load_lds_dwordx4 v[222:223], off
	s_add_i32 m0, s68, 0x2000
	v_lshl_add_u64 v[226:227], s[30:31], 0, v[128:129]
	global_load_lds_dwordx4 v[224:225], off
	s_mov_b32 m0, s72
	v_lshl_add_u64 v[228:229], s[30:31], 0, v[130:131]
	global_load_lds_dwordx4 v[226:227], off
	s_mov_b32 m0, s73
	s_nop 0
	global_load_lds_dwordx4 v[228:229], off
	s_waitcnt vmcnt(8)
	s_waitcnt lgkmcnt(0)
	s_barrier
	s_setprio 1
	s_waitcnt lgkmcnt(0)
	v_mfma_f32_16x16x32_bf16 v[60:63], v[148:151], v[184:187], v[60:63]
	v_mfma_f32_16x16x32_bf16 v[56:59], v[156:159], v[184:187], v[56:59]
	v_mfma_f32_16x16x32_bf16 v[44:47], v[148:151], v[192:195], v[44:47]
	v_mfma_f32_16x16x32_bf16 v[40:43], v[156:159], v[192:195], v[40:43]
	v_mfma_f32_16x16x32_bf16 v[28:31], v[148:151], v[200:203], v[28:31]
	v_mfma_f32_16x16x32_bf16 v[24:27], v[156:159], v[200:203], v[24:27]
	v_mfma_f32_16x16x32_bf16 v[12:15], v[148:151], v[212:215], v[12:15]
	v_mfma_f32_16x16x32_bf16 v[8:11], v[156:159], v[212:215], v[8:11]
	v_mfma_f32_16x16x32_bf16 v[60:63], v[152:155], v[188:191], v[60:63]
	v_mfma_f32_16x16x32_bf16 v[56:59], v[160:163], v[188:191], v[56:59]
	v_mfma_f32_16x16x32_bf16 v[44:47], v[152:155], v[196:199], v[44:47]
	v_mfma_f32_16x16x32_bf16 v[40:43], v[160:163], v[196:199], v[40:43]
	v_mfma_f32_16x16x32_bf16 v[28:31], v[152:155], v[204:207], v[28:31]
	v_mfma_f32_16x16x32_bf16 v[24:27], v[160:163], v[204:207], v[24:27]
	v_mfma_f32_16x16x32_bf16 v[12:15], v[152:155], v[216:219], v[12:15]
	v_mfma_f32_16x16x32_bf16 v[8:11], v[160:163], v[216:219], v[8:11]
	v_mfma_f32_16x16x32_bf16 v[52:55], v[164:167], v[184:187], v[52:55]
	v_mfma_f32_16x16x32_bf16 v[48:51], v[176:179], v[184:187], v[48:51]
	v_mfma_f32_16x16x32_bf16 v[36:39], v[164:167], v[192:195], v[36:39]
	v_mfma_f32_16x16x32_bf16 v[32:35], v[176:179], v[192:195], v[32:35]
	v_mfma_f32_16x16x32_bf16 v[20:23], v[164:167], v[200:203], v[20:23]
	v_mfma_f32_16x16x32_bf16 v[16:19], v[176:179], v[200:203], v[16:19]
	v_mfma_f32_16x16x32_bf16 v[4:7], v[164:167], v[212:215], v[4:7]
	v_mfma_f32_16x16x32_bf16 v[0:3], v[176:179], v[212:215], v[0:3]
	v_mfma_f32_16x16x32_bf16 v[52:55], v[172:175], v[188:191], v[52:55]
	v_mfma_f32_16x16x32_bf16 v[48:51], v[180:183], v[188:191], v[48:51]
	v_mfma_f32_16x16x32_bf16 v[36:39], v[172:175], v[196:199], v[36:39]
	v_mfma_f32_16x16x32_bf16 v[32:35], v[180:183], v[196:199], v[32:35]
	v_mfma_f32_16x16x32_bf16 v[20:23], v[172:175], v[204:207], v[20:23]
	v_mfma_f32_16x16x32_bf16 v[16:19], v[180:183], v[204:207], v[16:19]
	v_mfma_f32_16x16x32_bf16 v[4:7], v[172:175], v[216:219], v[4:7]
	v_mfma_f32_16x16x32_bf16 v[0:3], v[180:183], v[216:219], v[0:3]
	s_setprio 0
	s_barrier
; #define PG8_STAGE(bufoff, gbase, voff) do { _Pragma("unroll") for (int _i = 0; _i < 2; ++_i) \
;         __builtin_amdgcn_global_load_lds((const unsigned*)((const char*)(gbase) + (voff)[_i]), (PG8_LAS unsigned*)(lds + (bufoff) + ldsw + _i * 8192), 16, 0, 0); } while (0)
; #define PG8_LDA(dst, b, h) do { _Pragma("unroll") for (int m = 0; m < 4; ++m) _Pragma("unroll") for (int k = 0; k < 2; ++k) dst[m][k] = *(const PG8_LAS bf16x8*)(lds + PG8_SA(b, h) + aoff + m * 2048 + k * 1024); } while (0)
; #define PG8_LDB(dst, b, h) do { _Pragma("unroll") for (int n = 0; n < 2; ++n) _Pragma("unroll") for (int k = 0; k < 2; ++k) dst[n][k] = *(const PG8_LAS bf16x8*)(lds + PG8_SB(b, h) + boff + n * 2048 + k * 1024); } while (0)
; #define PG8_MMA(ai, bj, At, Bt) do { __builtin_amdgcn_s_setprio(1); _Pragma("unroll") for (int m = 0; m < 4; ++m) _Pragma("unroll") for (int n = 0; n < 2; ++n) _Pragma("unroll") for (int k = 0; k < 2; ++k) \
;         acc[ai][bj][m][n] = mma16<Epi::F16>(Bt[n][k], At[m][k], acc[ai][bj][m][n]); __builtin_amdgcn_s_setprio(0); } while (0)
; #define PG8_WAIT_V(n) asm volatile("s_waitcnt vmcnt(" #n ")" ::: "memory")
; #define PG8_WAIT_L(n) asm volatile("s_waitcnt lgkmcnt(" #n ")" ::: "memory")
; #define PG8_BAR __builtin_amdgcn_s_barrier()
; #define PG8_SCHED __builtin_amdgcn_sched_barrier(0)
; template <class Epi, class Sched, bool ALIGN_EPI = false, bool SP2 = false>
; __device__ __forceinline__ void gemm_phase(PG8_LAS unsigned char* lds, const Gemm g, const Sched& S, const Epi& E) {
;     ...
;         for (int t = 0; t < nt; t += 2) {
;             const bool last = (t == nt - 2);
;             const char* a1 = cA + (size_t)(t + 1) * kstep;
;             const char* a2 = last ? nA : cA + (size_t)(t + 2) * kstep; const char* b2 = last ? nB : cB + (size_t)(t + 2) * kstep;
;     ...
;             PG8_LDB(B0, 1, 0); PG8_LDB(B1, 1, 1); PG8_SCHED; PG8_LDA(At, 1, 0); PG8_STAGE(PG8_SA(0, 1), a2 + hstep, voffA);
;             PG8_WAIT_V(8); PG8_WAIT_L(0); PG8_BAR; PG8_MMA(0, 0, At, B0); PG8_MMA(0, 1, At, B1); PG8_BAR; PG8_SCHED;
;             PG8_LDA(At, 1, 1); PG8_STAGE(PG8_SB(1, 0), b3, voffB); PG8_STAGE(PG8_SB(1, 1), b3 + hstep, voffB); PG8_STAGE(PG8_SA(1, 0), a3, voffA);
;             PG8_WAIT_V(8); PG8_WAIT_L(0); PG8_BAR; PG8_MMA(1, 0, At, B0); PG8_MMA(1, 1, At, B1); PG8_BAR; PG8_SCHED;
	s_add_i32 s44, 0, 0x18000
	s_add_i32 s45, 0, 0x1c000
	v_add_u32_e32 v160, s44, v170
	v_add_u32_e32 v180, s45, v170
	ds_read_b128 v[148:151], v160
	ds_read_b128 v[152:155], v160 offset:1024
	ds_read_b128 v[156:159], v160 offset:2048
	ds_read_b128 v[160:163], v160 offset:3072
	ds_read_b128 v[164:167], v180
	ds_read_b128 v[172:175], v180 offset:1024
	ds_read_b128 v[176:179], v180 offset:2048
	ds_read_b128 v[180:183], v180 offset:3072
	s_add_u32 s30, s30, s50
	s_addc_u32 s31, s31, s51
	s_mov_b32 m0, s7
	v_lshl_add_u64 v[230:231], s[30:31], 0, v[128:129]
	ds_read_b128 v[184:187], v171 offset:32768
	ds_read_b128 v[188:191], v171 offset:33792
	ds_read_b128 v[192:195], v171 offset:34816
	ds_read_b128 v[196:199], v171 offset:35840
	ds_read_b128 v[200:203], v171 offset:36864
	ds_read_b128 v[204:207], v171 offset:37888
	ds_read_b128 v[212:215], v171 offset:38912
	ds_read_b128 v[216:219], v171 offset:39936
	global_load_lds_dwordx4 v[230:231], off
	v_lshl_add_u64 v[230:231], s[30:31], 0, v[130:131]
	s_mov_b32 m0, s8
	s_nop 0
	global_load_lds_dwordx4 v[230:231], off
	s_waitcnt vmcnt(8)
	s_waitcnt lgkmcnt(0)
	s_barrier
	s_setprio 1
	s_waitcnt lgkmcnt(0)
	v_mfma_f32_16x16x32_bf16 v[124:127], v[148:151], v[184:187], v[124:127]
	v_mfma_f32_16x16x32_bf16 v[120:123], v[156:159], v[184:187], v[120:123]
	v_mfma_f32_16x16x32_bf16 v[108:111], v[148:151], v[192:195], v[108:111]
	v_mfma_f32_16x16x32_bf16 v[104:107], v[156:159], v[192:195], v[104:107]
	v_mfma_f32_16x16x32_bf16 v[92:95], v[148:151], v[200:203], v[92:95]
	v_mfma_f32_16x16x32_bf16 v[88:91], v[156:159], v[200:203], v[88:91]
	v_mfma_f32_16x16x32_bf16 v[76:79], v[148:151], v[212:215], v[76:79]
	v_mfma_f32_16x16x32_bf16 v[72:75], v[156:159], v[212:215], v[72:75]
	v_mfma_f32_16x16x32_bf16 v[124:127], v[152:155], v[188:191], v[124:127]
	v_mfma_f32_16x16x32_bf16 v[120:123], v[160:163], v[188:191], v[120:123]
	v_mfma_f32_16x16x32_bf16 v[108:111], v[152:155], v[196:199], v[108:111]
	v_mfma_f32_16x16x32_bf16 v[104:107], v[160:163], v[196:199], v[104:107]
	v_mfma_f32_16x16x32_bf16 v[92:95], v[152:155], v[204:207], v[92:95]
	v_mfma_f32_16x16x32_bf16 v[88:91], v[160:163], v[204:207], v[88:91]
	v_mfma_f32_16x16x32_bf16 v[76:79], v[152:155], v[216:219], v[76:79]
	v_mfma_f32_16x16x32_bf16 v[72:75], v[160:163], v[216:219], v[72:75]
	v_mfma_f32_16x16x32_bf16 v[116:119], v[164:167], v[184:187], v[116:119]
	v_mfma_f32_16x16x32_bf16 v[112:115], v[176:179], v[184:187], v[112:115]
	v_mfma_f32_16x16x32_bf16 v[100:103], v[164:167], v[192:195], v[100:103]
	v_mfma_f32_16x16x32_bf16 v[96:99], v[176:179], v[192:195], v[96:99]
	v_mfma_f32_16x16x32_bf16 v[84:87], v[164:167], v[200:203], v[84:87]
	v_mfma_f32_16x16x32_bf16 v[80:83], v[176:179], v[200:203], v[80:83]
	v_mfma_f32_16x16x32_bf16 v[68:71], v[164:167], v[212:215], v[68:71]
	v_mfma_f32_16x16x32_bf16 v[64:67], v[176:179], v[212:215], v[64:67]
	v_mfma_f32_16x16x32_bf16 v[116:119], v[172:175], v[188:191], v[116:119]
	v_mfma_f32_16x16x32_bf16 v[112:115], v[180:183], v[188:191], v[112:115]
	v_mfma_f32_16x16x32_bf16 v[100:103], v[172:175], v[196:199], v[100:103]
	v_mfma_f32_16x16x32_bf16 v[96:99], v[180:183], v[196:199], v[96:99]
	v_mfma_f32_16x16x32_bf16 v[84:87], v[172:175], v[204:207], v[84:87]
	v_mfma_f32_16x16x32_bf16 v[80:83], v[180:183], v[204:207], v[80:83]
	v_mfma_f32_16x16x32_bf16 v[68:71], v[172:175], v[216:219], v[68:71]
	v_mfma_f32_16x16x32_bf16 v[64:67], v[180:183], v[216:219], v[64:67]
	s_setprio 0
	s_barrier
	s_add_i32 s30, s44, s71
	v_lshl_add_u64 v[168:169], v[168:169], 0, s[20:21]
	s_mov_b32 m0, s30
	ds_read_b128 v[184:187], v171 offset:49152
	ds_read_b128 v[188:191], v171 offset:50176
	ds_read_b128 v[192:195], v171 offset:51200
	ds_read_b128 v[196:199], v171 offset:52224
	ds_read_b128 v[200:203], v171 offset:53248
	ds_read_b128 v[204:207], v171 offset:54272
	ds_read_b128 v[212:215], v171 offset:55296
	ds_read_b128 v[216:219], v171 offset:56320
	global_load_lds_dwordx4 v[168:169], off
	v_lshl_add_u64 v[168:169], v[220:221], 0, s[20:21]
	s_add_i32 m0, s30, 0x2000
	s_add_i32 s30, s45, s71
	global_load_lds_dwordx4 v[168:169], off
	v_lshl_add_u64 v[168:169], v[222:223], 0, s[20:21]
	s_mov_b32 m0, s30
	s_nop 0
	global_load_lds_dwordx4 v[168:169], off
	v_lshl_add_u64 v[168:169], v[224:225], 0, s[20:21]
	s_add_i32 m0, s30, 0x2000
	s_nop 0
	global_load_lds_dwordx4 v[168:169], off
	v_lshl_add_u64 v[168:169], v[226:227], 0, s[20:21]
	s_mov_b32 m0, s9
	s_nop 0
	global_load_lds_dwordx4 v[168:169], off
	v_lshl_add_u64 v[168:169], v[228:229], 0, s[20:21]
	s_mov_b32 m0, s84
	s_nop 0
	global_load_lds_dwordx4 v[168:169], off
	s_waitcnt vmcnt(8)
	s_waitcnt lgkmcnt(0)
	s_barrier
	s_setprio 1
	s_waitcnt lgkmcnt(0)
	v_mfma_f32_16x16x32_bf16 v[60:63], v[148:151], v[184:187], v[60:63]
	v_mfma_f32_16x16x32_bf16 v[56:59], v[156:159], v[184:187], v[56:59]
	v_mfma_f32_16x16x32_bf16 v[44:47], v[148:151], v[192:195], v[44:47]
	v_mfma_f32_16x16x32_bf16 v[40:43], v[156:159], v[192:195], v[40:43]
	v_mfma_f32_16x16x32_bf16 v[28:31], v[148:151], v[200:203], v[28:31]
	v_mfma_f32_16x16x32_bf16 v[24:27], v[156:159], v[200:203], v[24:27]
	v_mfma_f32_16x16x32_bf16 v[12:15], v[148:151], v[212:215], v[12:15]
	v_mfma_f32_16x16x32_bf16 v[8:11], v[156:159], v[212:215], v[8:11]
	v_mfma_f32_16x16x32_bf16 v[60:63], v[152:155], v[188:191], v[60:63]
	v_mfma_f32_16x16x32_bf16 v[56:59], v[160:163], v[188:191], v[56:59]
	v_mfma_f32_16x16x32_bf16 v[44:47], v[152:155], v[196:199], v[44:47]
	v_mfma_f32_16x16x32_bf16 v[40:43], v[160:163], v[196:199], v[40:43]
	v_mfma_f32_16x16x32_bf16 v[28:31], v[152:155], v[204:207], v[28:31]
	v_mfma_f32_16x16x32_bf16 v[24:27], v[160:163], v[204:207], v[24:27]
	v_mfma_f32_16x16x32_bf16 v[12:15], v[152:155], v[216:219], v[12:15]
	v_mfma_f32_16x16x32_bf16 v[8:11], v[160:163], v[216:219], v[8:11]
	v_mfma_f32_16x16x32_bf16 v[52:55], v[164:167], v[184:187], v[52:55]
	v_mfma_f32_16x16x32_bf16 v[48:51], v[176:179], v[184:187], v[48:51]
	v_mfma_f32_16x16x32_bf16 v[36:39], v[164:167], v[192:195], v[36:39]
	v_mfma_f32_16x16x32_bf16 v[32:35], v[176:179], v[192:195], v[32:35]
	v_mfma_f32_16x16x32_bf16 v[20:23], v[164:167], v[200:203], v[20:23]
	v_mfma_f32_16x16x32_bf16 v[16:19], v[176:179], v[200:203], v[16:19]
	v_mfma_f32_16x16x32_bf16 v[4:7], v[164:167], v[212:215], v[4:7]
	v_mfma_f32_16x16x32_bf16 v[0:3], v[176:179], v[212:215], v[0:3]
	v_mfma_f32_16x16x32_bf16 v[52:55], v[172:175], v[188:191], v[52:55]
	v_mfma_f32_16x16x32_bf16 v[48:51], v[180:183], v[188:191], v[48:51]
	v_mfma_f32_16x16x32_bf16 v[36:39], v[172:175], v[196:199], v[36:39]
	v_mfma_f32_16x16x32_bf16 v[32:35], v[180:183], v[196:199], v[32:35]
	v_mfma_f32_16x16x32_bf16 v[20:23], v[172:175], v[204:207], v[20:23]
	v_mfma_f32_16x16x32_bf16 v[16:19], v[180:183], v[204:207], v[16:19]
	v_mfma_f32_16x16x32_bf16 v[4:7], v[172:175], v[216:219], v[4:7]
	v_mfma_f32_16x16x32_bf16 v[0:3], v[180:183], v[216:219], v[0:3]
	s_setprio 0
	s_barrier
	s_add_u32 s28, s28, 0x100
	s_addc_u32 s29, s29, 0
	s_add_u32 s34, s34, 0x100
	s_addc_u32 s35, s35, 0
	s_cmp_ge_i32 s43, s96
	s_mov_b32 s30, s43
	s_cbranch_scc0 .LBB0_901

; #define PG8_STAGE(bufoff, gbase, voff) do { _Pragma("unroll") for (int _i = 0; _i < 2; ++_i) \
;         __builtin_amdgcn_global_load_lds((const unsigned*)((const char*)(gbase) + (voff)[_i]), (PG8_LAS unsigned*)(lds + (bufoff) + ldsw + _i * 8192), 16, 0, 0); } while (0)
; #define PG8_LDA(dst, b, h) do { _Pragma("unroll") for (int m = 0; m < 4; ++m) _Pragma("unroll") for (int k = 0; k < 2; ++k) dst[m][k] = *(const PG8_LAS bf16x8*)(lds + PG8_SA(b, h) + aoff + m * 2048 + k * 1024); } while (0)
; #define PG8_LDB(dst, b, h) do { _Pragma("unroll") for (int n = 0; n < 2; ++n) _Pragma("unroll") for (int k = 0; k < 2; ++k) dst[n][k] = *(const PG8_LAS bf16x8*)(lds + PG8_SB(b, h) + boff + n * 2048 + k * 1024); } while (0)
; #define PG8_MMA(ai, bj, At, Bt) do { __builtin_amdgcn_s_setprio(1); _Pragma("unroll") for (int m = 0; m < 4; ++m) _Pragma("unroll") for (int n = 0; n < 2; ++n) _Pragma("unroll") for (int k = 0; k < 2; ++k) \
;         acc[ai][bj][m][n] = mma16<Epi::F16>(Bt[n][k], At[m][k], acc[ai][bj][m][n]); __builtin_amdgcn_s_setprio(0); } while (0)
; #define PG8_WAIT_V(n) asm volatile("s_waitcnt vmcnt(" #n ")" ::: "memory")
; template <class Epi, class Sched, bool ALIGN_EPI = false, bool SP2 = false>
; __device__ __forceinline__ void gemm_phase(PG8_LAS unsigned char* lds, const Gemm g, const Sched& S, const Epi& E) {
;     ...
;         const bool has_next = S.next(ui + 1, nxt);
;         const char* nA = has_next ? (const char*)g.A + (size_t)nxt.pm * tstep : cA; const char* nB = has_next ? (const char*)g.Bt + (size_t)nxt.pn * tstep : cB;
;         for (int t = 0; t < nt; t += 2) {
;             const bool last = (t == nt - 2);
;             const char* a1 = cA + (size_t)(t + 1) * kstep;
;             const char* a2 = last ? nA : cA + (size_t)(t + 2) * kstep; const char* b2 = last ? nB : cB + (size_t)(t + 2) * kstep;
;             const char* a3 = a2 + kstep; const char* b3 = b2 + kstep;
;             if (last && has_next) S.a_ready(nxt);
;             if constexpr (SP2) {
;             PG8_LDB(B0, 0, 0); PG8_LDB(B1, 0, 1); PG8_SCHED; PG8_LDA(At, 0, 0); PG8_STAGE(PG8_SA(1, 1), a1 + hstep, voffA);
;             PG8_WAIT_V(8); PG8_WAIT_L(0); PG8_BAR; PG8_MMA(0, 0, At, B0); PG8_MMA(0, 1, At, B1); PG8_BAR; PG8_SCHED;
;             PG8_LDA(At, 0, 1); PG8_STAGE(PG8_SB(0, 0), b2, voffB); PG8_STAGE(PG8_SB(0, 1), b2 + hstep, voffB); PG8_STAGE(PG8_SA(0, 0), a2, voffA);
.Lpeel_k7:
	s_add_u32 s30, s30, 0x80
	s_addc_u32 s31, s31, 0
	s_add_u32 s69, s34, 0x100
	s_addc_u32 s70, s35, 0
	s_mov_b32 s34, 0
	s_add_i32 s71, s34, 2
	s_add_u32 s72, s30, 0x80
	s_addc_u32 s35, s31, 0
	s_add_i32 s77, 0, 0x10000
	s_cmp_eq_u32 s65, s34
	s_cselect_b32 s35, s1, s35
	s_cselect_b32 s34, s0, s72
	s_cselect_b32 s73, s55, s70
	s_cselect_b32 s72, s54, s69
	s_add_i32 s82, 0, 0x14000
	v_add_u32_e32 v140, s77, v191
	v_add_u32_e32 v156, s82, v191
	ds_read_b128 v[128:131], v140
	ds_read_b128 v[132:135], v140 offset:1024
	ds_read_b128 v[136:139], v140 offset:2048
	ds_read_b128 v[140:143], v140 offset:3072
	ds_read_b128 v[144:147], v156
	ds_read_b128 v[148:151], v156 offset:1024
	ds_read_b128 v[152:155], v156 offset:2048
	ds_read_b128 v[156:159], v156 offset:3072
	v_lshl_add_u64 v[192:193], s[30:31], 0, v[182:183]
	s_add_i32 m0, s48, 0xc000
	ds_read_b128 v[160:163], v195
	ds_read_b128 v[164:167], v195 offset:1024
	ds_read_b128 v[168:171], v195 offset:2048
	ds_read_b128 v[172:175], v195 offset:3072
	ds_read_b128 v[186:189], v195 offset:4096
	ds_read_b128 v[196:199], v195 offset:5120
	ds_read_b128 v[200:203], v195 offset:6144
	ds_read_b128 v[204:207], v195 offset:7168
	global_load_lds_dwordx4 v[192:193], off
	v_lshl_add_u64 v[192:193], s[30:31], 0, v[184:185]
	s_add_i32 m0, s48, 0xe000
	s_nop 0
	global_load_lds_dwordx4 v[192:193], off
	s_waitcnt vmcnt(8)
	s_waitcnt lgkmcnt(0)
	s_barrier
	s_setprio 1
	s_waitcnt lgkmcnt(0)
	v_mfma_f32_16x16x32_bf16 v[124:127], v[128:131], v[160:163], 0
	v_mfma_f32_16x16x32_bf16 v[120:123], v[136:139], v[160:163], 0
	v_mfma_f32_16x16x32_bf16 v[108:111], v[128:131], v[168:171], 0
	v_mfma_f32_16x16x32_bf16 v[104:107], v[136:139], v[168:171], 0
	v_mfma_f32_16x16x32_bf16 v[92:95], v[128:131], v[186:189], 0
	v_mfma_f32_16x16x32_bf16 v[88:91], v[136:139], v[186:189], 0
	v_mfma_f32_16x16x32_bf16 v[76:79], v[128:131], v[200:203], 0
	v_mfma_f32_16x16x32_bf16 v[72:75], v[136:139], v[200:203], 0
	v_mfma_f32_16x16x32_bf16 v[124:127], v[132:135], v[164:167], v[124:127]
	v_mfma_f32_16x16x32_bf16 v[120:123], v[140:143], v[164:167], v[120:123]
	v_mfma_f32_16x16x32_bf16 v[108:111], v[132:135], v[172:175], v[108:111]
	v_mfma_f32_16x16x32_bf16 v[104:107], v[140:143], v[172:175], v[104:107]
	v_mfma_f32_16x16x32_bf16 v[92:95], v[132:135], v[196:199], v[92:95]
	v_mfma_f32_16x16x32_bf16 v[88:91], v[140:143], v[196:199], v[88:91]
	v_mfma_f32_16x16x32_bf16 v[76:79], v[132:135], v[204:207], v[76:79]
	v_mfma_f32_16x16x32_bf16 v[72:75], v[140:143], v[204:207], v[72:75]
	v_mfma_f32_16x16x32_bf16 v[116:119], v[144:147], v[160:163], 0
	v_mfma_f32_16x16x32_bf16 v[112:115], v[152:155], v[160:163], 0
	v_mfma_f32_16x16x32_bf16 v[100:103], v[144:147], v[168:171], 0
	v_mfma_f32_16x16x32_bf16 v[96:99], v[152:155], v[168:171], 0
	v_mfma_f32_16x16x32_bf16 v[84:87], v[144:147], v[186:189], 0
	v_mfma_f32_16x16x32_bf16 v[80:83], v[152:155], v[186:189], 0
	v_mfma_f32_16x16x32_bf16 v[68:71], v[144:147], v[200:203], 0
	v_mfma_f32_16x16x32_bf16 v[64:67], v[152:155], v[200:203], 0
	v_mfma_f32_16x16x32_bf16 v[116:119], v[148:151], v[164:167], v[116:119]
	v_mfma_f32_16x16x32_bf16 v[112:115], v[156:159], v[164:167], v[112:115]
	v_mfma_f32_16x16x32_bf16 v[100:103], v[148:151], v[172:175], v[100:103]
	v_mfma_f32_16x16x32_bf16 v[96:99], v[156:159], v[172:175], v[96:99]
	v_mfma_f32_16x16x32_bf16 v[84:87], v[148:151], v[196:199], v[84:87]
	v_mfma_f32_16x16x32_bf16 v[80:83], v[156:159], v[196:199], v[80:83]
	v_mfma_f32_16x16x32_bf16 v[68:71], v[148:151], v[204:207], v[68:71]
	v_mfma_f32_16x16x32_bf16 v[64:67], v[156:159], v[204:207], v[64:67]
	s_setprio 0
	s_barrier
	s_add_i32 s77, s77, s3
	v_lshl_add_u64 v[192:193], s[72:73], 0, v[178:179]
	s_mov_b32 m0, s77
	ds_read_b128 v[160:163], v195 offset:16384
	ds_read_b128 v[164:167], v195 offset:17408
	ds_read_b128 v[168:171], v195 offset:18432
	ds_read_b128 v[172:175], v195 offset:19456
	ds_read_b128 v[186:189], v195 offset:20480
	ds_read_b128 v[196:199], v195 offset:21504
	ds_read_b128 v[200:203], v195 offset:22528
	ds_read_b128 v[204:207], v195 offset:23552
	global_load_lds_dwordx4 v[192:193], off
	s_add_i32 m0, s77, 0x2000
	v_lshl_add_u64 v[212:213], s[72:73], 0, v[176:177]
	s_add_u32 s72, s72, s42
	s_addc_u32 s73, s73, s43
	s_add_i32 s77, s82, s3
	global_load_lds_dwordx4 v[212:213], off
	v_lshl_add_u64 v[214:215], s[72:73], 0, v[178:179]
	s_mov_b32 m0, s77
	v_lshl_add_u64 v[216:217], s[72:73], 0, v[176:177]
	global_load_lds_dwordx4 v[214:215], off
	s_add_i32 m0, s77, 0x2000
	v_lshl_add_u64 v[218:219], s[34:35], 0, v[178:179]
	global_load_lds_dwordx4 v[216:217], off
	s_mov_b32 m0, s48
	v_lshl_add_u64 v[220:221], s[34:35], 0, v[176:177]
	global_load_lds_dwordx4 v[218:219], off
	s_mov_b32 m0, s56
	s_nop 0
	global_load_lds_dwordx4 v[220:221], off
	s_waitcnt vmcnt(8)
	s_waitcnt lgkmcnt(0)
	s_barrier
; #define PG8_STAGE(bufoff, gbase, voff) do { _Pragma("unroll") for (int _i = 0; _i < 2; ++_i) \
;         __builtin_amdgcn_global_load_lds((const unsigned*)((const char*)(gbase) + (voff)[_i]), (PG8_LAS unsigned*)(lds + (bufoff) + ldsw + _i * 8192), 16, 0, 0); } while (0)
; #define PG8_LDA(dst, b, h) do { _Pragma("unroll") for (int m = 0; m < 4; ++m) _Pragma("unroll") for (int k = 0; k < 2; ++k) dst[m][k] = *(const PG8_LAS bf16x8*)(lds + PG8_SA(b, h) + aoff + m * 2048 + k * 1024); } while (0)
; #define PG8_LDB(dst, b, h) do { _Pragma("unroll") for (int n = 0; n < 2; ++n) _Pragma("unroll") for (int k = 0; k < 2; ++k) dst[n][k] = *(const PG8_LAS bf16x8*)(lds + PG8_SB(b, h) + boff + n * 2048 + k * 1024); } while (0)
; #define PG8_MMA(ai, bj, At, Bt) do { __builtin_amdgcn_s_setprio(1); _Pragma("unroll") for (int m = 0; m < 4; ++m) _Pragma("unroll") for (int n = 0; n < 2; ++n) _Pragma("unroll") for (int k = 0; k < 2; ++k) \
;         acc[ai][bj][m][n] = mma16<Epi::F16>(Bt[n][k], At[m][k], acc[ai][bj][m][n]); __builtin_amdgcn_s_setprio(0); } while (0)
; #define PG8_WAIT_V(n) asm volatile("s_waitcnt vmcnt(" #n ")" ::: "memory")
; #define PG8_WAIT_L(n) asm volatile("s_waitcnt lgkmcnt(" #n ")" ::: "memory")
; #define PG8_BAR __builtin_amdgcn_s_barrier()
; #define PG8_SCHED __builtin_amdgcn_sched_barrier(0)
; template <class Epi, class Sched, bool ALIGN_EPI = false, bool SP2 = false>
; __device__ __forceinline__ void gemm_phase(PG8_LAS unsigned char* lds, const Gemm g, const Sched& S, const Epi& E) {
;     ...
;             PG8_LDA(At, 0, 1); PG8_STAGE(PG8_SB(0, 0), b2, voffB); PG8_STAGE(PG8_SB(0, 1), b2 + hstep, voffB); PG8_STAGE(PG8_SA(0, 0), a2, voffA);
;             PG8_WAIT_V(8); PG8_WAIT_L(0); PG8_BAR; PG8_MMA(1, 0, At, B0); PG8_MMA(1, 1, At, B1); PG8_BAR; PG8_SCHED;
;             PG8_LDB(B0, 1, 0); PG8_LDB(B1, 1, 1); PG8_SCHED; PG8_LDA(At, 1, 0); PG8_STAGE(PG8_SA(0, 1), a2 + hstep, voffA);
;             PG8_WAIT_V(8); PG8_WAIT_L(0); PG8_BAR; PG8_MMA(0, 0, At, B0); PG8_MMA(0, 1, At, B1); PG8_BAR; PG8_SCHED;
	s_setprio 1
	s_waitcnt lgkmcnt(0)
	v_mfma_f32_16x16x32_bf16 v[60:63], v[128:131], v[160:163], 0
	v_mfma_f32_16x16x32_bf16 v[56:59], v[136:139], v[160:163], 0
	v_mfma_f32_16x16x32_bf16 v[44:47], v[128:131], v[168:171], 0
	v_mfma_f32_16x16x32_bf16 v[40:43], v[136:139], v[168:171], 0
	v_mfma_f32_16x16x32_bf16 v[28:31], v[128:131], v[186:189], 0
	v_mfma_f32_16x16x32_bf16 v[24:27], v[136:139], v[186:189], 0
	v_mfma_f32_16x16x32_bf16 v[12:15], v[128:131], v[200:203], 0
	v_mfma_f32_16x16x32_bf16 v[8:11], v[136:139], v[200:203], 0
	v_mfma_f32_16x16x32_bf16 v[60:63], v[132:135], v[164:167], v[60:63]
	v_mfma_f32_16x16x32_bf16 v[56:59], v[140:143], v[164:167], v[56:59]
	v_mfma_f32_16x16x32_bf16 v[44:47], v[132:135], v[172:175], v[44:47]
	v_mfma_f32_16x16x32_bf16 v[40:43], v[140:143], v[172:175], v[40:43]
	v_mfma_f32_16x16x32_bf16 v[28:31], v[132:135], v[196:199], v[28:31]
	v_mfma_f32_16x16x32_bf16 v[24:27], v[140:143], v[196:199], v[24:27]
	v_mfma_f32_16x16x32_bf16 v[12:15], v[132:135], v[204:207], v[12:15]
	v_mfma_f32_16x16x32_bf16 v[8:11], v[140:143], v[204:207], v[8:11]
	v_mfma_f32_16x16x32_bf16 v[52:55], v[144:147], v[160:163], 0
	v_mfma_f32_16x16x32_bf16 v[48:51], v[152:155], v[160:163], 0
	v_mfma_f32_16x16x32_bf16 v[36:39], v[144:147], v[168:171], 0
	v_mfma_f32_16x16x32_bf16 v[32:35], v[152:155], v[168:171], 0
	v_mfma_f32_16x16x32_bf16 v[20:23], v[144:147], v[186:189], 0
	v_mfma_f32_16x16x32_bf16 v[16:19], v[152:155], v[186:189], 0
	v_mfma_f32_16x16x32_bf16 v[4:7], v[144:147], v[200:203], 0
	v_mfma_f32_16x16x32_bf16 v[0:3], v[152:155], v[200:203], 0
	v_mfma_f32_16x16x32_bf16 v[52:55], v[148:151], v[164:167], v[52:55]
	v_mfma_f32_16x16x32_bf16 v[48:51], v[156:159], v[164:167], v[48:51]
	v_mfma_f32_16x16x32_bf16 v[36:39], v[148:151], v[172:175], v[36:39]
	v_mfma_f32_16x16x32_bf16 v[32:35], v[156:159], v[172:175], v[32:35]
	v_mfma_f32_16x16x32_bf16 v[20:23], v[148:151], v[196:199], v[20:23]
	v_mfma_f32_16x16x32_bf16 v[16:19], v[156:159], v[196:199], v[16:19]
	v_mfma_f32_16x16x32_bf16 v[4:7], v[148:151], v[204:207], v[4:7]
	v_mfma_f32_16x16x32_bf16 v[0:3], v[156:159], v[204:207], v[0:3]
	s_setprio 0
	s_barrier
	s_add_i32 s72, 0, 0x18000
	s_add_i32 s73, 0, 0x1c000
	v_add_u32_e32 v140, s72, v191
	v_add_u32_e32 v156, s73, v191
	ds_read_b128 v[128:131], v140
	ds_read_b128 v[132:135], v140 offset:1024
	ds_read_b128 v[136:139], v140 offset:2048
	ds_read_b128 v[140:143], v140 offset:3072
	ds_read_b128 v[144:147], v156
	ds_read_b128 v[148:151], v156 offset:1024
	ds_read_b128 v[152:155], v156 offset:2048
	ds_read_b128 v[156:159], v156 offset:3072
	s_add_u32 s34, s34, s42
	s_addc_u32 s35, s35, s43
	s_mov_b32 m0, s57
	v_lshl_add_u64 v[222:223], s[34:35], 0, v[178:179]
	ds_read_b128 v[160:163], v195 offset:32768
	ds_read_b128 v[164:167], v195 offset:33792
	ds_read_b128 v[168:171], v195 offset:34816
	ds_read_b128 v[172:175], v195 offset:35840
	ds_read_b128 v[186:189], v195 offset:36864
	ds_read_b128 v[196:199], v195 offset:37888
	ds_read_b128 v[200:203], v195 offset:38912
	ds_read_b128 v[204:207], v195 offset:39936
	global_load_lds_dwordx4 v[222:223], off
	v_lshl_add_u64 v[222:223], s[34:35], 0, v[176:177]
	s_mov_b32 m0, s59
	s_nop 0
	global_load_lds_dwordx4 v[222:223], off
	s_waitcnt vmcnt(8)
	s_waitcnt lgkmcnt(0)
	s_barrier
	s_setprio 1
	s_waitcnt lgkmcnt(0)
	v_mfma_f32_16x16x32_bf16 v[124:127], v[128:131], v[160:163], v[124:127]
	v_mfma_f32_16x16x32_bf16 v[120:123], v[136:139], v[160:163], v[120:123]
	v_mfma_f32_16x16x32_bf16 v[108:111], v[128:131], v[168:171], v[108:111]
	v_mfma_f32_16x16x32_bf16 v[104:107], v[136:139], v[168:171], v[104:107]
	v_mfma_f32_16x16x32_bf16 v[92:95], v[128:131], v[186:189], v[92:95]
	v_mfma_f32_16x16x32_bf16 v[88:91], v[136:139], v[186:189], v[88:91]
	v_mfma_f32_16x16x32_bf16 v[76:79], v[128:131], v[200:203], v[76:79]
	v_mfma_f32_16x16x32_bf16 v[72:75], v[136:139], v[200:203], v[72:75]
	v_mfma_f32_16x16x32_bf16 v[124:127], v[132:135], v[164:167], v[124:127]
	v_mfma_f32_16x16x32_bf16 v[120:123], v[140:143], v[164:167], v[120:123]
	v_mfma_f32_16x16x32_bf16 v[108:111], v[132:135], v[172:175], v[108:111]
	v_mfma_f32_16x16x32_bf16 v[104:107], v[140:143], v[172:175], v[104:107]
	v_mfma_f32_16x16x32_bf16 v[92:95], v[132:135], v[196:199], v[92:95]
	v_mfma_f32_16x16x32_bf16 v[88:91], v[140:143], v[196:199], v[88:91]
	v_mfma_f32_16x16x32_bf16 v[76:79], v[132:135], v[204:207], v[76:79]
	v_mfma_f32_16x16x32_bf16 v[72:75], v[140:143], v[204:207], v[72:75]
	v_mfma_f32_16x16x32_bf16 v[116:119], v[144:147], v[160:163], v[116:119]
	v_mfma_f32_16x16x32_bf16 v[112:115], v[152:155], v[160:163], v[112:115]
	v_mfma_f32_16x16x32_bf16 v[100:103], v[144:147], v[168:171], v[100:103]
	v_mfma_f32_16x16x32_bf16 v[96:99], v[152:155], v[168:171], v[96:99]
	v_mfma_f32_16x16x32_bf16 v[84:87], v[144:147], v[186:189], v[84:87]
	v_mfma_f32_16x16x32_bf16 v[80:83], v[152:155], v[186:189], v[80:83]
	v_mfma_f32_16x16x32_bf16 v[68:71], v[144:147], v[200:203], v[68:71]
	v_mfma_f32_16x16x32_bf16 v[64:67], v[152:155], v[200:203], v[64:67]
	v_mfma_f32_16x16x32_bf16 v[116:119], v[148:151], v[164:167], v[116:119]
	v_mfma_f32_16x16x32_bf16 v[112:115], v[156:159], v[164:167], v[112:115]
	v_mfma_f32_16x16x32_bf16 v[100:103], v[148:151], v[172:175], v[100:103]
	v_mfma_f32_16x16x32_bf16 v[96:99], v[156:159], v[172:175], v[96:99]
	v_mfma_f32_16x16x32_bf16 v[84:87], v[148:151], v[196:199], v[84:87]
	v_mfma_f32_16x16x32_bf16 v[80:83], v[156:159], v[196:199], v[80:83]
	v_mfma_f32_16x16x32_bf16 v[68:71], v[148:151], v[204:207], v[68:71]
	v_mfma_f32_16x16x32_bf16 v[64:67], v[156:159], v[204:207], v[64:67]
	s_setprio 0
	s_barrier
; #define PG8_STAGE(bufoff, gbase, voff) do { _Pragma("unroll") for (int _i = 0; _i < 2; ++_i) \
;         __builtin_amdgcn_global_load_lds((const unsigned*)((const char*)(gbase) + (voff)[_i]), (PG8_LAS unsigned*)(lds + (bufoff) + ldsw + _i * 8192), 16, 0, 0); } while (0)
; #define PG8_LDA(dst, b, h) do { _Pragma("unroll") for (int m = 0; m < 4; ++m) _Pragma("unroll") for (int k = 0; k < 2; ++k) dst[m][k] = *(const PG8_LAS bf16x8*)(lds + PG8_SA(b, h) + aoff + m * 2048 + k * 1024); } while (0)
; #define PG8_LDB(dst, b, h) do { _Pragma("unroll") for (int n = 0; n < 2; ++n) _Pragma("unroll") for (int k = 0; k < 2; ++k) dst[n][k] = *(const PG8_LAS bf16x8*)(lds + PG8_SB(b, h) + boff + n * 2048 + k * 1024); } while (0)
; #define PG8_MMA(ai, bj, At, Bt) do { __builtin_amdgcn_s_setprio(1); _Pragma("unroll") for (int m = 0; m < 4; ++m) _Pragma("unroll") for (int n = 0; n < 2; ++n) _Pragma("unroll") for (int k = 0; k < 2; ++k) \
;         acc[ai][bj][m][n] = mma16<Epi::F16>(Bt[n][k], At[m][k], acc[ai][bj][m][n]); __builtin_amdgcn_s_setprio(0); } while (0)
; #define PG8_WAIT_V(n) asm volatile("s_waitcnt vmcnt(" #n ")" ::: "memory")
; #define PG8_WAIT_L(n) asm volatile("s_waitcnt lgkmcnt(" #n ")" ::: "memory")
; #define PG8_BAR __builtin_amdgcn_s_barrier()
; #define PG8_SCHED __builtin_amdgcn_sched_barrier(0)
; template <class Epi, class Sched, bool ALIGN_EPI = false, bool SP2 = false>
; __device__ __forceinline__ void gemm_phase(PG8_LAS unsigned char* lds, const Gemm g, const Sched& S, const Epi& E) {
;     ...
;         for (int t = 0; t < nt; t += 2) {
;             const bool last = (t == nt - 2);
;             const char* a1 = cA + (size_t)(t + 1) * kstep;
;             const char* a2 = last ? nA : cA + (size_t)(t + 2) * kstep; const char* b2 = last ? nB : cB + (size_t)(t + 2) * kstep;
;             const char* a3 = a2 + kstep; const char* b3 = b2 + kstep;
;             if (last && has_next) S.a_ready(nxt);
;             if constexpr (SP2) {
;             PG8_LDB(B0, 0, 0); PG8_LDB(B1, 0, 1); PG8_SCHED; PG8_LDA(At, 0, 0); PG8_STAGE(PG8_SA(1, 1), a1 + hstep, voffA);
;     ...
;             PG8_LDA(At, 1, 1); PG8_STAGE(PG8_SB(1, 0), b3, voffB); PG8_STAGE(PG8_SB(1, 1), b3 + hstep, voffB); PG8_STAGE(PG8_SA(1, 0), a3, voffA);
;             PG8_WAIT_V(8); PG8_WAIT_L(0); PG8_BAR; PG8_MMA(1, 0, At, B0); PG8_MMA(1, 1, At, B1); PG8_BAR; PG8_SCHED;
	s_add_i32 s34, s72, s3
	v_lshl_add_u64 v[192:193], v[192:193], 0, s[20:21]
	s_mov_b32 m0, s34
	ds_read_b128 v[160:163], v195 offset:49152
	ds_read_b128 v[164:167], v195 offset:50176
	ds_read_b128 v[168:171], v195 offset:51200
	ds_read_b128 v[172:175], v195 offset:52224
	ds_read_b128 v[186:189], v195 offset:53248
	ds_read_b128 v[196:199], v195 offset:54272
	ds_read_b128 v[200:203], v195 offset:55296
	ds_read_b128 v[204:207], v195 offset:56320
	global_load_lds_dwordx4 v[192:193], off
	v_lshl_add_u64 v[192:193], v[212:213], 0, s[20:21]
	s_add_i32 m0, s34, 0x2000
	s_add_i32 s34, s73, s3
	global_load_lds_dwordx4 v[192:193], off
	v_lshl_add_u64 v[192:193], v[214:215], 0, s[20:21]
	s_mov_b32 m0, s34
	s_nop 0
	global_load_lds_dwordx4 v[192:193], off
	v_lshl_add_u64 v[192:193], v[216:217], 0, s[20:21]
	s_add_i32 m0, s34, 0x2000
	s_nop 0
	global_load_lds_dwordx4 v[192:193], off
	v_lshl_add_u64 v[192:193], v[218:219], 0, s[20:21]
	s_mov_b32 m0, s63
	s_nop 0
	global_load_lds_dwordx4 v[192:193], off
	v_lshl_add_u64 v[192:193], v[220:221], 0, s[20:21]
	s_mov_b32 m0, s64
	s_nop 0
	global_load_lds_dwordx4 v[192:193], off
	s_waitcnt vmcnt(8)
	s_waitcnt lgkmcnt(0)
	s_barrier
	s_setprio 1
	s_waitcnt lgkmcnt(0)
	v_mfma_f32_16x16x32_bf16 v[60:63], v[128:131], v[160:163], v[60:63]
	v_mfma_f32_16x16x32_bf16 v[56:59], v[136:139], v[160:163], v[56:59]
	v_mfma_f32_16x16x32_bf16 v[44:47], v[128:131], v[168:171], v[44:47]
	v_mfma_f32_16x16x32_bf16 v[40:43], v[136:139], v[168:171], v[40:43]
	v_mfma_f32_16x16x32_bf16 v[28:31], v[128:131], v[186:189], v[28:31]
	v_mfma_f32_16x16x32_bf16 v[24:27], v[136:139], v[186:189], v[24:27]
	v_mfma_f32_16x16x32_bf16 v[12:15], v[128:131], v[200:203], v[12:15]
	v_mfma_f32_16x16x32_bf16 v[8:11], v[136:139], v[200:203], v[8:11]
	v_mfma_f32_16x16x32_bf16 v[60:63], v[132:135], v[164:167], v[60:63]
	v_mfma_f32_16x16x32_bf16 v[56:59], v[140:143], v[164:167], v[56:59]
	v_mfma_f32_16x16x32_bf16 v[44:47], v[132:135], v[172:175], v[44:47]
	v_mfma_f32_16x16x32_bf16 v[40:43], v[140:143], v[172:175], v[40:43]
	v_mfma_f32_16x16x32_bf16 v[28:31], v[132:135], v[196:199], v[28:31]
	v_mfma_f32_16x16x32_bf16 v[24:27], v[140:143], v[196:199], v[24:27]
	v_mfma_f32_16x16x32_bf16 v[12:15], v[132:135], v[204:207], v[12:15]
	v_mfma_f32_16x16x32_bf16 v[8:11], v[140:143], v[204:207], v[8:11]
	v_mfma_f32_16x16x32_bf16 v[52:55], v[144:147], v[160:163], v[52:55]
	v_mfma_f32_16x16x32_bf16 v[48:51], v[152:155], v[160:163], v[48:51]
	v_mfma_f32_16x16x32_bf16 v[36:39], v[144:147], v[168:171], v[36:39]
	v_mfma_f32_16x16x32_bf16 v[32:35], v[152:155], v[168:171], v[32:35]
	v_mfma_f32_16x16x32_bf16 v[20:23], v[144:147], v[186:189], v[20:23]
	v_mfma_f32_16x16x32_bf16 v[16:19], v[152:155], v[186:189], v[16:19]
	v_mfma_f32_16x16x32_bf16 v[4:7], v[144:147], v[200:203], v[4:7]
	v_mfma_f32_16x16x32_bf16 v[0:3], v[152:155], v[200:203], v[0:3]
	v_mfma_f32_16x16x32_bf16 v[52:55], v[148:151], v[164:167], v[52:55]
	v_mfma_f32_16x16x32_bf16 v[48:51], v[156:159], v[164:167], v[48:51]
	v_mfma_f32_16x16x32_bf16 v[36:39], v[148:151], v[172:175], v[36:39]
	v_mfma_f32_16x16x32_bf16 v[32:35], v[156:159], v[172:175], v[32:35]
	v_mfma_f32_16x16x32_bf16 v[20:23], v[148:151], v[196:199], v[20:23]
	v_mfma_f32_16x16x32_bf16 v[16:19], v[156:159], v[196:199], v[16:19]
	v_mfma_f32_16x16x32_bf16 v[4:7], v[148:151], v[204:207], v[4:7]
	v_mfma_f32_16x16x32_bf16 v[0:3], v[156:159], v[204:207], v[0:3]
	s_setprio 0
	s_barrier
	s_add_u32 s30, s30, 0x100
	s_addc_u32 s31, s31, 0
	s_add_u32 s69, s69, 0x100
	s_addc_u32 s70, s70, 0
	s_cmp_ge_i32 s71, s60
	s_mov_b32 s34, s71
	s_cbranch_scc0 .LBB0_1147
	s_branch .LBB0_1148
.LBB0_1147:
	s_add_i32 s71, s34, 2
	s_add_u32 s72, s30, 0x80
	s_addc_u32 s35, s31, 0
	s_add_i32 s77, 0, 0x10000
	s_cmp_eq_u32 s65, s34
	s_cselect_b32 s35, s1, s35
	s_cselect_b32 s34, s0, s72
	s_cselect_b32 s73, s55, s70
	s_cselect_b32 s72, s54, s69
	s_add_i32 s82, 0, 0x14000
	v_add_u32_e32 v140, s77, v191
	v_add_u32_e32 v156, s82, v191
	ds_read_b128 v[128:131], v140
	ds_read_b128 v[132:135], v140 offset:1024
	ds_read_b128 v[136:139], v140 offset:2048
	ds_read_b128 v[140:143], v140 offset:3072
	ds_read_b128 v[144:147], v156
	ds_read_b128 v[148:151], v156 offset:1024
	ds_read_b128 v[152:155], v156 offset:2048
	ds_read_b128 v[156:159], v156 offset:3072
	v_lshl_add_u64 v[192:193], s[30:31], 0, v[182:183]
	s_add_i32 m0, s48, 0xc000
	ds_read_b128 v[160:163], v195
	ds_read_b128 v[164:167], v195 offset:1024
	ds_read_b128 v[168:171], v195 offset:2048
	ds_read_b128 v[172:175], v195 offset:3072
	ds_read_b128 v[186:189], v195 offset:4096
	ds_read_b128 v[196:199], v195 offset:5120
	ds_read_b128 v[200:203], v195 offset:6144
	ds_read_b128 v[204:207], v195 offset:7168
	global_load_lds_dwordx4 v[192:193], off
	v_lshl_add_u64 v[192:193], s[30:31], 0, v[184:185]
	s_add_i32 m0, s48, 0xe000
	s_nop 0
	global_load_lds_dwordx4 v[192:193], off
	s_waitcnt vmcnt(8)
	s_waitcnt lgkmcnt(0)
	s_barrier
; #define PG8_STAGE(bufoff, gbase, voff) do { _Pragma("unroll") for (int _i = 0; _i < 2; ++_i) \
;         __builtin_amdgcn_global_load_lds((const unsigned*)((const char*)(gbase) + (voff)[_i]), (PG8_LAS unsigned*)(lds + (bufoff) + ldsw + _i * 8192), 16, 0, 0); } while (0)
; #define PG8_LDA(dst, b, h) do { _Pragma("unroll") for (int m = 0; m < 4; ++m) _Pragma("unroll") for (int k = 0; k < 2; ++k) dst[m][k] = *(const PG8_LAS bf16x8*)(lds + PG8_SA(b, h) + aoff + m * 2048 + k * 1024); } while (0)
; #define PG8_MMA(ai, bj, At, Bt) do { __builtin_amdgcn_s_setprio(1); _Pragma("unroll") for (int m = 0; m < 4; ++m) _Pragma("unroll") for (int n = 0; n < 2; ++n) _Pragma("unroll") for (int k = 0; k < 2; ++k) \
;         acc[ai][bj][m][n] = mma16<Epi::F16>(Bt[n][k], At[m][k], acc[ai][bj][m][n]); __builtin_amdgcn_s_setprio(0); } while (0)
; #define PG8_WAIT_V(n) asm volatile("s_waitcnt vmcnt(" #n ")" ::: "memory")
; #define PG8_WAIT_L(n) asm volatile("s_waitcnt lgkmcnt(" #n ")" ::: "memory")
; #define PG8_BAR __builtin_amdgcn_s_barrier()
; #define PG8_SCHED __builtin_amdgcn_sched_barrier(0)
; template <class Epi, class Sched, bool ALIGN_EPI = false, bool SP2 = false>
; __device__ __forceinline__ void gemm_phase(PG8_LAS unsigned char* lds, const Gemm g, const Sched& S, const Epi& E) {
;     ...
;             PG8_WAIT_V(8); PG8_WAIT_L(0); PG8_BAR; PG8_MMA(0, 0, At, B0); PG8_MMA(0, 1, At, B1); PG8_BAR; PG8_SCHED;
;             PG8_LDA(At, 0, 1); PG8_STAGE(PG8_SB(0, 0), b2, voffB); PG8_STAGE(PG8_SB(0, 1), b2 + hstep, voffB); PG8_STAGE(PG8_SA(0, 0), a2, voffA);
;             PG8_WAIT_V(8); PG8_WAIT_L(0); PG8_BAR; PG8_MMA(1, 0, At, B0); PG8_MMA(1, 1, At, B1); PG8_BAR; PG8_SCHED;
	s_setprio 1
	s_waitcnt lgkmcnt(0)
	v_mfma_f32_16x16x32_bf16 v[124:127], v[128:131], v[160:163], v[124:127]
	v_mfma_f32_16x16x32_bf16 v[120:123], v[136:139], v[160:163], v[120:123]
	v_mfma_f32_16x16x32_bf16 v[108:111], v[128:131], v[168:171], v[108:111]
	v_mfma_f32_16x16x32_bf16 v[104:107], v[136:139], v[168:171], v[104:107]
	v_mfma_f32_16x16x32_bf16 v[92:95], v[128:131], v[186:189], v[92:95]
	v_mfma_f32_16x16x32_bf16 v[88:91], v[136:139], v[186:189], v[88:91]
	v_mfma_f32_16x16x32_bf16 v[76:79], v[128:131], v[200:203], v[76:79]
	v_mfma_f32_16x16x32_bf16 v[72:75], v[136:139], v[200:203], v[72:75]
	v_mfma_f32_16x16x32_bf16 v[124:127], v[132:135], v[164:167], v[124:127]
	v_mfma_f32_16x16x32_bf16 v[120:123], v[140:143], v[164:167], v[120:123]
	v_mfma_f32_16x16x32_bf16 v[108:111], v[132:135], v[172:175], v[108:111]
	v_mfma_f32_16x16x32_bf16 v[104:107], v[140:143], v[172:175], v[104:107]
	v_mfma_f32_16x16x32_bf16 v[92:95], v[132:135], v[196:199], v[92:95]
	v_mfma_f32_16x16x32_bf16 v[88:91], v[140:143], v[196:199], v[88:91]
	v_mfma_f32_16x16x32_bf16 v[76:79], v[132:135], v[204:207], v[76:79]
	v_mfma_f32_16x16x32_bf16 v[72:75], v[140:143], v[204:207], v[72:75]
	v_mfma_f32_16x16x32_bf16 v[116:119], v[144:147], v[160:163], v[116:119]
	v_mfma_f32_16x16x32_bf16 v[112:115], v[152:155], v[160:163], v[112:115]
	v_mfma_f32_16x16x32_bf16 v[100:103], v[144:147], v[168:171], v[100:103]
	v_mfma_f32_16x16x32_bf16 v[96:99], v[152:155], v[168:171], v[96:99]
	v_mfma_f32_16x16x32_bf16 v[84:87], v[144:147], v[186:189], v[84:87]
	v_mfma_f32_16x16x32_bf16 v[80:83], v[152:155], v[186:189], v[80:83]
	v_mfma_f32_16x16x32_bf16 v[68:71], v[144:147], v[200:203], v[68:71]
	v_mfma_f32_16x16x32_bf16 v[64:67], v[152:155], v[200:203], v[64:67]
	v_mfma_f32_16x16x32_bf16 v[116:119], v[148:151], v[164:167], v[116:119]
	v_mfma_f32_16x16x32_bf16 v[112:115], v[156:159], v[164:167], v[112:115]
	v_mfma_f32_16x16x32_bf16 v[100:103], v[148:151], v[172:175], v[100:103]
	v_mfma_f32_16x16x32_bf16 v[96:99], v[156:159], v[172:175], v[96:99]
	v_mfma_f32_16x16x32_bf16 v[84:87], v[148:151], v[196:199], v[84:87]
	v_mfma_f32_16x16x32_bf16 v[80:83], v[156:159], v[196:199], v[80:83]
	v_mfma_f32_16x16x32_bf16 v[68:71], v[148:151], v[204:207], v[68:71]
	v_mfma_f32_16x16x32_bf16 v[64:67], v[156:159], v[204:207], v[64:67]
	s_setprio 0
	s_barrier
	s_add_i32 s77, s77, s3
	v_lshl_add_u64 v[192:193], s[72:73], 0, v[178:179]
	s_mov_b32 m0, s77
	ds_read_b128 v[160:163], v195 offset:16384
	ds_read_b128 v[164:167], v195 offset:17408
	ds_read_b128 v[168:171], v195 offset:18432
	ds_read_b128 v[172:175], v195 offset:19456
	ds_read_b128 v[186:189], v195 offset:20480
	ds_read_b128 v[196:199], v195 offset:21504
	ds_read_b128 v[200:203], v195 offset:22528
	ds_read_b128 v[204:207], v195 offset:23552
	global_load_lds_dwordx4 v[192:193], off
	s_add_i32 m0, s77, 0x2000
	v_lshl_add_u64 v[212:213], s[72:73], 0, v[176:177]
	s_add_u32 s72, s72, s42
	s_addc_u32 s73, s73, s43
	s_add_i32 s77, s82, s3
	global_load_lds_dwordx4 v[212:213], off
	v_lshl_add_u64 v[214:215], s[72:73], 0, v[178:179]
	s_mov_b32 m0, s77
	v_lshl_add_u64 v[216:217], s[72:73], 0, v[176:177]
	global_load_lds_dwordx4 v[214:215], off
	s_add_i32 m0, s77, 0x2000
	v_lshl_add_u64 v[218:219], s[34:35], 0, v[178:179]
	global_load_lds_dwordx4 v[216:217], off
	s_mov_b32 m0, s48
	v_lshl_add_u64 v[220:221], s[34:35], 0, v[176:177]
	global_load_lds_dwordx4 v[218:219], off
	s_mov_b32 m0, s56
	s_nop 0
	global_load_lds_dwordx4 v[220:221], off
	s_waitcnt vmcnt(8)
	s_waitcnt lgkmcnt(0)
	s_barrier
	s_setprio 1
	s_waitcnt lgkmcnt(0)
	v_mfma_f32_16x16x32_bf16 v[60:63], v[128:131], v[160:163], v[60:63]
	v_mfma_f32_16x16x32_bf16 v[56:59], v[136:139], v[160:163], v[56:59]
	v_mfma_f32_16x16x32_bf16 v[44:47], v[128:131], v[168:171], v[44:47]
	v_mfma_f32_16x16x32_bf16 v[40:43], v[136:139], v[168:171], v[40:43]
	v_mfma_f32_16x16x32_bf16 v[28:31], v[128:131], v[186:189], v[28:31]
	v_mfma_f32_16x16x32_bf16 v[24:27], v[136:139], v[186:189], v[24:27]
	v_mfma_f32_16x16x32_bf16 v[12:15], v[128:131], v[200:203], v[12:15]
	v_mfma_f32_16x16x32_bf16 v[8:11], v[136:139], v[200:203], v[8:11]
	v_mfma_f32_16x16x32_bf16 v[60:63], v[132:135], v[164:167], v[60:63]
	v_mfma_f32_16x16x32_bf16 v[56:59], v[140:143], v[164:167], v[56:59]
	v_mfma_f32_16x16x32_bf16 v[44:47], v[132:135], v[172:175], v[44:47]
	v_mfma_f32_16x16x32_bf16 v[40:43], v[140:143], v[172:175], v[40:43]
	v_mfma_f32_16x16x32_bf16 v[28:31], v[132:135], v[196:199], v[28:31]
	v_mfma_f32_16x16x32_bf16 v[24:27], v[140:143], v[196:199], v[24:27]
	v_mfma_f32_16x16x32_bf16 v[12:15], v[132:135], v[204:207], v[12:15]
	v_mfma_f32_16x16x32_bf16 v[8:11], v[140:143], v[204:207], v[8:11]
	v_mfma_f32_16x16x32_bf16 v[52:55], v[144:147], v[160:163], v[52:55]
	v_mfma_f32_16x16x32_bf16 v[48:51], v[152:155], v[160:163], v[48:51]
	v_mfma_f32_16x16x32_bf16 v[36:39], v[144:147], v[168:171], v[36:39]
	v_mfma_f32_16x16x32_bf16 v[32:35], v[152:155], v[168:171], v[32:35]
	v_mfma_f32_16x16x32_bf16 v[20:23], v[144:147], v[186:189], v[20:23]
	v_mfma_f32_16x16x32_bf16 v[16:19], v[152:155], v[186:189], v[16:19]
	v_mfma_f32_16x16x32_bf16 v[4:7], v[144:147], v[200:203], v[4:7]
	v_mfma_f32_16x16x32_bf16 v[0:3], v[152:155], v[200:203], v[0:3]
	v_mfma_f32_16x16x32_bf16 v[52:55], v[148:151], v[164:167], v[52:55]
	v_mfma_f32_16x16x32_bf16 v[48:51], v[156:159], v[164:167], v[48:51]
	v_mfma_f32_16x16x32_bf16 v[36:39], v[148:151], v[172:175], v[36:39]
	v_mfma_f32_16x16x32_bf16 v[32:35], v[156:159], v[172:175], v[32:35]
	v_mfma_f32_16x16x32_bf16 v[20:23], v[148:151], v[196:199], v[20:23]
	v_mfma_f32_16x16x32_bf16 v[16:19], v[156:159], v[196:199], v[16:19]
	v_mfma_f32_16x16x32_bf16 v[4:7], v[148:151], v[204:207], v[4:7]
	v_mfma_f32_16x16x32_bf16 v[0:3], v[156:159], v[204:207], v[0:3]
	s_setprio 0
	s_barrier
; #define PG8_STAGE(bufoff, gbase, voff) do { _Pragma("unroll") for (int _i = 0; _i < 2; ++_i) \
;         __builtin_amdgcn_global_load_lds((const unsigned*)((const char*)(gbase) + (voff)[_i]), (PG8_LAS unsigned*)(lds + (bufoff) + ldsw + _i * 8192), 16, 0, 0); } while (0)
; #define PG8_LDA(dst, b, h) do { _Pragma("unroll") for (int m = 0; m < 4; ++m) _Pragma("unroll") for (int k = 0; k < 2; ++k) dst[m][k] = *(const PG8_LAS bf16x8*)(lds + PG8_SA(b, h) + aoff + m * 2048 + k * 1024); } while (0)
; #define PG8_LDB(dst, b, h) do { _Pragma("unroll") for (int n = 0; n < 2; ++n) _Pragma("unroll") for (int k = 0; k < 2; ++k) dst[n][k] = *(const PG8_LAS bf16x8*)(lds + PG8_SB(b, h) + boff + n * 2048 + k * 1024); } while (0)
; #define PG8_MMA(ai, bj, At, Bt) do { __builtin_amdgcn_s_setprio(1); _Pragma("unroll") for (int m = 0; m < 4; ++m) _Pragma("unroll") for (int n = 0; n < 2; ++n) _Pragma("unroll") for (int k = 0; k < 2; ++k) \
;         acc[ai][bj][m][n] = mma16<Epi::F16>(Bt[n][k], At[m][k], acc[ai][bj][m][n]); __builtin_amdgcn_s_setprio(0); } while (0)
; #define PG8_WAIT_V(n) asm volatile("s_waitcnt vmcnt(" #n ")" ::: "memory")
; #define PG8_WAIT_L(n) asm volatile("s_waitcnt lgkmcnt(" #n ")" ::: "memory")
; #define PG8_BAR __builtin_amdgcn_s_barrier()
; #define PG8_SCHED __builtin_amdgcn_sched_barrier(0)
; template <class Epi, class Sched, bool ALIGN_EPI = false, bool SP2 = false>
; __device__ __forceinline__ void gemm_phase(PG8_LAS unsigned char* lds, const Gemm g, const Sched& S, const Epi& E) {
;     ...
;             PG8_LDB(B0, 1, 0); PG8_LDB(B1, 1, 1); PG8_SCHED; PG8_LDA(At, 1, 0); PG8_STAGE(PG8_SA(0, 1), a2 + hstep, voffA);
;             PG8_WAIT_V(8); PG8_WAIT_L(0); PG8_BAR; PG8_MMA(0, 0, At, B0); PG8_MMA(0, 1, At, B1); PG8_BAR; PG8_SCHED;
;             PG8_LDA(At, 1, 1); PG8_STAGE(PG8_SB(1, 0), b3, voffB); PG8_STAGE(PG8_SB(1, 1), b3 + hstep, voffB); PG8_STAGE(PG8_SA(1, 0), a3, voffA);
;             PG8_WAIT_V(8); PG8_WAIT_L(0); PG8_BAR; PG8_MMA(1, 0, At, B0); PG8_MMA(1, 1, At, B1); PG8_BAR; PG8_SCHED;
	s_add_i32 s72, 0, 0x18000
	s_add_i32 s73, 0, 0x1c000
	v_add_u32_e32 v140, s72, v191
	v_add_u32_e32 v156, s73, v191
	ds_read_b128 v[128:131], v140
	ds_read_b128 v[132:135], v140 offset:1024
	ds_read_b128 v[136:139], v140 offset:2048
	ds_read_b128 v[140:143], v140 offset:3072
	ds_read_b128 v[144:147], v156
	ds_read_b128 v[148:151], v156 offset:1024
	ds_read_b128 v[152:155], v156 offset:2048
	ds_read_b128 v[156:159], v156 offset:3072
	s_add_u32 s34, s34, s42
	s_addc_u32 s35, s35, s43
	s_mov_b32 m0, s57
	v_lshl_add_u64 v[222:223], s[34:35], 0, v[178:179]
	ds_read_b128 v[160:163], v195 offset:32768
	ds_read_b128 v[164:167], v195 offset:33792
	ds_read_b128 v[168:171], v195 offset:34816
	ds_read_b128 v[172:175], v195 offset:35840
	ds_read_b128 v[186:189], v195 offset:36864
	ds_read_b128 v[196:199], v195 offset:37888
	ds_read_b128 v[200:203], v195 offset:38912
	ds_read_b128 v[204:207], v195 offset:39936
	global_load_lds_dwordx4 v[222:223], off
	v_lshl_add_u64 v[222:223], s[34:35], 0, v[176:177]
	s_mov_b32 m0, s59
	s_nop 0
	global_load_lds_dwordx4 v[222:223], off
	s_waitcnt vmcnt(8)
	s_waitcnt lgkmcnt(0)
	s_barrier
	s_setprio 1
	s_waitcnt lgkmcnt(0)
	v_mfma_f32_16x16x32_bf16 v[124:127], v[128:131], v[160:163], v[124:127]
	v_mfma_f32_16x16x32_bf16 v[120:123], v[136:139], v[160:163], v[120:123]
	v_mfma_f32_16x16x32_bf16 v[108:111], v[128:131], v[168:171], v[108:111]
	v_mfma_f32_16x16x32_bf16 v[104:107], v[136:139], v[168:171], v[104:107]
	v_mfma_f32_16x16x32_bf16 v[92:95], v[128:131], v[186:189], v[92:95]
	v_mfma_f32_16x16x32_bf16 v[88:91], v[136:139], v[186:189], v[88:91]
	v_mfma_f32_16x16x32_bf16 v[76:79], v[128:131], v[200:203], v[76:79]
	v_mfma_f32_16x16x32_bf16 v[72:75], v[136:139], v[200:203], v[72:75]
	v_mfma_f32_16x16x32_bf16 v[124:127], v[132:135], v[164:167], v[124:127]
	v_mfma_f32_16x16x32_bf16 v[120:123], v[140:143], v[164:167], v[120:123]
	v_mfma_f32_16x16x32_bf16 v[108:111], v[132:135], v[172:175], v[108:111]
	v_mfma_f32_16x16x32_bf16 v[104:107], v[140:143], v[172:175], v[104:107]
	v_mfma_f32_16x16x32_bf16 v[92:95], v[132:135], v[196:199], v[92:95]
	v_mfma_f32_16x16x32_bf16 v[88:91], v[140:143], v[196:199], v[88:91]
	v_mfma_f32_16x16x32_bf16 v[76:79], v[132:135], v[204:207], v[76:79]
	v_mfma_f32_16x16x32_bf16 v[72:75], v[140:143], v[204:207], v[72:75]
	v_mfma_f32_16x16x32_bf16 v[116:119], v[144:147], v[160:163], v[116:119]
	v_mfma_f32_16x16x32_bf16 v[112:115], v[152:155], v[160:163], v[112:115]
	v_mfma_f32_16x16x32_bf16 v[100:103], v[144:147], v[168:171], v[100:103]
	v_mfma_f32_16x16x32_bf16 v[96:99], v[152:155], v[168:171], v[96:99]
	v_mfma_f32_16x16x32_bf16 v[84:87], v[144:147], v[186:189], v[84:87]
	v_mfma_f32_16x16x32_bf16 v[80:83], v[152:155], v[186:189], v[80:83]
	v_mfma_f32_16x16x32_bf16 v[68:71], v[144:147], v[200:203], v[68:71]
	v_mfma_f32_16x16x32_bf16 v[64:67], v[152:155], v[200:203], v[64:67]
	v_mfma_f32_16x16x32_bf16 v[116:119], v[148:151], v[164:167], v[116:119]
	v_mfma_f32_16x16x32_bf16 v[112:115], v[156:159], v[164:167], v[112:115]
	v_mfma_f32_16x16x32_bf16 v[100:103], v[148:151], v[172:175], v[100:103]
	v_mfma_f32_16x16x32_bf16 v[96:99], v[156:159], v[172:175], v[96:99]
	v_mfma_f32_16x16x32_bf16 v[84:87], v[148:151], v[196:199], v[84:87]
	v_mfma_f32_16x16x32_bf16 v[80:83], v[156:159], v[196:199], v[80:83]
	v_mfma_f32_16x16x32_bf16 v[68:71], v[148:151], v[204:207], v[68:71]
	v_mfma_f32_16x16x32_bf16 v[64:67], v[156:159], v[204:207], v[64:67]
	s_setprio 0
	s_barrier
	s_add_i32 s34, s72, s3
	v_lshl_add_u64 v[192:193], v[192:193], 0, s[20:21]
	s_mov_b32 m0, s34
	ds_read_b128 v[160:163], v195 offset:49152
	ds_read_b128 v[164:167], v195 offset:50176
	ds_read_b128 v[168:171], v195 offset:51200
	ds_read_b128 v[172:175], v195 offset:52224
	ds_read_b128 v[186:189], v195 offset:53248
	ds_read_b128 v[196:199], v195 offset:54272
	ds_read_b128 v[200:203], v195 offset:55296
	ds_read_b128 v[204:207], v195 offset:56320
	global_load_lds_dwordx4 v[192:193], off
	v_lshl_add_u64 v[192:193], v[212:213], 0, s[20:21]
	s_add_i32 m0, s34, 0x2000
	s_add_i32 s34, s73, s3
	global_load_lds_dwordx4 v[192:193], off
	v_lshl_add_u64 v[192:193], v[214:215], 0, s[20:21]
	s_mov_b32 m0, s34
	s_nop 0
	global_load_lds_dwordx4 v[192:193], off
	v_lshl_add_u64 v[192:193], v[216:217], 0, s[20:21]
	s_add_i32 m0, s34, 0x2000
	s_nop 0
	global_load_lds_dwordx4 v[192:193], off
	v_lshl_add_u64 v[192:193], v[218:219], 0, s[20:21]
	s_mov_b32 m0, s63
	s_nop 0
	global_load_lds_dwordx4 v[192:193], off
	v_lshl_add_u64 v[192:193], v[220:221], 0, s[20:21]
	s_mov_b32 m0, s64
	s_nop 0
	global_load_lds_dwordx4 v[192:193], off
	s_waitcnt vmcnt(8)
	s_waitcnt lgkmcnt(0)
	s_barrier
	s_setprio 1
	s_waitcnt lgkmcnt(0)
	v_mfma_f32_16x16x32_bf16 v[60:63], v[128:131], v[160:163], v[60:63]
	v_mfma_f32_16x16x32_bf16 v[56:59], v[136:139], v[160:163], v[56:59]
	v_mfma_f32_16x16x32_bf16 v[44:47], v[128:131], v[168:171], v[44:47]
	v_mfma_f32_16x16x32_bf16 v[40:43], v[136:139], v[168:171], v[40:43]
	v_mfma_f32_16x16x32_bf16 v[28:31], v[128:131], v[186:189], v[28:31]
	v_mfma_f32_16x16x32_bf16 v[24:27], v[136:139], v[186:189], v[24:27]
	v_mfma_f32_16x16x32_bf16 v[12:15], v[128:131], v[200:203], v[12:15]
	v_mfma_f32_16x16x32_bf16 v[8:11], v[136:139], v[200:203], v[8:11]
	v_mfma_f32_16x16x32_bf16 v[60:63], v[132:135], v[164:167], v[60:63]
	v_mfma_f32_16x16x32_bf16 v[56:59], v[140:143], v[164:167], v[56:59]
	v_mfma_f32_16x16x32_bf16 v[44:47], v[132:135], v[172:175], v[44:47]
	v_mfma_f32_16x16x32_bf16 v[40:43], v[140:143], v[172:175], v[40:43]
	v_mfma_f32_16x16x32_bf16 v[28:31], v[132:135], v[196:199], v[28:31]
	v_mfma_f32_16x16x32_bf16 v[24:27], v[140:143], v[196:199], v[24:27]
	v_mfma_f32_16x16x32_bf16 v[12:15], v[132:135], v[204:207], v[12:15]
	v_mfma_f32_16x16x32_bf16 v[8:11], v[140:143], v[204:207], v[8:11]
	v_mfma_f32_16x16x32_bf16 v[52:55], v[144:147], v[160:163], v[52:55]
	v_mfma_f32_16x16x32_bf16 v[48:51], v[152:155], v[160:163], v[48:51]
	v_mfma_f32_16x16x32_bf16 v[36:39], v[144:147], v[168:171], v[36:39]
	v_mfma_f32_16x16x32_bf16 v[32:35], v[152:155], v[168:171], v[32:35]
	v_mfma_f32_16x16x32_bf16 v[20:23], v[144:147], v[186:189], v[20:23]
	v_mfma_f32_16x16x32_bf16 v[16:19], v[152:155], v[186:189], v[16:19]
	v_mfma_f32_16x16x32_bf16 v[4:7], v[144:147], v[200:203], v[4:7]
	v_mfma_f32_16x16x32_bf16 v[0:3], v[152:155], v[200:203], v[0:3]
	v_mfma_f32_16x16x32_bf16 v[52:55], v[148:151], v[164:167], v[52:55]
	v_mfma_f32_16x16x32_bf16 v[48:51], v[156:159], v[164:167], v[48:51]
	v_mfma_f32_16x16x32_bf16 v[36:39], v[148:151], v[172:175], v[36:39]
	v_mfma_f32_16x16x32_bf16 v[32:35], v[156:159], v[172:175], v[32:35]
	v_mfma_f32_16x16x32_bf16 v[20:23], v[148:151], v[196:199], v[20:23]
	v_mfma_f32_16x16x32_bf16 v[16:19], v[156:159], v[196:199], v[16:19]
	v_mfma_f32_16x16x32_bf16 v[4:7], v[148:151], v[204:207], v[4:7]
	v_mfma_f32_16x16x32_bf16 v[0:3], v[156:159], v[204:207], v[0:3]
	s_setprio 0
	s_barrier
	s_add_u32 s30, s30, 0x100
	s_addc_u32 s31, s31, 0
	s_add_u32 s69, s69, 0x100
	s_addc_u32 s70, s70, 0
	s_cmp_ge_i32 s71, s60
	s_mov_b32 s34, s71
	s_cbranch_scc0 .LBB0_1147

; #define PG8_STAGE(bufoff, gbase, voff) do { _Pragma("unroll") for (int _i = 0; _i < 2; ++_i) \
;         __builtin_amdgcn_global_load_lds((const unsigned*)((const char*)(gbase) + (voff)[_i]), (PG8_LAS unsigned*)(lds + (bufoff) + ldsw + _i * 8192), 16, 0, 0); } while (0)
; #define PG8_LDA(dst, b, h) do { _Pragma("unroll") for (int m = 0; m < 4; ++m) _Pragma("unroll") for (int k = 0; k < 2; ++k) dst[m][k] = *(const PG8_LAS bf16x8*)(lds + PG8_SA(b, h) + aoff + m * 2048 + k * 1024); } while (0)
; #define PG8_LDB(dst, b, h) do { _Pragma("unroll") for (int n = 0; n < 2; ++n) _Pragma("unroll") for (int k = 0; k < 2; ++k) dst[n][k] = *(const PG8_LAS bf16x8*)(lds + PG8_SB(b, h) + boff + n * 2048 + k * 1024); } while (0)
; #define PG8_MMA(ai, bj, At, Bt) do { __builtin_amdgcn_s_setprio(1); _Pragma("unroll") for (int m = 0; m < 4; ++m) _Pragma("unroll") for (int n = 0; n < 2; ++n) _Pragma("unroll") for (int k = 0; k < 2; ++k) \
;         acc[ai][bj][m][n] = mma16<Epi::F16>(Bt[n][k], At[m][k], acc[ai][bj][m][n]); __builtin_amdgcn_s_setprio(0); } while (0)
; #define PG8_WAIT_V(n) asm volatile("s_waitcnt vmcnt(" #n ")" ::: "memory")
; template <class Epi, class Sched, bool ALIGN_EPI = false, bool SP2 = false>
; __device__ __forceinline__ void gemm_phase(PG8_LAS unsigned char* lds, const Gemm g, const Sched& S, const Epi& E) {
;     ...
;         const bool has_next = S.next(ui + 1, nxt);
;         const char* nA = has_next ? (const char*)g.A + (size_t)nxt.pm * tstep : cA; const char* nB = has_next ? (const char*)g.Bt + (size_t)nxt.pn * tstep : cB;
;         for (int t = 0; t < nt; t += 2) {
;             const bool last = (t == nt - 2);
;             const char* a1 = cA + (size_t)(t + 1) * kstep;
;             const char* a2 = last ? nA : cA + (size_t)(t + 2) * kstep; const char* b2 = last ? nB : cB + (size_t)(t + 2) * kstep;
;             const char* a3 = a2 + kstep; const char* b3 = b2 + kstep;
;             if (last && has_next) S.a_ready(nxt);
;             if constexpr (SP2) {
;             PG8_LDB(B0, 0, 0); PG8_LDB(B1, 0, 1); PG8_SCHED; PG8_LDA(At, 0, 0); PG8_STAGE(PG8_SA(1, 1), a1 + hstep, voffA);
;             PG8_WAIT_V(8); PG8_WAIT_L(0); PG8_BAR; PG8_MMA(0, 0, At, B0); PG8_MMA(0, 1, At, B1); PG8_BAR; PG8_SCHED;
;             PG8_LDA(At, 0, 1); PG8_STAGE(PG8_SB(0, 0), b2, voffB); PG8_STAGE(PG8_SB(0, 1), b2 + hstep, voffB); PG8_STAGE(PG8_SA(0, 0), a2, voffA);
.Lpeel_k8:
	s_add_u32 s30, s30, 0x80
	s_addc_u32 s31, s31, 0
	s_add_u32 s40, s34, 0x100
	s_addc_u32 s41, s35, 0
	s_mov_b32 s34, 0
	s_add_i32 s71, s34, 2
	s_add_u32 s72, s30, 0x80
	s_addc_u32 s35, s31, 0
	s_add_i32 s77, 0, 0x10000
	s_cmp_eq_u32 s62, s34
	s_cselect_b32 s35, s1, s35
	s_cselect_b32 s34, s0, s72
	s_cselect_b32 s73, s29, s41
	s_cselect_b32 s72, s28, s40
	s_add_i32 s82, 0, 0x14000
	v_add_u32_e32 v140, s77, v190
	v_add_u32_e32 v156, s82, v190
	ds_read_b128 v[120:123], v140
	ds_read_b128 v[132:135], v140 offset:1024
	ds_read_b128 v[136:139], v140 offset:2048
	ds_read_b128 v[140:143], v140 offset:3072
	ds_read_b128 v[144:147], v156
	ds_read_b128 v[148:151], v156 offset:1024
	ds_read_b128 v[152:155], v156 offset:2048
	ds_read_b128 v[156:159], v156 offset:3072
	v_lshl_add_u64 v[204:205], s[30:31], 0, v[166:167]
	s_add_i32 m0, s8, 0xc000
	ds_read_b128 v[170:173], v191
	ds_read_b128 v[174:177], v191 offset:1024
	ds_read_b128 v[178:181], v191 offset:2048
	ds_read_b128 v[182:185], v191 offset:3072
	ds_read_b128 v[186:189], v191 offset:4096
	ds_read_b128 v[192:195], v191 offset:5120
	ds_read_b128 v[196:199], v191 offset:6144
	ds_read_b128 v[200:203], v191 offset:7168
	global_load_lds_dwordx4 v[204:205], off
	v_lshl_add_u64 v[204:205], s[30:31], 0, v[168:169]
	s_add_i32 m0, s8, 0xe000
	s_nop 0
	global_load_lds_dwordx4 v[204:205], off
	s_waitcnt vmcnt(8)
	s_waitcnt lgkmcnt(0)
	s_barrier
	s_setprio 1
	s_waitcnt lgkmcnt(0)
	v_mfma_f32_16x16x32_bf16 v[128:131], v[120:123], v[170:173], 0
	v_mfma_f32_16x16x32_bf16 v[124:127], v[136:139], v[170:173], 0
	v_mfma_f32_16x16x32_bf16 v[108:111], v[120:123], v[178:181], 0
	v_mfma_f32_16x16x32_bf16 v[104:107], v[136:139], v[178:181], 0
	v_mfma_f32_16x16x32_bf16 v[92:95], v[120:123], v[186:189], 0
	v_mfma_f32_16x16x32_bf16 v[88:91], v[136:139], v[186:189], 0
	v_mfma_f32_16x16x32_bf16 v[76:79], v[120:123], v[196:199], 0
	v_mfma_f32_16x16x32_bf16 v[72:75], v[136:139], v[196:199], 0
	v_mfma_f32_16x16x32_bf16 v[128:131], v[132:135], v[174:177], v[128:131]
	v_mfma_f32_16x16x32_bf16 v[124:127], v[140:143], v[174:177], v[124:127]
	v_mfma_f32_16x16x32_bf16 v[108:111], v[132:135], v[182:185], v[108:111]
	v_mfma_f32_16x16x32_bf16 v[104:107], v[140:143], v[182:185], v[104:107]
	v_mfma_f32_16x16x32_bf16 v[92:95], v[132:135], v[192:195], v[92:95]
	v_mfma_f32_16x16x32_bf16 v[88:91], v[140:143], v[192:195], v[88:91]
	v_mfma_f32_16x16x32_bf16 v[76:79], v[132:135], v[200:203], v[76:79]
	v_mfma_f32_16x16x32_bf16 v[72:75], v[140:143], v[200:203], v[72:75]
	v_mfma_f32_16x16x32_bf16 v[116:119], v[144:147], v[170:173], 0
	v_mfma_f32_16x16x32_bf16 v[112:115], v[152:155], v[170:173], 0
	v_mfma_f32_16x16x32_bf16 v[100:103], v[144:147], v[178:181], 0
	v_mfma_f32_16x16x32_bf16 v[96:99], v[152:155], v[178:181], 0
	v_mfma_f32_16x16x32_bf16 v[84:87], v[144:147], v[186:189], 0
	v_mfma_f32_16x16x32_bf16 v[80:83], v[152:155], v[186:189], 0
	v_mfma_f32_16x16x32_bf16 v[68:71], v[144:147], v[196:199], 0
	v_mfma_f32_16x16x32_bf16 v[64:67], v[152:155], v[196:199], 0
	v_mfma_f32_16x16x32_bf16 v[116:119], v[148:151], v[174:177], v[116:119]
	v_mfma_f32_16x16x32_bf16 v[112:115], v[156:159], v[174:177], v[112:115]
	v_mfma_f32_16x16x32_bf16 v[100:103], v[148:151], v[182:185], v[100:103]
	v_mfma_f32_16x16x32_bf16 v[96:99], v[156:159], v[182:185], v[96:99]
	v_mfma_f32_16x16x32_bf16 v[84:87], v[148:151], v[192:195], v[84:87]
	v_mfma_f32_16x16x32_bf16 v[80:83], v[156:159], v[192:195], v[80:83]
	v_mfma_f32_16x16x32_bf16 v[68:71], v[148:151], v[200:203], v[68:71]
	v_mfma_f32_16x16x32_bf16 v[64:67], v[156:159], v[200:203], v[64:67]
	s_setprio 0
	s_barrier
	s_add_i32 s77, s77, s3
	v_lshl_add_u64 v[204:205], s[72:73], 0, v[160:161]
	s_mov_b32 m0, s77
	ds_read_b128 v[170:173], v191 offset:16384
	ds_read_b128 v[174:177], v191 offset:17408
	ds_read_b128 v[178:181], v191 offset:18432
	ds_read_b128 v[182:185], v191 offset:19456
	ds_read_b128 v[186:189], v191 offset:20480
	ds_read_b128 v[192:195], v191 offset:21504
	ds_read_b128 v[196:199], v191 offset:22528
	ds_read_b128 v[200:203], v191 offset:23552
	global_load_lds_dwordx4 v[204:205], off
	s_add_i32 m0, s77, 0x2000
	v_lshl_add_u64 v[206:207], s[72:73], 0, v[162:163]
	s_add_u32 s72, s72, s42
	s_addc_u32 s73, s73, s43
	s_add_i32 s77, s82, s3
	global_load_lds_dwordx4 v[206:207], off
	v_lshl_add_u64 v[212:213], s[72:73], 0, v[160:161]
	s_mov_b32 m0, s77
	v_lshl_add_u64 v[214:215], s[72:73], 0, v[162:163]
	global_load_lds_dwordx4 v[212:213], off
	s_add_i32 m0, s77, 0x2000
	v_lshl_add_u64 v[216:217], s[34:35], 0, v[160:161]
	global_load_lds_dwordx4 v[214:215], off
	s_mov_b32 m0, s8
	v_lshl_add_u64 v[218:219], s[34:35], 0, v[162:163]
	global_load_lds_dwordx4 v[216:217], off
	s_mov_b32 m0, s9
	s_nop 0
	global_load_lds_dwordx4 v[218:219], off
	s_waitcnt vmcnt(8)
	s_waitcnt lgkmcnt(0)
	s_barrier
; #define PG8_STAGE(bufoff, gbase, voff) do { _Pragma("unroll") for (int _i = 0; _i < 2; ++_i) \
;         __builtin_amdgcn_global_load_lds((const unsigned*)((const char*)(gbase) + (voff)[_i]), (PG8_LAS unsigned*)(lds + (bufoff) + ldsw + _i * 8192), 16, 0, 0); } while (0)
; #define PG8_LDA(dst, b, h) do { _Pragma("unroll") for (int m = 0; m < 4; ++m) _Pragma("unroll") for (int k = 0; k < 2; ++k) dst[m][k] = *(const PG8_LAS bf16x8*)(lds + PG8_SA(b, h) + aoff + m * 2048 + k * 1024); } while (0)
; #define PG8_LDB(dst, b, h) do { _Pragma("unroll") for (int n = 0; n < 2; ++n) _Pragma("unroll") for (int k = 0; k < 2; ++k) dst[n][k] = *(const PG8_LAS bf16x8*)(lds + PG8_SB(b, h) + boff + n * 2048 + k * 1024); } while (0)
; #define PG8_MMA(ai, bj, At, Bt) do { __builtin_amdgcn_s_setprio(1); _Pragma("unroll") for (int m = 0; m < 4; ++m) _Pragma("unroll") for (int n = 0; n < 2; ++n) _Pragma("unroll") for (int k = 0; k < 2; ++k) \
;         acc[ai][bj][m][n] = mma16<Epi::F16>(Bt[n][k], At[m][k], acc[ai][bj][m][n]); __builtin_amdgcn_s_setprio(0); } while (0)
; #define PG8_WAIT_V(n) asm volatile("s_waitcnt vmcnt(" #n ")" ::: "memory")
; #define PG8_WAIT_L(n) asm volatile("s_waitcnt lgkmcnt(" #n ")" ::: "memory")
; #define PG8_BAR __builtin_amdgcn_s_barrier()
; #define PG8_SCHED __builtin_amdgcn_sched_barrier(0)
; template <class Epi, class Sched, bool ALIGN_EPI = false, bool SP2 = false>
; __device__ __forceinline__ void gemm_phase(PG8_LAS unsigned char* lds, const Gemm g, const Sched& S, const Epi& E) {
;     ...
;             PG8_LDA(At, 0, 1); PG8_STAGE(PG8_SB(0, 0), b2, voffB); PG8_STAGE(PG8_SB(0, 1), b2 + hstep, voffB); PG8_STAGE(PG8_SA(0, 0), a2, voffA);
;             PG8_WAIT_V(8); PG8_WAIT_L(0); PG8_BAR; PG8_MMA(1, 0, At, B0); PG8_MMA(1, 1, At, B1); PG8_BAR; PG8_SCHED;
;             PG8_LDB(B0, 1, 0); PG8_LDB(B1, 1, 1); PG8_SCHED; PG8_LDA(At, 1, 0); PG8_STAGE(PG8_SA(0, 1), a2 + hstep, voffA);
;             PG8_WAIT_V(8); PG8_WAIT_L(0); PG8_BAR; PG8_MMA(0, 0, At, B0); PG8_MMA(0, 1, At, B1); PG8_BAR; PG8_SCHED;
	s_setprio 1
	s_waitcnt lgkmcnt(0)
	v_mfma_f32_16x16x32_bf16 v[60:63], v[120:123], v[170:173], 0
	v_mfma_f32_16x16x32_bf16 v[56:59], v[136:139], v[170:173], 0
	v_mfma_f32_16x16x32_bf16 v[44:47], v[120:123], v[178:181], 0
	v_mfma_f32_16x16x32_bf16 v[40:43], v[136:139], v[178:181], 0
	v_mfma_f32_16x16x32_bf16 v[28:31], v[120:123], v[186:189], 0
	v_mfma_f32_16x16x32_bf16 v[24:27], v[136:139], v[186:189], 0
	v_mfma_f32_16x16x32_bf16 v[12:15], v[120:123], v[196:199], 0
	v_mfma_f32_16x16x32_bf16 v[8:11], v[136:139], v[196:199], 0
	v_mfma_f32_16x16x32_bf16 v[60:63], v[132:135], v[174:177], v[60:63]
	v_mfma_f32_16x16x32_bf16 v[56:59], v[140:143], v[174:177], v[56:59]
	v_mfma_f32_16x16x32_bf16 v[44:47], v[132:135], v[182:185], v[44:47]
	v_mfma_f32_16x16x32_bf16 v[40:43], v[140:143], v[182:185], v[40:43]
	v_mfma_f32_16x16x32_bf16 v[28:31], v[132:135], v[192:195], v[28:31]
	v_mfma_f32_16x16x32_bf16 v[24:27], v[140:143], v[192:195], v[24:27]
	v_mfma_f32_16x16x32_bf16 v[12:15], v[132:135], v[200:203], v[12:15]
	v_mfma_f32_16x16x32_bf16 v[8:11], v[140:143], v[200:203], v[8:11]
	v_mfma_f32_16x16x32_bf16 v[52:55], v[144:147], v[170:173], 0
	v_mfma_f32_16x16x32_bf16 v[48:51], v[152:155], v[170:173], 0
	v_mfma_f32_16x16x32_bf16 v[36:39], v[144:147], v[178:181], 0
	v_mfma_f32_16x16x32_bf16 v[32:35], v[152:155], v[178:181], 0
	v_mfma_f32_16x16x32_bf16 v[20:23], v[144:147], v[186:189], 0
	v_mfma_f32_16x16x32_bf16 v[16:19], v[152:155], v[186:189], 0
	v_mfma_f32_16x16x32_bf16 v[4:7], v[144:147], v[196:199], 0
	v_mfma_f32_16x16x32_bf16 v[0:3], v[152:155], v[196:199], 0
	v_mfma_f32_16x16x32_bf16 v[52:55], v[148:151], v[174:177], v[52:55]
	v_mfma_f32_16x16x32_bf16 v[48:51], v[156:159], v[174:177], v[48:51]
	v_mfma_f32_16x16x32_bf16 v[36:39], v[148:151], v[182:185], v[36:39]
	v_mfma_f32_16x16x32_bf16 v[32:35], v[156:159], v[182:185], v[32:35]
	v_mfma_f32_16x16x32_bf16 v[20:23], v[148:151], v[192:195], v[20:23]
	v_mfma_f32_16x16x32_bf16 v[16:19], v[156:159], v[192:195], v[16:19]
	v_mfma_f32_16x16x32_bf16 v[4:7], v[148:151], v[200:203], v[4:7]
	v_mfma_f32_16x16x32_bf16 v[0:3], v[156:159], v[200:203], v[0:3]
	s_setprio 0
	s_barrier
	s_add_i32 s72, 0, 0x18000
	s_add_i32 s73, 0, 0x1c000
	v_add_u32_e32 v140, s72, v190
	v_add_u32_e32 v156, s73, v190
	ds_read_b128 v[120:123], v140
	ds_read_b128 v[132:135], v140 offset:1024
	ds_read_b128 v[136:139], v140 offset:2048
	ds_read_b128 v[140:143], v140 offset:3072
	ds_read_b128 v[144:147], v156
	ds_read_b128 v[148:151], v156 offset:1024
	ds_read_b128 v[152:155], v156 offset:2048
	ds_read_b128 v[156:159], v156 offset:3072
	s_add_u32 s34, s34, s42
	s_addc_u32 s35, s35, s43
	s_mov_b32 m0, s11
	v_lshl_add_u64 v[220:221], s[34:35], 0, v[160:161]
	ds_read_b128 v[170:173], v191 offset:32768
	ds_read_b128 v[174:177], v191 offset:33792
	ds_read_b128 v[178:181], v191 offset:34816
	ds_read_b128 v[182:185], v191 offset:35840
	ds_read_b128 v[186:189], v191 offset:36864
	ds_read_b128 v[192:195], v191 offset:37888
	ds_read_b128 v[196:199], v191 offset:38912
	ds_read_b128 v[200:203], v191 offset:39936
	global_load_lds_dwordx4 v[220:221], off
	v_lshl_add_u64 v[220:221], s[34:35], 0, v[162:163]
	s_mov_b32 m0, s36
	s_nop 0
	global_load_lds_dwordx4 v[220:221], off
	s_waitcnt vmcnt(8)
	s_waitcnt lgkmcnt(0)
	s_barrier
	s_setprio 1
	s_waitcnt lgkmcnt(0)
	v_mfma_f32_16x16x32_bf16 v[128:131], v[120:123], v[170:173], v[128:131]
	v_mfma_f32_16x16x32_bf16 v[124:127], v[136:139], v[170:173], v[124:127]
	v_mfma_f32_16x16x32_bf16 v[108:111], v[120:123], v[178:181], v[108:111]
	v_mfma_f32_16x16x32_bf16 v[104:107], v[136:139], v[178:181], v[104:107]
	v_mfma_f32_16x16x32_bf16 v[92:95], v[120:123], v[186:189], v[92:95]
	v_mfma_f32_16x16x32_bf16 v[88:91], v[136:139], v[186:189], v[88:91]
	v_mfma_f32_16x16x32_bf16 v[76:79], v[120:123], v[196:199], v[76:79]
	v_mfma_f32_16x16x32_bf16 v[72:75], v[136:139], v[196:199], v[72:75]
	v_mfma_f32_16x16x32_bf16 v[128:131], v[132:135], v[174:177], v[128:131]
	v_mfma_f32_16x16x32_bf16 v[124:127], v[140:143], v[174:177], v[124:127]
	v_mfma_f32_16x16x32_bf16 v[108:111], v[132:135], v[182:185], v[108:111]
	v_mfma_f32_16x16x32_bf16 v[104:107], v[140:143], v[182:185], v[104:107]
	v_mfma_f32_16x16x32_bf16 v[92:95], v[132:135], v[192:195], v[92:95]
	v_mfma_f32_16x16x32_bf16 v[88:91], v[140:143], v[192:195], v[88:91]
	v_mfma_f32_16x16x32_bf16 v[76:79], v[132:135], v[200:203], v[76:79]
	v_mfma_f32_16x16x32_bf16 v[72:75], v[140:143], v[200:203], v[72:75]
	v_mfma_f32_16x16x32_bf16 v[116:119], v[144:147], v[170:173], v[116:119]
	v_mfma_f32_16x16x32_bf16 v[112:115], v[152:155], v[170:173], v[112:115]
	v_mfma_f32_16x16x32_bf16 v[100:103], v[144:147], v[178:181], v[100:103]
	v_mfma_f32_16x16x32_bf16 v[96:99], v[152:155], v[178:181], v[96:99]
	v_mfma_f32_16x16x32_bf16 v[84:87], v[144:147], v[186:189], v[84:87]
	v_mfma_f32_16x16x32_bf16 v[80:83], v[152:155], v[186:189], v[80:83]
	v_mfma_f32_16x16x32_bf16 v[68:71], v[144:147], v[196:199], v[68:71]
	v_mfma_f32_16x16x32_bf16 v[64:67], v[152:155], v[196:199], v[64:67]
	v_mfma_f32_16x16x32_bf16 v[116:119], v[148:151], v[174:177], v[116:119]
	v_mfma_f32_16x16x32_bf16 v[112:115], v[156:159], v[174:177], v[112:115]
	v_mfma_f32_16x16x32_bf16 v[100:103], v[148:151], v[182:185], v[100:103]
	v_mfma_f32_16x16x32_bf16 v[96:99], v[156:159], v[182:185], v[96:99]
	v_mfma_f32_16x16x32_bf16 v[84:87], v[148:151], v[192:195], v[84:87]
	v_mfma_f32_16x16x32_bf16 v[80:83], v[156:159], v[192:195], v[80:83]
	v_mfma_f32_16x16x32_bf16 v[68:71], v[148:151], v[200:203], v[68:71]
	v_mfma_f32_16x16x32_bf16 v[64:67], v[156:159], v[200:203], v[64:67]
	s_setprio 0
	s_barrier
; #define PG8_STAGE(bufoff, gbase, voff) do { _Pragma("unroll") for (int _i = 0; _i < 2; ++_i) \
;         __builtin_amdgcn_global_load_lds((const unsigned*)((const char*)(gbase) + (voff)[_i]), (PG8_LAS unsigned*)(lds + (bufoff) + ldsw + _i * 8192), 16, 0, 0); } while (0)
; #define PG8_LDA(dst, b, h) do { _Pragma("unroll") for (int m = 0; m < 4; ++m) _Pragma("unroll") for (int k = 0; k < 2; ++k) dst[m][k] = *(const PG8_LAS bf16x8*)(lds + PG8_SA(b, h) + aoff + m * 2048 + k * 1024); } while (0)
; #define PG8_LDB(dst, b, h) do { _Pragma("unroll") for (int n = 0; n < 2; ++n) _Pragma("unroll") for (int k = 0; k < 2; ++k) dst[n][k] = *(const PG8_LAS bf16x8*)(lds + PG8_SB(b, h) + boff + n * 2048 + k * 1024); } while (0)
; #define PG8_MMA(ai, bj, At, Bt) do { __builtin_amdgcn_s_setprio(1); _Pragma("unroll") for (int m = 0; m < 4; ++m) _Pragma("unroll") for (int n = 0; n < 2; ++n) _Pragma("unroll") for (int k = 0; k < 2; ++k) \
;         acc[ai][bj][m][n] = mma16<Epi::F16>(Bt[n][k], At[m][k], acc[ai][bj][m][n]); __builtin_amdgcn_s_setprio(0); } while (0)
; #define PG8_WAIT_V(n) asm volatile("s_waitcnt vmcnt(" #n ")" ::: "memory")
; #define PG8_WAIT_L(n) asm volatile("s_waitcnt lgkmcnt(" #n ")" ::: "memory")
; #define PG8_BAR __builtin_amdgcn_s_barrier()
; #define PG8_SCHED __builtin_amdgcn_sched_barrier(0)
; template <class Epi, class Sched, bool ALIGN_EPI = false, bool SP2 = false>
; __device__ __forceinline__ void gemm_phase(PG8_LAS unsigned char* lds, const Gemm g, const Sched& S, const Epi& E) {
;     ...
;         for (int t = 0; t < nt; t += 2) {
;             const bool last = (t == nt - 2);
;             const char* a1 = cA + (size_t)(t + 1) * kstep;
;             const char* a2 = last ? nA : cA + (size_t)(t + 2) * kstep; const char* b2 = last ? nB : cB + (size_t)(t + 2) * kstep;
;             const char* a3 = a2 + kstep; const char* b3 = b2 + kstep;
;             if (last && has_next) S.a_ready(nxt);
;             if constexpr (SP2) {
;             PG8_LDB(B0, 0, 0); PG8_LDB(B1, 0, 1); PG8_SCHED; PG8_LDA(At, 0, 0); PG8_STAGE(PG8_SA(1, 1), a1 + hstep, voffA);
;     ...
;             PG8_LDA(At, 1, 1); PG8_STAGE(PG8_SB(1, 0), b3, voffB); PG8_STAGE(PG8_SB(1, 1), b3 + hstep, voffB); PG8_STAGE(PG8_SA(1, 0), a3, voffA);
;             PG8_WAIT_V(8); PG8_WAIT_L(0); PG8_BAR; PG8_MMA(1, 0, At, B0); PG8_MMA(1, 1, At, B1); PG8_BAR; PG8_SCHED;
	s_add_i32 s34, s72, s3
	v_lshl_add_u64 v[204:205], v[204:205], 0, s[20:21]
	s_mov_b32 m0, s34
	ds_read_b128 v[170:173], v191 offset:49152
	ds_read_b128 v[174:177], v191 offset:50176
	ds_read_b128 v[178:181], v191 offset:51200
	ds_read_b128 v[182:185], v191 offset:52224
	ds_read_b128 v[186:189], v191 offset:53248
	ds_read_b128 v[192:195], v191 offset:54272
	ds_read_b128 v[196:199], v191 offset:55296
	ds_read_b128 v[200:203], v191 offset:56320
	global_load_lds_dwordx4 v[204:205], off
	v_lshl_add_u64 v[204:205], v[206:207], 0, s[20:21]
	s_add_i32 m0, s34, 0x2000
	s_add_i32 s34, s73, s3
	global_load_lds_dwordx4 v[204:205], off
	v_lshl_add_u64 v[204:205], v[212:213], 0, s[20:21]
	s_mov_b32 m0, s34
	s_nop 0
	global_load_lds_dwordx4 v[204:205], off
	v_lshl_add_u64 v[204:205], v[214:215], 0, s[20:21]
	s_add_i32 m0, s34, 0x2000
	s_nop 0
	global_load_lds_dwordx4 v[204:205], off
	v_lshl_add_u64 v[204:205], v[216:217], 0, s[20:21]
	s_mov_b32 m0, s60
	s_nop 0
	global_load_lds_dwordx4 v[204:205], off
	v_lshl_add_u64 v[204:205], v[218:219], 0, s[20:21]
	s_mov_b32 m0, s61
	s_nop 0
	global_load_lds_dwordx4 v[204:205], off
	s_waitcnt vmcnt(8)
	s_waitcnt lgkmcnt(0)
	s_barrier
	s_setprio 1
	s_waitcnt lgkmcnt(0)
	v_mfma_f32_16x16x32_bf16 v[60:63], v[120:123], v[170:173], v[60:63]
	v_mfma_f32_16x16x32_bf16 v[56:59], v[136:139], v[170:173], v[56:59]
	v_mfma_f32_16x16x32_bf16 v[44:47], v[120:123], v[178:181], v[44:47]
	v_mfma_f32_16x16x32_bf16 v[40:43], v[136:139], v[178:181], v[40:43]
	v_mfma_f32_16x16x32_bf16 v[28:31], v[120:123], v[186:189], v[28:31]
	v_mfma_f32_16x16x32_bf16 v[24:27], v[136:139], v[186:189], v[24:27]
	v_mfma_f32_16x16x32_bf16 v[12:15], v[120:123], v[196:199], v[12:15]
	v_mfma_f32_16x16x32_bf16 v[8:11], v[136:139], v[196:199], v[8:11]
	v_mfma_f32_16x16x32_bf16 v[60:63], v[132:135], v[174:177], v[60:63]
	v_mfma_f32_16x16x32_bf16 v[56:59], v[140:143], v[174:177], v[56:59]
	v_mfma_f32_16x16x32_bf16 v[44:47], v[132:135], v[182:185], v[44:47]
	v_mfma_f32_16x16x32_bf16 v[40:43], v[140:143], v[182:185], v[40:43]
	v_mfma_f32_16x16x32_bf16 v[28:31], v[132:135], v[192:195], v[28:31]
	v_mfma_f32_16x16x32_bf16 v[24:27], v[140:143], v[192:195], v[24:27]
	v_mfma_f32_16x16x32_bf16 v[12:15], v[132:135], v[200:203], v[12:15]
	v_mfma_f32_16x16x32_bf16 v[8:11], v[140:143], v[200:203], v[8:11]
	v_mfma_f32_16x16x32_bf16 v[52:55], v[144:147], v[170:173], v[52:55]
	v_mfma_f32_16x16x32_bf16 v[48:51], v[152:155], v[170:173], v[48:51]
	v_mfma_f32_16x16x32_bf16 v[36:39], v[144:147], v[178:181], v[36:39]
	v_mfma_f32_16x16x32_bf16 v[32:35], v[152:155], v[178:181], v[32:35]
	v_mfma_f32_16x16x32_bf16 v[20:23], v[144:147], v[186:189], v[20:23]
	v_mfma_f32_16x16x32_bf16 v[16:19], v[152:155], v[186:189], v[16:19]
	v_mfma_f32_16x16x32_bf16 v[4:7], v[144:147], v[196:199], v[4:7]
	v_mfma_f32_16x16x32_bf16 v[0:3], v[152:155], v[196:199], v[0:3]
	v_mfma_f32_16x16x32_bf16 v[52:55], v[148:151], v[174:177], v[52:55]
	v_mfma_f32_16x16x32_bf16 v[48:51], v[156:159], v[174:177], v[48:51]
	v_mfma_f32_16x16x32_bf16 v[36:39], v[148:151], v[182:185], v[36:39]
	v_mfma_f32_16x16x32_bf16 v[32:35], v[156:159], v[182:185], v[32:35]
	v_mfma_f32_16x16x32_bf16 v[20:23], v[148:151], v[192:195], v[20:23]
	v_mfma_f32_16x16x32_bf16 v[16:19], v[156:159], v[192:195], v[16:19]
	v_mfma_f32_16x16x32_bf16 v[4:7], v[148:151], v[200:203], v[4:7]
	v_mfma_f32_16x16x32_bf16 v[0:3], v[156:159], v[200:203], v[0:3]
	s_setprio 0
	s_barrier
	s_add_u32 s30, s30, 0x100
	s_addc_u32 s31, s31, 0
	s_add_u32 s40, s40, 0x100
	s_addc_u32 s41, s41, 0
	s_cmp_ge_i32 s71, s48
	s_mov_b32 s34, s71
	s_cbranch_scc0 .LBB0_1170
	s_branch .LBB0_1171
.LBB0_1170:
	s_add_i32 s71, s34, 2
	s_add_u32 s72, s30, 0x80
	s_addc_u32 s35, s31, 0
	s_add_i32 s77, 0, 0x10000
	s_cmp_eq_u32 s62, s34
	s_cselect_b32 s35, s1, s35
	s_cselect_b32 s34, s0, s72
	s_cselect_b32 s73, s29, s41
	s_cselect_b32 s72, s28, s40
	s_add_i32 s82, 0, 0x14000
	v_add_u32_e32 v140, s77, v190
	v_add_u32_e32 v156, s82, v190
	ds_read_b128 v[120:123], v140
	ds_read_b128 v[132:135], v140 offset:1024
	ds_read_b128 v[136:139], v140 offset:2048
	ds_read_b128 v[140:143], v140 offset:3072
	ds_read_b128 v[144:147], v156
	ds_read_b128 v[148:151], v156 offset:1024
	ds_read_b128 v[152:155], v156 offset:2048
	ds_read_b128 v[156:159], v156 offset:3072
	v_lshl_add_u64 v[204:205], s[30:31], 0, v[166:167]
	s_add_i32 m0, s8, 0xc000
	ds_read_b128 v[170:173], v191
	ds_read_b128 v[174:177], v191 offset:1024
	ds_read_b128 v[178:181], v191 offset:2048
	ds_read_b128 v[182:185], v191 offset:3072
	ds_read_b128 v[186:189], v191 offset:4096
	ds_read_b128 v[192:195], v191 offset:5120
	ds_read_b128 v[196:199], v191 offset:6144
	ds_read_b128 v[200:203], v191 offset:7168
	global_load_lds_dwordx4 v[204:205], off
	v_lshl_add_u64 v[204:205], s[30:31], 0, v[168:169]
	s_add_i32 m0, s8, 0xe000
	s_nop 0
	global_load_lds_dwordx4 v[204:205], off
	s_waitcnt vmcnt(8)
	s_waitcnt lgkmcnt(0)
	s_barrier
; #define PG8_STAGE(bufoff, gbase, voff) do { _Pragma("unroll") for (int _i = 0; _i < 2; ++_i) \
;         __builtin_amdgcn_global_load_lds((const unsigned*)((const char*)(gbase) + (voff)[_i]), (PG8_LAS unsigned*)(lds + (bufoff) + ldsw + _i * 8192), 16, 0, 0); } while (0)
; #define PG8_LDA(dst, b, h) do { _Pragma("unroll") for (int m = 0; m < 4; ++m) _Pragma("unroll") for (int k = 0; k < 2; ++k) dst[m][k] = *(const PG8_LAS bf16x8*)(lds + PG8_SA(b, h) + aoff + m * 2048 + k * 1024); } while (0)
; #define PG8_MMA(ai, bj, At, Bt) do { __builtin_amdgcn_s_setprio(1); _Pragma("unroll") for (int m = 0; m < 4; ++m) _Pragma("unroll") for (int n = 0; n < 2; ++n) _Pragma("unroll") for (int k = 0; k < 2; ++k) \
;         acc[ai][bj][m][n] = mma16<Epi::F16>(Bt[n][k], At[m][k], acc[ai][bj][m][n]); __builtin_amdgcn_s_setprio(0); } while (0)
; #define PG8_WAIT_V(n) asm volatile("s_waitcnt vmcnt(" #n ")" ::: "memory")
; #define PG8_WAIT_L(n) asm volatile("s_waitcnt lgkmcnt(" #n ")" ::: "memory")
; #define PG8_BAR __builtin_amdgcn_s_barrier()
; #define PG8_SCHED __builtin_amdgcn_sched_barrier(0)
; template <class Epi, class Sched, bool ALIGN_EPI = false, bool SP2 = false>
; __device__ __forceinline__ void gemm_phase(PG8_LAS unsigned char* lds, const Gemm g, const Sched& S, const Epi& E) {
;     ...
;             PG8_WAIT_V(8); PG8_WAIT_L(0); PG8_BAR; PG8_MMA(0, 0, At, B0); PG8_MMA(0, 1, At, B1); PG8_BAR; PG8_SCHED;
;             PG8_LDA(At, 0, 1); PG8_STAGE(PG8_SB(0, 0), b2, voffB); PG8_STAGE(PG8_SB(0, 1), b2 + hstep, voffB); PG8_STAGE(PG8_SA(0, 0), a2, voffA);
;             PG8_WAIT_V(8); PG8_WAIT_L(0); PG8_BAR; PG8_MMA(1, 0, At, B0); PG8_MMA(1, 1, At, B1); PG8_BAR; PG8_SCHED;
	s_setprio 1
	s_waitcnt lgkmcnt(0)
	v_mfma_f32_16x16x32_bf16 v[128:131], v[120:123], v[170:173], v[128:131]
	v_mfma_f32_16x16x32_bf16 v[124:127], v[136:139], v[170:173], v[124:127]
	v_mfma_f32_16x16x32_bf16 v[108:111], v[120:123], v[178:181], v[108:111]
	v_mfma_f32_16x16x32_bf16 v[104:107], v[136:139], v[178:181], v[104:107]
	v_mfma_f32_16x16x32_bf16 v[92:95], v[120:123], v[186:189], v[92:95]
	v_mfma_f32_16x16x32_bf16 v[88:91], v[136:139], v[186:189], v[88:91]
	v_mfma_f32_16x16x32_bf16 v[76:79], v[120:123], v[196:199], v[76:79]
	v_mfma_f32_16x16x32_bf16 v[72:75], v[136:139], v[196:199], v[72:75]
	v_mfma_f32_16x16x32_bf16 v[128:131], v[132:135], v[174:177], v[128:131]
	v_mfma_f32_16x16x32_bf16 v[124:127], v[140:143], v[174:177], v[124:127]
	v_mfma_f32_16x16x32_bf16 v[108:111], v[132:135], v[182:185], v[108:111]
	v_mfma_f32_16x16x32_bf16 v[104:107], v[140:143], v[182:185], v[104:107]
	v_mfma_f32_16x16x32_bf16 v[92:95], v[132:135], v[192:195], v[92:95]
	v_mfma_f32_16x16x32_bf16 v[88:91], v[140:143], v[192:195], v[88:91]
	v_mfma_f32_16x16x32_bf16 v[76:79], v[132:135], v[200:203], v[76:79]
	v_mfma_f32_16x16x32_bf16 v[72:75], v[140:143], v[200:203], v[72:75]
	v_mfma_f32_16x16x32_bf16 v[116:119], v[144:147], v[170:173], v[116:119]
	v_mfma_f32_16x16x32_bf16 v[112:115], v[152:155], v[170:173], v[112:115]
	v_mfma_f32_16x16x32_bf16 v[100:103], v[144:147], v[178:181], v[100:103]
	v_mfma_f32_16x16x32_bf16 v[96:99], v[152:155], v[178:181], v[96:99]
	v_mfma_f32_16x16x32_bf16 v[84:87], v[144:147], v[186:189], v[84:87]
	v_mfma_f32_16x16x32_bf16 v[80:83], v[152:155], v[186:189], v[80:83]
	v_mfma_f32_16x16x32_bf16 v[68:71], v[144:147], v[196:199], v[68:71]
	v_mfma_f32_16x16x32_bf16 v[64:67], v[152:155], v[196:199], v[64:67]
	v_mfma_f32_16x16x32_bf16 v[116:119], v[148:151], v[174:177], v[116:119]
	v_mfma_f32_16x16x32_bf16 v[112:115], v[156:159], v[174:177], v[112:115]
	v_mfma_f32_16x16x32_bf16 v[100:103], v[148:151], v[182:185], v[100:103]
	v_mfma_f32_16x16x32_bf16 v[96:99], v[156:159], v[182:185], v[96:99]
	v_mfma_f32_16x16x32_bf16 v[84:87], v[148:151], v[192:195], v[84:87]
	v_mfma_f32_16x16x32_bf16 v[80:83], v[156:159], v[192:195], v[80:83]
	v_mfma_f32_16x16x32_bf16 v[68:71], v[148:151], v[200:203], v[68:71]
	v_mfma_f32_16x16x32_bf16 v[64:67], v[156:159], v[200:203], v[64:67]
	s_setprio 0
	s_barrier
	s_add_i32 s77, s77, s3
	v_lshl_add_u64 v[204:205], s[72:73], 0, v[160:161]
	s_mov_b32 m0, s77
	ds_read_b128 v[170:173], v191 offset:16384
	ds_read_b128 v[174:177], v191 offset:17408
	ds_read_b128 v[178:181], v191 offset:18432
	ds_read_b128 v[182:185], v191 offset:19456
	ds_read_b128 v[186:189], v191 offset:20480
	ds_read_b128 v[192:195], v191 offset:21504
	ds_read_b128 v[196:199], v191 offset:22528
	ds_read_b128 v[200:203], v191 offset:23552
	global_load_lds_dwordx4 v[204:205], off
	s_add_i32 m0, s77, 0x2000
	v_lshl_add_u64 v[206:207], s[72:73], 0, v[162:163]
	s_add_u32 s72, s72, s42
	s_addc_u32 s73, s73, s43
	s_add_i32 s77, s82, s3
	global_load_lds_dwordx4 v[206:207], off
	v_lshl_add_u64 v[212:213], s[72:73], 0, v[160:161]
	s_mov_b32 m0, s77
	v_lshl_add_u64 v[214:215], s[72:73], 0, v[162:163]
	global_load_lds_dwordx4 v[212:213], off
	s_add_i32 m0, s77, 0x2000
	v_lshl_add_u64 v[216:217], s[34:35], 0, v[160:161]
	global_load_lds_dwordx4 v[214:215], off
	s_mov_b32 m0, s8
	v_lshl_add_u64 v[218:219], s[34:35], 0, v[162:163]
	global_load_lds_dwordx4 v[216:217], off
	s_mov_b32 m0, s9
	s_nop 0
	global_load_lds_dwordx4 v[218:219], off
	s_waitcnt vmcnt(8)
	s_waitcnt lgkmcnt(0)
	s_barrier
	s_setprio 1
	s_waitcnt lgkmcnt(0)
	v_mfma_f32_16x16x32_bf16 v[60:63], v[120:123], v[170:173], v[60:63]
	v_mfma_f32_16x16x32_bf16 v[56:59], v[136:139], v[170:173], v[56:59]
	v_mfma_f32_16x16x32_bf16 v[44:47], v[120:123], v[178:181], v[44:47]
	v_mfma_f32_16x16x32_bf16 v[40:43], v[136:139], v[178:181], v[40:43]
	v_mfma_f32_16x16x32_bf16 v[28:31], v[120:123], v[186:189], v[28:31]
	v_mfma_f32_16x16x32_bf16 v[24:27], v[136:139], v[186:189], v[24:27]
	v_mfma_f32_16x16x32_bf16 v[12:15], v[120:123], v[196:199], v[12:15]
	v_mfma_f32_16x16x32_bf16 v[8:11], v[136:139], v[196:199], v[8:11]
	v_mfma_f32_16x16x32_bf16 v[60:63], v[132:135], v[174:177], v[60:63]
	v_mfma_f32_16x16x32_bf16 v[56:59], v[140:143], v[174:177], v[56:59]
	v_mfma_f32_16x16x32_bf16 v[44:47], v[132:135], v[182:185], v[44:47]
	v_mfma_f32_16x16x32_bf16 v[40:43], v[140:143], v[182:185], v[40:43]
	v_mfma_f32_16x16x32_bf16 v[28:31], v[132:135], v[192:195], v[28:31]
	v_mfma_f32_16x16x32_bf16 v[24:27], v[140:143], v[192:195], v[24:27]
	v_mfma_f32_16x16x32_bf16 v[12:15], v[132:135], v[200:203], v[12:15]
	v_mfma_f32_16x16x32_bf16 v[8:11], v[140:143], v[200:203], v[8:11]
	v_mfma_f32_16x16x32_bf16 v[52:55], v[144:147], v[170:173], v[52:55]
	v_mfma_f32_16x16x32_bf16 v[48:51], v[152:155], v[170:173], v[48:51]
	v_mfma_f32_16x16x32_bf16 v[36:39], v[144:147], v[178:181], v[36:39]
	v_mfma_f32_16x16x32_bf16 v[32:35], v[152:155], v[178:181], v[32:35]
	v_mfma_f32_16x16x32_bf16 v[20:23], v[144:147], v[186:189], v[20:23]
	v_mfma_f32_16x16x32_bf16 v[16:19], v[152:155], v[186:189], v[16:19]
	v_mfma_f32_16x16x32_bf16 v[4:7], v[144:147], v[196:199], v[4:7]
	v_mfma_f32_16x16x32_bf16 v[0:3], v[152:155], v[196:199], v[0:3]
	v_mfma_f32_16x16x32_bf16 v[52:55], v[148:151], v[174:177], v[52:55]
	v_mfma_f32_16x16x32_bf16 v[48:51], v[156:159], v[174:177], v[48:51]
	v_mfma_f32_16x16x32_bf16 v[36:39], v[148:151], v[182:185], v[36:39]
	v_mfma_f32_16x16x32_bf16 v[32:35], v[156:159], v[182:185], v[32:35]
	v_mfma_f32_16x16x32_bf16 v[20:23], v[148:151], v[192:195], v[20:23]
	v_mfma_f32_16x16x32_bf16 v[16:19], v[156:159], v[192:195], v[16:19]
	v_mfma_f32_16x16x32_bf16 v[4:7], v[148:151], v[200:203], v[4:7]
	v_mfma_f32_16x16x32_bf16 v[0:3], v[156:159], v[200:203], v[0:3]
	s_setprio 0
	s_barrier
; #define PG8_STAGE(bufoff, gbase, voff) do { _Pragma("unroll") for (int _i = 0; _i < 2; ++_i) \
;         __builtin_amdgcn_global_load_lds((const unsigned*)((const char*)(gbase) + (voff)[_i]), (PG8_LAS unsigned*)(lds + (bufoff) + ldsw + _i * 8192), 16, 0, 0); } while (0)
; #define PG8_LDA(dst, b, h) do { _Pragma("unroll") for (int m = 0; m < 4; ++m) _Pragma("unroll") for (int k = 0; k < 2; ++k) dst[m][k] = *(const PG8_LAS bf16x8*)(lds + PG8_SA(b, h) + aoff + m * 2048 + k * 1024); } while (0)
; #define PG8_LDB(dst, b, h) do { _Pragma("unroll") for (int n = 0; n < 2; ++n) _Pragma("unroll") for (int k = 0; k < 2; ++k) dst[n][k] = *(const PG8_LAS bf16x8*)(lds + PG8_SB(b, h) + boff + n * 2048 + k * 1024); } while (0)
; #define PG8_MMA(ai, bj, At, Bt) do { __builtin_amdgcn_s_setprio(1); _Pragma("unroll") for (int m = 0; m < 4; ++m) _Pragma("unroll") for (int n = 0; n < 2; ++n) _Pragma("unroll") for (int k = 0; k < 2; ++k) \
;         acc[ai][bj][m][n] = mma16<Epi::F16>(Bt[n][k], At[m][k], acc[ai][bj][m][n]); __builtin_amdgcn_s_setprio(0); } while (0)
; #define PG8_WAIT_V(n) asm volatile("s_waitcnt vmcnt(" #n ")" ::: "memory")
; #define PG8_WAIT_L(n) asm volatile("s_waitcnt lgkmcnt(" #n ")" ::: "memory")
; #define PG8_BAR __builtin_amdgcn_s_barrier()
; #define PG8_SCHED __builtin_amdgcn_sched_barrier(0)
; template <class Epi, class Sched, bool ALIGN_EPI = false, bool SP2 = false>
; __device__ __forceinline__ void gemm_phase(PG8_LAS unsigned char* lds, const Gemm g, const Sched& S, const Epi& E) {
;     ...
;             PG8_LDB(B0, 1, 0); PG8_LDB(B1, 1, 1); PG8_SCHED; PG8_LDA(At, 1, 0); PG8_STAGE(PG8_SA(0, 1), a2 + hstep, voffA);
;             PG8_WAIT_V(8); PG8_WAIT_L(0); PG8_BAR; PG8_MMA(0, 0, At, B0); PG8_MMA(0, 1, At, B1); PG8_BAR; PG8_SCHED;
;             PG8_LDA(At, 1, 1); PG8_STAGE(PG8_SB(1, 0), b3, voffB); PG8_STAGE(PG8_SB(1, 1), b3 + hstep, voffB); PG8_STAGE(PG8_SA(1, 0), a3, voffA);
;             PG8_WAIT_V(8); PG8_WAIT_L(0); PG8_BAR; PG8_MMA(1, 0, At, B0); PG8_MMA(1, 1, At, B1); PG8_BAR; PG8_SCHED;
	s_add_i32 s72, 0, 0x18000
	s_add_i32 s73, 0, 0x1c000
	v_add_u32_e32 v140, s72, v190
	v_add_u32_e32 v156, s73, v190
	ds_read_b128 v[120:123], v140
	ds_read_b128 v[132:135], v140 offset:1024
	ds_read_b128 v[136:139], v140 offset:2048
	ds_read_b128 v[140:143], v140 offset:3072
	ds_read_b128 v[144:147], v156
	ds_read_b128 v[148:151], v156 offset:1024
	ds_read_b128 v[152:155], v156 offset:2048
	ds_read_b128 v[156:159], v156 offset:3072
	s_add_u32 s34, s34, s42
	s_addc_u32 s35, s35, s43
	s_mov_b32 m0, s11
	v_lshl_add_u64 v[220:221], s[34:35], 0, v[160:161]
	ds_read_b128 v[170:173], v191 offset:32768
	ds_read_b128 v[174:177], v191 offset:33792
	ds_read_b128 v[178:181], v191 offset:34816
	ds_read_b128 v[182:185], v191 offset:35840
	ds_read_b128 v[186:189], v191 offset:36864
	ds_read_b128 v[192:195], v191 offset:37888
	ds_read_b128 v[196:199], v191 offset:38912
	ds_read_b128 v[200:203], v191 offset:39936
	global_load_lds_dwordx4 v[220:221], off
	v_lshl_add_u64 v[220:221], s[34:35], 0, v[162:163]
	s_mov_b32 m0, s36
	s_nop 0
	global_load_lds_dwordx4 v[220:221], off
	s_waitcnt vmcnt(8)
	s_waitcnt lgkmcnt(0)
	s_barrier
	s_setprio 1
	s_waitcnt lgkmcnt(0)
	v_mfma_f32_16x16x32_bf16 v[128:131], v[120:123], v[170:173], v[128:131]
	v_mfma_f32_16x16x32_bf16 v[124:127], v[136:139], v[170:173], v[124:127]
	v_mfma_f32_16x16x32_bf16 v[108:111], v[120:123], v[178:181], v[108:111]
	v_mfma_f32_16x16x32_bf16 v[104:107], v[136:139], v[178:181], v[104:107]
	v_mfma_f32_16x16x32_bf16 v[92:95], v[120:123], v[186:189], v[92:95]
	v_mfma_f32_16x16x32_bf16 v[88:91], v[136:139], v[186:189], v[88:91]
	v_mfma_f32_16x16x32_bf16 v[76:79], v[120:123], v[196:199], v[76:79]
	v_mfma_f32_16x16x32_bf16 v[72:75], v[136:139], v[196:199], v[72:75]
	v_mfma_f32_16x16x32_bf16 v[128:131], v[132:135], v[174:177], v[128:131]
	v_mfma_f32_16x16x32_bf16 v[124:127], v[140:143], v[174:177], v[124:127]
	v_mfma_f32_16x16x32_bf16 v[108:111], v[132:135], v[182:185], v[108:111]
	v_mfma_f32_16x16x32_bf16 v[104:107], v[140:143], v[182:185], v[104:107]
	v_mfma_f32_16x16x32_bf16 v[92:95], v[132:135], v[192:195], v[92:95]
	v_mfma_f32_16x16x32_bf16 v[88:91], v[140:143], v[192:195], v[88:91]
	v_mfma_f32_16x16x32_bf16 v[76:79], v[132:135], v[200:203], v[76:79]
	v_mfma_f32_16x16x32_bf16 v[72:75], v[140:143], v[200:203], v[72:75]
	v_mfma_f32_16x16x32_bf16 v[116:119], v[144:147], v[170:173], v[116:119]
	v_mfma_f32_16x16x32_bf16 v[112:115], v[152:155], v[170:173], v[112:115]
	v_mfma_f32_16x16x32_bf16 v[100:103], v[144:147], v[178:181], v[100:103]
	v_mfma_f32_16x16x32_bf16 v[96:99], v[152:155], v[178:181], v[96:99]
	v_mfma_f32_16x16x32_bf16 v[84:87], v[144:147], v[186:189], v[84:87]
	v_mfma_f32_16x16x32_bf16 v[80:83], v[152:155], v[186:189], v[80:83]
	v_mfma_f32_16x16x32_bf16 v[68:71], v[144:147], v[196:199], v[68:71]
	v_mfma_f32_16x16x32_bf16 v[64:67], v[152:155], v[196:199], v[64:67]
	v_mfma_f32_16x16x32_bf16 v[116:119], v[148:151], v[174:177], v[116:119]
	v_mfma_f32_16x16x32_bf16 v[112:115], v[156:159], v[174:177], v[112:115]
	v_mfma_f32_16x16x32_bf16 v[100:103], v[148:151], v[182:185], v[100:103]
	v_mfma_f32_16x16x32_bf16 v[96:99], v[156:159], v[182:185], v[96:99]
	v_mfma_f32_16x16x32_bf16 v[84:87], v[148:151], v[192:195], v[84:87]
	v_mfma_f32_16x16x32_bf16 v[80:83], v[156:159], v[192:195], v[80:83]
	v_mfma_f32_16x16x32_bf16 v[68:71], v[148:151], v[200:203], v[68:71]
	v_mfma_f32_16x16x32_bf16 v[64:67], v[156:159], v[200:203], v[64:67]
	s_setprio 0
	s_barrier
	s_add_i32 s34, s72, s3
	v_lshl_add_u64 v[204:205], v[204:205], 0, s[20:21]
	s_mov_b32 m0, s34
	ds_read_b128 v[170:173], v191 offset:49152
	ds_read_b128 v[174:177], v191 offset:50176
	ds_read_b128 v[178:181], v191 offset:51200
	ds_read_b128 v[182:185], v191 offset:52224
	ds_read_b128 v[186:189], v191 offset:53248
	ds_read_b128 v[192:195], v191 offset:54272
	ds_read_b128 v[196:199], v191 offset:55296
	ds_read_b128 v[200:203], v191 offset:56320
	global_load_lds_dwordx4 v[204:205], off
	v_lshl_add_u64 v[204:205], v[206:207], 0, s[20:21]
	s_add_i32 m0, s34, 0x2000
	s_add_i32 s34, s73, s3
	global_load_lds_dwordx4 v[204:205], off
	v_lshl_add_u64 v[204:205], v[212:213], 0, s[20:21]
	s_mov_b32 m0, s34
	s_nop 0
	global_load_lds_dwordx4 v[204:205], off
	v_lshl_add_u64 v[204:205], v[214:215], 0, s[20:21]
	s_add_i32 m0, s34, 0x2000
	s_nop 0
	global_load_lds_dwordx4 v[204:205], off
	v_lshl_add_u64 v[204:205], v[216:217], 0, s[20:21]
	s_mov_b32 m0, s60
	s_nop 0
	global_load_lds_dwordx4 v[204:205], off
	v_lshl_add_u64 v[204:205], v[218:219], 0, s[20:21]
	s_mov_b32 m0, s61
	s_nop 0
	global_load_lds_dwordx4 v[204:205], off
	s_waitcnt vmcnt(8)
	s_waitcnt lgkmcnt(0)
	s_barrier
	s_setprio 1
	s_waitcnt lgkmcnt(0)
	v_mfma_f32_16x16x32_bf16 v[60:63], v[120:123], v[170:173], v[60:63]
	v_mfma_f32_16x16x32_bf16 v[56:59], v[136:139], v[170:173], v[56:59]
	v_mfma_f32_16x16x32_bf16 v[44:47], v[120:123], v[178:181], v[44:47]
	v_mfma_f32_16x16x32_bf16 v[40:43], v[136:139], v[178:181], v[40:43]
	v_mfma_f32_16x16x32_bf16 v[28:31], v[120:123], v[186:189], v[28:31]
	v_mfma_f32_16x16x32_bf16 v[24:27], v[136:139], v[186:189], v[24:27]
	v_mfma_f32_16x16x32_bf16 v[12:15], v[120:123], v[196:199], v[12:15]
	v_mfma_f32_16x16x32_bf16 v[8:11], v[136:139], v[196:199], v[8:11]
	v_mfma_f32_16x16x32_bf16 v[60:63], v[132:135], v[174:177], v[60:63]
	v_mfma_f32_16x16x32_bf16 v[56:59], v[140:143], v[174:177], v[56:59]
	v_mfma_f32_16x16x32_bf16 v[44:47], v[132:135], v[182:185], v[44:47]
	v_mfma_f32_16x16x32_bf16 v[40:43], v[140:143], v[182:185], v[40:43]
	v_mfma_f32_16x16x32_bf16 v[28:31], v[132:135], v[192:195], v[28:31]
	v_mfma_f32_16x16x32_bf16 v[24:27], v[140:143], v[192:195], v[24:27]
	v_mfma_f32_16x16x32_bf16 v[12:15], v[132:135], v[200:203], v[12:15]
	v_mfma_f32_16x16x32_bf16 v[8:11], v[140:143], v[200:203], v[8:11]
	v_mfma_f32_16x16x32_bf16 v[52:55], v[144:147], v[170:173], v[52:55]
	v_mfma_f32_16x16x32_bf16 v[48:51], v[152:155], v[170:173], v[48:51]
	v_mfma_f32_16x16x32_bf16 v[36:39], v[144:147], v[178:181], v[36:39]
	v_mfma_f32_16x16x32_bf16 v[32:35], v[152:155], v[178:181], v[32:35]
	v_mfma_f32_16x16x32_bf16 v[20:23], v[144:147], v[186:189], v[20:23]
	v_mfma_f32_16x16x32_bf16 v[16:19], v[152:155], v[186:189], v[16:19]
	v_mfma_f32_16x16x32_bf16 v[4:7], v[144:147], v[196:199], v[4:7]
	v_mfma_f32_16x16x32_bf16 v[0:3], v[152:155], v[196:199], v[0:3]
	v_mfma_f32_16x16x32_bf16 v[52:55], v[148:151], v[174:177], v[52:55]
	v_mfma_f32_16x16x32_bf16 v[48:51], v[156:159], v[174:177], v[48:51]
	v_mfma_f32_16x16x32_bf16 v[36:39], v[148:151], v[182:185], v[36:39]
	v_mfma_f32_16x16x32_bf16 v[32:35], v[156:159], v[182:185], v[32:35]
	v_mfma_f32_16x16x32_bf16 v[20:23], v[148:151], v[192:195], v[20:23]
	v_mfma_f32_16x16x32_bf16 v[16:19], v[156:159], v[192:195], v[16:19]
	v_mfma_f32_16x16x32_bf16 v[4:7], v[148:151], v[200:203], v[4:7]
	v_mfma_f32_16x16x32_bf16 v[0:3], v[156:159], v[200:203], v[0:3]
	s_setprio 0
	s_barrier
	s_add_u32 s30, s30, 0x100
	s_addc_u32 s31, s31, 0
	s_add_u32 s40, s40, 0x100
	s_addc_u32 s41, s41, 0
	s_cmp_ge_i32 s71, s48
	s_mov_b32 s34, s71
	s_cbranch_scc0 .LBB0_1170

; #define PG8_STAGE(bufoff, gbase, voff) do { _Pragma("unroll") for (int _i = 0; _i < 2; ++_i) \
;         __builtin_amdgcn_global_load_lds((const unsigned*)((const char*)(gbase) + (voff)[_i]), (PG8_LAS unsigned*)(lds + (bufoff) + ldsw + _i * 8192), 16, 0, 0); } while (0)
; #define PG8_LDA(dst, b, h) do { _Pragma("unroll") for (int m = 0; m < 4; ++m) _Pragma("unroll") for (int k = 0; k < 2; ++k) dst[m][k] = *(const PG8_LAS bf16x8*)(lds + PG8_SA(b, h) + aoff + m * 2048 + k * 1024); } while (0)
; #define PG8_LDB(dst, b, h) do { _Pragma("unroll") for (int n = 0; n < 2; ++n) _Pragma("unroll") for (int k = 0; k < 2; ++k) dst[n][k] = *(const PG8_LAS bf16x8*)(lds + PG8_SB(b, h) + boff + n * 2048 + k * 1024); } while (0)
; #define PG8_MMA(ai, bj, At, Bt) do { __builtin_amdgcn_s_setprio(1); _Pragma("unroll") for (int m = 0; m < 4; ++m) _Pragma("unroll") for (int n = 0; n < 2; ++n) _Pragma("unroll") for (int k = 0; k < 2; ++k) \
;         acc[ai][bj][m][n] = mma16<Epi::F16>(Bt[n][k], At[m][k], acc[ai][bj][m][n]); __builtin_amdgcn_s_setprio(0); } while (0)
; #define PG8_WAIT_V(n) asm volatile("s_waitcnt vmcnt(" #n ")" ::: "memory")
; template <class Epi, class Sched, bool ALIGN_EPI = false, bool SP2 = false>
; __device__ __forceinline__ void gemm_phase(PG8_LAS unsigned char* lds, const Gemm g, const Sched& S, const Epi& E) {
;     ...
;         const bool has_next = S.next(ui + 1, nxt);
;         const char* nA = has_next ? (const char*)g.A + (size_t)nxt.pm * tstep : cA; const char* nB = has_next ? (const char*)g.Bt + (size_t)nxt.pn * tstep : cB;
;         for (int t = 0; t < nt; t += 2) {
;             const bool last = (t == nt - 2);
;             const char* a1 = cA + (size_t)(t + 1) * kstep;
;             const char* a2 = last ? nA : cA + (size_t)(t + 2) * kstep; const char* b2 = last ? nB : cB + (size_t)(t + 2) * kstep;
;             const char* a3 = a2 + kstep; const char* b3 = b2 + kstep;
;             if (last && has_next) S.a_ready(nxt);
;             if constexpr (SP2) {
;             PG8_LDB(B0, 0, 0); PG8_LDB(B1, 0, 1); PG8_SCHED; PG8_LDA(At, 0, 0); PG8_STAGE(PG8_SA(1, 1), a1 + hstep, voffA);
;             PG8_WAIT_V(8); PG8_WAIT_L(0); PG8_BAR; PG8_MMA(0, 0, At, B0); PG8_MMA(0, 1, At, B1); PG8_BAR; PG8_SCHED;
;             PG8_LDA(At, 0, 1); PG8_STAGE(PG8_SB(0, 0), b2, voffB); PG8_STAGE(PG8_SB(0, 1), b2 + hstep, voffB); PG8_STAGE(PG8_SA(0, 0), a2, voffA);
.Lpeel_k9:
	s_add_u32 s30, s30, 0x80
	s_addc_u32 s31, s31, 0
	s_add_u32 s29, s34, 0x100
	s_addc_u32 s71, s35, 0
	s_mov_b32 s34, 0
	s_add_i32 s72, s34, 2
	s_add_u32 s73, s30, 0x80
	s_addc_u32 s35, s31, 0
	s_add_i32 s77, 0, 0x10000
	s_cmp_eq_u32 s59, s34
	s_cselect_b32 s35, s1, s35
	s_cselect_b32 s34, s0, s73
	v_add_u32_e32 v131, s77, v133
	s_cselect_b32 s85, s57, s71
	s_cselect_b32 s84, s56, s29
	s_add_i32 s73, 0, 0x14000
	ds_read_b128 v[140:143], v131
	ds_read_b128 v[144:147], v131 offset:1024
	ds_read_b128 v[148:151], v131 offset:2048
	ds_read_b128 v[152:155], v131 offset:3072
	v_add_u32_e32 v131, s73, v133
	ds_read_b128 v[156:159], v131
	ds_read_b128 v[160:163], v131 offset:1024
	ds_read_b128 v[164:167], v131 offset:2048
	ds_read_b128 v[168:171], v131 offset:3072
	v_lshl_add_u64 v[212:213], s[30:31], 0, v[136:137]
	s_add_i32 m0, s9, 0xc000
	ds_read_b128 v[172:175], v199
	ds_read_b128 v[176:179], v199 offset:1024
	ds_read_b128 v[180:183], v199 offset:2048
	ds_read_b128 v[184:187], v199 offset:3072
	ds_read_b128 v[188:191], v199 offset:4096
	ds_read_b128 v[192:195], v199 offset:5120
	ds_read_b128 v[200:203], v199 offset:6144
	ds_read_b128 v[204:207], v199 offset:7168
	global_load_lds_dwordx4 v[212:213], off
	v_lshl_add_u64 v[212:213], s[30:31], 0, v[138:139]
	s_add_i32 m0, s9, 0xe000
	s_nop 0
	global_load_lds_dwordx4 v[212:213], off
	s_waitcnt vmcnt(8)
	s_waitcnt lgkmcnt(0)
	s_barrier
	s_setprio 1
	s_waitcnt lgkmcnt(0)
	v_mfma_f32_16x16x32_bf16 v[120:123], v[140:143], v[172:175], 0
	v_mfma_f32_16x16x32_bf16 v[124:127], v[148:151], v[172:175], 0
	v_mfma_f32_16x16x32_bf16 v[108:111], v[140:143], v[180:183], 0
	v_mfma_f32_16x16x32_bf16 v[104:107], v[148:151], v[180:183], 0
	v_mfma_f32_16x16x32_bf16 v[92:95], v[140:143], v[188:191], 0
	v_mfma_f32_16x16x32_bf16 v[88:91], v[148:151], v[188:191], 0
	v_mfma_f32_16x16x32_bf16 v[76:79], v[140:143], v[200:203], 0
	v_mfma_f32_16x16x32_bf16 v[72:75], v[148:151], v[200:203], 0
	v_mfma_f32_16x16x32_bf16 v[120:123], v[144:147], v[176:179], v[120:123]
	v_mfma_f32_16x16x32_bf16 v[124:127], v[152:155], v[176:179], v[124:127]
	v_mfma_f32_16x16x32_bf16 v[108:111], v[144:147], v[184:187], v[108:111]
	v_mfma_f32_16x16x32_bf16 v[104:107], v[152:155], v[184:187], v[104:107]
	v_mfma_f32_16x16x32_bf16 v[92:95], v[144:147], v[192:195], v[92:95]
	v_mfma_f32_16x16x32_bf16 v[88:91], v[152:155], v[192:195], v[88:91]
	v_mfma_f32_16x16x32_bf16 v[76:79], v[144:147], v[204:207], v[76:79]
	v_mfma_f32_16x16x32_bf16 v[72:75], v[152:155], v[204:207], v[72:75]
	v_mfma_f32_16x16x32_bf16 v[116:119], v[156:159], v[172:175], 0
	v_mfma_f32_16x16x32_bf16 v[112:115], v[164:167], v[172:175], 0
	v_mfma_f32_16x16x32_bf16 v[100:103], v[156:159], v[180:183], 0
	v_mfma_f32_16x16x32_bf16 v[96:99], v[164:167], v[180:183], 0
	v_mfma_f32_16x16x32_bf16 v[84:87], v[156:159], v[188:191], 0
	v_mfma_f32_16x16x32_bf16 v[80:83], v[164:167], v[188:191], 0
	v_mfma_f32_16x16x32_bf16 v[68:71], v[156:159], v[200:203], 0
	v_mfma_f32_16x16x32_bf16 v[64:67], v[164:167], v[200:203], 0
	v_mfma_f32_16x16x32_bf16 v[116:119], v[160:163], v[176:179], v[116:119]
	v_mfma_f32_16x16x32_bf16 v[112:115], v[168:171], v[176:179], v[112:115]
	v_mfma_f32_16x16x32_bf16 v[100:103], v[160:163], v[184:187], v[100:103]
	v_mfma_f32_16x16x32_bf16 v[96:99], v[168:171], v[184:187], v[96:99]
	v_mfma_f32_16x16x32_bf16 v[84:87], v[160:163], v[192:195], v[84:87]
	v_mfma_f32_16x16x32_bf16 v[80:83], v[168:171], v[192:195], v[80:83]
	v_mfma_f32_16x16x32_bf16 v[68:71], v[160:163], v[204:207], v[68:71]
	v_mfma_f32_16x16x32_bf16 v[64:67], v[168:171], v[204:207], v[64:67]
	s_setprio 0
	s_barrier
	s_add_i32 s77, s77, s8
	v_lshl_add_u64 v[212:213], s[84:85], 0, v[208:209]
	s_mov_b32 m0, s77
	ds_read_b128 v[172:175], v199 offset:16384
	ds_read_b128 v[176:179], v199 offset:17408
	ds_read_b128 v[180:183], v199 offset:18432
	ds_read_b128 v[184:187], v199 offset:19456
	ds_read_b128 v[188:191], v199 offset:20480
	ds_read_b128 v[192:195], v199 offset:21504
	ds_read_b128 v[200:203], v199 offset:22528
	ds_read_b128 v[204:207], v199 offset:23552
	global_load_lds_dwordx4 v[212:213], off
	s_add_i32 m0, s77, 0x2000
	v_lshl_add_u64 v[214:215], s[84:85], 0, v[128:129]
	s_add_u32 s84, s84, s42
	s_addc_u32 s85, s85, s43
	s_add_i32 s73, s73, s8
	global_load_lds_dwordx4 v[214:215], off
	v_lshl_add_u64 v[216:217], s[84:85], 0, v[208:209]
	s_mov_b32 m0, s73
	v_lshl_add_u64 v[218:219], s[84:85], 0, v[128:129]
	global_load_lds_dwordx4 v[216:217], off
	s_add_i32 m0, s73, 0x2000
	v_lshl_add_u64 v[220:221], s[34:35], 0, v[208:209]
	global_load_lds_dwordx4 v[218:219], off
	s_mov_b32 m0, s9
	v_lshl_add_u64 v[222:223], s[34:35], 0, v[128:129]
	global_load_lds_dwordx4 v[220:221], off
	s_mov_b32 m0, s11
	s_nop 0
	global_load_lds_dwordx4 v[222:223], off
	s_waitcnt vmcnt(8)
	s_waitcnt lgkmcnt(0)
	s_barrier
; #define PG8_STAGE(bufoff, gbase, voff) do { _Pragma("unroll") for (int _i = 0; _i < 2; ++_i) \
;         __builtin_amdgcn_global_load_lds((const unsigned*)((const char*)(gbase) + (voff)[_i]), (PG8_LAS unsigned*)(lds + (bufoff) + ldsw + _i * 8192), 16, 0, 0); } while (0)
; #define PG8_LDA(dst, b, h) do { _Pragma("unroll") for (int m = 0; m < 4; ++m) _Pragma("unroll") for (int k = 0; k < 2; ++k) dst[m][k] = *(const PG8_LAS bf16x8*)(lds + PG8_SA(b, h) + aoff + m * 2048 + k * 1024); } while (0)
; #define PG8_LDB(dst, b, h) do { _Pragma("unroll") for (int n = 0; n < 2; ++n) _Pragma("unroll") for (int k = 0; k < 2; ++k) dst[n][k] = *(const PG8_LAS bf16x8*)(lds + PG8_SB(b, h) + boff + n * 2048 + k * 1024); } while (0)
; #define PG8_MMA(ai, bj, At, Bt) do { __builtin_amdgcn_s_setprio(1); _Pragma("unroll") for (int m = 0; m < 4; ++m) _Pragma("unroll") for (int n = 0; n < 2; ++n) _Pragma("unroll") for (int k = 0; k < 2; ++k) \
;         acc[ai][bj][m][n] = mma16<Epi::F16>(Bt[n][k], At[m][k], acc[ai][bj][m][n]); __builtin_amdgcn_s_setprio(0); } while (0)
; #define PG8_WAIT_V(n) asm volatile("s_waitcnt vmcnt(" #n ")" ::: "memory")
; #define PG8_WAIT_L(n) asm volatile("s_waitcnt lgkmcnt(" #n ")" ::: "memory")
; #define PG8_BAR __builtin_amdgcn_s_barrier()
; #define PG8_SCHED __builtin_amdgcn_sched_barrier(0)
; template <class Epi, class Sched, bool ALIGN_EPI = false, bool SP2 = false>
; __device__ __forceinline__ void gemm_phase(PG8_LAS unsigned char* lds, const Gemm g, const Sched& S, const Epi& E) {
;     ...
;             PG8_LDA(At, 0, 1); PG8_STAGE(PG8_SB(0, 0), b2, voffB); PG8_STAGE(PG8_SB(0, 1), b2 + hstep, voffB); PG8_STAGE(PG8_SA(0, 0), a2, voffA);
;             PG8_WAIT_V(8); PG8_WAIT_L(0); PG8_BAR; PG8_MMA(1, 0, At, B0); PG8_MMA(1, 1, At, B1); PG8_BAR; PG8_SCHED;
;             PG8_LDB(B0, 1, 0); PG8_LDB(B1, 1, 1); PG8_SCHED; PG8_LDA(At, 1, 0); PG8_STAGE(PG8_SA(0, 1), a2 + hstep, voffA);
;             PG8_WAIT_V(8); PG8_WAIT_L(0); PG8_BAR; PG8_MMA(0, 0, At, B0); PG8_MMA(0, 1, At, B1); PG8_BAR; PG8_SCHED;
	s_setprio 1
	s_waitcnt lgkmcnt(0)
	v_mfma_f32_16x16x32_bf16 v[60:63], v[140:143], v[172:175], 0
	v_mfma_f32_16x16x32_bf16 v[56:59], v[148:151], v[172:175], 0
	v_mfma_f32_16x16x32_bf16 v[44:47], v[140:143], v[180:183], 0
	v_mfma_f32_16x16x32_bf16 v[40:43], v[148:151], v[180:183], 0
	v_mfma_f32_16x16x32_bf16 v[28:31], v[140:143], v[188:191], 0
	v_mfma_f32_16x16x32_bf16 v[24:27], v[148:151], v[188:191], 0
	v_mfma_f32_16x16x32_bf16 v[12:15], v[140:143], v[200:203], 0
	v_mfma_f32_16x16x32_bf16 v[8:11], v[148:151], v[200:203], 0
	v_mfma_f32_16x16x32_bf16 v[60:63], v[144:147], v[176:179], v[60:63]
	v_mfma_f32_16x16x32_bf16 v[56:59], v[152:155], v[176:179], v[56:59]
	v_mfma_f32_16x16x32_bf16 v[44:47], v[144:147], v[184:187], v[44:47]
	v_mfma_f32_16x16x32_bf16 v[40:43], v[152:155], v[184:187], v[40:43]
	v_mfma_f32_16x16x32_bf16 v[28:31], v[144:147], v[192:195], v[28:31]
	v_mfma_f32_16x16x32_bf16 v[24:27], v[152:155], v[192:195], v[24:27]
	v_mfma_f32_16x16x32_bf16 v[12:15], v[144:147], v[204:207], v[12:15]
	v_mfma_f32_16x16x32_bf16 v[8:11], v[152:155], v[204:207], v[8:11]
	v_mfma_f32_16x16x32_bf16 v[52:55], v[156:159], v[172:175], 0
	v_mfma_f32_16x16x32_bf16 v[48:51], v[164:167], v[172:175], 0
	v_mfma_f32_16x16x32_bf16 v[36:39], v[156:159], v[180:183], 0
	v_mfma_f32_16x16x32_bf16 v[32:35], v[164:167], v[180:183], 0
	v_mfma_f32_16x16x32_bf16 v[20:23], v[156:159], v[188:191], 0
	v_mfma_f32_16x16x32_bf16 v[16:19], v[164:167], v[188:191], 0
	v_mfma_f32_16x16x32_bf16 v[4:7], v[156:159], v[200:203], 0
	v_mfma_f32_16x16x32_bf16 v[0:3], v[164:167], v[200:203], 0
	v_mfma_f32_16x16x32_bf16 v[52:55], v[160:163], v[176:179], v[52:55]
	v_mfma_f32_16x16x32_bf16 v[48:51], v[168:171], v[176:179], v[48:51]
	v_mfma_f32_16x16x32_bf16 v[36:39], v[160:163], v[184:187], v[36:39]
	v_mfma_f32_16x16x32_bf16 v[32:35], v[168:171], v[184:187], v[32:35]
	v_mfma_f32_16x16x32_bf16 v[20:23], v[160:163], v[192:195], v[20:23]
	v_mfma_f32_16x16x32_bf16 v[16:19], v[168:171], v[192:195], v[16:19]
	v_mfma_f32_16x16x32_bf16 v[4:7], v[160:163], v[204:207], v[4:7]
	v_mfma_f32_16x16x32_bf16 v[0:3], v[168:171], v[204:207], v[0:3]
	s_setprio 0
	s_barrier
	s_add_i32 s73, 0, 0x18000
	v_add_u32_e32 v131, s73, v133
	s_add_i32 s77, 0, 0x1c000
	ds_read_b128 v[140:143], v131
	ds_read_b128 v[144:147], v131 offset:1024
	ds_read_b128 v[148:151], v131 offset:2048
	ds_read_b128 v[152:155], v131 offset:3072
	v_add_u32_e32 v131, s77, v133
	ds_read_b128 v[156:159], v131
	ds_read_b128 v[160:163], v131 offset:1024
	ds_read_b128 v[164:167], v131 offset:2048
	ds_read_b128 v[168:171], v131 offset:3072
	s_add_u32 s34, s34, s42
	s_addc_u32 s35, s35, s43
	s_mov_b32 m0, s18
	v_lshl_add_u64 v[224:225], s[34:35], 0, v[208:209]
	ds_read_b128 v[172:175], v199 offset:32768
	ds_read_b128 v[176:179], v199 offset:33792
	ds_read_b128 v[180:183], v199 offset:34816
	ds_read_b128 v[184:187], v199 offset:35840
	ds_read_b128 v[188:191], v199 offset:36864
	ds_read_b128 v[192:195], v199 offset:37888
	ds_read_b128 v[200:203], v199 offset:38912
	ds_read_b128 v[204:207], v199 offset:39936
	global_load_lds_dwordx4 v[224:225], off
	v_lshl_add_u64 v[224:225], s[34:35], 0, v[128:129]
	s_mov_b32 m0, s36
	s_nop 0
	global_load_lds_dwordx4 v[224:225], off
	s_waitcnt vmcnt(8)
	s_waitcnt lgkmcnt(0)
	s_barrier
	s_setprio 1
	s_waitcnt lgkmcnt(0)
	v_mfma_f32_16x16x32_bf16 v[120:123], v[140:143], v[172:175], v[120:123]
	v_mfma_f32_16x16x32_bf16 v[124:127], v[148:151], v[172:175], v[124:127]
	v_mfma_f32_16x16x32_bf16 v[108:111], v[140:143], v[180:183], v[108:111]
	v_mfma_f32_16x16x32_bf16 v[104:107], v[148:151], v[180:183], v[104:107]
	v_mfma_f32_16x16x32_bf16 v[92:95], v[140:143], v[188:191], v[92:95]
	v_mfma_f32_16x16x32_bf16 v[88:91], v[148:151], v[188:191], v[88:91]
	v_mfma_f32_16x16x32_bf16 v[76:79], v[140:143], v[200:203], v[76:79]
	v_mfma_f32_16x16x32_bf16 v[72:75], v[148:151], v[200:203], v[72:75]
	v_mfma_f32_16x16x32_bf16 v[120:123], v[144:147], v[176:179], v[120:123]
	v_mfma_f32_16x16x32_bf16 v[124:127], v[152:155], v[176:179], v[124:127]
	v_mfma_f32_16x16x32_bf16 v[108:111], v[144:147], v[184:187], v[108:111]
	v_mfma_f32_16x16x32_bf16 v[104:107], v[152:155], v[184:187], v[104:107]
	v_mfma_f32_16x16x32_bf16 v[92:95], v[144:147], v[192:195], v[92:95]
	v_mfma_f32_16x16x32_bf16 v[88:91], v[152:155], v[192:195], v[88:91]
	v_mfma_f32_16x16x32_bf16 v[76:79], v[144:147], v[204:207], v[76:79]
	v_mfma_f32_16x16x32_bf16 v[72:75], v[152:155], v[204:207], v[72:75]
	v_mfma_f32_16x16x32_bf16 v[116:119], v[156:159], v[172:175], v[116:119]
	v_mfma_f32_16x16x32_bf16 v[112:115], v[164:167], v[172:175], v[112:115]
	v_mfma_f32_16x16x32_bf16 v[100:103], v[156:159], v[180:183], v[100:103]
	v_mfma_f32_16x16x32_bf16 v[96:99], v[164:167], v[180:183], v[96:99]
	v_mfma_f32_16x16x32_bf16 v[84:87], v[156:159], v[188:191], v[84:87]
	v_mfma_f32_16x16x32_bf16 v[80:83], v[164:167], v[188:191], v[80:83]
	v_mfma_f32_16x16x32_bf16 v[68:71], v[156:159], v[200:203], v[68:71]
	v_mfma_f32_16x16x32_bf16 v[64:67], v[164:167], v[200:203], v[64:67]
	v_mfma_f32_16x16x32_bf16 v[116:119], v[160:163], v[176:179], v[116:119]
	v_mfma_f32_16x16x32_bf16 v[112:115], v[168:171], v[176:179], v[112:115]
	v_mfma_f32_16x16x32_bf16 v[100:103], v[160:163], v[184:187], v[100:103]
	v_mfma_f32_16x16x32_bf16 v[96:99], v[168:171], v[184:187], v[96:99]
	v_mfma_f32_16x16x32_bf16 v[84:87], v[160:163], v[192:195], v[84:87]
	v_mfma_f32_16x16x32_bf16 v[80:83], v[168:171], v[192:195], v[80:83]
	v_mfma_f32_16x16x32_bf16 v[68:71], v[160:163], v[204:207], v[68:71]
	v_mfma_f32_16x16x32_bf16 v[64:67], v[168:171], v[204:207], v[64:67]
	s_setprio 0
	s_barrier
; #define PG8_STAGE(bufoff, gbase, voff) do { _Pragma("unroll") for (int _i = 0; _i < 2; ++_i) \
;         __builtin_amdgcn_global_load_lds((const unsigned*)((const char*)(gbase) + (voff)[_i]), (PG8_LAS unsigned*)(lds + (bufoff) + ldsw + _i * 8192), 16, 0, 0); } while (0)
; #define PG8_LDA(dst, b, h) do { _Pragma("unroll") for (int m = 0; m < 4; ++m) _Pragma("unroll") for (int k = 0; k < 2; ++k) dst[m][k] = *(const PG8_LAS bf16x8*)(lds + PG8_SA(b, h) + aoff + m * 2048 + k * 1024); } while (0)
; #define PG8_LDB(dst, b, h) do { _Pragma("unroll") for (int n = 0; n < 2; ++n) _Pragma("unroll") for (int k = 0; k < 2; ++k) dst[n][k] = *(const PG8_LAS bf16x8*)(lds + PG8_SB(b, h) + boff + n * 2048 + k * 1024); } while (0)
; #define PG8_MMA(ai, bj, At, Bt) do { __builtin_amdgcn_s_setprio(1); _Pragma("unroll") for (int m = 0; m < 4; ++m) _Pragma("unroll") for (int n = 0; n < 2; ++n) _Pragma("unroll") for (int k = 0; k < 2; ++k) \
;         acc[ai][bj][m][n] = mma16<Epi::F16>(Bt[n][k], At[m][k], acc[ai][bj][m][n]); __builtin_amdgcn_s_setprio(0); } while (0)
; #define PG8_WAIT_V(n) asm volatile("s_waitcnt vmcnt(" #n ")" ::: "memory")
; #define PG8_WAIT_L(n) asm volatile("s_waitcnt lgkmcnt(" #n ")" ::: "memory")
; #define PG8_BAR __builtin_amdgcn_s_barrier()
; #define PG8_SCHED __builtin_amdgcn_sched_barrier(0)
; template <class Epi, class Sched, bool ALIGN_EPI = false, bool SP2 = false>
; __device__ __forceinline__ void gemm_phase(PG8_LAS unsigned char* lds, const Gemm g, const Sched& S, const Epi& E) {
;     ...
;         for (int t = 0; t < nt; t += 2) {
;             const bool last = (t == nt - 2);
;             const char* a1 = cA + (size_t)(t + 1) * kstep;
;             const char* a2 = last ? nA : cA + (size_t)(t + 2) * kstep; const char* b2 = last ? nB : cB + (size_t)(t + 2) * kstep;
;             const char* a3 = a2 + kstep; const char* b3 = b2 + kstep;
;             if (last && has_next) S.a_ready(nxt);
;             if constexpr (SP2) {
;             PG8_LDB(B0, 0, 0); PG8_LDB(B1, 0, 1); PG8_SCHED; PG8_LDA(At, 0, 0); PG8_STAGE(PG8_SA(1, 1), a1 + hstep, voffA);
;     ...
;             PG8_LDA(At, 1, 1); PG8_STAGE(PG8_SB(1, 0), b3, voffB); PG8_STAGE(PG8_SB(1, 1), b3 + hstep, voffB); PG8_STAGE(PG8_SA(1, 0), a3, voffA);
;             PG8_WAIT_V(8); PG8_WAIT_L(0); PG8_BAR; PG8_MMA(1, 0, At, B0); PG8_MMA(1, 1, At, B1); PG8_BAR; PG8_SCHED;
	s_add_i32 s34, s73, s8
	v_lshl_add_u64 v[212:213], v[212:213], 0, s[20:21]
	s_mov_b32 m0, s34
	ds_read_b128 v[172:175], v199 offset:49152
	ds_read_b128 v[176:179], v199 offset:50176
	ds_read_b128 v[180:183], v199 offset:51200
	ds_read_b128 v[184:187], v199 offset:52224
	ds_read_b128 v[188:191], v199 offset:53248
	ds_read_b128 v[192:195], v199 offset:54272
	ds_read_b128 v[200:203], v199 offset:55296
	ds_read_b128 v[204:207], v199 offset:56320
	global_load_lds_dwordx4 v[212:213], off
	v_lshl_add_u64 v[212:213], v[214:215], 0, s[20:21]
	s_add_i32 m0, s34, 0x2000
	s_add_i32 s34, s77, s8
	global_load_lds_dwordx4 v[212:213], off
	v_lshl_add_u64 v[212:213], v[216:217], 0, s[20:21]
	s_mov_b32 m0, s34
	s_nop 0
	global_load_lds_dwordx4 v[212:213], off
	v_lshl_add_u64 v[212:213], v[218:219], 0, s[20:21]
	s_add_i32 m0, s34, 0x2000
	s_nop 0
	global_load_lds_dwordx4 v[212:213], off
	v_lshl_add_u64 v[212:213], v[220:221], 0, s[20:21]
	s_mov_b32 m0, s37
	s_nop 0
	global_load_lds_dwordx4 v[212:213], off
	v_lshl_add_u64 v[212:213], v[222:223], 0, s[20:21]
	s_mov_b32 m0, s48
	s_nop 0
	global_load_lds_dwordx4 v[212:213], off
	s_waitcnt vmcnt(8)
	s_waitcnt lgkmcnt(0)
	s_barrier
	s_setprio 1
	s_waitcnt lgkmcnt(0)
	v_mfma_f32_16x16x32_bf16 v[60:63], v[140:143], v[172:175], v[60:63]
	v_mfma_f32_16x16x32_bf16 v[56:59], v[148:151], v[172:175], v[56:59]
	v_mfma_f32_16x16x32_bf16 v[44:47], v[140:143], v[180:183], v[44:47]
	v_mfma_f32_16x16x32_bf16 v[40:43], v[148:151], v[180:183], v[40:43]
	v_mfma_f32_16x16x32_bf16 v[28:31], v[140:143], v[188:191], v[28:31]
	v_mfma_f32_16x16x32_bf16 v[24:27], v[148:151], v[188:191], v[24:27]
	v_mfma_f32_16x16x32_bf16 v[12:15], v[140:143], v[200:203], v[12:15]
	v_mfma_f32_16x16x32_bf16 v[8:11], v[148:151], v[200:203], v[8:11]
	v_mfma_f32_16x16x32_bf16 v[60:63], v[144:147], v[176:179], v[60:63]
	v_mfma_f32_16x16x32_bf16 v[56:59], v[152:155], v[176:179], v[56:59]
	v_mfma_f32_16x16x32_bf16 v[44:47], v[144:147], v[184:187], v[44:47]
	v_mfma_f32_16x16x32_bf16 v[40:43], v[152:155], v[184:187], v[40:43]
	v_mfma_f32_16x16x32_bf16 v[28:31], v[144:147], v[192:195], v[28:31]
	v_mfma_f32_16x16x32_bf16 v[24:27], v[152:155], v[192:195], v[24:27]
	v_mfma_f32_16x16x32_bf16 v[12:15], v[144:147], v[204:207], v[12:15]
	v_mfma_f32_16x16x32_bf16 v[8:11], v[152:155], v[204:207], v[8:11]
	v_mfma_f32_16x16x32_bf16 v[52:55], v[156:159], v[172:175], v[52:55]
	v_mfma_f32_16x16x32_bf16 v[48:51], v[164:167], v[172:175], v[48:51]
	v_mfma_f32_16x16x32_bf16 v[36:39], v[156:159], v[180:183], v[36:39]
	v_mfma_f32_16x16x32_bf16 v[32:35], v[164:167], v[180:183], v[32:35]
	v_mfma_f32_16x16x32_bf16 v[20:23], v[156:159], v[188:191], v[20:23]
	v_mfma_f32_16x16x32_bf16 v[16:19], v[164:167], v[188:191], v[16:19]
	v_mfma_f32_16x16x32_bf16 v[4:7], v[156:159], v[200:203], v[4:7]
	v_mfma_f32_16x16x32_bf16 v[0:3], v[164:167], v[200:203], v[0:3]
	v_mfma_f32_16x16x32_bf16 v[52:55], v[160:163], v[176:179], v[52:55]
	v_mfma_f32_16x16x32_bf16 v[48:51], v[168:171], v[176:179], v[48:51]
	v_mfma_f32_16x16x32_bf16 v[36:39], v[160:163], v[184:187], v[36:39]
	v_mfma_f32_16x16x32_bf16 v[32:35], v[168:171], v[184:187], v[32:35]
	v_mfma_f32_16x16x32_bf16 v[20:23], v[160:163], v[192:195], v[20:23]
	v_mfma_f32_16x16x32_bf16 v[16:19], v[168:171], v[192:195], v[16:19]
	v_mfma_f32_16x16x32_bf16 v[4:7], v[160:163], v[204:207], v[4:7]
	v_mfma_f32_16x16x32_bf16 v[0:3], v[168:171], v[204:207], v[0:3]
	s_setprio 0
	s_barrier
	s_add_u32 s30, s30, 0x100
	s_addc_u32 s31, s31, 0
	s_add_u32 s29, s29, 0x100
	s_addc_u32 s71, s71, 0
	s_cmp_ge_i32 s72, s58
	s_mov_b32 s34, s72
	s_cbranch_scc0 .LBB0_1480
	s_branch .LBB0_1481
.LBB0_1480:
	s_add_i32 s72, s34, 2
	s_add_u32 s73, s30, 0x80
	s_addc_u32 s35, s31, 0
	s_add_i32 s77, 0, 0x10000
	s_cmp_eq_u32 s59, s34
	s_cselect_b32 s35, s1, s35
	s_cselect_b32 s34, s0, s73
	v_add_u32_e32 v131, s77, v133
	s_cselect_b32 s85, s57, s71
	s_cselect_b32 s84, s56, s29
	s_add_i32 s73, 0, 0x14000
	ds_read_b128 v[140:143], v131
	ds_read_b128 v[144:147], v131 offset:1024
	ds_read_b128 v[148:151], v131 offset:2048
	ds_read_b128 v[152:155], v131 offset:3072
	v_add_u32_e32 v131, s73, v133
	ds_read_b128 v[156:159], v131
	ds_read_b128 v[160:163], v131 offset:1024
	ds_read_b128 v[164:167], v131 offset:2048
	ds_read_b128 v[168:171], v131 offset:3072
	v_lshl_add_u64 v[212:213], s[30:31], 0, v[136:137]
	s_add_i32 m0, s9, 0xc000
	ds_read_b128 v[172:175], v199
	ds_read_b128 v[176:179], v199 offset:1024
	ds_read_b128 v[180:183], v199 offset:2048
	ds_read_b128 v[184:187], v199 offset:3072
	ds_read_b128 v[188:191], v199 offset:4096
	ds_read_b128 v[192:195], v199 offset:5120
	ds_read_b128 v[200:203], v199 offset:6144
	ds_read_b128 v[204:207], v199 offset:7168
	global_load_lds_dwordx4 v[212:213], off
	v_lshl_add_u64 v[212:213], s[30:31], 0, v[138:139]
	s_add_i32 m0, s9, 0xe000
	s_nop 0
	global_load_lds_dwordx4 v[212:213], off
	s_waitcnt vmcnt(8)
	s_waitcnt lgkmcnt(0)
	s_barrier
; #define PG8_STAGE(bufoff, gbase, voff) do { _Pragma("unroll") for (int _i = 0; _i < 2; ++_i) \
;         __builtin_amdgcn_global_load_lds((const unsigned*)((const char*)(gbase) + (voff)[_i]), (PG8_LAS unsigned*)(lds + (bufoff) + ldsw + _i * 8192), 16, 0, 0); } while (0)
; #define PG8_LDA(dst, b, h) do { _Pragma("unroll") for (int m = 0; m < 4; ++m) _Pragma("unroll") for (int k = 0; k < 2; ++k) dst[m][k] = *(const PG8_LAS bf16x8*)(lds + PG8_SA(b, h) + aoff + m * 2048 + k * 1024); } while (0)
; #define PG8_MMA(ai, bj, At, Bt) do { __builtin_amdgcn_s_setprio(1); _Pragma("unroll") for (int m = 0; m < 4; ++m) _Pragma("unroll") for (int n = 0; n < 2; ++n) _Pragma("unroll") for (int k = 0; k < 2; ++k) \
;         acc[ai][bj][m][n] = mma16<Epi::F16>(Bt[n][k], At[m][k], acc[ai][bj][m][n]); __builtin_amdgcn_s_setprio(0); } while (0)
; #define PG8_WAIT_V(n) asm volatile("s_waitcnt vmcnt(" #n ")" ::: "memory")
; #define PG8_WAIT_L(n) asm volatile("s_waitcnt lgkmcnt(" #n ")" ::: "memory")
; #define PG8_BAR __builtin_amdgcn_s_barrier()
; #define PG8_SCHED __builtin_amdgcn_sched_barrier(0)
; template <class Epi, class Sched, bool ALIGN_EPI = false, bool SP2 = false>
; __device__ __forceinline__ void gemm_phase(PG8_LAS unsigned char* lds, const Gemm g, const Sched& S, const Epi& E) {
;     ...
;             PG8_WAIT_V(8); PG8_WAIT_L(0); PG8_BAR; PG8_MMA(0, 0, At, B0); PG8_MMA(0, 1, At, B1); PG8_BAR; PG8_SCHED;
;             PG8_LDA(At, 0, 1); PG8_STAGE(PG8_SB(0, 0), b2, voffB); PG8_STAGE(PG8_SB(0, 1), b2 + hstep, voffB); PG8_STAGE(PG8_SA(0, 0), a2, voffA);
;             PG8_WAIT_V(8); PG8_WAIT_L(0); PG8_BAR; PG8_MMA(1, 0, At, B0); PG8_MMA(1, 1, At, B1); PG8_BAR; PG8_SCHED;
	s_setprio 1
	s_waitcnt lgkmcnt(0)
	v_mfma_f32_16x16x32_bf16 v[120:123], v[140:143], v[172:175], v[120:123]
	v_mfma_f32_16x16x32_bf16 v[124:127], v[148:151], v[172:175], v[124:127]
	v_mfma_f32_16x16x32_bf16 v[108:111], v[140:143], v[180:183], v[108:111]
	v_mfma_f32_16x16x32_bf16 v[104:107], v[148:151], v[180:183], v[104:107]
	v_mfma_f32_16x16x32_bf16 v[92:95], v[140:143], v[188:191], v[92:95]
	v_mfma_f32_16x16x32_bf16 v[88:91], v[148:151], v[188:191], v[88:91]
	v_mfma_f32_16x16x32_bf16 v[76:79], v[140:143], v[200:203], v[76:79]
	v_mfma_f32_16x16x32_bf16 v[72:75], v[148:151], v[200:203], v[72:75]
	v_mfma_f32_16x16x32_bf16 v[120:123], v[144:147], v[176:179], v[120:123]
	v_mfma_f32_16x16x32_bf16 v[124:127], v[152:155], v[176:179], v[124:127]
	v_mfma_f32_16x16x32_bf16 v[108:111], v[144:147], v[184:187], v[108:111]
	v_mfma_f32_16x16x32_bf16 v[104:107], v[152:155], v[184:187], v[104:107]
	v_mfma_f32_16x16x32_bf16 v[92:95], v[144:147], v[192:195], v[92:95]
	v_mfma_f32_16x16x32_bf16 v[88:91], v[152:155], v[192:195], v[88:91]
	v_mfma_f32_16x16x32_bf16 v[76:79], v[144:147], v[204:207], v[76:79]
	v_mfma_f32_16x16x32_bf16 v[72:75], v[152:155], v[204:207], v[72:75]
	v_mfma_f32_16x16x32_bf16 v[116:119], v[156:159], v[172:175], v[116:119]
	v_mfma_f32_16x16x32_bf16 v[112:115], v[164:167], v[172:175], v[112:115]
	v_mfma_f32_16x16x32_bf16 v[100:103], v[156:159], v[180:183], v[100:103]
	v_mfma_f32_16x16x32_bf16 v[96:99], v[164:167], v[180:183], v[96:99]
	v_mfma_f32_16x16x32_bf16 v[84:87], v[156:159], v[188:191], v[84:87]
	v_mfma_f32_16x16x32_bf16 v[80:83], v[164:167], v[188:191], v[80:83]
	v_mfma_f32_16x16x32_bf16 v[68:71], v[156:159], v[200:203], v[68:71]
	v_mfma_f32_16x16x32_bf16 v[64:67], v[164:167], v[200:203], v[64:67]
	v_mfma_f32_16x16x32_bf16 v[116:119], v[160:163], v[176:179], v[116:119]
	v_mfma_f32_16x16x32_bf16 v[112:115], v[168:171], v[176:179], v[112:115]
	v_mfma_f32_16x16x32_bf16 v[100:103], v[160:163], v[184:187], v[100:103]
	v_mfma_f32_16x16x32_bf16 v[96:99], v[168:171], v[184:187], v[96:99]
	v_mfma_f32_16x16x32_bf16 v[84:87], v[160:163], v[192:195], v[84:87]
	v_mfma_f32_16x16x32_bf16 v[80:83], v[168:171], v[192:195], v[80:83]
	v_mfma_f32_16x16x32_bf16 v[68:71], v[160:163], v[204:207], v[68:71]
	v_mfma_f32_16x16x32_bf16 v[64:67], v[168:171], v[204:207], v[64:67]
	s_setprio 0
	s_barrier
	s_add_i32 s77, s77, s8
	v_lshl_add_u64 v[212:213], s[84:85], 0, v[208:209]
	s_mov_b32 m0, s77
	ds_read_b128 v[172:175], v199 offset:16384
	ds_read_b128 v[176:179], v199 offset:17408
	ds_read_b128 v[180:183], v199 offset:18432
	ds_read_b128 v[184:187], v199 offset:19456
	ds_read_b128 v[188:191], v199 offset:20480
	ds_read_b128 v[192:195], v199 offset:21504
	ds_read_b128 v[200:203], v199 offset:22528
	ds_read_b128 v[204:207], v199 offset:23552
	global_load_lds_dwordx4 v[212:213], off
	s_add_i32 m0, s77, 0x2000
	v_lshl_add_u64 v[214:215], s[84:85], 0, v[128:129]
	s_add_u32 s84, s84, s42
	s_addc_u32 s85, s85, s43
	s_add_i32 s73, s73, s8
	global_load_lds_dwordx4 v[214:215], off
	v_lshl_add_u64 v[216:217], s[84:85], 0, v[208:209]
	s_mov_b32 m0, s73
	v_lshl_add_u64 v[218:219], s[84:85], 0, v[128:129]
	global_load_lds_dwordx4 v[216:217], off
	s_add_i32 m0, s73, 0x2000
	v_lshl_add_u64 v[220:221], s[34:35], 0, v[208:209]
	global_load_lds_dwordx4 v[218:219], off
	s_mov_b32 m0, s9
	v_lshl_add_u64 v[222:223], s[34:35], 0, v[128:129]
	global_load_lds_dwordx4 v[220:221], off
	s_mov_b32 m0, s11
	s_nop 0
	global_load_lds_dwordx4 v[222:223], off
	s_waitcnt vmcnt(8)
	s_waitcnt lgkmcnt(0)
	s_barrier
	s_setprio 1
	s_waitcnt lgkmcnt(0)
	v_mfma_f32_16x16x32_bf16 v[60:63], v[140:143], v[172:175], v[60:63]
	v_mfma_f32_16x16x32_bf16 v[56:59], v[148:151], v[172:175], v[56:59]
	v_mfma_f32_16x16x32_bf16 v[44:47], v[140:143], v[180:183], v[44:47]
	v_mfma_f32_16x16x32_bf16 v[40:43], v[148:151], v[180:183], v[40:43]
	v_mfma_f32_16x16x32_bf16 v[28:31], v[140:143], v[188:191], v[28:31]
	v_mfma_f32_16x16x32_bf16 v[24:27], v[148:151], v[188:191], v[24:27]
	v_mfma_f32_16x16x32_bf16 v[12:15], v[140:143], v[200:203], v[12:15]
	v_mfma_f32_16x16x32_bf16 v[8:11], v[148:151], v[200:203], v[8:11]
	v_mfma_f32_16x16x32_bf16 v[60:63], v[144:147], v[176:179], v[60:63]
	v_mfma_f32_16x16x32_bf16 v[56:59], v[152:155], v[176:179], v[56:59]
	v_mfma_f32_16x16x32_bf16 v[44:47], v[144:147], v[184:187], v[44:47]
	v_mfma_f32_16x16x32_bf16 v[40:43], v[152:155], v[184:187], v[40:43]
	v_mfma_f32_16x16x32_bf16 v[28:31], v[144:147], v[192:195], v[28:31]
	v_mfma_f32_16x16x32_bf16 v[24:27], v[152:155], v[192:195], v[24:27]
	v_mfma_f32_16x16x32_bf16 v[12:15], v[144:147], v[204:207], v[12:15]
	v_mfma_f32_16x16x32_bf16 v[8:11], v[152:155], v[204:207], v[8:11]
	v_mfma_f32_16x16x32_bf16 v[52:55], v[156:159], v[172:175], v[52:55]
	v_mfma_f32_16x16x32_bf16 v[48:51], v[164:167], v[172:175], v[48:51]
	v_mfma_f32_16x16x32_bf16 v[36:39], v[156:159], v[180:183], v[36:39]
	v_mfma_f32_16x16x32_bf16 v[32:35], v[164:167], v[180:183], v[32:35]
	v_mfma_f32_16x16x32_bf16 v[20:23], v[156:159], v[188:191], v[20:23]
	v_mfma_f32_16x16x32_bf16 v[16:19], v[164:167], v[188:191], v[16:19]
	v_mfma_f32_16x16x32_bf16 v[4:7], v[156:159], v[200:203], v[4:7]
	v_mfma_f32_16x16x32_bf16 v[0:3], v[164:167], v[200:203], v[0:3]
	v_mfma_f32_16x16x32_bf16 v[52:55], v[160:163], v[176:179], v[52:55]
	v_mfma_f32_16x16x32_bf16 v[48:51], v[168:171], v[176:179], v[48:51]
	v_mfma_f32_16x16x32_bf16 v[36:39], v[160:163], v[184:187], v[36:39]
	v_mfma_f32_16x16x32_bf16 v[32:35], v[168:171], v[184:187], v[32:35]
	v_mfma_f32_16x16x32_bf16 v[20:23], v[160:163], v[192:195], v[20:23]
	v_mfma_f32_16x16x32_bf16 v[16:19], v[168:171], v[192:195], v[16:19]
	v_mfma_f32_16x16x32_bf16 v[4:7], v[160:163], v[204:207], v[4:7]
	v_mfma_f32_16x16x32_bf16 v[0:3], v[168:171], v[204:207], v[0:3]
	s_setprio 0
	s_barrier
; #define PG8_STAGE(bufoff, gbase, voff) do { _Pragma("unroll") for (int _i = 0; _i < 2; ++_i) \
;         __builtin_amdgcn_global_load_lds((const unsigned*)((const char*)(gbase) + (voff)[_i]), (PG8_LAS unsigned*)(lds + (bufoff) + ldsw + _i * 8192), 16, 0, 0); } while (0)
; #define PG8_LDA(dst, b, h) do { _Pragma("unroll") for (int m = 0; m < 4; ++m) _Pragma("unroll") for (int k = 0; k < 2; ++k) dst[m][k] = *(const PG8_LAS bf16x8*)(lds + PG8_SA(b, h) + aoff + m * 2048 + k * 1024); } while (0)
; #define PG8_LDB(dst, b, h) do { _Pragma("unroll") for (int n = 0; n < 2; ++n) _Pragma("unroll") for (int k = 0; k < 2; ++k) dst[n][k] = *(const PG8_LAS bf16x8*)(lds + PG8_SB(b, h) + boff + n * 2048 + k * 1024); } while (0)
; #define PG8_MMA(ai, bj, At, Bt) do { __builtin_amdgcn_s_setprio(1); _Pragma("unroll") for (int m = 0; m < 4; ++m) _Pragma("unroll") for (int n = 0; n < 2; ++n) _Pragma("unroll") for (int k = 0; k < 2; ++k) \
;         acc[ai][bj][m][n] = mma16<Epi::F16>(Bt[n][k], At[m][k], acc[ai][bj][m][n]); __builtin_amdgcn_s_setprio(0); } while (0)
; #define PG8_WAIT_V(n) asm volatile("s_waitcnt vmcnt(" #n ")" ::: "memory")
; #define PG8_WAIT_L(n) asm volatile("s_waitcnt lgkmcnt(" #n ")" ::: "memory")
; #define PG8_BAR __builtin_amdgcn_s_barrier()
; #define PG8_SCHED __builtin_amdgcn_sched_barrier(0)
; template <class Epi, class Sched, bool ALIGN_EPI = false, bool SP2 = false>
; __device__ __forceinline__ void gemm_phase(PG8_LAS unsigned char* lds, const Gemm g, const Sched& S, const Epi& E) {
;     ...
;             PG8_LDB(B0, 1, 0); PG8_LDB(B1, 1, 1); PG8_SCHED; PG8_LDA(At, 1, 0); PG8_STAGE(PG8_SA(0, 1), a2 + hstep, voffA);
;             PG8_WAIT_V(8); PG8_WAIT_L(0); PG8_BAR; PG8_MMA(0, 0, At, B0); PG8_MMA(0, 1, At, B1); PG8_BAR; PG8_SCHED;
;             PG8_LDA(At, 1, 1); PG8_STAGE(PG8_SB(1, 0), b3, voffB); PG8_STAGE(PG8_SB(1, 1), b3 + hstep, voffB); PG8_STAGE(PG8_SA(1, 0), a3, voffA);
;             PG8_WAIT_V(8); PG8_WAIT_L(0); PG8_BAR; PG8_MMA(1, 0, At, B0); PG8_MMA(1, 1, At, B1); PG8_BAR; PG8_SCHED;
	s_add_i32 s73, 0, 0x18000
	v_add_u32_e32 v131, s73, v133
	s_add_i32 s77, 0, 0x1c000
	ds_read_b128 v[140:143], v131
	ds_read_b128 v[144:147], v131 offset:1024
	ds_read_b128 v[148:151], v131 offset:2048
	ds_read_b128 v[152:155], v131 offset:3072
	v_add_u32_e32 v131, s77, v133
	ds_read_b128 v[156:159], v131
	ds_read_b128 v[160:163], v131 offset:1024
	ds_read_b128 v[164:167], v131 offset:2048
	ds_read_b128 v[168:171], v131 offset:3072
	s_add_u32 s34, s34, s42
	s_addc_u32 s35, s35, s43
	s_mov_b32 m0, s18
	v_lshl_add_u64 v[224:225], s[34:35], 0, v[208:209]
	ds_read_b128 v[172:175], v199 offset:32768
	ds_read_b128 v[176:179], v199 offset:33792
	ds_read_b128 v[180:183], v199 offset:34816
	ds_read_b128 v[184:187], v199 offset:35840
	ds_read_b128 v[188:191], v199 offset:36864
	ds_read_b128 v[192:195], v199 offset:37888
	ds_read_b128 v[200:203], v199 offset:38912
	ds_read_b128 v[204:207], v199 offset:39936
	global_load_lds_dwordx4 v[224:225], off
	v_lshl_add_u64 v[224:225], s[34:35], 0, v[128:129]
	s_mov_b32 m0, s36
	s_nop 0
	global_load_lds_dwordx4 v[224:225], off
	s_waitcnt vmcnt(8)
	s_waitcnt lgkmcnt(0)
	s_barrier
	s_setprio 1
	s_waitcnt lgkmcnt(0)
	v_mfma_f32_16x16x32_bf16 v[120:123], v[140:143], v[172:175], v[120:123]
	v_mfma_f32_16x16x32_bf16 v[124:127], v[148:151], v[172:175], v[124:127]
	v_mfma_f32_16x16x32_bf16 v[108:111], v[140:143], v[180:183], v[108:111]
	v_mfma_f32_16x16x32_bf16 v[104:107], v[148:151], v[180:183], v[104:107]
	v_mfma_f32_16x16x32_bf16 v[92:95], v[140:143], v[188:191], v[92:95]
	v_mfma_f32_16x16x32_bf16 v[88:91], v[148:151], v[188:191], v[88:91]
	v_mfma_f32_16x16x32_bf16 v[76:79], v[140:143], v[200:203], v[76:79]
	v_mfma_f32_16x16x32_bf16 v[72:75], v[148:151], v[200:203], v[72:75]
	v_mfma_f32_16x16x32_bf16 v[120:123], v[144:147], v[176:179], v[120:123]
	v_mfma_f32_16x16x32_bf16 v[124:127], v[152:155], v[176:179], v[124:127]
	v_mfma_f32_16x16x32_bf16 v[108:111], v[144:147], v[184:187], v[108:111]
	v_mfma_f32_16x16x32_bf16 v[104:107], v[152:155], v[184:187], v[104:107]
	v_mfma_f32_16x16x32_bf16 v[92:95], v[144:147], v[192:195], v[92:95]
	v_mfma_f32_16x16x32_bf16 v[88:91], v[152:155], v[192:195], v[88:91]
	v_mfma_f32_16x16x32_bf16 v[76:79], v[144:147], v[204:207], v[76:79]
	v_mfma_f32_16x16x32_bf16 v[72:75], v[152:155], v[204:207], v[72:75]
	v_mfma_f32_16x16x32_bf16 v[116:119], v[156:159], v[172:175], v[116:119]
	v_mfma_f32_16x16x32_bf16 v[112:115], v[164:167], v[172:175], v[112:115]
	v_mfma_f32_16x16x32_bf16 v[100:103], v[156:159], v[180:183], v[100:103]
	v_mfma_f32_16x16x32_bf16 v[96:99], v[164:167], v[180:183], v[96:99]
	v_mfma_f32_16x16x32_bf16 v[84:87], v[156:159], v[188:191], v[84:87]
	v_mfma_f32_16x16x32_bf16 v[80:83], v[164:167], v[188:191], v[80:83]
	v_mfma_f32_16x16x32_bf16 v[68:71], v[156:159], v[200:203], v[68:71]
	v_mfma_f32_16x16x32_bf16 v[64:67], v[164:167], v[200:203], v[64:67]
	v_mfma_f32_16x16x32_bf16 v[116:119], v[160:163], v[176:179], v[116:119]
	v_mfma_f32_16x16x32_bf16 v[112:115], v[168:171], v[176:179], v[112:115]
	v_mfma_f32_16x16x32_bf16 v[100:103], v[160:163], v[184:187], v[100:103]
	v_mfma_f32_16x16x32_bf16 v[96:99], v[168:171], v[184:187], v[96:99]
	v_mfma_f32_16x16x32_bf16 v[84:87], v[160:163], v[192:195], v[84:87]
	v_mfma_f32_16x16x32_bf16 v[80:83], v[168:171], v[192:195], v[80:83]
	v_mfma_f32_16x16x32_bf16 v[68:71], v[160:163], v[204:207], v[68:71]
	v_mfma_f32_16x16x32_bf16 v[64:67], v[168:171], v[204:207], v[64:67]
	s_setprio 0
	s_barrier
	s_add_i32 s34, s73, s8
	v_lshl_add_u64 v[212:213], v[212:213], 0, s[20:21]
	s_mov_b32 m0, s34
	ds_read_b128 v[172:175], v199 offset:49152
	ds_read_b128 v[176:179], v199 offset:50176
	ds_read_b128 v[180:183], v199 offset:51200
	ds_read_b128 v[184:187], v199 offset:52224
	ds_read_b128 v[188:191], v199 offset:53248
	ds_read_b128 v[192:195], v199 offset:54272
	ds_read_b128 v[200:203], v199 offset:55296
	ds_read_b128 v[204:207], v199 offset:56320
	global_load_lds_dwordx4 v[212:213], off
	v_lshl_add_u64 v[212:213], v[214:215], 0, s[20:21]
	s_add_i32 m0, s34, 0x2000
	s_add_i32 s34, s77, s8
	global_load_lds_dwordx4 v[212:213], off
	v_lshl_add_u64 v[212:213], v[216:217], 0, s[20:21]
	s_mov_b32 m0, s34
	s_nop 0
	global_load_lds_dwordx4 v[212:213], off
	v_lshl_add_u64 v[212:213], v[218:219], 0, s[20:21]
	s_add_i32 m0, s34, 0x2000
	s_nop 0
	global_load_lds_dwordx4 v[212:213], off
	v_lshl_add_u64 v[212:213], v[220:221], 0, s[20:21]
	s_mov_b32 m0, s37
	s_nop 0
	global_load_lds_dwordx4 v[212:213], off
	v_lshl_add_u64 v[212:213], v[222:223], 0, s[20:21]
	s_mov_b32 m0, s48
	s_nop 0
	global_load_lds_dwordx4 v[212:213], off
	s_waitcnt vmcnt(8)
	s_waitcnt lgkmcnt(0)
	s_barrier
	s_setprio 1
	s_waitcnt lgkmcnt(0)
	v_mfma_f32_16x16x32_bf16 v[60:63], v[140:143], v[172:175], v[60:63]
	v_mfma_f32_16x16x32_bf16 v[56:59], v[148:151], v[172:175], v[56:59]
	v_mfma_f32_16x16x32_bf16 v[44:47], v[140:143], v[180:183], v[44:47]
	v_mfma_f32_16x16x32_bf16 v[40:43], v[148:151], v[180:183], v[40:43]
	v_mfma_f32_16x16x32_bf16 v[28:31], v[140:143], v[188:191], v[28:31]
	v_mfma_f32_16x16x32_bf16 v[24:27], v[148:151], v[188:191], v[24:27]
	v_mfma_f32_16x16x32_bf16 v[12:15], v[140:143], v[200:203], v[12:15]
	v_mfma_f32_16x16x32_bf16 v[8:11], v[148:151], v[200:203], v[8:11]
	v_mfma_f32_16x16x32_bf16 v[60:63], v[144:147], v[176:179], v[60:63]
	v_mfma_f32_16x16x32_bf16 v[56:59], v[152:155], v[176:179], v[56:59]
	v_mfma_f32_16x16x32_bf16 v[44:47], v[144:147], v[184:187], v[44:47]
	v_mfma_f32_16x16x32_bf16 v[40:43], v[152:155], v[184:187], v[40:43]
	v_mfma_f32_16x16x32_bf16 v[28:31], v[144:147], v[192:195], v[28:31]
	v_mfma_f32_16x16x32_bf16 v[24:27], v[152:155], v[192:195], v[24:27]
	v_mfma_f32_16x16x32_bf16 v[12:15], v[144:147], v[204:207], v[12:15]
	v_mfma_f32_16x16x32_bf16 v[8:11], v[152:155], v[204:207], v[8:11]
	v_mfma_f32_16x16x32_bf16 v[52:55], v[156:159], v[172:175], v[52:55]
	v_mfma_f32_16x16x32_bf16 v[48:51], v[164:167], v[172:175], v[48:51]
	v_mfma_f32_16x16x32_bf16 v[36:39], v[156:159], v[180:183], v[36:39]
	v_mfma_f32_16x16x32_bf16 v[32:35], v[164:167], v[180:183], v[32:35]
	v_mfma_f32_16x16x32_bf16 v[20:23], v[156:159], v[188:191], v[20:23]
	v_mfma_f32_16x16x32_bf16 v[16:19], v[164:167], v[188:191], v[16:19]
	v_mfma_f32_16x16x32_bf16 v[4:7], v[156:159], v[200:203], v[4:7]
	v_mfma_f32_16x16x32_bf16 v[0:3], v[164:167], v[200:203], v[0:3]
	v_mfma_f32_16x16x32_bf16 v[52:55], v[160:163], v[176:179], v[52:55]
	v_mfma_f32_16x16x32_bf16 v[48:51], v[168:171], v[176:179], v[48:51]
	v_mfma_f32_16x16x32_bf16 v[36:39], v[160:163], v[184:187], v[36:39]
	v_mfma_f32_16x16x32_bf16 v[32:35], v[168:171], v[184:187], v[32:35]
	v_mfma_f32_16x16x32_bf16 v[20:23], v[160:163], v[192:195], v[20:23]
	v_mfma_f32_16x16x32_bf16 v[16:19], v[168:171], v[192:195], v[16:19]
	v_mfma_f32_16x16x32_bf16 v[4:7], v[160:163], v[204:207], v[4:7]
	v_mfma_f32_16x16x32_bf16 v[0:3], v[168:171], v[204:207], v[0:3]
	s_setprio 0
	s_barrier
	s_add_u32 s30, s30, 0x100
	s_addc_u32 s31, s31, 0
	s_add_u32 s29, s29, 0x100
	s_addc_u32 s71, s71, 0
	s_cmp_ge_i32 s72, s58
	s_mov_b32 s34, s72
	s_cbranch_scc0 .LBB0_1480
